# quadrant K-loops: LDS fragment reads issued before the LDS-DMA staging so their latency overlaps the staging issue
# speedup vs baseline: 1.0103x; 1.0094x over previous
.Lq_lin_0_k:
	v_add_u32_e32 v165, 0x10000, v162
	ds_read_b128 v[138:141], v165
	ds_read_b128 v[166:169], v165 offset:1024
	ds_read_b128 v[170:173], v165 offset:2048
	ds_read_b128 v[174:177], v165 offset:3072
	ds_read_b128 v[206:209], v164 offset:0
	ds_read_b128 v[210:213], v164 offset:1024
	ds_read_b128 v[214:217], v164 offset:2048
	ds_read_b128 v[218:221], v164 offset:3072
	ds_read_b128 v[222:225], v164 offset:4096
	ds_read_b128 v[226:229], v164 offset:5120
	ds_read_b128 v[230:233], v164 offset:6144
	ds_read_b128 v[234:237], v164 offset:7168
	v_lshl_add_u64 v[142:143], s[74:75], 0, v[132:133]
	s_add_i32 m0, s5, 0xc000
	v_lshl_add_u64 v[160:161], s[74:75], 0, v[130:131]
	global_load_lds_dwordx4 v[142:143], off
	s_add_i32 m0, s5, 0xe000
	v_lshl_add_u64 v[178:179], s[2:3], 0, v[144:145]
	global_load_lds_dwordx4 v[160:161], off
	s_add_i32 m0, s5, 0x1c000
	v_lshl_add_u64 v[238:239], s[2:3], 0, v[128:129]
	global_load_lds_dwordx4 v[178:179], off
	s_add_i32 m0, s5, 0x1e000
	s_add_u32 s74, s74, 0x80
	s_addc_u32 s75, s75, 0
	global_load_lds_dwordx4 v[238:239], off
	s_add_u32 s2, s2, 0x80
	s_addc_u32 s3, s3, 0
	s_waitcnt vmcnt(8)
	s_waitcnt lgkmcnt(0)
	s_barrier
	s_setprio 1
	v_mfma_f32_16x16x32_bf16 v[124:127], v[138:141], v[206:209], v[124:127]
	v_mfma_f32_16x16x32_bf16 v[120:123], v[170:173], v[206:209], v[120:123]
	v_mfma_f32_16x16x32_bf16 v[108:111], v[138:141], v[214:217], v[108:111]
	v_mfma_f32_16x16x32_bf16 v[104:107], v[170:173], v[214:217], v[104:107]
	v_mfma_f32_16x16x32_bf16 v[92:95], v[138:141], v[222:225], v[92:95]
	v_mfma_f32_16x16x32_bf16 v[88:91], v[170:173], v[222:225], v[88:91]
	v_mfma_f32_16x16x32_bf16 v[76:79], v[138:141], v[230:233], v[76:79]
	v_mfma_f32_16x16x32_bf16 v[72:75], v[170:173], v[230:233], v[72:75]
	v_mfma_f32_16x16x32_bf16 v[124:127], v[166:169], v[210:213], v[124:127]
	v_mfma_f32_16x16x32_bf16 v[120:123], v[174:177], v[210:213], v[120:123]
	v_mfma_f32_16x16x32_bf16 v[108:111], v[166:169], v[218:221], v[108:111]
	v_mfma_f32_16x16x32_bf16 v[104:107], v[174:177], v[218:221], v[104:107]
	v_mfma_f32_16x16x32_bf16 v[92:95], v[166:169], v[226:229], v[92:95]
	v_mfma_f32_16x16x32_bf16 v[88:91], v[174:177], v[226:229], v[88:91]
	v_mfma_f32_16x16x32_bf16 v[76:79], v[166:169], v[234:237], v[76:79]
	v_mfma_f32_16x16x32_bf16 v[72:75], v[174:177], v[234:237], v[72:75]
	s_setprio 0
	s_barrier
	v_add_u32_e32 v165, 0x18000, v162
	ds_read_b128 v[138:141], v165
	ds_read_b128 v[166:169], v165 offset:1024
	ds_read_b128 v[170:173], v165 offset:2048
	ds_read_b128 v[174:177], v165 offset:3072
	ds_read_b128 v[206:209], v164 offset:32768
	ds_read_b128 v[210:213], v164 offset:33792
	ds_read_b128 v[214:217], v164 offset:34816
	ds_read_b128 v[218:221], v164 offset:35840
	ds_read_b128 v[222:225], v164 offset:36864
	ds_read_b128 v[226:229], v164 offset:37888
	ds_read_b128 v[230:233], v164 offset:38912
	ds_read_b128 v[234:237], v164 offset:39936
	v_lshl_add_u64 v[142:143], s[74:75], 0, v[132:133]
	s_add_i32 m0, s5, 0x0
	v_lshl_add_u64 v[160:161], s[74:75], 0, v[130:131]
	global_load_lds_dwordx4 v[142:143], off
	s_add_i32 m0, s5, 0x2000
	v_lshl_add_u64 v[178:179], s[2:3], 0, v[144:145]
	global_load_lds_dwordx4 v[160:161], off
	s_add_i32 m0, s5, 0x10000
	v_lshl_add_u64 v[238:239], s[2:3], 0, v[128:129]
	global_load_lds_dwordx4 v[178:179], off
	s_add_i32 m0, s5, 0x12000
	s_add_u32 s74, s74, 0x80
	s_addc_u32 s75, s75, 0
	global_load_lds_dwordx4 v[238:239], off
	s_add_u32 s2, s2, 0x80
	s_addc_u32 s3, s3, 0
	s_waitcnt vmcnt(8)
	s_waitcnt lgkmcnt(0)
	s_barrier
	s_setprio 1
	v_mfma_f32_16x16x32_bf16 v[124:127], v[138:141], v[206:209], v[124:127]
	v_mfma_f32_16x16x32_bf16 v[120:123], v[170:173], v[206:209], v[120:123]
	v_mfma_f32_16x16x32_bf16 v[108:111], v[138:141], v[214:217], v[108:111]
	v_mfma_f32_16x16x32_bf16 v[104:107], v[170:173], v[214:217], v[104:107]
	v_mfma_f32_16x16x32_bf16 v[92:95], v[138:141], v[222:225], v[92:95]
	v_mfma_f32_16x16x32_bf16 v[88:91], v[170:173], v[222:225], v[88:91]
	v_mfma_f32_16x16x32_bf16 v[76:79], v[138:141], v[230:233], v[76:79]
	v_mfma_f32_16x16x32_bf16 v[72:75], v[170:173], v[230:233], v[72:75]
	v_mfma_f32_16x16x32_bf16 v[124:127], v[166:169], v[210:213], v[124:127]
	v_mfma_f32_16x16x32_bf16 v[120:123], v[174:177], v[210:213], v[120:123]
	v_mfma_f32_16x16x32_bf16 v[108:111], v[166:169], v[218:221], v[108:111]
	v_mfma_f32_16x16x32_bf16 v[104:107], v[174:177], v[218:221], v[104:107]
	v_mfma_f32_16x16x32_bf16 v[92:95], v[166:169], v[226:229], v[92:95]
	v_mfma_f32_16x16x32_bf16 v[88:91], v[174:177], v[226:229], v[88:91]
	v_mfma_f32_16x16x32_bf16 v[76:79], v[166:169], v[234:237], v[76:79]
	v_mfma_f32_16x16x32_bf16 v[72:75], v[174:177], v[234:237], v[72:75]
	s_setprio 0
	s_barrier
	v_add_u32_e32 v165, 0x14000, v162
	ds_read_b128 v[138:141], v165
	ds_read_b128 v[166:169], v165 offset:1024
	ds_read_b128 v[170:173], v165 offset:2048
	ds_read_b128 v[174:177], v165 offset:3072
	ds_read_b128 v[206:209], v164 offset:16384
	ds_read_b128 v[210:213], v164 offset:17408
	ds_read_b128 v[214:217], v164 offset:18432
	ds_read_b128 v[218:221], v164 offset:19456
	ds_read_b128 v[222:225], v164 offset:20480
	ds_read_b128 v[226:229], v164 offset:21504
	ds_read_b128 v[230:233], v164 offset:22528
	ds_read_b128 v[234:237], v164 offset:23552
	v_lshl_add_u64 v[142:143], s[74:75], 0, v[132:133]
	s_add_i32 m0, s5, 0x8000
	v_lshl_add_u64 v[160:161], s[74:75], 0, v[130:131]
	global_load_lds_dwordx4 v[142:143], off
	s_add_i32 m0, s5, 0xa000
	v_lshl_add_u64 v[178:179], s[2:3], 0, v[144:145]
	global_load_lds_dwordx4 v[160:161], off
	s_add_i32 m0, s5, 0x18000
	v_lshl_add_u64 v[238:239], s[2:3], 0, v[128:129]
	global_load_lds_dwordx4 v[178:179], off
	s_add_i32 m0, s5, 0x1a000
	s_add_u32 s74, s74, 0x80
	s_addc_u32 s75, s75, 0
	global_load_lds_dwordx4 v[238:239], off
	s_add_u32 s2, s2, 0x80
	s_addc_u32 s3, s3, 0
	s_waitcnt vmcnt(8)
	s_waitcnt lgkmcnt(0)
	s_barrier
	s_setprio 1
	v_mfma_f32_16x16x32_bf16 v[124:127], v[138:141], v[206:209], v[124:127]
	v_mfma_f32_16x16x32_bf16 v[120:123], v[170:173], v[206:209], v[120:123]
	v_mfma_f32_16x16x32_bf16 v[108:111], v[138:141], v[214:217], v[108:111]
	v_mfma_f32_16x16x32_bf16 v[104:107], v[170:173], v[214:217], v[104:107]
	v_mfma_f32_16x16x32_bf16 v[92:95], v[138:141], v[222:225], v[92:95]
	v_mfma_f32_16x16x32_bf16 v[88:91], v[170:173], v[222:225], v[88:91]
	v_mfma_f32_16x16x32_bf16 v[76:79], v[138:141], v[230:233], v[76:79]
	v_mfma_f32_16x16x32_bf16 v[72:75], v[170:173], v[230:233], v[72:75]
	v_mfma_f32_16x16x32_bf16 v[124:127], v[166:169], v[210:213], v[124:127]
	v_mfma_f32_16x16x32_bf16 v[120:123], v[174:177], v[210:213], v[120:123]
	v_mfma_f32_16x16x32_bf16 v[108:111], v[166:169], v[218:221], v[108:111]
	v_mfma_f32_16x16x32_bf16 v[104:107], v[174:177], v[218:221], v[104:107]
	v_mfma_f32_16x16x32_bf16 v[92:95], v[166:169], v[226:229], v[92:95]
	v_mfma_f32_16x16x32_bf16 v[88:91], v[174:177], v[226:229], v[88:91]
	v_mfma_f32_16x16x32_bf16 v[76:79], v[166:169], v[234:237], v[76:79]
	v_mfma_f32_16x16x32_bf16 v[72:75], v[174:177], v[234:237], v[72:75]
	s_setprio 0
	s_barrier
	v_add_u32_e32 v165, 0x1c000, v162
	ds_read_b128 v[138:141], v165
	ds_read_b128 v[166:169], v165 offset:1024
	ds_read_b128 v[170:173], v165 offset:2048
	ds_read_b128 v[174:177], v165 offset:3072
	ds_read_b128 v[206:209], v164 offset:49152
	ds_read_b128 v[210:213], v164 offset:50176
	ds_read_b128 v[214:217], v164 offset:51200
	ds_read_b128 v[218:221], v164 offset:52224
	ds_read_b128 v[222:225], v164 offset:53248
	ds_read_b128 v[226:229], v164 offset:54272
	ds_read_b128 v[230:233], v164 offset:55296
	ds_read_b128 v[234:237], v164 offset:56320
	v_lshl_add_u64 v[142:143], s[74:75], 0, v[132:133]
	s_add_i32 m0, s5, 0x4000
	v_lshl_add_u64 v[160:161], s[74:75], 0, v[130:131]
	global_load_lds_dwordx4 v[142:143], off
	s_add_i32 m0, s5, 0x6000
	v_lshl_add_u64 v[178:179], s[2:3], 0, v[144:145]
	global_load_lds_dwordx4 v[160:161], off
	s_add_i32 m0, s5, 0x14000
	v_lshl_add_u64 v[238:239], s[2:3], 0, v[128:129]
	global_load_lds_dwordx4 v[178:179], off
	s_add_i32 m0, s5, 0x16000
	s_add_u32 s74, s74, 0x80
	s_addc_u32 s75, s75, 0
	global_load_lds_dwordx4 v[238:239], off
	s_add_u32 s2, s2, 0x80
	s_addc_u32 s3, s3, 0
	s_waitcnt vmcnt(8)
	s_waitcnt lgkmcnt(0)
	s_barrier
	s_setprio 1
	v_mfma_f32_16x16x32_bf16 v[124:127], v[138:141], v[206:209], v[124:127]
	v_mfma_f32_16x16x32_bf16 v[120:123], v[170:173], v[206:209], v[120:123]
	v_mfma_f32_16x16x32_bf16 v[108:111], v[138:141], v[214:217], v[108:111]
	v_mfma_f32_16x16x32_bf16 v[104:107], v[170:173], v[214:217], v[104:107]
	v_mfma_f32_16x16x32_bf16 v[92:95], v[138:141], v[222:225], v[92:95]
	v_mfma_f32_16x16x32_bf16 v[88:91], v[170:173], v[222:225], v[88:91]
	v_mfma_f32_16x16x32_bf16 v[76:79], v[138:141], v[230:233], v[76:79]
	v_mfma_f32_16x16x32_bf16 v[72:75], v[170:173], v[230:233], v[72:75]
	v_mfma_f32_16x16x32_bf16 v[124:127], v[166:169], v[210:213], v[124:127]
	v_mfma_f32_16x16x32_bf16 v[120:123], v[174:177], v[210:213], v[120:123]
	v_mfma_f32_16x16x32_bf16 v[108:111], v[166:169], v[218:221], v[108:111]
	v_mfma_f32_16x16x32_bf16 v[104:107], v[174:177], v[218:221], v[104:107]
	v_mfma_f32_16x16x32_bf16 v[92:95], v[166:169], v[226:229], v[92:95]
	v_mfma_f32_16x16x32_bf16 v[88:91], v[174:177], v[226:229], v[88:91]
	v_mfma_f32_16x16x32_bf16 v[76:79], v[166:169], v[234:237], v[76:79]
	v_mfma_f32_16x16x32_bf16 v[72:75], v[174:177], v[234:237], v[72:75]
	s_setprio 0
	s_barrier
	s_add_i32 s8, s8, 1
	s_cmp_lt_u32 s8, 7
	s_cbranch_scc1 .Lq_lin_0_k
	v_add_u32_e32 v165, 0x10000, v162
	ds_read_b128 v[138:141], v165
	ds_read_b128 v[166:169], v165 offset:1024
	ds_read_b128 v[170:173], v165 offset:2048
	ds_read_b128 v[174:177], v165 offset:3072
	ds_read_b128 v[206:209], v164 offset:0
	ds_read_b128 v[210:213], v164 offset:1024
	ds_read_b128 v[214:217], v164 offset:2048
	ds_read_b128 v[218:221], v164 offset:3072
	ds_read_b128 v[222:225], v164 offset:4096
	ds_read_b128 v[226:229], v164 offset:5120
	ds_read_b128 v[230:233], v164 offset:6144
	ds_read_b128 v[234:237], v164 offset:7168
	v_lshl_add_u64 v[142:143], s[74:75], 0, v[132:133]
	s_add_i32 m0, s5, 0xc000
	v_lshl_add_u64 v[160:161], s[74:75], 0, v[130:131]
	global_load_lds_dwordx4 v[142:143], off
	s_add_i32 m0, s5, 0xe000
	v_lshl_add_u64 v[178:179], s[2:3], 0, v[144:145]
	global_load_lds_dwordx4 v[160:161], off
	s_add_i32 m0, s5, 0x1c000
	v_lshl_add_u64 v[238:239], s[2:3], 0, v[128:129]
	global_load_lds_dwordx4 v[178:179], off
	s_add_i32 m0, s5, 0x1e000
	s_add_u32 s74, s74, 0x80
	s_addc_u32 s75, s75, 0
	global_load_lds_dwordx4 v[238:239], off
	s_add_u32 s2, s2, 0x80
	s_addc_u32 s3, s3, 0
	s_waitcnt vmcnt(8)
	s_waitcnt lgkmcnt(0)
	s_barrier
	s_setprio 1
	v_mfma_f32_16x16x32_bf16 v[124:127], v[138:141], v[206:209], v[124:127]
	v_mfma_f32_16x16x32_bf16 v[120:123], v[170:173], v[206:209], v[120:123]
	v_mfma_f32_16x16x32_bf16 v[108:111], v[138:141], v[214:217], v[108:111]
	v_mfma_f32_16x16x32_bf16 v[104:107], v[170:173], v[214:217], v[104:107]
	v_mfma_f32_16x16x32_bf16 v[92:95], v[138:141], v[222:225], v[92:95]
	v_mfma_f32_16x16x32_bf16 v[88:91], v[170:173], v[222:225], v[88:91]
	v_mfma_f32_16x16x32_bf16 v[76:79], v[138:141], v[230:233], v[76:79]
	v_mfma_f32_16x16x32_bf16 v[72:75], v[170:173], v[230:233], v[72:75]
	v_mfma_f32_16x16x32_bf16 v[124:127], v[166:169], v[210:213], v[124:127]
	v_mfma_f32_16x16x32_bf16 v[120:123], v[174:177], v[210:213], v[120:123]
	v_mfma_f32_16x16x32_bf16 v[108:111], v[166:169], v[218:221], v[108:111]
	v_mfma_f32_16x16x32_bf16 v[104:107], v[174:177], v[218:221], v[104:107]
	v_mfma_f32_16x16x32_bf16 v[92:95], v[166:169], v[226:229], v[92:95]
	v_mfma_f32_16x16x32_bf16 v[88:91], v[174:177], v[226:229], v[88:91]
	v_mfma_f32_16x16x32_bf16 v[76:79], v[166:169], v[234:237], v[76:79]
	v_mfma_f32_16x16x32_bf16 v[72:75], v[174:177], v[234:237], v[72:75]
	s_setprio 0
	s_barrier
	v_add_u32_e32 v165, 0x18000, v162
	ds_read_b128 v[138:141], v165
	ds_read_b128 v[166:169], v165 offset:1024
	ds_read_b128 v[170:173], v165 offset:2048
	ds_read_b128 v[174:177], v165 offset:3072
	ds_read_b128 v[206:209], v164 offset:32768
	ds_read_b128 v[210:213], v164 offset:33792
	ds_read_b128 v[214:217], v164 offset:34816
	ds_read_b128 v[218:221], v164 offset:35840
	ds_read_b128 v[222:225], v164 offset:36864
	ds_read_b128 v[226:229], v164 offset:37888
	ds_read_b128 v[230:233], v164 offset:38912
	ds_read_b128 v[234:237], v164 offset:39936
	s_waitcnt vmcnt(4)
	s_waitcnt lgkmcnt(0)
	s_barrier
	s_setprio 1
	v_mfma_f32_16x16x32_bf16 v[124:127], v[138:141], v[206:209], v[124:127]
	v_mfma_f32_16x16x32_bf16 v[120:123], v[170:173], v[206:209], v[120:123]
	v_mfma_f32_16x16x32_bf16 v[108:111], v[138:141], v[214:217], v[108:111]
	v_mfma_f32_16x16x32_bf16 v[104:107], v[170:173], v[214:217], v[104:107]
	v_mfma_f32_16x16x32_bf16 v[92:95], v[138:141], v[222:225], v[92:95]
	v_mfma_f32_16x16x32_bf16 v[88:91], v[170:173], v[222:225], v[88:91]
	v_mfma_f32_16x16x32_bf16 v[76:79], v[138:141], v[230:233], v[76:79]
	v_mfma_f32_16x16x32_bf16 v[72:75], v[170:173], v[230:233], v[72:75]
	v_mfma_f32_16x16x32_bf16 v[124:127], v[166:169], v[210:213], v[124:127]
	v_mfma_f32_16x16x32_bf16 v[120:123], v[174:177], v[210:213], v[120:123]
	v_mfma_f32_16x16x32_bf16 v[108:111], v[166:169], v[218:221], v[108:111]
	v_mfma_f32_16x16x32_bf16 v[104:107], v[174:177], v[218:221], v[104:107]
	v_mfma_f32_16x16x32_bf16 v[92:95], v[166:169], v[226:229], v[92:95]
	v_mfma_f32_16x16x32_bf16 v[88:91], v[174:177], v[226:229], v[88:91]
	v_mfma_f32_16x16x32_bf16 v[76:79], v[166:169], v[234:237], v[76:79]
	v_mfma_f32_16x16x32_bf16 v[72:75], v[174:177], v[234:237], v[72:75]
	s_setprio 0
	s_barrier
	v_add_u32_e32 v165, 0x14000, v162
	ds_read_b128 v[138:141], v165
	ds_read_b128 v[166:169], v165 offset:1024
	ds_read_b128 v[170:173], v165 offset:2048
	ds_read_b128 v[174:177], v165 offset:3072
	ds_read_b128 v[206:209], v164 offset:16384
	ds_read_b128 v[210:213], v164 offset:17408
	ds_read_b128 v[214:217], v164 offset:18432
	ds_read_b128 v[218:221], v164 offset:19456
	ds_read_b128 v[222:225], v164 offset:20480
	ds_read_b128 v[226:229], v164 offset:21504
	ds_read_b128 v[230:233], v164 offset:22528
	ds_read_b128 v[234:237], v164 offset:23552
	s_waitcnt vmcnt(0)
	s_waitcnt lgkmcnt(0)
	s_barrier
	s_setprio 1
	v_mfma_f32_16x16x32_bf16 v[124:127], v[138:141], v[206:209], v[124:127]
	v_mfma_f32_16x16x32_bf16 v[120:123], v[170:173], v[206:209], v[120:123]
	v_mfma_f32_16x16x32_bf16 v[108:111], v[138:141], v[214:217], v[108:111]
	v_mfma_f32_16x16x32_bf16 v[104:107], v[170:173], v[214:217], v[104:107]
	v_mfma_f32_16x16x32_bf16 v[92:95], v[138:141], v[222:225], v[92:95]
	v_mfma_f32_16x16x32_bf16 v[88:91], v[170:173], v[222:225], v[88:91]
	v_mfma_f32_16x16x32_bf16 v[76:79], v[138:141], v[230:233], v[76:79]
	v_mfma_f32_16x16x32_bf16 v[72:75], v[170:173], v[230:233], v[72:75]
	v_mfma_f32_16x16x32_bf16 v[124:127], v[166:169], v[210:213], v[124:127]
	v_mfma_f32_16x16x32_bf16 v[120:123], v[174:177], v[210:213], v[120:123]
	v_mfma_f32_16x16x32_bf16 v[108:111], v[166:169], v[218:221], v[108:111]
	v_mfma_f32_16x16x32_bf16 v[104:107], v[174:177], v[218:221], v[104:107]
	v_mfma_f32_16x16x32_bf16 v[92:95], v[166:169], v[226:229], v[92:95]
	v_mfma_f32_16x16x32_bf16 v[88:91], v[174:177], v[226:229], v[88:91]
	v_mfma_f32_16x16x32_bf16 v[76:79], v[166:169], v[234:237], v[76:79]
	v_mfma_f32_16x16x32_bf16 v[72:75], v[174:177], v[234:237], v[72:75]
	s_setprio 0
	s_barrier
	v_add_u32_e32 v165, 0x1c000, v162
	ds_read_b128 v[138:141], v165
	ds_read_b128 v[166:169], v165 offset:1024
	ds_read_b128 v[170:173], v165 offset:2048
	ds_read_b128 v[174:177], v165 offset:3072
	ds_read_b128 v[206:209], v164 offset:49152
	ds_read_b128 v[210:213], v164 offset:50176
	ds_read_b128 v[214:217], v164 offset:51200
	ds_read_b128 v[218:221], v164 offset:52224
	ds_read_b128 v[222:225], v164 offset:53248
	ds_read_b128 v[226:229], v164 offset:54272
	ds_read_b128 v[230:233], v164 offset:55296
	ds_read_b128 v[234:237], v164 offset:56320
	s_waitcnt lgkmcnt(0)
	s_barrier
	s_setprio 1
	v_mfma_f32_16x16x32_bf16 v[124:127], v[138:141], v[206:209], v[124:127]
	v_mfma_f32_16x16x32_bf16 v[120:123], v[170:173], v[206:209], v[120:123]
	v_mfma_f32_16x16x32_bf16 v[108:111], v[138:141], v[214:217], v[108:111]
	v_mfma_f32_16x16x32_bf16 v[104:107], v[170:173], v[214:217], v[104:107]
	v_mfma_f32_16x16x32_bf16 v[92:95], v[138:141], v[222:225], v[92:95]
	v_mfma_f32_16x16x32_bf16 v[88:91], v[170:173], v[222:225], v[88:91]
	v_mfma_f32_16x16x32_bf16 v[76:79], v[138:141], v[230:233], v[76:79]
	v_mfma_f32_16x16x32_bf16 v[72:75], v[170:173], v[230:233], v[72:75]
	v_mfma_f32_16x16x32_bf16 v[124:127], v[166:169], v[210:213], v[124:127]
	v_mfma_f32_16x16x32_bf16 v[120:123], v[174:177], v[210:213], v[120:123]
	v_mfma_f32_16x16x32_bf16 v[108:111], v[166:169], v[218:221], v[108:111]
	v_mfma_f32_16x16x32_bf16 v[104:107], v[174:177], v[218:221], v[104:107]
	v_mfma_f32_16x16x32_bf16 v[92:95], v[166:169], v[226:229], v[92:95]
	v_mfma_f32_16x16x32_bf16 v[88:91], v[174:177], v[226:229], v[88:91]
	v_mfma_f32_16x16x32_bf16 v[76:79], v[166:169], v[234:237], v[76:79]
	v_mfma_f32_16x16x32_bf16 v[72:75], v[174:177], v[234:237], v[72:75]
	s_setprio 0
	s_barrier
	s_branch .Lq_lin_exit

.Lq_lin_1_k:
	v_add_u32_e32 v165, 0x14000, v162
	ds_read_b128 v[190:193], v165
	ds_read_b128 v[194:197], v165 offset:1024
	ds_read_b128 v[198:201], v165 offset:2048
	ds_read_b128 v[202:205], v165 offset:3072
	ds_read_b128 v[206:209], v164 offset:0
	ds_read_b128 v[210:213], v164 offset:1024
	ds_read_b128 v[214:217], v164 offset:2048
	ds_read_b128 v[218:221], v164 offset:3072
	ds_read_b128 v[222:225], v164 offset:4096
	ds_read_b128 v[226:229], v164 offset:5120
	ds_read_b128 v[230:233], v164 offset:6144
	ds_read_b128 v[234:237], v164 offset:7168
	v_lshl_add_u64 v[142:143], s[74:75], 0, v[132:133]
	s_add_i32 m0, s5, 0xc000
	v_lshl_add_u64 v[160:161], s[74:75], 0, v[130:131]
	global_load_lds_dwordx4 v[142:143], off
	s_add_i32 m0, s5, 0xe000
	v_lshl_add_u64 v[178:179], s[2:3], 0, v[144:145]
	global_load_lds_dwordx4 v[160:161], off
	s_add_i32 m0, s5, 0x18000
	v_lshl_add_u64 v[238:239], s[2:3], 0, v[128:129]
	global_load_lds_dwordx4 v[178:179], off
	s_add_i32 m0, s5, 0x1a000
	s_add_u32 s74, s74, 0x80
	s_addc_u32 s75, s75, 0
	global_load_lds_dwordx4 v[238:239], off
	s_add_u32 s2, s2, 0x80
	s_addc_u32 s3, s3, 0
	s_waitcnt vmcnt(8)
	s_waitcnt lgkmcnt(0)
	s_barrier
	s_setprio 1
	v_mfma_f32_16x16x32_bf16 v[116:119], v[190:193], v[206:209], v[116:119]
	v_mfma_f32_16x16x32_bf16 v[112:115], v[198:201], v[206:209], v[112:115]
	v_mfma_f32_16x16x32_bf16 v[100:103], v[190:193], v[214:217], v[100:103]
	v_mfma_f32_16x16x32_bf16 v[96:99], v[198:201], v[214:217], v[96:99]
	v_mfma_f32_16x16x32_bf16 v[84:87], v[190:193], v[222:225], v[84:87]
	v_mfma_f32_16x16x32_bf16 v[80:83], v[198:201], v[222:225], v[80:83]
	v_mfma_f32_16x16x32_bf16 v[68:71], v[190:193], v[230:233], v[68:71]
	v_mfma_f32_16x16x32_bf16 v[64:67], v[198:201], v[230:233], v[64:67]
	v_mfma_f32_16x16x32_bf16 v[116:119], v[194:197], v[210:213], v[116:119]
	v_mfma_f32_16x16x32_bf16 v[112:115], v[202:205], v[210:213], v[112:115]
	v_mfma_f32_16x16x32_bf16 v[100:103], v[194:197], v[218:221], v[100:103]
	v_mfma_f32_16x16x32_bf16 v[96:99], v[202:205], v[218:221], v[96:99]
	v_mfma_f32_16x16x32_bf16 v[84:87], v[194:197], v[226:229], v[84:87]
	v_mfma_f32_16x16x32_bf16 v[80:83], v[202:205], v[226:229], v[80:83]
	v_mfma_f32_16x16x32_bf16 v[68:71], v[194:197], v[234:237], v[68:71]
	v_mfma_f32_16x16x32_bf16 v[64:67], v[202:205], v[234:237], v[64:67]
	s_setprio 0
	s_barrier
	v_add_u32_e32 v165, 0x1c000, v162
	ds_read_b128 v[190:193], v165
	ds_read_b128 v[194:197], v165 offset:1024
	ds_read_b128 v[198:201], v165 offset:2048
	ds_read_b128 v[202:205], v165 offset:3072
	ds_read_b128 v[206:209], v164 offset:32768
	ds_read_b128 v[210:213], v164 offset:33792
	ds_read_b128 v[214:217], v164 offset:34816
	ds_read_b128 v[218:221], v164 offset:35840
	ds_read_b128 v[222:225], v164 offset:36864
	ds_read_b128 v[226:229], v164 offset:37888
	ds_read_b128 v[230:233], v164 offset:38912
	ds_read_b128 v[234:237], v164 offset:39936
	v_lshl_add_u64 v[142:143], s[74:75], 0, v[132:133]
	s_add_i32 m0, s5, 0x0
	v_lshl_add_u64 v[160:161], s[74:75], 0, v[130:131]
	global_load_lds_dwordx4 v[142:143], off
	s_add_i32 m0, s5, 0x2000
	v_lshl_add_u64 v[178:179], s[2:3], 0, v[144:145]
	global_load_lds_dwordx4 v[160:161], off
	s_add_i32 m0, s5, 0x14000
	v_lshl_add_u64 v[238:239], s[2:3], 0, v[128:129]
	global_load_lds_dwordx4 v[178:179], off
	s_add_i32 m0, s5, 0x16000
	s_add_u32 s74, s74, 0x80
	s_addc_u32 s75, s75, 0
	global_load_lds_dwordx4 v[238:239], off
	s_add_u32 s2, s2, 0x80
	s_addc_u32 s3, s3, 0
	s_waitcnt vmcnt(8)
	s_waitcnt lgkmcnt(0)
	s_barrier
	s_setprio 1
	v_mfma_f32_16x16x32_bf16 v[116:119], v[190:193], v[206:209], v[116:119]
	v_mfma_f32_16x16x32_bf16 v[112:115], v[198:201], v[206:209], v[112:115]
	v_mfma_f32_16x16x32_bf16 v[100:103], v[190:193], v[214:217], v[100:103]
	v_mfma_f32_16x16x32_bf16 v[96:99], v[198:201], v[214:217], v[96:99]
	v_mfma_f32_16x16x32_bf16 v[84:87], v[190:193], v[222:225], v[84:87]
	v_mfma_f32_16x16x32_bf16 v[80:83], v[198:201], v[222:225], v[80:83]
	v_mfma_f32_16x16x32_bf16 v[68:71], v[190:193], v[230:233], v[68:71]
	v_mfma_f32_16x16x32_bf16 v[64:67], v[198:201], v[230:233], v[64:67]
	v_mfma_f32_16x16x32_bf16 v[116:119], v[194:197], v[210:213], v[116:119]
	v_mfma_f32_16x16x32_bf16 v[112:115], v[202:205], v[210:213], v[112:115]
	v_mfma_f32_16x16x32_bf16 v[100:103], v[194:197], v[218:221], v[100:103]
	v_mfma_f32_16x16x32_bf16 v[96:99], v[202:205], v[218:221], v[96:99]
	v_mfma_f32_16x16x32_bf16 v[84:87], v[194:197], v[226:229], v[84:87]
	v_mfma_f32_16x16x32_bf16 v[80:83], v[202:205], v[226:229], v[80:83]
	v_mfma_f32_16x16x32_bf16 v[68:71], v[194:197], v[234:237], v[68:71]
	v_mfma_f32_16x16x32_bf16 v[64:67], v[202:205], v[234:237], v[64:67]
	s_setprio 0
	s_barrier
	v_add_u32_e32 v165, 0x10000, v162
	ds_read_b128 v[190:193], v165
	ds_read_b128 v[194:197], v165 offset:1024
	ds_read_b128 v[198:201], v165 offset:2048
	ds_read_b128 v[202:205], v165 offset:3072
	ds_read_b128 v[206:209], v164 offset:16384
	ds_read_b128 v[210:213], v164 offset:17408
	ds_read_b128 v[214:217], v164 offset:18432
	ds_read_b128 v[218:221], v164 offset:19456
	ds_read_b128 v[222:225], v164 offset:20480
	ds_read_b128 v[226:229], v164 offset:21504
	ds_read_b128 v[230:233], v164 offset:22528
	ds_read_b128 v[234:237], v164 offset:23552
	v_lshl_add_u64 v[142:143], s[74:75], 0, v[132:133]
	s_add_i32 m0, s5, 0x8000
	v_lshl_add_u64 v[160:161], s[74:75], 0, v[130:131]
	global_load_lds_dwordx4 v[142:143], off
	s_add_i32 m0, s5, 0xa000
	v_lshl_add_u64 v[178:179], s[2:3], 0, v[144:145]
	global_load_lds_dwordx4 v[160:161], off
	s_add_i32 m0, s5, 0x1c000
	v_lshl_add_u64 v[238:239], s[2:3], 0, v[128:129]
	global_load_lds_dwordx4 v[178:179], off
	s_add_i32 m0, s5, 0x1e000
	s_add_u32 s74, s74, 0x80
	s_addc_u32 s75, s75, 0
	global_load_lds_dwordx4 v[238:239], off
	s_add_u32 s2, s2, 0x80
	s_addc_u32 s3, s3, 0
	s_waitcnt vmcnt(8)
	s_waitcnt lgkmcnt(0)
	s_barrier
	s_setprio 1
	v_mfma_f32_16x16x32_bf16 v[116:119], v[190:193], v[206:209], v[116:119]
	v_mfma_f32_16x16x32_bf16 v[112:115], v[198:201], v[206:209], v[112:115]
	v_mfma_f32_16x16x32_bf16 v[100:103], v[190:193], v[214:217], v[100:103]
	v_mfma_f32_16x16x32_bf16 v[96:99], v[198:201], v[214:217], v[96:99]
	v_mfma_f32_16x16x32_bf16 v[84:87], v[190:193], v[222:225], v[84:87]
	v_mfma_f32_16x16x32_bf16 v[80:83], v[198:201], v[222:225], v[80:83]
	v_mfma_f32_16x16x32_bf16 v[68:71], v[190:193], v[230:233], v[68:71]
	v_mfma_f32_16x16x32_bf16 v[64:67], v[198:201], v[230:233], v[64:67]
	v_mfma_f32_16x16x32_bf16 v[116:119], v[194:197], v[210:213], v[116:119]
	v_mfma_f32_16x16x32_bf16 v[112:115], v[202:205], v[210:213], v[112:115]
	v_mfma_f32_16x16x32_bf16 v[100:103], v[194:197], v[218:221], v[100:103]
	v_mfma_f32_16x16x32_bf16 v[96:99], v[202:205], v[218:221], v[96:99]
	v_mfma_f32_16x16x32_bf16 v[84:87], v[194:197], v[226:229], v[84:87]
	v_mfma_f32_16x16x32_bf16 v[80:83], v[202:205], v[226:229], v[80:83]
	v_mfma_f32_16x16x32_bf16 v[68:71], v[194:197], v[234:237], v[68:71]
	v_mfma_f32_16x16x32_bf16 v[64:67], v[202:205], v[234:237], v[64:67]
	s_setprio 0
	s_barrier
	v_add_u32_e32 v165, 0x18000, v162
	ds_read_b128 v[190:193], v165
	ds_read_b128 v[194:197], v165 offset:1024
	ds_read_b128 v[198:201], v165 offset:2048
	ds_read_b128 v[202:205], v165 offset:3072
	ds_read_b128 v[206:209], v164 offset:49152
	ds_read_b128 v[210:213], v164 offset:50176
	ds_read_b128 v[214:217], v164 offset:51200
	ds_read_b128 v[218:221], v164 offset:52224
	ds_read_b128 v[222:225], v164 offset:53248
	ds_read_b128 v[226:229], v164 offset:54272
	ds_read_b128 v[230:233], v164 offset:55296
	ds_read_b128 v[234:237], v164 offset:56320
	v_lshl_add_u64 v[142:143], s[74:75], 0, v[132:133]
	s_add_i32 m0, s5, 0x4000
	v_lshl_add_u64 v[160:161], s[74:75], 0, v[130:131]
	global_load_lds_dwordx4 v[142:143], off
	s_add_i32 m0, s5, 0x6000
	v_lshl_add_u64 v[178:179], s[2:3], 0, v[144:145]
	global_load_lds_dwordx4 v[160:161], off
	s_add_i32 m0, s5, 0x10000
	v_lshl_add_u64 v[238:239], s[2:3], 0, v[128:129]
	global_load_lds_dwordx4 v[178:179], off
	s_add_i32 m0, s5, 0x12000
	s_add_u32 s74, s74, 0x80
	s_addc_u32 s75, s75, 0
	global_load_lds_dwordx4 v[238:239], off
	s_add_u32 s2, s2, 0x80
	s_addc_u32 s3, s3, 0
	s_waitcnt vmcnt(8)
	s_waitcnt lgkmcnt(0)
	s_barrier
	s_setprio 1
	v_mfma_f32_16x16x32_bf16 v[116:119], v[190:193], v[206:209], v[116:119]
	v_mfma_f32_16x16x32_bf16 v[112:115], v[198:201], v[206:209], v[112:115]
	v_mfma_f32_16x16x32_bf16 v[100:103], v[190:193], v[214:217], v[100:103]
	v_mfma_f32_16x16x32_bf16 v[96:99], v[198:201], v[214:217], v[96:99]
	v_mfma_f32_16x16x32_bf16 v[84:87], v[190:193], v[222:225], v[84:87]
	v_mfma_f32_16x16x32_bf16 v[80:83], v[198:201], v[222:225], v[80:83]
	v_mfma_f32_16x16x32_bf16 v[68:71], v[190:193], v[230:233], v[68:71]
	v_mfma_f32_16x16x32_bf16 v[64:67], v[198:201], v[230:233], v[64:67]
	v_mfma_f32_16x16x32_bf16 v[116:119], v[194:197], v[210:213], v[116:119]
	v_mfma_f32_16x16x32_bf16 v[112:115], v[202:205], v[210:213], v[112:115]
	v_mfma_f32_16x16x32_bf16 v[100:103], v[194:197], v[218:221], v[100:103]
	v_mfma_f32_16x16x32_bf16 v[96:99], v[202:205], v[218:221], v[96:99]
	v_mfma_f32_16x16x32_bf16 v[84:87], v[194:197], v[226:229], v[84:87]
	v_mfma_f32_16x16x32_bf16 v[80:83], v[202:205], v[226:229], v[80:83]
	v_mfma_f32_16x16x32_bf16 v[68:71], v[194:197], v[234:237], v[68:71]
	v_mfma_f32_16x16x32_bf16 v[64:67], v[202:205], v[234:237], v[64:67]
	s_setprio 0
	s_barrier
	s_add_i32 s8, s8, 1
	s_cmp_lt_u32 s8, 7
	s_cbranch_scc1 .Lq_lin_1_k
	v_add_u32_e32 v165, 0x14000, v162
	ds_read_b128 v[190:193], v165
	ds_read_b128 v[194:197], v165 offset:1024
	ds_read_b128 v[198:201], v165 offset:2048
	ds_read_b128 v[202:205], v165 offset:3072
	ds_read_b128 v[206:209], v164 offset:0
	ds_read_b128 v[210:213], v164 offset:1024
	ds_read_b128 v[214:217], v164 offset:2048
	ds_read_b128 v[218:221], v164 offset:3072
	ds_read_b128 v[222:225], v164 offset:4096
	ds_read_b128 v[226:229], v164 offset:5120
	ds_read_b128 v[230:233], v164 offset:6144
	ds_read_b128 v[234:237], v164 offset:7168
	v_lshl_add_u64 v[142:143], s[74:75], 0, v[132:133]
	s_add_i32 m0, s5, 0xc000
	v_lshl_add_u64 v[160:161], s[74:75], 0, v[130:131]
	global_load_lds_dwordx4 v[142:143], off
	s_add_i32 m0, s5, 0xe000
	v_lshl_add_u64 v[178:179], s[2:3], 0, v[144:145]
	global_load_lds_dwordx4 v[160:161], off
	s_add_i32 m0, s5, 0x18000
	v_lshl_add_u64 v[238:239], s[2:3], 0, v[128:129]
	global_load_lds_dwordx4 v[178:179], off
	s_add_i32 m0, s5, 0x1a000
	s_add_u32 s74, s74, 0x80
	s_addc_u32 s75, s75, 0
	global_load_lds_dwordx4 v[238:239], off
	s_add_u32 s2, s2, 0x80
	s_addc_u32 s3, s3, 0
	s_waitcnt vmcnt(8)
	s_waitcnt lgkmcnt(0)
	s_barrier
	s_setprio 1
	v_mfma_f32_16x16x32_bf16 v[116:119], v[190:193], v[206:209], v[116:119]
	v_mfma_f32_16x16x32_bf16 v[112:115], v[198:201], v[206:209], v[112:115]
	v_mfma_f32_16x16x32_bf16 v[100:103], v[190:193], v[214:217], v[100:103]
	v_mfma_f32_16x16x32_bf16 v[96:99], v[198:201], v[214:217], v[96:99]
	v_mfma_f32_16x16x32_bf16 v[84:87], v[190:193], v[222:225], v[84:87]
	v_mfma_f32_16x16x32_bf16 v[80:83], v[198:201], v[222:225], v[80:83]
	v_mfma_f32_16x16x32_bf16 v[68:71], v[190:193], v[230:233], v[68:71]
	v_mfma_f32_16x16x32_bf16 v[64:67], v[198:201], v[230:233], v[64:67]
	v_mfma_f32_16x16x32_bf16 v[116:119], v[194:197], v[210:213], v[116:119]
	v_mfma_f32_16x16x32_bf16 v[112:115], v[202:205], v[210:213], v[112:115]
	v_mfma_f32_16x16x32_bf16 v[100:103], v[194:197], v[218:221], v[100:103]
	v_mfma_f32_16x16x32_bf16 v[96:99], v[202:205], v[218:221], v[96:99]
	v_mfma_f32_16x16x32_bf16 v[84:87], v[194:197], v[226:229], v[84:87]
	v_mfma_f32_16x16x32_bf16 v[80:83], v[202:205], v[226:229], v[80:83]
	v_mfma_f32_16x16x32_bf16 v[68:71], v[194:197], v[234:237], v[68:71]
	v_mfma_f32_16x16x32_bf16 v[64:67], v[202:205], v[234:237], v[64:67]
	s_setprio 0
	s_barrier
	v_add_u32_e32 v165, 0x1c000, v162
	ds_read_b128 v[190:193], v165
	ds_read_b128 v[194:197], v165 offset:1024
	ds_read_b128 v[198:201], v165 offset:2048
	ds_read_b128 v[202:205], v165 offset:3072
	ds_read_b128 v[206:209], v164 offset:32768
	ds_read_b128 v[210:213], v164 offset:33792
	ds_read_b128 v[214:217], v164 offset:34816
	ds_read_b128 v[218:221], v164 offset:35840
	ds_read_b128 v[222:225], v164 offset:36864
	ds_read_b128 v[226:229], v164 offset:37888
	ds_read_b128 v[230:233], v164 offset:38912
	ds_read_b128 v[234:237], v164 offset:39936
	s_waitcnt vmcnt(4)
	s_waitcnt lgkmcnt(0)
	s_barrier
	s_setprio 1
	v_mfma_f32_16x16x32_bf16 v[116:119], v[190:193], v[206:209], v[116:119]
	v_mfma_f32_16x16x32_bf16 v[112:115], v[198:201], v[206:209], v[112:115]
	v_mfma_f32_16x16x32_bf16 v[100:103], v[190:193], v[214:217], v[100:103]
	v_mfma_f32_16x16x32_bf16 v[96:99], v[198:201], v[214:217], v[96:99]
	v_mfma_f32_16x16x32_bf16 v[84:87], v[190:193], v[222:225], v[84:87]
	v_mfma_f32_16x16x32_bf16 v[80:83], v[198:201], v[222:225], v[80:83]
	v_mfma_f32_16x16x32_bf16 v[68:71], v[190:193], v[230:233], v[68:71]
	v_mfma_f32_16x16x32_bf16 v[64:67], v[198:201], v[230:233], v[64:67]
	v_mfma_f32_16x16x32_bf16 v[116:119], v[194:197], v[210:213], v[116:119]
	v_mfma_f32_16x16x32_bf16 v[112:115], v[202:205], v[210:213], v[112:115]
	v_mfma_f32_16x16x32_bf16 v[100:103], v[194:197], v[218:221], v[100:103]
	v_mfma_f32_16x16x32_bf16 v[96:99], v[202:205], v[218:221], v[96:99]
	v_mfma_f32_16x16x32_bf16 v[84:87], v[194:197], v[226:229], v[84:87]
	v_mfma_f32_16x16x32_bf16 v[80:83], v[202:205], v[226:229], v[80:83]
	v_mfma_f32_16x16x32_bf16 v[68:71], v[194:197], v[234:237], v[68:71]
	v_mfma_f32_16x16x32_bf16 v[64:67], v[202:205], v[234:237], v[64:67]
	s_setprio 0
	s_barrier
	v_add_u32_e32 v165, 0x10000, v162
	ds_read_b128 v[190:193], v165
	ds_read_b128 v[194:197], v165 offset:1024
	ds_read_b128 v[198:201], v165 offset:2048
	ds_read_b128 v[202:205], v165 offset:3072
	ds_read_b128 v[206:209], v164 offset:16384
	ds_read_b128 v[210:213], v164 offset:17408
	ds_read_b128 v[214:217], v164 offset:18432
	ds_read_b128 v[218:221], v164 offset:19456
	ds_read_b128 v[222:225], v164 offset:20480
	ds_read_b128 v[226:229], v164 offset:21504
	ds_read_b128 v[230:233], v164 offset:22528
	ds_read_b128 v[234:237], v164 offset:23552
	s_waitcnt vmcnt(0)
	s_waitcnt lgkmcnt(0)
	s_barrier
	s_setprio 1
	v_mfma_f32_16x16x32_bf16 v[116:119], v[190:193], v[206:209], v[116:119]
	v_mfma_f32_16x16x32_bf16 v[112:115], v[198:201], v[206:209], v[112:115]
	v_mfma_f32_16x16x32_bf16 v[100:103], v[190:193], v[214:217], v[100:103]
	v_mfma_f32_16x16x32_bf16 v[96:99], v[198:201], v[214:217], v[96:99]
	v_mfma_f32_16x16x32_bf16 v[84:87], v[190:193], v[222:225], v[84:87]
	v_mfma_f32_16x16x32_bf16 v[80:83], v[198:201], v[222:225], v[80:83]
	v_mfma_f32_16x16x32_bf16 v[68:71], v[190:193], v[230:233], v[68:71]
	v_mfma_f32_16x16x32_bf16 v[64:67], v[198:201], v[230:233], v[64:67]
	v_mfma_f32_16x16x32_bf16 v[116:119], v[194:197], v[210:213], v[116:119]
	v_mfma_f32_16x16x32_bf16 v[112:115], v[202:205], v[210:213], v[112:115]
	v_mfma_f32_16x16x32_bf16 v[100:103], v[194:197], v[218:221], v[100:103]
	v_mfma_f32_16x16x32_bf16 v[96:99], v[202:205], v[218:221], v[96:99]
	v_mfma_f32_16x16x32_bf16 v[84:87], v[194:197], v[226:229], v[84:87]
	v_mfma_f32_16x16x32_bf16 v[80:83], v[202:205], v[226:229], v[80:83]
	v_mfma_f32_16x16x32_bf16 v[68:71], v[194:197], v[234:237], v[68:71]
	v_mfma_f32_16x16x32_bf16 v[64:67], v[202:205], v[234:237], v[64:67]
	s_setprio 0
	s_barrier
	v_add_u32_e32 v165, 0x18000, v162
	ds_read_b128 v[190:193], v165
	ds_read_b128 v[194:197], v165 offset:1024
	ds_read_b128 v[198:201], v165 offset:2048
	ds_read_b128 v[202:205], v165 offset:3072
	ds_read_b128 v[206:209], v164 offset:49152
	ds_read_b128 v[210:213], v164 offset:50176
	ds_read_b128 v[214:217], v164 offset:51200
	ds_read_b128 v[218:221], v164 offset:52224
	ds_read_b128 v[222:225], v164 offset:53248
	ds_read_b128 v[226:229], v164 offset:54272
	ds_read_b128 v[230:233], v164 offset:55296
	ds_read_b128 v[234:237], v164 offset:56320
	s_waitcnt lgkmcnt(0)
	s_barrier
	s_setprio 1
	v_mfma_f32_16x16x32_bf16 v[116:119], v[190:193], v[206:209], v[116:119]
	v_mfma_f32_16x16x32_bf16 v[112:115], v[198:201], v[206:209], v[112:115]
	v_mfma_f32_16x16x32_bf16 v[100:103], v[190:193], v[214:217], v[100:103]
	v_mfma_f32_16x16x32_bf16 v[96:99], v[198:201], v[214:217], v[96:99]
	v_mfma_f32_16x16x32_bf16 v[84:87], v[190:193], v[222:225], v[84:87]
	v_mfma_f32_16x16x32_bf16 v[80:83], v[198:201], v[222:225], v[80:83]
	v_mfma_f32_16x16x32_bf16 v[68:71], v[190:193], v[230:233], v[68:71]
	v_mfma_f32_16x16x32_bf16 v[64:67], v[198:201], v[230:233], v[64:67]
	v_mfma_f32_16x16x32_bf16 v[116:119], v[194:197], v[210:213], v[116:119]
	v_mfma_f32_16x16x32_bf16 v[112:115], v[202:205], v[210:213], v[112:115]
	v_mfma_f32_16x16x32_bf16 v[100:103], v[194:197], v[218:221], v[100:103]
	v_mfma_f32_16x16x32_bf16 v[96:99], v[202:205], v[218:221], v[96:99]
	v_mfma_f32_16x16x32_bf16 v[84:87], v[194:197], v[226:229], v[84:87]
	v_mfma_f32_16x16x32_bf16 v[80:83], v[202:205], v[226:229], v[80:83]
	v_mfma_f32_16x16x32_bf16 v[68:71], v[194:197], v[234:237], v[68:71]
	v_mfma_f32_16x16x32_bf16 v[64:67], v[202:205], v[234:237], v[64:67]
	s_setprio 0
	s_barrier
	s_branch .Lq_lin_exit

.Lq_lin_2_k:
	v_add_u32_e32 v165, 0x10000, v162
	ds_read_b128 v[138:141], v165
	ds_read_b128 v[166:169], v165 offset:1024
	ds_read_b128 v[170:173], v165 offset:2048
	ds_read_b128 v[174:177], v165 offset:3072
	ds_read_b128 v[206:209], v164 offset:16384
	ds_read_b128 v[210:213], v164 offset:17408
	ds_read_b128 v[214:217], v164 offset:18432
	ds_read_b128 v[218:221], v164 offset:19456
	ds_read_b128 v[222:225], v164 offset:20480
	ds_read_b128 v[226:229], v164 offset:21504
	ds_read_b128 v[230:233], v164 offset:22528
	ds_read_b128 v[234:237], v164 offset:23552
	v_lshl_add_u64 v[142:143], s[74:75], 0, v[132:133]
	s_add_i32 m0, s5, 0x8000
	v_lshl_add_u64 v[160:161], s[74:75], 0, v[130:131]
	global_load_lds_dwordx4 v[142:143], off
	s_add_i32 m0, s5, 0xa000
	v_lshl_add_u64 v[178:179], s[2:3], 0, v[144:145]
	global_load_lds_dwordx4 v[160:161], off
	s_add_i32 m0, s5, 0x1c000
	v_lshl_add_u64 v[238:239], s[2:3], 0, v[128:129]
	global_load_lds_dwordx4 v[178:179], off
	s_add_i32 m0, s5, 0x1e000
	s_add_u32 s74, s74, 0x80
	s_addc_u32 s75, s75, 0
	global_load_lds_dwordx4 v[238:239], off
	s_add_u32 s2, s2, 0x80
	s_addc_u32 s3, s3, 0
	s_waitcnt vmcnt(8)
	s_waitcnt lgkmcnt(0)
	s_barrier
	s_setprio 1
	v_mfma_f32_16x16x32_bf16 v[60:63], v[138:141], v[206:209], v[60:63]
	v_mfma_f32_16x16x32_bf16 v[56:59], v[170:173], v[206:209], v[56:59]
	v_mfma_f32_16x16x32_bf16 v[44:47], v[138:141], v[214:217], v[44:47]
	v_mfma_f32_16x16x32_bf16 v[40:43], v[170:173], v[214:217], v[40:43]
	v_mfma_f32_16x16x32_bf16 v[28:31], v[138:141], v[222:225], v[28:31]
	v_mfma_f32_16x16x32_bf16 v[24:27], v[170:173], v[222:225], v[24:27]
	v_mfma_f32_16x16x32_bf16 v[12:15], v[138:141], v[230:233], v[12:15]
	v_mfma_f32_16x16x32_bf16 v[8:11], v[170:173], v[230:233], v[8:11]
	v_mfma_f32_16x16x32_bf16 v[60:63], v[166:169], v[210:213], v[60:63]
	v_mfma_f32_16x16x32_bf16 v[56:59], v[174:177], v[210:213], v[56:59]
	v_mfma_f32_16x16x32_bf16 v[44:47], v[166:169], v[218:221], v[44:47]
	v_mfma_f32_16x16x32_bf16 v[40:43], v[174:177], v[218:221], v[40:43]
	v_mfma_f32_16x16x32_bf16 v[28:31], v[166:169], v[226:229], v[28:31]
	v_mfma_f32_16x16x32_bf16 v[24:27], v[174:177], v[226:229], v[24:27]
	v_mfma_f32_16x16x32_bf16 v[12:15], v[166:169], v[234:237], v[12:15]
	v_mfma_f32_16x16x32_bf16 v[8:11], v[174:177], v[234:237], v[8:11]
	s_setprio 0
	s_barrier
	v_add_u32_e32 v165, 0x18000, v162
	ds_read_b128 v[138:141], v165
	ds_read_b128 v[166:169], v165 offset:1024
	ds_read_b128 v[170:173], v165 offset:2048
	ds_read_b128 v[174:177], v165 offset:3072
	ds_read_b128 v[206:209], v164 offset:49152
	ds_read_b128 v[210:213], v164 offset:50176
	ds_read_b128 v[214:217], v164 offset:51200
	ds_read_b128 v[218:221], v164 offset:52224
	ds_read_b128 v[222:225], v164 offset:53248
	ds_read_b128 v[226:229], v164 offset:54272
	ds_read_b128 v[230:233], v164 offset:55296
	ds_read_b128 v[234:237], v164 offset:56320
	v_lshl_add_u64 v[142:143], s[74:75], 0, v[132:133]
	s_add_i32 m0, s5, 0x4000
	v_lshl_add_u64 v[160:161], s[74:75], 0, v[130:131]
	global_load_lds_dwordx4 v[142:143], off
	s_add_i32 m0, s5, 0x6000
	v_lshl_add_u64 v[178:179], s[2:3], 0, v[144:145]
	global_load_lds_dwordx4 v[160:161], off
	s_add_i32 m0, s5, 0x10000
	v_lshl_add_u64 v[238:239], s[2:3], 0, v[128:129]
	global_load_lds_dwordx4 v[178:179], off
	s_add_i32 m0, s5, 0x12000
	s_add_u32 s74, s74, 0x80
	s_addc_u32 s75, s75, 0
	global_load_lds_dwordx4 v[238:239], off
	s_add_u32 s2, s2, 0x80
	s_addc_u32 s3, s3, 0
	s_waitcnt vmcnt(8)
	s_waitcnt lgkmcnt(0)
	s_barrier
	s_setprio 1
	v_mfma_f32_16x16x32_bf16 v[60:63], v[138:141], v[206:209], v[60:63]
	v_mfma_f32_16x16x32_bf16 v[56:59], v[170:173], v[206:209], v[56:59]
	v_mfma_f32_16x16x32_bf16 v[44:47], v[138:141], v[214:217], v[44:47]
	v_mfma_f32_16x16x32_bf16 v[40:43], v[170:173], v[214:217], v[40:43]
	v_mfma_f32_16x16x32_bf16 v[28:31], v[138:141], v[222:225], v[28:31]
	v_mfma_f32_16x16x32_bf16 v[24:27], v[170:173], v[222:225], v[24:27]
	v_mfma_f32_16x16x32_bf16 v[12:15], v[138:141], v[230:233], v[12:15]
	v_mfma_f32_16x16x32_bf16 v[8:11], v[170:173], v[230:233], v[8:11]
	v_mfma_f32_16x16x32_bf16 v[60:63], v[166:169], v[210:213], v[60:63]
	v_mfma_f32_16x16x32_bf16 v[56:59], v[174:177], v[210:213], v[56:59]
	v_mfma_f32_16x16x32_bf16 v[44:47], v[166:169], v[218:221], v[44:47]
	v_mfma_f32_16x16x32_bf16 v[40:43], v[174:177], v[218:221], v[40:43]
	v_mfma_f32_16x16x32_bf16 v[28:31], v[166:169], v[226:229], v[28:31]
	v_mfma_f32_16x16x32_bf16 v[24:27], v[174:177], v[226:229], v[24:27]
	v_mfma_f32_16x16x32_bf16 v[12:15], v[166:169], v[234:237], v[12:15]
	v_mfma_f32_16x16x32_bf16 v[8:11], v[174:177], v[234:237], v[8:11]
	s_setprio 0
	s_barrier
	v_add_u32_e32 v165, 0x14000, v162
	ds_read_b128 v[138:141], v165
	ds_read_b128 v[166:169], v165 offset:1024
	ds_read_b128 v[170:173], v165 offset:2048
	ds_read_b128 v[174:177], v165 offset:3072
	ds_read_b128 v[206:209], v164 offset:0
	ds_read_b128 v[210:213], v164 offset:1024
	ds_read_b128 v[214:217], v164 offset:2048
	ds_read_b128 v[218:221], v164 offset:3072
	ds_read_b128 v[222:225], v164 offset:4096
	ds_read_b128 v[226:229], v164 offset:5120
	ds_read_b128 v[230:233], v164 offset:6144
	ds_read_b128 v[234:237], v164 offset:7168
	v_lshl_add_u64 v[142:143], s[74:75], 0, v[132:133]
	s_add_i32 m0, s5, 0xc000
	v_lshl_add_u64 v[160:161], s[74:75], 0, v[130:131]
	global_load_lds_dwordx4 v[142:143], off
	s_add_i32 m0, s5, 0xe000
	v_lshl_add_u64 v[178:179], s[2:3], 0, v[144:145]
	global_load_lds_dwordx4 v[160:161], off
	s_add_i32 m0, s5, 0x18000
	v_lshl_add_u64 v[238:239], s[2:3], 0, v[128:129]
	global_load_lds_dwordx4 v[178:179], off
	s_add_i32 m0, s5, 0x1a000
	s_add_u32 s74, s74, 0x80
	s_addc_u32 s75, s75, 0
	global_load_lds_dwordx4 v[238:239], off
	s_add_u32 s2, s2, 0x80
	s_addc_u32 s3, s3, 0
	s_waitcnt vmcnt(8)
	s_waitcnt lgkmcnt(0)
	s_barrier
	s_setprio 1
	v_mfma_f32_16x16x32_bf16 v[60:63], v[138:141], v[206:209], v[60:63]
	v_mfma_f32_16x16x32_bf16 v[56:59], v[170:173], v[206:209], v[56:59]
	v_mfma_f32_16x16x32_bf16 v[44:47], v[138:141], v[214:217], v[44:47]
	v_mfma_f32_16x16x32_bf16 v[40:43], v[170:173], v[214:217], v[40:43]
	v_mfma_f32_16x16x32_bf16 v[28:31], v[138:141], v[222:225], v[28:31]
	v_mfma_f32_16x16x32_bf16 v[24:27], v[170:173], v[222:225], v[24:27]
	v_mfma_f32_16x16x32_bf16 v[12:15], v[138:141], v[230:233], v[12:15]
	v_mfma_f32_16x16x32_bf16 v[8:11], v[170:173], v[230:233], v[8:11]
	v_mfma_f32_16x16x32_bf16 v[60:63], v[166:169], v[210:213], v[60:63]
	v_mfma_f32_16x16x32_bf16 v[56:59], v[174:177], v[210:213], v[56:59]
	v_mfma_f32_16x16x32_bf16 v[44:47], v[166:169], v[218:221], v[44:47]
	v_mfma_f32_16x16x32_bf16 v[40:43], v[174:177], v[218:221], v[40:43]
	v_mfma_f32_16x16x32_bf16 v[28:31], v[166:169], v[226:229], v[28:31]
	v_mfma_f32_16x16x32_bf16 v[24:27], v[174:177], v[226:229], v[24:27]
	v_mfma_f32_16x16x32_bf16 v[12:15], v[166:169], v[234:237], v[12:15]
	v_mfma_f32_16x16x32_bf16 v[8:11], v[174:177], v[234:237], v[8:11]
	s_setprio 0
	s_barrier
	v_add_u32_e32 v165, 0x1c000, v162
	ds_read_b128 v[138:141], v165
	ds_read_b128 v[166:169], v165 offset:1024
	ds_read_b128 v[170:173], v165 offset:2048
	ds_read_b128 v[174:177], v165 offset:3072
	ds_read_b128 v[206:209], v164 offset:32768
	ds_read_b128 v[210:213], v164 offset:33792
	ds_read_b128 v[214:217], v164 offset:34816
	ds_read_b128 v[218:221], v164 offset:35840
	ds_read_b128 v[222:225], v164 offset:36864
	ds_read_b128 v[226:229], v164 offset:37888
	ds_read_b128 v[230:233], v164 offset:38912
	ds_read_b128 v[234:237], v164 offset:39936
	v_lshl_add_u64 v[142:143], s[74:75], 0, v[132:133]
	s_add_i32 m0, s5, 0x0
	v_lshl_add_u64 v[160:161], s[74:75], 0, v[130:131]
	global_load_lds_dwordx4 v[142:143], off
	s_add_i32 m0, s5, 0x2000
	v_lshl_add_u64 v[178:179], s[2:3], 0, v[144:145]
	global_load_lds_dwordx4 v[160:161], off
	s_add_i32 m0, s5, 0x14000
	v_lshl_add_u64 v[238:239], s[2:3], 0, v[128:129]
	global_load_lds_dwordx4 v[178:179], off
	s_add_i32 m0, s5, 0x16000
	s_add_u32 s74, s74, 0x80
	s_addc_u32 s75, s75, 0
	global_load_lds_dwordx4 v[238:239], off
	s_add_u32 s2, s2, 0x80
	s_addc_u32 s3, s3, 0
	s_waitcnt vmcnt(8)
	s_waitcnt lgkmcnt(0)
	s_barrier
	s_setprio 1
	v_mfma_f32_16x16x32_bf16 v[60:63], v[138:141], v[206:209], v[60:63]
	v_mfma_f32_16x16x32_bf16 v[56:59], v[170:173], v[206:209], v[56:59]
	v_mfma_f32_16x16x32_bf16 v[44:47], v[138:141], v[214:217], v[44:47]
	v_mfma_f32_16x16x32_bf16 v[40:43], v[170:173], v[214:217], v[40:43]
	v_mfma_f32_16x16x32_bf16 v[28:31], v[138:141], v[222:225], v[28:31]
	v_mfma_f32_16x16x32_bf16 v[24:27], v[170:173], v[222:225], v[24:27]
	v_mfma_f32_16x16x32_bf16 v[12:15], v[138:141], v[230:233], v[12:15]
	v_mfma_f32_16x16x32_bf16 v[8:11], v[170:173], v[230:233], v[8:11]
	v_mfma_f32_16x16x32_bf16 v[60:63], v[166:169], v[210:213], v[60:63]
	v_mfma_f32_16x16x32_bf16 v[56:59], v[174:177], v[210:213], v[56:59]
	v_mfma_f32_16x16x32_bf16 v[44:47], v[166:169], v[218:221], v[44:47]
	v_mfma_f32_16x16x32_bf16 v[40:43], v[174:177], v[218:221], v[40:43]
	v_mfma_f32_16x16x32_bf16 v[28:31], v[166:169], v[226:229], v[28:31]
	v_mfma_f32_16x16x32_bf16 v[24:27], v[174:177], v[226:229], v[24:27]
	v_mfma_f32_16x16x32_bf16 v[12:15], v[166:169], v[234:237], v[12:15]
	v_mfma_f32_16x16x32_bf16 v[8:11], v[174:177], v[234:237], v[8:11]
	s_setprio 0
	s_barrier
	s_add_i32 s8, s8, 1
	s_cmp_lt_u32 s8, 7
	s_cbranch_scc1 .Lq_lin_2_k
	v_add_u32_e32 v165, 0x10000, v162
	ds_read_b128 v[138:141], v165
	ds_read_b128 v[166:169], v165 offset:1024
	ds_read_b128 v[170:173], v165 offset:2048
	ds_read_b128 v[174:177], v165 offset:3072
	ds_read_b128 v[206:209], v164 offset:16384
	ds_read_b128 v[210:213], v164 offset:17408
	ds_read_b128 v[214:217], v164 offset:18432
	ds_read_b128 v[218:221], v164 offset:19456
	ds_read_b128 v[222:225], v164 offset:20480
	ds_read_b128 v[226:229], v164 offset:21504
	ds_read_b128 v[230:233], v164 offset:22528
	ds_read_b128 v[234:237], v164 offset:23552
	v_lshl_add_u64 v[142:143], s[74:75], 0, v[132:133]
	s_add_i32 m0, s5, 0x8000
	v_lshl_add_u64 v[160:161], s[74:75], 0, v[130:131]
	global_load_lds_dwordx4 v[142:143], off
	s_add_i32 m0, s5, 0xa000
	v_lshl_add_u64 v[178:179], s[2:3], 0, v[144:145]
	global_load_lds_dwordx4 v[160:161], off
	s_add_i32 m0, s5, 0x1c000
	v_lshl_add_u64 v[238:239], s[2:3], 0, v[128:129]
	global_load_lds_dwordx4 v[178:179], off
	s_add_i32 m0, s5, 0x1e000
	s_add_u32 s74, s74, 0x80
	s_addc_u32 s75, s75, 0
	global_load_lds_dwordx4 v[238:239], off
	s_add_u32 s2, s2, 0x80
	s_addc_u32 s3, s3, 0
	s_waitcnt vmcnt(8)
	s_waitcnt lgkmcnt(0)
	s_barrier
	s_setprio 1
	v_mfma_f32_16x16x32_bf16 v[60:63], v[138:141], v[206:209], v[60:63]
	v_mfma_f32_16x16x32_bf16 v[56:59], v[170:173], v[206:209], v[56:59]
	v_mfma_f32_16x16x32_bf16 v[44:47], v[138:141], v[214:217], v[44:47]
	v_mfma_f32_16x16x32_bf16 v[40:43], v[170:173], v[214:217], v[40:43]
	v_mfma_f32_16x16x32_bf16 v[28:31], v[138:141], v[222:225], v[28:31]
	v_mfma_f32_16x16x32_bf16 v[24:27], v[170:173], v[222:225], v[24:27]
	v_mfma_f32_16x16x32_bf16 v[12:15], v[138:141], v[230:233], v[12:15]
	v_mfma_f32_16x16x32_bf16 v[8:11], v[170:173], v[230:233], v[8:11]
	v_mfma_f32_16x16x32_bf16 v[60:63], v[166:169], v[210:213], v[60:63]
	v_mfma_f32_16x16x32_bf16 v[56:59], v[174:177], v[210:213], v[56:59]
	v_mfma_f32_16x16x32_bf16 v[44:47], v[166:169], v[218:221], v[44:47]
	v_mfma_f32_16x16x32_bf16 v[40:43], v[174:177], v[218:221], v[40:43]
	v_mfma_f32_16x16x32_bf16 v[28:31], v[166:169], v[226:229], v[28:31]
	v_mfma_f32_16x16x32_bf16 v[24:27], v[174:177], v[226:229], v[24:27]
	v_mfma_f32_16x16x32_bf16 v[12:15], v[166:169], v[234:237], v[12:15]
	v_mfma_f32_16x16x32_bf16 v[8:11], v[174:177], v[234:237], v[8:11]
	s_setprio 0
	s_barrier
	v_add_u32_e32 v165, 0x18000, v162
	ds_read_b128 v[138:141], v165
	ds_read_b128 v[166:169], v165 offset:1024
	ds_read_b128 v[170:173], v165 offset:2048
	ds_read_b128 v[174:177], v165 offset:3072
	ds_read_b128 v[206:209], v164 offset:49152
	ds_read_b128 v[210:213], v164 offset:50176
	ds_read_b128 v[214:217], v164 offset:51200
	ds_read_b128 v[218:221], v164 offset:52224
	ds_read_b128 v[222:225], v164 offset:53248
	ds_read_b128 v[226:229], v164 offset:54272
	ds_read_b128 v[230:233], v164 offset:55296
	ds_read_b128 v[234:237], v164 offset:56320
	s_waitcnt vmcnt(4)
	s_waitcnt lgkmcnt(0)
	s_barrier
	s_setprio 1
	v_mfma_f32_16x16x32_bf16 v[60:63], v[138:141], v[206:209], v[60:63]
	v_mfma_f32_16x16x32_bf16 v[56:59], v[170:173], v[206:209], v[56:59]
	v_mfma_f32_16x16x32_bf16 v[44:47], v[138:141], v[214:217], v[44:47]
	v_mfma_f32_16x16x32_bf16 v[40:43], v[170:173], v[214:217], v[40:43]
	v_mfma_f32_16x16x32_bf16 v[28:31], v[138:141], v[222:225], v[28:31]
	v_mfma_f32_16x16x32_bf16 v[24:27], v[170:173], v[222:225], v[24:27]
	v_mfma_f32_16x16x32_bf16 v[12:15], v[138:141], v[230:233], v[12:15]
	v_mfma_f32_16x16x32_bf16 v[8:11], v[170:173], v[230:233], v[8:11]
	v_mfma_f32_16x16x32_bf16 v[60:63], v[166:169], v[210:213], v[60:63]
	v_mfma_f32_16x16x32_bf16 v[56:59], v[174:177], v[210:213], v[56:59]
	v_mfma_f32_16x16x32_bf16 v[44:47], v[166:169], v[218:221], v[44:47]
	v_mfma_f32_16x16x32_bf16 v[40:43], v[174:177], v[218:221], v[40:43]
	v_mfma_f32_16x16x32_bf16 v[28:31], v[166:169], v[226:229], v[28:31]
	v_mfma_f32_16x16x32_bf16 v[24:27], v[174:177], v[226:229], v[24:27]
	v_mfma_f32_16x16x32_bf16 v[12:15], v[166:169], v[234:237], v[12:15]
	v_mfma_f32_16x16x32_bf16 v[8:11], v[174:177], v[234:237], v[8:11]
	s_setprio 0
	s_barrier
	v_add_u32_e32 v165, 0x14000, v162
	ds_read_b128 v[138:141], v165
	ds_read_b128 v[166:169], v165 offset:1024
	ds_read_b128 v[170:173], v165 offset:2048
	ds_read_b128 v[174:177], v165 offset:3072
	ds_read_b128 v[206:209], v164 offset:0
	ds_read_b128 v[210:213], v164 offset:1024
	ds_read_b128 v[214:217], v164 offset:2048
	ds_read_b128 v[218:221], v164 offset:3072
	ds_read_b128 v[222:225], v164 offset:4096
	ds_read_b128 v[226:229], v164 offset:5120
	ds_read_b128 v[230:233], v164 offset:6144
	ds_read_b128 v[234:237], v164 offset:7168
	s_waitcnt vmcnt(0)
	s_waitcnt lgkmcnt(0)
	s_barrier
	s_setprio 1
	v_mfma_f32_16x16x32_bf16 v[60:63], v[138:141], v[206:209], v[60:63]
	v_mfma_f32_16x16x32_bf16 v[56:59], v[170:173], v[206:209], v[56:59]
	v_mfma_f32_16x16x32_bf16 v[44:47], v[138:141], v[214:217], v[44:47]
	v_mfma_f32_16x16x32_bf16 v[40:43], v[170:173], v[214:217], v[40:43]
	v_mfma_f32_16x16x32_bf16 v[28:31], v[138:141], v[222:225], v[28:31]
	v_mfma_f32_16x16x32_bf16 v[24:27], v[170:173], v[222:225], v[24:27]
	v_mfma_f32_16x16x32_bf16 v[12:15], v[138:141], v[230:233], v[12:15]
	v_mfma_f32_16x16x32_bf16 v[8:11], v[170:173], v[230:233], v[8:11]
	v_mfma_f32_16x16x32_bf16 v[60:63], v[166:169], v[210:213], v[60:63]
	v_mfma_f32_16x16x32_bf16 v[56:59], v[174:177], v[210:213], v[56:59]
	v_mfma_f32_16x16x32_bf16 v[44:47], v[166:169], v[218:221], v[44:47]
	v_mfma_f32_16x16x32_bf16 v[40:43], v[174:177], v[218:221], v[40:43]
	v_mfma_f32_16x16x32_bf16 v[28:31], v[166:169], v[226:229], v[28:31]
	v_mfma_f32_16x16x32_bf16 v[24:27], v[174:177], v[226:229], v[24:27]
	v_mfma_f32_16x16x32_bf16 v[12:15], v[166:169], v[234:237], v[12:15]
	v_mfma_f32_16x16x32_bf16 v[8:11], v[174:177], v[234:237], v[8:11]
	s_setprio 0
	s_barrier
	v_add_u32_e32 v165, 0x1c000, v162
	ds_read_b128 v[138:141], v165
	ds_read_b128 v[166:169], v165 offset:1024
	ds_read_b128 v[170:173], v165 offset:2048
	ds_read_b128 v[174:177], v165 offset:3072
	ds_read_b128 v[206:209], v164 offset:32768
	ds_read_b128 v[210:213], v164 offset:33792
	ds_read_b128 v[214:217], v164 offset:34816
	ds_read_b128 v[218:221], v164 offset:35840
	ds_read_b128 v[222:225], v164 offset:36864
	ds_read_b128 v[226:229], v164 offset:37888
	ds_read_b128 v[230:233], v164 offset:38912
	ds_read_b128 v[234:237], v164 offset:39936
	s_waitcnt lgkmcnt(0)
	s_barrier
	s_setprio 1
	v_mfma_f32_16x16x32_bf16 v[60:63], v[138:141], v[206:209], v[60:63]
	v_mfma_f32_16x16x32_bf16 v[56:59], v[170:173], v[206:209], v[56:59]
	v_mfma_f32_16x16x32_bf16 v[44:47], v[138:141], v[214:217], v[44:47]
	v_mfma_f32_16x16x32_bf16 v[40:43], v[170:173], v[214:217], v[40:43]
	v_mfma_f32_16x16x32_bf16 v[28:31], v[138:141], v[222:225], v[28:31]
	v_mfma_f32_16x16x32_bf16 v[24:27], v[170:173], v[222:225], v[24:27]
	v_mfma_f32_16x16x32_bf16 v[12:15], v[138:141], v[230:233], v[12:15]
	v_mfma_f32_16x16x32_bf16 v[8:11], v[170:173], v[230:233], v[8:11]
	v_mfma_f32_16x16x32_bf16 v[60:63], v[166:169], v[210:213], v[60:63]
	v_mfma_f32_16x16x32_bf16 v[56:59], v[174:177], v[210:213], v[56:59]
	v_mfma_f32_16x16x32_bf16 v[44:47], v[166:169], v[218:221], v[44:47]
	v_mfma_f32_16x16x32_bf16 v[40:43], v[174:177], v[218:221], v[40:43]
	v_mfma_f32_16x16x32_bf16 v[28:31], v[166:169], v[226:229], v[28:31]
	v_mfma_f32_16x16x32_bf16 v[24:27], v[174:177], v[226:229], v[24:27]
	v_mfma_f32_16x16x32_bf16 v[12:15], v[166:169], v[234:237], v[12:15]
	v_mfma_f32_16x16x32_bf16 v[8:11], v[174:177], v[234:237], v[8:11]
	s_setprio 0
	s_barrier
	s_branch .Lq_lin_exit

.Lq_lin_3_k:
	v_add_u32_e32 v165, 0x14000, v162
	ds_read_b128 v[190:193], v165
	ds_read_b128 v[194:197], v165 offset:1024
	ds_read_b128 v[198:201], v165 offset:2048
	ds_read_b128 v[202:205], v165 offset:3072
	ds_read_b128 v[206:209], v164 offset:16384
	ds_read_b128 v[210:213], v164 offset:17408
	ds_read_b128 v[214:217], v164 offset:18432
	ds_read_b128 v[218:221], v164 offset:19456
	ds_read_b128 v[222:225], v164 offset:20480
	ds_read_b128 v[226:229], v164 offset:21504
	ds_read_b128 v[230:233], v164 offset:22528
	ds_read_b128 v[234:237], v164 offset:23552
	v_lshl_add_u64 v[142:143], s[74:75], 0, v[132:133]
	s_add_i32 m0, s5, 0x8000
	v_lshl_add_u64 v[160:161], s[74:75], 0, v[130:131]
	global_load_lds_dwordx4 v[142:143], off
	s_add_i32 m0, s5, 0xa000
	v_lshl_add_u64 v[178:179], s[2:3], 0, v[144:145]
	global_load_lds_dwordx4 v[160:161], off
	s_add_i32 m0, s5, 0x18000
	v_lshl_add_u64 v[238:239], s[2:3], 0, v[128:129]
	global_load_lds_dwordx4 v[178:179], off
	s_add_i32 m0, s5, 0x1a000
	s_add_u32 s74, s74, 0x80
	s_addc_u32 s75, s75, 0
	global_load_lds_dwordx4 v[238:239], off
	s_add_u32 s2, s2, 0x80
	s_addc_u32 s3, s3, 0
	s_waitcnt vmcnt(8)
	s_waitcnt lgkmcnt(0)
	s_barrier
	s_setprio 1
	v_mfma_f32_16x16x32_bf16 v[52:55], v[190:193], v[206:209], v[52:55]
	v_mfma_f32_16x16x32_bf16 v[48:51], v[198:201], v[206:209], v[48:51]
	v_mfma_f32_16x16x32_bf16 v[36:39], v[190:193], v[214:217], v[36:39]
	v_mfma_f32_16x16x32_bf16 v[32:35], v[198:201], v[214:217], v[32:35]
	v_mfma_f32_16x16x32_bf16 v[20:23], v[190:193], v[222:225], v[20:23]
	v_mfma_f32_16x16x32_bf16 v[16:19], v[198:201], v[222:225], v[16:19]
	v_mfma_f32_16x16x32_bf16 v[4:7], v[190:193], v[230:233], v[4:7]
	v_mfma_f32_16x16x32_bf16 v[0:3], v[198:201], v[230:233], v[0:3]
	v_mfma_f32_16x16x32_bf16 v[52:55], v[194:197], v[210:213], v[52:55]
	v_mfma_f32_16x16x32_bf16 v[48:51], v[202:205], v[210:213], v[48:51]
	v_mfma_f32_16x16x32_bf16 v[36:39], v[194:197], v[218:221], v[36:39]
	v_mfma_f32_16x16x32_bf16 v[32:35], v[202:205], v[218:221], v[32:35]
	v_mfma_f32_16x16x32_bf16 v[20:23], v[194:197], v[226:229], v[20:23]
	v_mfma_f32_16x16x32_bf16 v[16:19], v[202:205], v[226:229], v[16:19]
	v_mfma_f32_16x16x32_bf16 v[4:7], v[194:197], v[234:237], v[4:7]
	v_mfma_f32_16x16x32_bf16 v[0:3], v[202:205], v[234:237], v[0:3]
	s_setprio 0
	s_barrier
	v_add_u32_e32 v165, 0x1c000, v162
	ds_read_b128 v[190:193], v165
	ds_read_b128 v[194:197], v165 offset:1024
	ds_read_b128 v[198:201], v165 offset:2048
	ds_read_b128 v[202:205], v165 offset:3072
	ds_read_b128 v[206:209], v164 offset:49152
	ds_read_b128 v[210:213], v164 offset:50176
	ds_read_b128 v[214:217], v164 offset:51200
	ds_read_b128 v[218:221], v164 offset:52224
	ds_read_b128 v[222:225], v164 offset:53248
	ds_read_b128 v[226:229], v164 offset:54272
	ds_read_b128 v[230:233], v164 offset:55296
	ds_read_b128 v[234:237], v164 offset:56320
	v_lshl_add_u64 v[142:143], s[74:75], 0, v[132:133]
	s_add_i32 m0, s5, 0x4000
	v_lshl_add_u64 v[160:161], s[74:75], 0, v[130:131]
	global_load_lds_dwordx4 v[142:143], off
	s_add_i32 m0, s5, 0x6000
	v_lshl_add_u64 v[178:179], s[2:3], 0, v[144:145]
	global_load_lds_dwordx4 v[160:161], off
	s_add_i32 m0, s5, 0x14000
	v_lshl_add_u64 v[238:239], s[2:3], 0, v[128:129]
	global_load_lds_dwordx4 v[178:179], off
	s_add_i32 m0, s5, 0x16000
	s_add_u32 s74, s74, 0x80
	s_addc_u32 s75, s75, 0
	global_load_lds_dwordx4 v[238:239], off
	s_add_u32 s2, s2, 0x80
	s_addc_u32 s3, s3, 0
	s_waitcnt vmcnt(8)
	s_waitcnt lgkmcnt(0)
	s_barrier
	s_setprio 1
	v_mfma_f32_16x16x32_bf16 v[52:55], v[190:193], v[206:209], v[52:55]
	v_mfma_f32_16x16x32_bf16 v[48:51], v[198:201], v[206:209], v[48:51]
	v_mfma_f32_16x16x32_bf16 v[36:39], v[190:193], v[214:217], v[36:39]
	v_mfma_f32_16x16x32_bf16 v[32:35], v[198:201], v[214:217], v[32:35]
	v_mfma_f32_16x16x32_bf16 v[20:23], v[190:193], v[222:225], v[20:23]
	v_mfma_f32_16x16x32_bf16 v[16:19], v[198:201], v[222:225], v[16:19]
	v_mfma_f32_16x16x32_bf16 v[4:7], v[190:193], v[230:233], v[4:7]
	v_mfma_f32_16x16x32_bf16 v[0:3], v[198:201], v[230:233], v[0:3]
	v_mfma_f32_16x16x32_bf16 v[52:55], v[194:197], v[210:213], v[52:55]
	v_mfma_f32_16x16x32_bf16 v[48:51], v[202:205], v[210:213], v[48:51]
	v_mfma_f32_16x16x32_bf16 v[36:39], v[194:197], v[218:221], v[36:39]
	v_mfma_f32_16x16x32_bf16 v[32:35], v[202:205], v[218:221], v[32:35]
	v_mfma_f32_16x16x32_bf16 v[20:23], v[194:197], v[226:229], v[20:23]
	v_mfma_f32_16x16x32_bf16 v[16:19], v[202:205], v[226:229], v[16:19]
	v_mfma_f32_16x16x32_bf16 v[4:7], v[194:197], v[234:237], v[4:7]
	v_mfma_f32_16x16x32_bf16 v[0:3], v[202:205], v[234:237], v[0:3]
	s_setprio 0
	s_barrier
	v_add_u32_e32 v165, 0x10000, v162
	ds_read_b128 v[190:193], v165
	ds_read_b128 v[194:197], v165 offset:1024
	ds_read_b128 v[198:201], v165 offset:2048
	ds_read_b128 v[202:205], v165 offset:3072
	ds_read_b128 v[206:209], v164 offset:0
	ds_read_b128 v[210:213], v164 offset:1024
	ds_read_b128 v[214:217], v164 offset:2048
	ds_read_b128 v[218:221], v164 offset:3072
	ds_read_b128 v[222:225], v164 offset:4096
	ds_read_b128 v[226:229], v164 offset:5120
	ds_read_b128 v[230:233], v164 offset:6144
	ds_read_b128 v[234:237], v164 offset:7168
	v_lshl_add_u64 v[142:143], s[74:75], 0, v[132:133]
	s_add_i32 m0, s5, 0xc000
	v_lshl_add_u64 v[160:161], s[74:75], 0, v[130:131]
	global_load_lds_dwordx4 v[142:143], off
	s_add_i32 m0, s5, 0xe000
	v_lshl_add_u64 v[178:179], s[2:3], 0, v[144:145]
	global_load_lds_dwordx4 v[160:161], off
	s_add_i32 m0, s5, 0x1c000
	v_lshl_add_u64 v[238:239], s[2:3], 0, v[128:129]
	global_load_lds_dwordx4 v[178:179], off
	s_add_i32 m0, s5, 0x1e000
	s_add_u32 s74, s74, 0x80
	s_addc_u32 s75, s75, 0
	global_load_lds_dwordx4 v[238:239], off
	s_add_u32 s2, s2, 0x80
	s_addc_u32 s3, s3, 0
	s_waitcnt vmcnt(8)
	s_waitcnt lgkmcnt(0)
	s_barrier
	s_setprio 1
	v_mfma_f32_16x16x32_bf16 v[52:55], v[190:193], v[206:209], v[52:55]
	v_mfma_f32_16x16x32_bf16 v[48:51], v[198:201], v[206:209], v[48:51]
	v_mfma_f32_16x16x32_bf16 v[36:39], v[190:193], v[214:217], v[36:39]
	v_mfma_f32_16x16x32_bf16 v[32:35], v[198:201], v[214:217], v[32:35]
	v_mfma_f32_16x16x32_bf16 v[20:23], v[190:193], v[222:225], v[20:23]
	v_mfma_f32_16x16x32_bf16 v[16:19], v[198:201], v[222:225], v[16:19]
	v_mfma_f32_16x16x32_bf16 v[4:7], v[190:193], v[230:233], v[4:7]
	v_mfma_f32_16x16x32_bf16 v[0:3], v[198:201], v[230:233], v[0:3]
	v_mfma_f32_16x16x32_bf16 v[52:55], v[194:197], v[210:213], v[52:55]
	v_mfma_f32_16x16x32_bf16 v[48:51], v[202:205], v[210:213], v[48:51]
	v_mfma_f32_16x16x32_bf16 v[36:39], v[194:197], v[218:221], v[36:39]
	v_mfma_f32_16x16x32_bf16 v[32:35], v[202:205], v[218:221], v[32:35]
	v_mfma_f32_16x16x32_bf16 v[20:23], v[194:197], v[226:229], v[20:23]
	v_mfma_f32_16x16x32_bf16 v[16:19], v[202:205], v[226:229], v[16:19]
	v_mfma_f32_16x16x32_bf16 v[4:7], v[194:197], v[234:237], v[4:7]
	v_mfma_f32_16x16x32_bf16 v[0:3], v[202:205], v[234:237], v[0:3]
	s_setprio 0
	s_barrier
	v_add_u32_e32 v165, 0x18000, v162
	ds_read_b128 v[190:193], v165
	ds_read_b128 v[194:197], v165 offset:1024
	ds_read_b128 v[198:201], v165 offset:2048
	ds_read_b128 v[202:205], v165 offset:3072
	ds_read_b128 v[206:209], v164 offset:32768
	ds_read_b128 v[210:213], v164 offset:33792
	ds_read_b128 v[214:217], v164 offset:34816
	ds_read_b128 v[218:221], v164 offset:35840
	ds_read_b128 v[222:225], v164 offset:36864
	ds_read_b128 v[226:229], v164 offset:37888
	ds_read_b128 v[230:233], v164 offset:38912
	ds_read_b128 v[234:237], v164 offset:39936
	v_lshl_add_u64 v[142:143], s[74:75], 0, v[132:133]
	s_add_i32 m0, s5, 0x0
	v_lshl_add_u64 v[160:161], s[74:75], 0, v[130:131]
	global_load_lds_dwordx4 v[142:143], off
	s_add_i32 m0, s5, 0x2000
	v_lshl_add_u64 v[178:179], s[2:3], 0, v[144:145]
	global_load_lds_dwordx4 v[160:161], off
	s_add_i32 m0, s5, 0x10000
	v_lshl_add_u64 v[238:239], s[2:3], 0, v[128:129]
	global_load_lds_dwordx4 v[178:179], off
	s_add_i32 m0, s5, 0x12000
	s_add_u32 s74, s74, 0x80
	s_addc_u32 s75, s75, 0
	global_load_lds_dwordx4 v[238:239], off
	s_add_u32 s2, s2, 0x80
	s_addc_u32 s3, s3, 0
	s_waitcnt vmcnt(8)
	s_waitcnt lgkmcnt(0)
	s_barrier
	s_setprio 1
	v_mfma_f32_16x16x32_bf16 v[52:55], v[190:193], v[206:209], v[52:55]
	v_mfma_f32_16x16x32_bf16 v[48:51], v[198:201], v[206:209], v[48:51]
	v_mfma_f32_16x16x32_bf16 v[36:39], v[190:193], v[214:217], v[36:39]
	v_mfma_f32_16x16x32_bf16 v[32:35], v[198:201], v[214:217], v[32:35]
	v_mfma_f32_16x16x32_bf16 v[20:23], v[190:193], v[222:225], v[20:23]
	v_mfma_f32_16x16x32_bf16 v[16:19], v[198:201], v[222:225], v[16:19]
	v_mfma_f32_16x16x32_bf16 v[4:7], v[190:193], v[230:233], v[4:7]
	v_mfma_f32_16x16x32_bf16 v[0:3], v[198:201], v[230:233], v[0:3]
	v_mfma_f32_16x16x32_bf16 v[52:55], v[194:197], v[210:213], v[52:55]
	v_mfma_f32_16x16x32_bf16 v[48:51], v[202:205], v[210:213], v[48:51]
	v_mfma_f32_16x16x32_bf16 v[36:39], v[194:197], v[218:221], v[36:39]
	v_mfma_f32_16x16x32_bf16 v[32:35], v[202:205], v[218:221], v[32:35]
	v_mfma_f32_16x16x32_bf16 v[20:23], v[194:197], v[226:229], v[20:23]
	v_mfma_f32_16x16x32_bf16 v[16:19], v[202:205], v[226:229], v[16:19]
	v_mfma_f32_16x16x32_bf16 v[4:7], v[194:197], v[234:237], v[4:7]
	v_mfma_f32_16x16x32_bf16 v[0:3], v[202:205], v[234:237], v[0:3]
	s_setprio 0
	s_barrier
	s_add_i32 s8, s8, 1
	s_cmp_lt_u32 s8, 7
	s_cbranch_scc1 .Lq_lin_3_k
	v_add_u32_e32 v165, 0x14000, v162
	ds_read_b128 v[190:193], v165
	ds_read_b128 v[194:197], v165 offset:1024
	ds_read_b128 v[198:201], v165 offset:2048
	ds_read_b128 v[202:205], v165 offset:3072
	ds_read_b128 v[206:209], v164 offset:16384
	ds_read_b128 v[210:213], v164 offset:17408
	ds_read_b128 v[214:217], v164 offset:18432
	ds_read_b128 v[218:221], v164 offset:19456
	ds_read_b128 v[222:225], v164 offset:20480
	ds_read_b128 v[226:229], v164 offset:21504
	ds_read_b128 v[230:233], v164 offset:22528
	ds_read_b128 v[234:237], v164 offset:23552
	v_lshl_add_u64 v[142:143], s[74:75], 0, v[132:133]
	s_add_i32 m0, s5, 0x8000
	v_lshl_add_u64 v[160:161], s[74:75], 0, v[130:131]
	global_load_lds_dwordx4 v[142:143], off
	s_add_i32 m0, s5, 0xa000
	v_lshl_add_u64 v[178:179], s[2:3], 0, v[144:145]
	global_load_lds_dwordx4 v[160:161], off
	s_add_i32 m0, s5, 0x18000
	v_lshl_add_u64 v[238:239], s[2:3], 0, v[128:129]
	global_load_lds_dwordx4 v[178:179], off
	s_add_i32 m0, s5, 0x1a000
	s_add_u32 s74, s74, 0x80
	s_addc_u32 s75, s75, 0
	global_load_lds_dwordx4 v[238:239], off
	s_add_u32 s2, s2, 0x80
	s_addc_u32 s3, s3, 0
	s_waitcnt vmcnt(8)
	s_waitcnt lgkmcnt(0)
	s_barrier
	s_setprio 1
	v_mfma_f32_16x16x32_bf16 v[52:55], v[190:193], v[206:209], v[52:55]
	v_mfma_f32_16x16x32_bf16 v[48:51], v[198:201], v[206:209], v[48:51]
	v_mfma_f32_16x16x32_bf16 v[36:39], v[190:193], v[214:217], v[36:39]
	v_mfma_f32_16x16x32_bf16 v[32:35], v[198:201], v[214:217], v[32:35]
	v_mfma_f32_16x16x32_bf16 v[20:23], v[190:193], v[222:225], v[20:23]
	v_mfma_f32_16x16x32_bf16 v[16:19], v[198:201], v[222:225], v[16:19]
	v_mfma_f32_16x16x32_bf16 v[4:7], v[190:193], v[230:233], v[4:7]
	v_mfma_f32_16x16x32_bf16 v[0:3], v[198:201], v[230:233], v[0:3]
	v_mfma_f32_16x16x32_bf16 v[52:55], v[194:197], v[210:213], v[52:55]
	v_mfma_f32_16x16x32_bf16 v[48:51], v[202:205], v[210:213], v[48:51]
	v_mfma_f32_16x16x32_bf16 v[36:39], v[194:197], v[218:221], v[36:39]
	v_mfma_f32_16x16x32_bf16 v[32:35], v[202:205], v[218:221], v[32:35]
	v_mfma_f32_16x16x32_bf16 v[20:23], v[194:197], v[226:229], v[20:23]
	v_mfma_f32_16x16x32_bf16 v[16:19], v[202:205], v[226:229], v[16:19]
	v_mfma_f32_16x16x32_bf16 v[4:7], v[194:197], v[234:237], v[4:7]
	v_mfma_f32_16x16x32_bf16 v[0:3], v[202:205], v[234:237], v[0:3]
	s_setprio 0
	s_barrier
	v_add_u32_e32 v165, 0x1c000, v162
	ds_read_b128 v[190:193], v165
	ds_read_b128 v[194:197], v165 offset:1024
	ds_read_b128 v[198:201], v165 offset:2048
	ds_read_b128 v[202:205], v165 offset:3072
	ds_read_b128 v[206:209], v164 offset:49152
	ds_read_b128 v[210:213], v164 offset:50176
	ds_read_b128 v[214:217], v164 offset:51200
	ds_read_b128 v[218:221], v164 offset:52224
	ds_read_b128 v[222:225], v164 offset:53248
	ds_read_b128 v[226:229], v164 offset:54272
	ds_read_b128 v[230:233], v164 offset:55296
	ds_read_b128 v[234:237], v164 offset:56320
	s_waitcnt vmcnt(4)
	s_waitcnt lgkmcnt(0)
	s_barrier
	s_setprio 1
	v_mfma_f32_16x16x32_bf16 v[52:55], v[190:193], v[206:209], v[52:55]
	v_mfma_f32_16x16x32_bf16 v[48:51], v[198:201], v[206:209], v[48:51]
	v_mfma_f32_16x16x32_bf16 v[36:39], v[190:193], v[214:217], v[36:39]
	v_mfma_f32_16x16x32_bf16 v[32:35], v[198:201], v[214:217], v[32:35]
	v_mfma_f32_16x16x32_bf16 v[20:23], v[190:193], v[222:225], v[20:23]
	v_mfma_f32_16x16x32_bf16 v[16:19], v[198:201], v[222:225], v[16:19]
	v_mfma_f32_16x16x32_bf16 v[4:7], v[190:193], v[230:233], v[4:7]
	v_mfma_f32_16x16x32_bf16 v[0:3], v[198:201], v[230:233], v[0:3]
	v_mfma_f32_16x16x32_bf16 v[52:55], v[194:197], v[210:213], v[52:55]
	v_mfma_f32_16x16x32_bf16 v[48:51], v[202:205], v[210:213], v[48:51]
	v_mfma_f32_16x16x32_bf16 v[36:39], v[194:197], v[218:221], v[36:39]
	v_mfma_f32_16x16x32_bf16 v[32:35], v[202:205], v[218:221], v[32:35]
	v_mfma_f32_16x16x32_bf16 v[20:23], v[194:197], v[226:229], v[20:23]
	v_mfma_f32_16x16x32_bf16 v[16:19], v[202:205], v[226:229], v[16:19]
	v_mfma_f32_16x16x32_bf16 v[4:7], v[194:197], v[234:237], v[4:7]
	v_mfma_f32_16x16x32_bf16 v[0:3], v[202:205], v[234:237], v[0:3]
	s_setprio 0
	s_barrier
	v_add_u32_e32 v165, 0x10000, v162
	ds_read_b128 v[190:193], v165
	ds_read_b128 v[194:197], v165 offset:1024
	ds_read_b128 v[198:201], v165 offset:2048
	ds_read_b128 v[202:205], v165 offset:3072
	ds_read_b128 v[206:209], v164 offset:0
	ds_read_b128 v[210:213], v164 offset:1024
	ds_read_b128 v[214:217], v164 offset:2048
	ds_read_b128 v[218:221], v164 offset:3072
	ds_read_b128 v[222:225], v164 offset:4096
	ds_read_b128 v[226:229], v164 offset:5120
	ds_read_b128 v[230:233], v164 offset:6144
	ds_read_b128 v[234:237], v164 offset:7168
	s_waitcnt vmcnt(0)
	s_waitcnt lgkmcnt(0)
	s_barrier
	s_setprio 1
	v_mfma_f32_16x16x32_bf16 v[52:55], v[190:193], v[206:209], v[52:55]
	v_mfma_f32_16x16x32_bf16 v[48:51], v[198:201], v[206:209], v[48:51]
	v_mfma_f32_16x16x32_bf16 v[36:39], v[190:193], v[214:217], v[36:39]
	v_mfma_f32_16x16x32_bf16 v[32:35], v[198:201], v[214:217], v[32:35]
	v_mfma_f32_16x16x32_bf16 v[20:23], v[190:193], v[222:225], v[20:23]
	v_mfma_f32_16x16x32_bf16 v[16:19], v[198:201], v[222:225], v[16:19]
	v_mfma_f32_16x16x32_bf16 v[4:7], v[190:193], v[230:233], v[4:7]
	v_mfma_f32_16x16x32_bf16 v[0:3], v[198:201], v[230:233], v[0:3]
	v_mfma_f32_16x16x32_bf16 v[52:55], v[194:197], v[210:213], v[52:55]
	v_mfma_f32_16x16x32_bf16 v[48:51], v[202:205], v[210:213], v[48:51]
	v_mfma_f32_16x16x32_bf16 v[36:39], v[194:197], v[218:221], v[36:39]
	v_mfma_f32_16x16x32_bf16 v[32:35], v[202:205], v[218:221], v[32:35]
	v_mfma_f32_16x16x32_bf16 v[20:23], v[194:197], v[226:229], v[20:23]
	v_mfma_f32_16x16x32_bf16 v[16:19], v[202:205], v[226:229], v[16:19]
	v_mfma_f32_16x16x32_bf16 v[4:7], v[194:197], v[234:237], v[4:7]
	v_mfma_f32_16x16x32_bf16 v[0:3], v[202:205], v[234:237], v[0:3]
	s_setprio 0
	s_barrier
	v_add_u32_e32 v165, 0x18000, v162
	ds_read_b128 v[190:193], v165
	ds_read_b128 v[194:197], v165 offset:1024
	ds_read_b128 v[198:201], v165 offset:2048
	ds_read_b128 v[202:205], v165 offset:3072
	ds_read_b128 v[206:209], v164 offset:32768
	ds_read_b128 v[210:213], v164 offset:33792
	ds_read_b128 v[214:217], v164 offset:34816
	ds_read_b128 v[218:221], v164 offset:35840
	ds_read_b128 v[222:225], v164 offset:36864
	ds_read_b128 v[226:229], v164 offset:37888
	ds_read_b128 v[230:233], v164 offset:38912
	ds_read_b128 v[234:237], v164 offset:39936
	s_waitcnt lgkmcnt(0)
	s_barrier
	s_setprio 1
	v_mfma_f32_16x16x32_bf16 v[52:55], v[190:193], v[206:209], v[52:55]
	v_mfma_f32_16x16x32_bf16 v[48:51], v[198:201], v[206:209], v[48:51]
	v_mfma_f32_16x16x32_bf16 v[36:39], v[190:193], v[214:217], v[36:39]
	v_mfma_f32_16x16x32_bf16 v[32:35], v[198:201], v[214:217], v[32:35]
	v_mfma_f32_16x16x32_bf16 v[20:23], v[190:193], v[222:225], v[20:23]
	v_mfma_f32_16x16x32_bf16 v[16:19], v[198:201], v[222:225], v[16:19]
	v_mfma_f32_16x16x32_bf16 v[4:7], v[190:193], v[230:233], v[4:7]
	v_mfma_f32_16x16x32_bf16 v[0:3], v[198:201], v[230:233], v[0:3]
	v_mfma_f32_16x16x32_bf16 v[52:55], v[194:197], v[210:213], v[52:55]
	v_mfma_f32_16x16x32_bf16 v[48:51], v[202:205], v[210:213], v[48:51]
	v_mfma_f32_16x16x32_bf16 v[36:39], v[194:197], v[218:221], v[36:39]
	v_mfma_f32_16x16x32_bf16 v[32:35], v[202:205], v[218:221], v[32:35]
	v_mfma_f32_16x16x32_bf16 v[20:23], v[194:197], v[226:229], v[20:23]
	v_mfma_f32_16x16x32_bf16 v[16:19], v[202:205], v[226:229], v[16:19]
	v_mfma_f32_16x16x32_bf16 v[4:7], v[194:197], v[234:237], v[4:7]
	v_mfma_f32_16x16x32_bf16 v[0:3], v[202:205], v[234:237], v[0:3]
	s_setprio 0
	s_barrier
	s_branch .Lq_lin_exit

.Lq_lout_0_k:
	v_add_u32_e32 v144, 0x10000, v178
	ds_read_b128 v[28:31], v144
	ds_read_b128 v[32:35], v144 offset:1024
	ds_read_b128 v[40:43], v144 offset:2048
	ds_read_b128 v[44:47], v144 offset:3072
	ds_read_b128 v[200:203], v190 offset:0
	ds_read_b128 v[204:207], v190 offset:1024
	ds_read_b128 v[208:211], v190 offset:2048
	ds_read_b128 v[212:215], v190 offset:3072
	ds_read_b128 v[216:219], v190 offset:4096
	ds_read_b128 v[220:223], v190 offset:5120
	ds_read_b128 v[224:227], v190 offset:6144
	ds_read_b128 v[228:231], v190 offset:7168
	v_lshl_add_u64 v[176:177], s[88:89], 0, v[160:161]
	s_add_i32 m0, s9, 0xc000
	v_lshl_add_u64 v[232:233], s[88:89], 0, v[162:163]
	global_load_lds_dwordx4 v[176:177], off
	s_add_i32 m0, s9, 0xe000
	v_lshl_add_u64 v[234:235], s[82:83], 0, v[160:161]
	global_load_lds_dwordx4 v[232:233], off
	s_add_i32 m0, s9, 0x1c000
	v_lshl_add_u64 v[236:237], s[82:83], 0, v[162:163]
	global_load_lds_dwordx4 v[234:235], off
	s_add_i32 m0, s9, 0x1e000
	s_add_u32 s88, s88, 0x80
	s_addc_u32 s89, s89, 0
	global_load_lds_dwordx4 v[236:237], off
	s_add_u32 s82, s82, 0x80
	s_addc_u32 s83, s83, 0
	s_waitcnt vmcnt(8)
	s_waitcnt lgkmcnt(0)
	s_barrier
	s_setprio 1
	v_mfma_f32_16x16x32_bf16 v[140:143], v[28:31], v[200:203], v[140:143]
	v_mfma_f32_16x16x32_bf16 v[136:139], v[40:43], v[200:203], v[136:139]
	v_mfma_f32_16x16x32_bf16 v[124:127], v[28:31], v[208:211], v[124:127]
	v_mfma_f32_16x16x32_bf16 v[120:123], v[40:43], v[208:211], v[120:123]
	v_mfma_f32_16x16x32_bf16 v[108:111], v[28:31], v[216:219], v[108:111]
	v_mfma_f32_16x16x32_bf16 v[104:107], v[40:43], v[216:219], v[104:107]
	v_mfma_f32_16x16x32_bf16 v[92:95], v[28:31], v[224:227], v[92:95]
	v_mfma_f32_16x16x32_bf16 v[88:91], v[40:43], v[224:227], v[88:91]
	v_mfma_f32_16x16x32_bf16 v[140:143], v[32:35], v[204:207], v[140:143]
	v_mfma_f32_16x16x32_bf16 v[136:139], v[44:47], v[204:207], v[136:139]
	v_mfma_f32_16x16x32_bf16 v[124:127], v[32:35], v[212:215], v[124:127]
	v_mfma_f32_16x16x32_bf16 v[120:123], v[44:47], v[212:215], v[120:123]
	v_mfma_f32_16x16x32_bf16 v[108:111], v[32:35], v[220:223], v[108:111]
	v_mfma_f32_16x16x32_bf16 v[104:107], v[44:47], v[220:223], v[104:107]
	v_mfma_f32_16x16x32_bf16 v[92:95], v[32:35], v[228:231], v[92:95]
	v_mfma_f32_16x16x32_bf16 v[88:91], v[44:47], v[228:231], v[88:91]
	s_setprio 0
	s_barrier
	v_add_u32_e32 v144, 0x18000, v178
	ds_read_b128 v[28:31], v144
	ds_read_b128 v[32:35], v144 offset:1024
	ds_read_b128 v[40:43], v144 offset:2048
	ds_read_b128 v[44:47], v144 offset:3072
	ds_read_b128 v[200:203], v190 offset:32768
	ds_read_b128 v[204:207], v190 offset:33792
	ds_read_b128 v[208:211], v190 offset:34816
	ds_read_b128 v[212:215], v190 offset:35840
	ds_read_b128 v[216:219], v190 offset:36864
	ds_read_b128 v[220:223], v190 offset:37888
	ds_read_b128 v[224:227], v190 offset:38912
	ds_read_b128 v[228:231], v190 offset:39936
	v_lshl_add_u64 v[176:177], s[88:89], 0, v[160:161]
	s_add_i32 m0, s9, 0x0
	v_lshl_add_u64 v[232:233], s[88:89], 0, v[162:163]
	global_load_lds_dwordx4 v[176:177], off
	s_add_i32 m0, s9, 0x2000
	v_lshl_add_u64 v[234:235], s[82:83], 0, v[160:161]
	global_load_lds_dwordx4 v[232:233], off
	s_add_i32 m0, s9, 0x10000
	v_lshl_add_u64 v[236:237], s[82:83], 0, v[162:163]
	global_load_lds_dwordx4 v[234:235], off
	s_add_i32 m0, s9, 0x12000
	s_add_u32 s88, s88, 0x80
	s_addc_u32 s89, s89, 0
	global_load_lds_dwordx4 v[236:237], off
	s_add_u32 s82, s82, 0x80
	s_addc_u32 s83, s83, 0
	s_waitcnt vmcnt(8)
	s_waitcnt lgkmcnt(0)
	s_barrier
	s_setprio 1
	v_mfma_f32_16x16x32_bf16 v[140:143], v[28:31], v[200:203], v[140:143]
	v_mfma_f32_16x16x32_bf16 v[136:139], v[40:43], v[200:203], v[136:139]
	v_mfma_f32_16x16x32_bf16 v[124:127], v[28:31], v[208:211], v[124:127]
	v_mfma_f32_16x16x32_bf16 v[120:123], v[40:43], v[208:211], v[120:123]
	v_mfma_f32_16x16x32_bf16 v[108:111], v[28:31], v[216:219], v[108:111]
	v_mfma_f32_16x16x32_bf16 v[104:107], v[40:43], v[216:219], v[104:107]
	v_mfma_f32_16x16x32_bf16 v[92:95], v[28:31], v[224:227], v[92:95]
	v_mfma_f32_16x16x32_bf16 v[88:91], v[40:43], v[224:227], v[88:91]
	v_mfma_f32_16x16x32_bf16 v[140:143], v[32:35], v[204:207], v[140:143]
	v_mfma_f32_16x16x32_bf16 v[136:139], v[44:47], v[204:207], v[136:139]
	v_mfma_f32_16x16x32_bf16 v[124:127], v[32:35], v[212:215], v[124:127]
	v_mfma_f32_16x16x32_bf16 v[120:123], v[44:47], v[212:215], v[120:123]
	v_mfma_f32_16x16x32_bf16 v[108:111], v[32:35], v[220:223], v[108:111]
	v_mfma_f32_16x16x32_bf16 v[104:107], v[44:47], v[220:223], v[104:107]
	v_mfma_f32_16x16x32_bf16 v[92:95], v[32:35], v[228:231], v[92:95]
	v_mfma_f32_16x16x32_bf16 v[88:91], v[44:47], v[228:231], v[88:91]
	s_setprio 0
	s_barrier
	v_add_u32_e32 v144, 0x14000, v178
	ds_read_b128 v[28:31], v144
	ds_read_b128 v[32:35], v144 offset:1024
	ds_read_b128 v[40:43], v144 offset:2048
	ds_read_b128 v[44:47], v144 offset:3072
	ds_read_b128 v[200:203], v190 offset:16384
	ds_read_b128 v[204:207], v190 offset:17408
	ds_read_b128 v[208:211], v190 offset:18432
	ds_read_b128 v[212:215], v190 offset:19456
	ds_read_b128 v[216:219], v190 offset:20480
	ds_read_b128 v[220:223], v190 offset:21504
	ds_read_b128 v[224:227], v190 offset:22528
	ds_read_b128 v[228:231], v190 offset:23552
	v_lshl_add_u64 v[176:177], s[88:89], 0, v[160:161]
	s_add_i32 m0, s9, 0x8000
	v_lshl_add_u64 v[232:233], s[88:89], 0, v[162:163]
	global_load_lds_dwordx4 v[176:177], off
	s_add_i32 m0, s9, 0xa000
	v_lshl_add_u64 v[234:235], s[82:83], 0, v[160:161]
	global_load_lds_dwordx4 v[232:233], off
	s_add_i32 m0, s9, 0x18000
	v_lshl_add_u64 v[236:237], s[82:83], 0, v[162:163]
	global_load_lds_dwordx4 v[234:235], off
	s_add_i32 m0, s9, 0x1a000
	s_add_u32 s88, s88, 0x80
	s_addc_u32 s89, s89, 0
	global_load_lds_dwordx4 v[236:237], off
	s_add_u32 s82, s82, 0x80
	s_addc_u32 s83, s83, 0
	s_waitcnt vmcnt(8)
	s_waitcnt lgkmcnt(0)
	s_barrier
	s_setprio 1
	v_mfma_f32_16x16x32_bf16 v[140:143], v[28:31], v[200:203], v[140:143]
	v_mfma_f32_16x16x32_bf16 v[136:139], v[40:43], v[200:203], v[136:139]
	v_mfma_f32_16x16x32_bf16 v[124:127], v[28:31], v[208:211], v[124:127]
	v_mfma_f32_16x16x32_bf16 v[120:123], v[40:43], v[208:211], v[120:123]
	v_mfma_f32_16x16x32_bf16 v[108:111], v[28:31], v[216:219], v[108:111]
	v_mfma_f32_16x16x32_bf16 v[104:107], v[40:43], v[216:219], v[104:107]
	v_mfma_f32_16x16x32_bf16 v[92:95], v[28:31], v[224:227], v[92:95]
	v_mfma_f32_16x16x32_bf16 v[88:91], v[40:43], v[224:227], v[88:91]
	v_mfma_f32_16x16x32_bf16 v[140:143], v[32:35], v[204:207], v[140:143]
	v_mfma_f32_16x16x32_bf16 v[136:139], v[44:47], v[204:207], v[136:139]
	v_mfma_f32_16x16x32_bf16 v[124:127], v[32:35], v[212:215], v[124:127]
	v_mfma_f32_16x16x32_bf16 v[120:123], v[44:47], v[212:215], v[120:123]
	v_mfma_f32_16x16x32_bf16 v[108:111], v[32:35], v[220:223], v[108:111]
	v_mfma_f32_16x16x32_bf16 v[104:107], v[44:47], v[220:223], v[104:107]
	v_mfma_f32_16x16x32_bf16 v[92:95], v[32:35], v[228:231], v[92:95]
	v_mfma_f32_16x16x32_bf16 v[88:91], v[44:47], v[228:231], v[88:91]
	s_setprio 0
	s_barrier
	v_add_u32_e32 v144, 0x1c000, v178
	ds_read_b128 v[28:31], v144
	ds_read_b128 v[32:35], v144 offset:1024
	ds_read_b128 v[40:43], v144 offset:2048
	ds_read_b128 v[44:47], v144 offset:3072
	ds_read_b128 v[200:203], v190 offset:49152
	ds_read_b128 v[204:207], v190 offset:50176
	ds_read_b128 v[208:211], v190 offset:51200
	ds_read_b128 v[212:215], v190 offset:52224
	ds_read_b128 v[216:219], v190 offset:53248
	ds_read_b128 v[220:223], v190 offset:54272
	ds_read_b128 v[224:227], v190 offset:55296
	ds_read_b128 v[228:231], v190 offset:56320
	v_lshl_add_u64 v[176:177], s[88:89], 0, v[160:161]
	s_add_i32 m0, s9, 0x4000
	v_lshl_add_u64 v[232:233], s[88:89], 0, v[162:163]
	global_load_lds_dwordx4 v[176:177], off
	s_add_i32 m0, s9, 0x6000
	v_lshl_add_u64 v[234:235], s[82:83], 0, v[160:161]
	global_load_lds_dwordx4 v[232:233], off
	s_add_i32 m0, s9, 0x14000
	v_lshl_add_u64 v[236:237], s[82:83], 0, v[162:163]
	global_load_lds_dwordx4 v[234:235], off
	s_add_i32 m0, s9, 0x16000
	s_add_u32 s88, s88, 0x80
	s_addc_u32 s89, s89, 0
	global_load_lds_dwordx4 v[236:237], off
	s_add_u32 s82, s82, 0x80
	s_addc_u32 s83, s83, 0
	s_waitcnt vmcnt(8)
	s_waitcnt lgkmcnt(0)
	s_barrier
	s_setprio 1
	v_mfma_f32_16x16x32_bf16 v[140:143], v[28:31], v[200:203], v[140:143]
	v_mfma_f32_16x16x32_bf16 v[136:139], v[40:43], v[200:203], v[136:139]
	v_mfma_f32_16x16x32_bf16 v[124:127], v[28:31], v[208:211], v[124:127]
	v_mfma_f32_16x16x32_bf16 v[120:123], v[40:43], v[208:211], v[120:123]
	v_mfma_f32_16x16x32_bf16 v[108:111], v[28:31], v[216:219], v[108:111]
	v_mfma_f32_16x16x32_bf16 v[104:107], v[40:43], v[216:219], v[104:107]
	v_mfma_f32_16x16x32_bf16 v[92:95], v[28:31], v[224:227], v[92:95]
	v_mfma_f32_16x16x32_bf16 v[88:91], v[40:43], v[224:227], v[88:91]
	v_mfma_f32_16x16x32_bf16 v[140:143], v[32:35], v[204:207], v[140:143]
	v_mfma_f32_16x16x32_bf16 v[136:139], v[44:47], v[204:207], v[136:139]
	v_mfma_f32_16x16x32_bf16 v[124:127], v[32:35], v[212:215], v[124:127]
	v_mfma_f32_16x16x32_bf16 v[120:123], v[44:47], v[212:215], v[120:123]
	v_mfma_f32_16x16x32_bf16 v[108:111], v[32:35], v[220:223], v[108:111]
	v_mfma_f32_16x16x32_bf16 v[104:107], v[44:47], v[220:223], v[104:107]
	v_mfma_f32_16x16x32_bf16 v[92:95], v[32:35], v[228:231], v[92:95]
	v_mfma_f32_16x16x32_bf16 v[88:91], v[44:47], v[228:231], v[88:91]
	s_setprio 0
	s_barrier
	s_add_i32 s55, s55, 1
	s_cmp_lt_u32 s55, 7
	s_cbranch_scc1 .Lq_lout_0_k
	v_add_u32_e32 v144, 0x10000, v178
	ds_read_b128 v[28:31], v144
	ds_read_b128 v[32:35], v144 offset:1024
	ds_read_b128 v[40:43], v144 offset:2048
	ds_read_b128 v[44:47], v144 offset:3072
	ds_read_b128 v[200:203], v190 offset:0
	ds_read_b128 v[204:207], v190 offset:1024
	ds_read_b128 v[208:211], v190 offset:2048
	ds_read_b128 v[212:215], v190 offset:3072
	ds_read_b128 v[216:219], v190 offset:4096
	ds_read_b128 v[220:223], v190 offset:5120
	ds_read_b128 v[224:227], v190 offset:6144
	ds_read_b128 v[228:231], v190 offset:7168
	v_lshl_add_u64 v[176:177], s[88:89], 0, v[160:161]
	s_add_i32 m0, s9, 0xc000
	v_lshl_add_u64 v[232:233], s[88:89], 0, v[162:163]
	global_load_lds_dwordx4 v[176:177], off
	s_add_i32 m0, s9, 0xe000
	v_lshl_add_u64 v[234:235], s[82:83], 0, v[160:161]
	global_load_lds_dwordx4 v[232:233], off
	s_add_i32 m0, s9, 0x1c000
	v_lshl_add_u64 v[236:237], s[82:83], 0, v[162:163]
	global_load_lds_dwordx4 v[234:235], off
	s_add_i32 m0, s9, 0x1e000
	s_add_u32 s88, s88, 0x80
	s_addc_u32 s89, s89, 0
	global_load_lds_dwordx4 v[236:237], off
	s_add_u32 s82, s82, 0x80
	s_addc_u32 s83, s83, 0
	s_waitcnt vmcnt(8)
	s_waitcnt lgkmcnt(0)
	s_barrier
	s_setprio 1
	v_mfma_f32_16x16x32_bf16 v[140:143], v[28:31], v[200:203], v[140:143]
	v_mfma_f32_16x16x32_bf16 v[136:139], v[40:43], v[200:203], v[136:139]
	v_mfma_f32_16x16x32_bf16 v[124:127], v[28:31], v[208:211], v[124:127]
	v_mfma_f32_16x16x32_bf16 v[120:123], v[40:43], v[208:211], v[120:123]
	v_mfma_f32_16x16x32_bf16 v[108:111], v[28:31], v[216:219], v[108:111]
	v_mfma_f32_16x16x32_bf16 v[104:107], v[40:43], v[216:219], v[104:107]
	v_mfma_f32_16x16x32_bf16 v[92:95], v[28:31], v[224:227], v[92:95]
	v_mfma_f32_16x16x32_bf16 v[88:91], v[40:43], v[224:227], v[88:91]
	v_mfma_f32_16x16x32_bf16 v[140:143], v[32:35], v[204:207], v[140:143]
	v_mfma_f32_16x16x32_bf16 v[136:139], v[44:47], v[204:207], v[136:139]
	v_mfma_f32_16x16x32_bf16 v[124:127], v[32:35], v[212:215], v[124:127]
	v_mfma_f32_16x16x32_bf16 v[120:123], v[44:47], v[212:215], v[120:123]
	v_mfma_f32_16x16x32_bf16 v[108:111], v[32:35], v[220:223], v[108:111]
	v_mfma_f32_16x16x32_bf16 v[104:107], v[44:47], v[220:223], v[104:107]
	v_mfma_f32_16x16x32_bf16 v[92:95], v[32:35], v[228:231], v[92:95]
	v_mfma_f32_16x16x32_bf16 v[88:91], v[44:47], v[228:231], v[88:91]
	s_setprio 0
	s_barrier
	v_add_u32_e32 v144, 0x18000, v178
	ds_read_b128 v[28:31], v144
	ds_read_b128 v[32:35], v144 offset:1024
	ds_read_b128 v[40:43], v144 offset:2048
	ds_read_b128 v[44:47], v144 offset:3072
	ds_read_b128 v[200:203], v190 offset:32768
	ds_read_b128 v[204:207], v190 offset:33792
	ds_read_b128 v[208:211], v190 offset:34816
	ds_read_b128 v[212:215], v190 offset:35840
	ds_read_b128 v[216:219], v190 offset:36864
	ds_read_b128 v[220:223], v190 offset:37888
	ds_read_b128 v[224:227], v190 offset:38912
	ds_read_b128 v[228:231], v190 offset:39936
	s_waitcnt vmcnt(4)
	s_waitcnt lgkmcnt(0)
	s_barrier
	s_setprio 1
	v_mfma_f32_16x16x32_bf16 v[140:143], v[28:31], v[200:203], v[140:143]
	v_mfma_f32_16x16x32_bf16 v[136:139], v[40:43], v[200:203], v[136:139]
	v_mfma_f32_16x16x32_bf16 v[124:127], v[28:31], v[208:211], v[124:127]
	v_mfma_f32_16x16x32_bf16 v[120:123], v[40:43], v[208:211], v[120:123]
	v_mfma_f32_16x16x32_bf16 v[108:111], v[28:31], v[216:219], v[108:111]
	v_mfma_f32_16x16x32_bf16 v[104:107], v[40:43], v[216:219], v[104:107]
	v_mfma_f32_16x16x32_bf16 v[92:95], v[28:31], v[224:227], v[92:95]
	v_mfma_f32_16x16x32_bf16 v[88:91], v[40:43], v[224:227], v[88:91]
	v_mfma_f32_16x16x32_bf16 v[140:143], v[32:35], v[204:207], v[140:143]
	v_mfma_f32_16x16x32_bf16 v[136:139], v[44:47], v[204:207], v[136:139]
	v_mfma_f32_16x16x32_bf16 v[124:127], v[32:35], v[212:215], v[124:127]
	v_mfma_f32_16x16x32_bf16 v[120:123], v[44:47], v[212:215], v[120:123]
	v_mfma_f32_16x16x32_bf16 v[108:111], v[32:35], v[220:223], v[108:111]
	v_mfma_f32_16x16x32_bf16 v[104:107], v[44:47], v[220:223], v[104:107]
	v_mfma_f32_16x16x32_bf16 v[92:95], v[32:35], v[228:231], v[92:95]
	v_mfma_f32_16x16x32_bf16 v[88:91], v[44:47], v[228:231], v[88:91]
	s_setprio 0
	s_barrier
	v_add_u32_e32 v144, 0x14000, v178
	ds_read_b128 v[28:31], v144
	ds_read_b128 v[32:35], v144 offset:1024
	ds_read_b128 v[40:43], v144 offset:2048
	ds_read_b128 v[44:47], v144 offset:3072
	ds_read_b128 v[200:203], v190 offset:16384
	ds_read_b128 v[204:207], v190 offset:17408
	ds_read_b128 v[208:211], v190 offset:18432
	ds_read_b128 v[212:215], v190 offset:19456
	ds_read_b128 v[216:219], v190 offset:20480
	ds_read_b128 v[220:223], v190 offset:21504
	ds_read_b128 v[224:227], v190 offset:22528
	ds_read_b128 v[228:231], v190 offset:23552
	s_waitcnt vmcnt(0)
	s_waitcnt lgkmcnt(0)
	s_barrier
	s_setprio 1
	v_mfma_f32_16x16x32_bf16 v[140:143], v[28:31], v[200:203], v[140:143]
	v_mfma_f32_16x16x32_bf16 v[136:139], v[40:43], v[200:203], v[136:139]
	v_mfma_f32_16x16x32_bf16 v[124:127], v[28:31], v[208:211], v[124:127]
	v_mfma_f32_16x16x32_bf16 v[120:123], v[40:43], v[208:211], v[120:123]
	v_mfma_f32_16x16x32_bf16 v[108:111], v[28:31], v[216:219], v[108:111]
	v_mfma_f32_16x16x32_bf16 v[104:107], v[40:43], v[216:219], v[104:107]
	v_mfma_f32_16x16x32_bf16 v[92:95], v[28:31], v[224:227], v[92:95]
	v_mfma_f32_16x16x32_bf16 v[88:91], v[40:43], v[224:227], v[88:91]
	v_mfma_f32_16x16x32_bf16 v[140:143], v[32:35], v[204:207], v[140:143]
	v_mfma_f32_16x16x32_bf16 v[136:139], v[44:47], v[204:207], v[136:139]
	v_mfma_f32_16x16x32_bf16 v[124:127], v[32:35], v[212:215], v[124:127]
	v_mfma_f32_16x16x32_bf16 v[120:123], v[44:47], v[212:215], v[120:123]
	v_mfma_f32_16x16x32_bf16 v[108:111], v[32:35], v[220:223], v[108:111]
	v_mfma_f32_16x16x32_bf16 v[104:107], v[44:47], v[220:223], v[104:107]
	v_mfma_f32_16x16x32_bf16 v[92:95], v[32:35], v[228:231], v[92:95]
	v_mfma_f32_16x16x32_bf16 v[88:91], v[44:47], v[228:231], v[88:91]
	s_setprio 0
	s_barrier
	v_add_u32_e32 v144, 0x1c000, v178
	ds_read_b128 v[28:31], v144
	ds_read_b128 v[32:35], v144 offset:1024
	ds_read_b128 v[40:43], v144 offset:2048
	ds_read_b128 v[44:47], v144 offset:3072
	ds_read_b128 v[200:203], v190 offset:49152
	ds_read_b128 v[204:207], v190 offset:50176
	ds_read_b128 v[208:211], v190 offset:51200
	ds_read_b128 v[212:215], v190 offset:52224
	ds_read_b128 v[216:219], v190 offset:53248
	ds_read_b128 v[220:223], v190 offset:54272
	ds_read_b128 v[224:227], v190 offset:55296
	ds_read_b128 v[228:231], v190 offset:56320
	s_waitcnt lgkmcnt(0)
	s_barrier
	s_setprio 1
	v_mfma_f32_16x16x32_bf16 v[140:143], v[28:31], v[200:203], v[140:143]
	v_mfma_f32_16x16x32_bf16 v[136:139], v[40:43], v[200:203], v[136:139]
	v_mfma_f32_16x16x32_bf16 v[124:127], v[28:31], v[208:211], v[124:127]
	v_mfma_f32_16x16x32_bf16 v[120:123], v[40:43], v[208:211], v[120:123]
	v_mfma_f32_16x16x32_bf16 v[108:111], v[28:31], v[216:219], v[108:111]
	v_mfma_f32_16x16x32_bf16 v[104:107], v[40:43], v[216:219], v[104:107]
	v_mfma_f32_16x16x32_bf16 v[92:95], v[28:31], v[224:227], v[92:95]
	v_mfma_f32_16x16x32_bf16 v[88:91], v[40:43], v[224:227], v[88:91]
	v_mfma_f32_16x16x32_bf16 v[140:143], v[32:35], v[204:207], v[140:143]
	v_mfma_f32_16x16x32_bf16 v[136:139], v[44:47], v[204:207], v[136:139]
	v_mfma_f32_16x16x32_bf16 v[124:127], v[32:35], v[212:215], v[124:127]
	v_mfma_f32_16x16x32_bf16 v[120:123], v[44:47], v[212:215], v[120:123]
	v_mfma_f32_16x16x32_bf16 v[108:111], v[32:35], v[220:223], v[108:111]
	v_mfma_f32_16x16x32_bf16 v[104:107], v[44:47], v[220:223], v[104:107]
	v_mfma_f32_16x16x32_bf16 v[92:95], v[32:35], v[228:231], v[92:95]
	v_mfma_f32_16x16x32_bf16 v[88:91], v[44:47], v[228:231], v[88:91]
	s_setprio 0
	s_barrier
	s_branch .Lq_lout_exit

.Lq_lout_1_k:
	v_add_u32_e32 v144, 0x14000, v178
	ds_read_b128 v[168:171], v144
	ds_read_b128 v[172:175], v144 offset:1024
	ds_read_b128 v[192:195], v144 offset:2048
	ds_read_b128 v[196:199], v144 offset:3072
	ds_read_b128 v[200:203], v190 offset:0
	ds_read_b128 v[204:207], v190 offset:1024
	ds_read_b128 v[208:211], v190 offset:2048
	ds_read_b128 v[212:215], v190 offset:3072
	ds_read_b128 v[216:219], v190 offset:4096
	ds_read_b128 v[220:223], v190 offset:5120
	ds_read_b128 v[224:227], v190 offset:6144
	ds_read_b128 v[228:231], v190 offset:7168
	v_lshl_add_u64 v[176:177], s[88:89], 0, v[160:161]
	s_add_i32 m0, s9, 0xc000
	v_lshl_add_u64 v[232:233], s[88:89], 0, v[162:163]
	global_load_lds_dwordx4 v[176:177], off
	s_add_i32 m0, s9, 0xe000
	v_lshl_add_u64 v[234:235], s[82:83], 0, v[160:161]
	global_load_lds_dwordx4 v[232:233], off
	s_add_i32 m0, s9, 0x18000
	v_lshl_add_u64 v[236:237], s[82:83], 0, v[162:163]
	global_load_lds_dwordx4 v[234:235], off
	s_add_i32 m0, s9, 0x1a000
	s_add_u32 s88, s88, 0x80
	s_addc_u32 s89, s89, 0
	global_load_lds_dwordx4 v[236:237], off
	s_add_u32 s82, s82, 0x80
	s_addc_u32 s83, s83, 0
	s_waitcnt vmcnt(8)
	s_waitcnt lgkmcnt(0)
	s_barrier
	s_setprio 1
	v_mfma_f32_16x16x32_bf16 v[132:135], v[168:171], v[200:203], v[132:135]
	v_mfma_f32_16x16x32_bf16 v[128:131], v[192:195], v[200:203], v[128:131]
	v_mfma_f32_16x16x32_bf16 v[116:119], v[168:171], v[208:211], v[116:119]
	v_mfma_f32_16x16x32_bf16 v[112:115], v[192:195], v[208:211], v[112:115]
	v_mfma_f32_16x16x32_bf16 v[100:103], v[168:171], v[216:219], v[100:103]
	v_mfma_f32_16x16x32_bf16 v[96:99], v[192:195], v[216:219], v[96:99]
	v_mfma_f32_16x16x32_bf16 v[84:87], v[168:171], v[224:227], v[84:87]
	v_mfma_f32_16x16x32_bf16 v[80:83], v[192:195], v[224:227], v[80:83]
	v_mfma_f32_16x16x32_bf16 v[132:135], v[172:175], v[204:207], v[132:135]
	v_mfma_f32_16x16x32_bf16 v[128:131], v[196:199], v[204:207], v[128:131]
	v_mfma_f32_16x16x32_bf16 v[116:119], v[172:175], v[212:215], v[116:119]
	v_mfma_f32_16x16x32_bf16 v[112:115], v[196:199], v[212:215], v[112:115]
	v_mfma_f32_16x16x32_bf16 v[100:103], v[172:175], v[220:223], v[100:103]
	v_mfma_f32_16x16x32_bf16 v[96:99], v[196:199], v[220:223], v[96:99]
	v_mfma_f32_16x16x32_bf16 v[84:87], v[172:175], v[228:231], v[84:87]
	v_mfma_f32_16x16x32_bf16 v[80:83], v[196:199], v[228:231], v[80:83]
	s_setprio 0
	s_barrier
	v_add_u32_e32 v144, 0x1c000, v178
	ds_read_b128 v[168:171], v144
	ds_read_b128 v[172:175], v144 offset:1024
	ds_read_b128 v[192:195], v144 offset:2048
	ds_read_b128 v[196:199], v144 offset:3072
	ds_read_b128 v[200:203], v190 offset:32768
	ds_read_b128 v[204:207], v190 offset:33792
	ds_read_b128 v[208:211], v190 offset:34816
	ds_read_b128 v[212:215], v190 offset:35840
	ds_read_b128 v[216:219], v190 offset:36864
	ds_read_b128 v[220:223], v190 offset:37888
	ds_read_b128 v[224:227], v190 offset:38912
	ds_read_b128 v[228:231], v190 offset:39936
	v_lshl_add_u64 v[176:177], s[88:89], 0, v[160:161]
	s_add_i32 m0, s9, 0x0
	v_lshl_add_u64 v[232:233], s[88:89], 0, v[162:163]
	global_load_lds_dwordx4 v[176:177], off
	s_add_i32 m0, s9, 0x2000
	v_lshl_add_u64 v[234:235], s[82:83], 0, v[160:161]
	global_load_lds_dwordx4 v[232:233], off
	s_add_i32 m0, s9, 0x14000
	v_lshl_add_u64 v[236:237], s[82:83], 0, v[162:163]
	global_load_lds_dwordx4 v[234:235], off
	s_add_i32 m0, s9, 0x16000
	s_add_u32 s88, s88, 0x80
	s_addc_u32 s89, s89, 0
	global_load_lds_dwordx4 v[236:237], off
	s_add_u32 s82, s82, 0x80
	s_addc_u32 s83, s83, 0
	s_waitcnt vmcnt(8)
	s_waitcnt lgkmcnt(0)
	s_barrier
	s_setprio 1
	v_mfma_f32_16x16x32_bf16 v[132:135], v[168:171], v[200:203], v[132:135]
	v_mfma_f32_16x16x32_bf16 v[128:131], v[192:195], v[200:203], v[128:131]
	v_mfma_f32_16x16x32_bf16 v[116:119], v[168:171], v[208:211], v[116:119]
	v_mfma_f32_16x16x32_bf16 v[112:115], v[192:195], v[208:211], v[112:115]
	v_mfma_f32_16x16x32_bf16 v[100:103], v[168:171], v[216:219], v[100:103]
	v_mfma_f32_16x16x32_bf16 v[96:99], v[192:195], v[216:219], v[96:99]
	v_mfma_f32_16x16x32_bf16 v[84:87], v[168:171], v[224:227], v[84:87]
	v_mfma_f32_16x16x32_bf16 v[80:83], v[192:195], v[224:227], v[80:83]
	v_mfma_f32_16x16x32_bf16 v[132:135], v[172:175], v[204:207], v[132:135]
	v_mfma_f32_16x16x32_bf16 v[128:131], v[196:199], v[204:207], v[128:131]
	v_mfma_f32_16x16x32_bf16 v[116:119], v[172:175], v[212:215], v[116:119]
	v_mfma_f32_16x16x32_bf16 v[112:115], v[196:199], v[212:215], v[112:115]
	v_mfma_f32_16x16x32_bf16 v[100:103], v[172:175], v[220:223], v[100:103]
	v_mfma_f32_16x16x32_bf16 v[96:99], v[196:199], v[220:223], v[96:99]
	v_mfma_f32_16x16x32_bf16 v[84:87], v[172:175], v[228:231], v[84:87]
	v_mfma_f32_16x16x32_bf16 v[80:83], v[196:199], v[228:231], v[80:83]
	s_setprio 0
	s_barrier
	v_add_u32_e32 v144, 0x10000, v178
	ds_read_b128 v[168:171], v144
	ds_read_b128 v[172:175], v144 offset:1024
	ds_read_b128 v[192:195], v144 offset:2048
	ds_read_b128 v[196:199], v144 offset:3072
	ds_read_b128 v[200:203], v190 offset:16384
	ds_read_b128 v[204:207], v190 offset:17408
	ds_read_b128 v[208:211], v190 offset:18432
	ds_read_b128 v[212:215], v190 offset:19456
	ds_read_b128 v[216:219], v190 offset:20480
	ds_read_b128 v[220:223], v190 offset:21504
	ds_read_b128 v[224:227], v190 offset:22528
	ds_read_b128 v[228:231], v190 offset:23552
	v_lshl_add_u64 v[176:177], s[88:89], 0, v[160:161]
	s_add_i32 m0, s9, 0x8000
	v_lshl_add_u64 v[232:233], s[88:89], 0, v[162:163]
	global_load_lds_dwordx4 v[176:177], off
	s_add_i32 m0, s9, 0xa000
	v_lshl_add_u64 v[234:235], s[82:83], 0, v[160:161]
	global_load_lds_dwordx4 v[232:233], off
	s_add_i32 m0, s9, 0x1c000
	v_lshl_add_u64 v[236:237], s[82:83], 0, v[162:163]
	global_load_lds_dwordx4 v[234:235], off
	s_add_i32 m0, s9, 0x1e000
	s_add_u32 s88, s88, 0x80
	s_addc_u32 s89, s89, 0
	global_load_lds_dwordx4 v[236:237], off
	s_add_u32 s82, s82, 0x80
	s_addc_u32 s83, s83, 0
	s_waitcnt vmcnt(8)
	s_waitcnt lgkmcnt(0)
	s_barrier
	s_setprio 1
	v_mfma_f32_16x16x32_bf16 v[132:135], v[168:171], v[200:203], v[132:135]
	v_mfma_f32_16x16x32_bf16 v[128:131], v[192:195], v[200:203], v[128:131]
	v_mfma_f32_16x16x32_bf16 v[116:119], v[168:171], v[208:211], v[116:119]
	v_mfma_f32_16x16x32_bf16 v[112:115], v[192:195], v[208:211], v[112:115]
	v_mfma_f32_16x16x32_bf16 v[100:103], v[168:171], v[216:219], v[100:103]
	v_mfma_f32_16x16x32_bf16 v[96:99], v[192:195], v[216:219], v[96:99]
	v_mfma_f32_16x16x32_bf16 v[84:87], v[168:171], v[224:227], v[84:87]
	v_mfma_f32_16x16x32_bf16 v[80:83], v[192:195], v[224:227], v[80:83]
	v_mfma_f32_16x16x32_bf16 v[132:135], v[172:175], v[204:207], v[132:135]
	v_mfma_f32_16x16x32_bf16 v[128:131], v[196:199], v[204:207], v[128:131]
	v_mfma_f32_16x16x32_bf16 v[116:119], v[172:175], v[212:215], v[116:119]
	v_mfma_f32_16x16x32_bf16 v[112:115], v[196:199], v[212:215], v[112:115]
	v_mfma_f32_16x16x32_bf16 v[100:103], v[172:175], v[220:223], v[100:103]
	v_mfma_f32_16x16x32_bf16 v[96:99], v[196:199], v[220:223], v[96:99]
	v_mfma_f32_16x16x32_bf16 v[84:87], v[172:175], v[228:231], v[84:87]
	v_mfma_f32_16x16x32_bf16 v[80:83], v[196:199], v[228:231], v[80:83]
	s_setprio 0
	s_barrier
	v_add_u32_e32 v144, 0x18000, v178
	ds_read_b128 v[168:171], v144
	ds_read_b128 v[172:175], v144 offset:1024
	ds_read_b128 v[192:195], v144 offset:2048
	ds_read_b128 v[196:199], v144 offset:3072
	ds_read_b128 v[200:203], v190 offset:49152
	ds_read_b128 v[204:207], v190 offset:50176
	ds_read_b128 v[208:211], v190 offset:51200
	ds_read_b128 v[212:215], v190 offset:52224
	ds_read_b128 v[216:219], v190 offset:53248
	ds_read_b128 v[220:223], v190 offset:54272
	ds_read_b128 v[224:227], v190 offset:55296
	ds_read_b128 v[228:231], v190 offset:56320
	v_lshl_add_u64 v[176:177], s[88:89], 0, v[160:161]
	s_add_i32 m0, s9, 0x4000
	v_lshl_add_u64 v[232:233], s[88:89], 0, v[162:163]
	global_load_lds_dwordx4 v[176:177], off
	s_add_i32 m0, s9, 0x6000
	v_lshl_add_u64 v[234:235], s[82:83], 0, v[160:161]
	global_load_lds_dwordx4 v[232:233], off
	s_add_i32 m0, s9, 0x10000
	v_lshl_add_u64 v[236:237], s[82:83], 0, v[162:163]
	global_load_lds_dwordx4 v[234:235], off
	s_add_i32 m0, s9, 0x12000
	s_add_u32 s88, s88, 0x80
	s_addc_u32 s89, s89, 0
	global_load_lds_dwordx4 v[236:237], off
	s_add_u32 s82, s82, 0x80
	s_addc_u32 s83, s83, 0
	s_waitcnt vmcnt(8)
	s_waitcnt lgkmcnt(0)
	s_barrier
	s_setprio 1
	v_mfma_f32_16x16x32_bf16 v[132:135], v[168:171], v[200:203], v[132:135]
	v_mfma_f32_16x16x32_bf16 v[128:131], v[192:195], v[200:203], v[128:131]
	v_mfma_f32_16x16x32_bf16 v[116:119], v[168:171], v[208:211], v[116:119]
	v_mfma_f32_16x16x32_bf16 v[112:115], v[192:195], v[208:211], v[112:115]
	v_mfma_f32_16x16x32_bf16 v[100:103], v[168:171], v[216:219], v[100:103]
	v_mfma_f32_16x16x32_bf16 v[96:99], v[192:195], v[216:219], v[96:99]
	v_mfma_f32_16x16x32_bf16 v[84:87], v[168:171], v[224:227], v[84:87]
	v_mfma_f32_16x16x32_bf16 v[80:83], v[192:195], v[224:227], v[80:83]
	v_mfma_f32_16x16x32_bf16 v[132:135], v[172:175], v[204:207], v[132:135]
	v_mfma_f32_16x16x32_bf16 v[128:131], v[196:199], v[204:207], v[128:131]
	v_mfma_f32_16x16x32_bf16 v[116:119], v[172:175], v[212:215], v[116:119]
	v_mfma_f32_16x16x32_bf16 v[112:115], v[196:199], v[212:215], v[112:115]
	v_mfma_f32_16x16x32_bf16 v[100:103], v[172:175], v[220:223], v[100:103]
	v_mfma_f32_16x16x32_bf16 v[96:99], v[196:199], v[220:223], v[96:99]
	v_mfma_f32_16x16x32_bf16 v[84:87], v[172:175], v[228:231], v[84:87]
	v_mfma_f32_16x16x32_bf16 v[80:83], v[196:199], v[228:231], v[80:83]
	s_setprio 0
	s_barrier
	s_add_i32 s55, s55, 1
	s_cmp_lt_u32 s55, 7
	s_cbranch_scc1 .Lq_lout_1_k
	v_add_u32_e32 v144, 0x14000, v178
	ds_read_b128 v[168:171], v144
	ds_read_b128 v[172:175], v144 offset:1024
	ds_read_b128 v[192:195], v144 offset:2048
	ds_read_b128 v[196:199], v144 offset:3072
	ds_read_b128 v[200:203], v190 offset:0
	ds_read_b128 v[204:207], v190 offset:1024
	ds_read_b128 v[208:211], v190 offset:2048
	ds_read_b128 v[212:215], v190 offset:3072
	ds_read_b128 v[216:219], v190 offset:4096
	ds_read_b128 v[220:223], v190 offset:5120
	ds_read_b128 v[224:227], v190 offset:6144
	ds_read_b128 v[228:231], v190 offset:7168
	v_lshl_add_u64 v[176:177], s[88:89], 0, v[160:161]
	s_add_i32 m0, s9, 0xc000
	v_lshl_add_u64 v[232:233], s[88:89], 0, v[162:163]
	global_load_lds_dwordx4 v[176:177], off
	s_add_i32 m0, s9, 0xe000
	v_lshl_add_u64 v[234:235], s[82:83], 0, v[160:161]
	global_load_lds_dwordx4 v[232:233], off
	s_add_i32 m0, s9, 0x18000
	v_lshl_add_u64 v[236:237], s[82:83], 0, v[162:163]
	global_load_lds_dwordx4 v[234:235], off
	s_add_i32 m0, s9, 0x1a000
	s_add_u32 s88, s88, 0x80
	s_addc_u32 s89, s89, 0
	global_load_lds_dwordx4 v[236:237], off
	s_add_u32 s82, s82, 0x80
	s_addc_u32 s83, s83, 0
	s_waitcnt vmcnt(8)
	s_waitcnt lgkmcnt(0)
	s_barrier
	s_setprio 1
	v_mfma_f32_16x16x32_bf16 v[132:135], v[168:171], v[200:203], v[132:135]
	v_mfma_f32_16x16x32_bf16 v[128:131], v[192:195], v[200:203], v[128:131]
	v_mfma_f32_16x16x32_bf16 v[116:119], v[168:171], v[208:211], v[116:119]
	v_mfma_f32_16x16x32_bf16 v[112:115], v[192:195], v[208:211], v[112:115]
	v_mfma_f32_16x16x32_bf16 v[100:103], v[168:171], v[216:219], v[100:103]
	v_mfma_f32_16x16x32_bf16 v[96:99], v[192:195], v[216:219], v[96:99]
	v_mfma_f32_16x16x32_bf16 v[84:87], v[168:171], v[224:227], v[84:87]
	v_mfma_f32_16x16x32_bf16 v[80:83], v[192:195], v[224:227], v[80:83]
	v_mfma_f32_16x16x32_bf16 v[132:135], v[172:175], v[204:207], v[132:135]
	v_mfma_f32_16x16x32_bf16 v[128:131], v[196:199], v[204:207], v[128:131]
	v_mfma_f32_16x16x32_bf16 v[116:119], v[172:175], v[212:215], v[116:119]
	v_mfma_f32_16x16x32_bf16 v[112:115], v[196:199], v[212:215], v[112:115]
	v_mfma_f32_16x16x32_bf16 v[100:103], v[172:175], v[220:223], v[100:103]
	v_mfma_f32_16x16x32_bf16 v[96:99], v[196:199], v[220:223], v[96:99]
	v_mfma_f32_16x16x32_bf16 v[84:87], v[172:175], v[228:231], v[84:87]
	v_mfma_f32_16x16x32_bf16 v[80:83], v[196:199], v[228:231], v[80:83]
	s_setprio 0
	s_barrier
	v_add_u32_e32 v144, 0x1c000, v178
	ds_read_b128 v[168:171], v144
	ds_read_b128 v[172:175], v144 offset:1024
	ds_read_b128 v[192:195], v144 offset:2048
	ds_read_b128 v[196:199], v144 offset:3072
	ds_read_b128 v[200:203], v190 offset:32768
	ds_read_b128 v[204:207], v190 offset:33792
	ds_read_b128 v[208:211], v190 offset:34816
	ds_read_b128 v[212:215], v190 offset:35840
	ds_read_b128 v[216:219], v190 offset:36864
	ds_read_b128 v[220:223], v190 offset:37888
	ds_read_b128 v[224:227], v190 offset:38912
	ds_read_b128 v[228:231], v190 offset:39936
	s_waitcnt vmcnt(4)
	s_waitcnt lgkmcnt(0)
	s_barrier
	s_setprio 1
	v_mfma_f32_16x16x32_bf16 v[132:135], v[168:171], v[200:203], v[132:135]
	v_mfma_f32_16x16x32_bf16 v[128:131], v[192:195], v[200:203], v[128:131]
	v_mfma_f32_16x16x32_bf16 v[116:119], v[168:171], v[208:211], v[116:119]
	v_mfma_f32_16x16x32_bf16 v[112:115], v[192:195], v[208:211], v[112:115]
	v_mfma_f32_16x16x32_bf16 v[100:103], v[168:171], v[216:219], v[100:103]
	v_mfma_f32_16x16x32_bf16 v[96:99], v[192:195], v[216:219], v[96:99]
	v_mfma_f32_16x16x32_bf16 v[84:87], v[168:171], v[224:227], v[84:87]
	v_mfma_f32_16x16x32_bf16 v[80:83], v[192:195], v[224:227], v[80:83]
	v_mfma_f32_16x16x32_bf16 v[132:135], v[172:175], v[204:207], v[132:135]
	v_mfma_f32_16x16x32_bf16 v[128:131], v[196:199], v[204:207], v[128:131]
	v_mfma_f32_16x16x32_bf16 v[116:119], v[172:175], v[212:215], v[116:119]
	v_mfma_f32_16x16x32_bf16 v[112:115], v[196:199], v[212:215], v[112:115]
	v_mfma_f32_16x16x32_bf16 v[100:103], v[172:175], v[220:223], v[100:103]
	v_mfma_f32_16x16x32_bf16 v[96:99], v[196:199], v[220:223], v[96:99]
	v_mfma_f32_16x16x32_bf16 v[84:87], v[172:175], v[228:231], v[84:87]
	v_mfma_f32_16x16x32_bf16 v[80:83], v[196:199], v[228:231], v[80:83]
	s_setprio 0
	s_barrier
	v_add_u32_e32 v144, 0x10000, v178
	ds_read_b128 v[168:171], v144
	ds_read_b128 v[172:175], v144 offset:1024
	ds_read_b128 v[192:195], v144 offset:2048
	ds_read_b128 v[196:199], v144 offset:3072
	ds_read_b128 v[200:203], v190 offset:16384
	ds_read_b128 v[204:207], v190 offset:17408
	ds_read_b128 v[208:211], v190 offset:18432
	ds_read_b128 v[212:215], v190 offset:19456
	ds_read_b128 v[216:219], v190 offset:20480
	ds_read_b128 v[220:223], v190 offset:21504
	ds_read_b128 v[224:227], v190 offset:22528
	ds_read_b128 v[228:231], v190 offset:23552
	s_waitcnt vmcnt(0)
	s_waitcnt lgkmcnt(0)
	s_barrier
	s_setprio 1
	v_mfma_f32_16x16x32_bf16 v[132:135], v[168:171], v[200:203], v[132:135]
	v_mfma_f32_16x16x32_bf16 v[128:131], v[192:195], v[200:203], v[128:131]
	v_mfma_f32_16x16x32_bf16 v[116:119], v[168:171], v[208:211], v[116:119]
	v_mfma_f32_16x16x32_bf16 v[112:115], v[192:195], v[208:211], v[112:115]
	v_mfma_f32_16x16x32_bf16 v[100:103], v[168:171], v[216:219], v[100:103]
	v_mfma_f32_16x16x32_bf16 v[96:99], v[192:195], v[216:219], v[96:99]
	v_mfma_f32_16x16x32_bf16 v[84:87], v[168:171], v[224:227], v[84:87]
	v_mfma_f32_16x16x32_bf16 v[80:83], v[192:195], v[224:227], v[80:83]
	v_mfma_f32_16x16x32_bf16 v[132:135], v[172:175], v[204:207], v[132:135]
	v_mfma_f32_16x16x32_bf16 v[128:131], v[196:199], v[204:207], v[128:131]
	v_mfma_f32_16x16x32_bf16 v[116:119], v[172:175], v[212:215], v[116:119]
	v_mfma_f32_16x16x32_bf16 v[112:115], v[196:199], v[212:215], v[112:115]
	v_mfma_f32_16x16x32_bf16 v[100:103], v[172:175], v[220:223], v[100:103]
	v_mfma_f32_16x16x32_bf16 v[96:99], v[196:199], v[220:223], v[96:99]
	v_mfma_f32_16x16x32_bf16 v[84:87], v[172:175], v[228:231], v[84:87]
	v_mfma_f32_16x16x32_bf16 v[80:83], v[196:199], v[228:231], v[80:83]
	s_setprio 0
	s_barrier
	v_add_u32_e32 v144, 0x18000, v178
	ds_read_b128 v[168:171], v144
	ds_read_b128 v[172:175], v144 offset:1024
	ds_read_b128 v[192:195], v144 offset:2048
	ds_read_b128 v[196:199], v144 offset:3072
	ds_read_b128 v[200:203], v190 offset:49152
	ds_read_b128 v[204:207], v190 offset:50176
	ds_read_b128 v[208:211], v190 offset:51200
	ds_read_b128 v[212:215], v190 offset:52224
	ds_read_b128 v[216:219], v190 offset:53248
	ds_read_b128 v[220:223], v190 offset:54272
	ds_read_b128 v[224:227], v190 offset:55296
	ds_read_b128 v[228:231], v190 offset:56320
	s_waitcnt lgkmcnt(0)
	s_barrier
	s_setprio 1
	v_mfma_f32_16x16x32_bf16 v[132:135], v[168:171], v[200:203], v[132:135]
	v_mfma_f32_16x16x32_bf16 v[128:131], v[192:195], v[200:203], v[128:131]
	v_mfma_f32_16x16x32_bf16 v[116:119], v[168:171], v[208:211], v[116:119]
	v_mfma_f32_16x16x32_bf16 v[112:115], v[192:195], v[208:211], v[112:115]
	v_mfma_f32_16x16x32_bf16 v[100:103], v[168:171], v[216:219], v[100:103]
	v_mfma_f32_16x16x32_bf16 v[96:99], v[192:195], v[216:219], v[96:99]
	v_mfma_f32_16x16x32_bf16 v[84:87], v[168:171], v[224:227], v[84:87]
	v_mfma_f32_16x16x32_bf16 v[80:83], v[192:195], v[224:227], v[80:83]
	v_mfma_f32_16x16x32_bf16 v[132:135], v[172:175], v[204:207], v[132:135]
	v_mfma_f32_16x16x32_bf16 v[128:131], v[196:199], v[204:207], v[128:131]
	v_mfma_f32_16x16x32_bf16 v[116:119], v[172:175], v[212:215], v[116:119]
	v_mfma_f32_16x16x32_bf16 v[112:115], v[196:199], v[212:215], v[112:115]
	v_mfma_f32_16x16x32_bf16 v[100:103], v[172:175], v[220:223], v[100:103]
	v_mfma_f32_16x16x32_bf16 v[96:99], v[196:199], v[220:223], v[96:99]
	v_mfma_f32_16x16x32_bf16 v[84:87], v[172:175], v[228:231], v[84:87]
	v_mfma_f32_16x16x32_bf16 v[80:83], v[196:199], v[228:231], v[80:83]
	s_setprio 0
	s_barrier
	s_branch .Lq_lout_exit

.Lq_lout_2_k:
	v_add_u32_e32 v144, 0x10000, v178
	ds_read_b128 v[28:31], v144
	ds_read_b128 v[32:35], v144 offset:1024
	ds_read_b128 v[40:43], v144 offset:2048
	ds_read_b128 v[44:47], v144 offset:3072
	ds_read_b128 v[200:203], v190 offset:16384
	ds_read_b128 v[204:207], v190 offset:17408
	ds_read_b128 v[208:211], v190 offset:18432
	ds_read_b128 v[212:215], v190 offset:19456
	ds_read_b128 v[216:219], v190 offset:20480
	ds_read_b128 v[220:223], v190 offset:21504
	ds_read_b128 v[224:227], v190 offset:22528
	ds_read_b128 v[228:231], v190 offset:23552
	v_lshl_add_u64 v[176:177], s[88:89], 0, v[160:161]
	s_add_i32 m0, s9, 0x8000
	v_lshl_add_u64 v[232:233], s[88:89], 0, v[162:163]
	global_load_lds_dwordx4 v[176:177], off
	s_add_i32 m0, s9, 0xa000
	v_lshl_add_u64 v[234:235], s[82:83], 0, v[160:161]
	global_load_lds_dwordx4 v[232:233], off
	s_add_i32 m0, s9, 0x1c000
	v_lshl_add_u64 v[236:237], s[82:83], 0, v[162:163]
	global_load_lds_dwordx4 v[234:235], off
	s_add_i32 m0, s9, 0x1e000
	s_add_u32 s88, s88, 0x80
	s_addc_u32 s89, s89, 0
	global_load_lds_dwordx4 v[236:237], off
	s_add_u32 s82, s82, 0x80
	s_addc_u32 s83, s83, 0
	s_waitcnt vmcnt(8)
	s_waitcnt lgkmcnt(0)
	s_barrier
	s_setprio 1
	v_mfma_f32_16x16x32_bf16 v[76:79], v[28:31], v[200:203], v[76:79]
	v_mfma_f32_16x16x32_bf16 v[72:75], v[40:43], v[200:203], v[72:75]
	v_mfma_f32_16x16x32_bf16 v[60:63], v[28:31], v[208:211], v[60:63]
	v_mfma_f32_16x16x32_bf16 v[56:59], v[40:43], v[208:211], v[56:59]
	v_mfma_f32_16x16x32_bf16 v[36:39], v[28:31], v[216:219], v[36:39]
	v_mfma_f32_16x16x32_bf16 v[24:27], v[40:43], v[216:219], v[24:27]
	v_mfma_f32_16x16x32_bf16 v[12:15], v[28:31], v[224:227], v[12:15]
	v_mfma_f32_16x16x32_bf16 v[8:11], v[40:43], v[224:227], v[8:11]
	v_mfma_f32_16x16x32_bf16 v[76:79], v[32:35], v[204:207], v[76:79]
	v_mfma_f32_16x16x32_bf16 v[72:75], v[44:47], v[204:207], v[72:75]
	v_mfma_f32_16x16x32_bf16 v[60:63], v[32:35], v[212:215], v[60:63]
	v_mfma_f32_16x16x32_bf16 v[56:59], v[44:47], v[212:215], v[56:59]
	v_mfma_f32_16x16x32_bf16 v[36:39], v[32:35], v[220:223], v[36:39]
	v_mfma_f32_16x16x32_bf16 v[24:27], v[44:47], v[220:223], v[24:27]
	v_mfma_f32_16x16x32_bf16 v[12:15], v[32:35], v[228:231], v[12:15]
	v_mfma_f32_16x16x32_bf16 v[8:11], v[44:47], v[228:231], v[8:11]
	s_setprio 0
	s_barrier
	v_add_u32_e32 v144, 0x18000, v178
	ds_read_b128 v[28:31], v144
	ds_read_b128 v[32:35], v144 offset:1024
	ds_read_b128 v[40:43], v144 offset:2048
	ds_read_b128 v[44:47], v144 offset:3072
	ds_read_b128 v[200:203], v190 offset:49152
	ds_read_b128 v[204:207], v190 offset:50176
	ds_read_b128 v[208:211], v190 offset:51200
	ds_read_b128 v[212:215], v190 offset:52224
	ds_read_b128 v[216:219], v190 offset:53248
	ds_read_b128 v[220:223], v190 offset:54272
	ds_read_b128 v[224:227], v190 offset:55296
	ds_read_b128 v[228:231], v190 offset:56320
	v_lshl_add_u64 v[176:177], s[88:89], 0, v[160:161]
	s_add_i32 m0, s9, 0x4000
	v_lshl_add_u64 v[232:233], s[88:89], 0, v[162:163]
	global_load_lds_dwordx4 v[176:177], off
	s_add_i32 m0, s9, 0x6000
	v_lshl_add_u64 v[234:235], s[82:83], 0, v[160:161]
	global_load_lds_dwordx4 v[232:233], off
	s_add_i32 m0, s9, 0x10000
	v_lshl_add_u64 v[236:237], s[82:83], 0, v[162:163]
	global_load_lds_dwordx4 v[234:235], off
	s_add_i32 m0, s9, 0x12000
	s_add_u32 s88, s88, 0x80
	s_addc_u32 s89, s89, 0
	global_load_lds_dwordx4 v[236:237], off
	s_add_u32 s82, s82, 0x80
	s_addc_u32 s83, s83, 0
	s_waitcnt vmcnt(8)
	s_waitcnt lgkmcnt(0)
	s_barrier
	s_setprio 1
	v_mfma_f32_16x16x32_bf16 v[76:79], v[28:31], v[200:203], v[76:79]
	v_mfma_f32_16x16x32_bf16 v[72:75], v[40:43], v[200:203], v[72:75]
	v_mfma_f32_16x16x32_bf16 v[60:63], v[28:31], v[208:211], v[60:63]
	v_mfma_f32_16x16x32_bf16 v[56:59], v[40:43], v[208:211], v[56:59]
	v_mfma_f32_16x16x32_bf16 v[36:39], v[28:31], v[216:219], v[36:39]
	v_mfma_f32_16x16x32_bf16 v[24:27], v[40:43], v[216:219], v[24:27]
	v_mfma_f32_16x16x32_bf16 v[12:15], v[28:31], v[224:227], v[12:15]
	v_mfma_f32_16x16x32_bf16 v[8:11], v[40:43], v[224:227], v[8:11]
	v_mfma_f32_16x16x32_bf16 v[76:79], v[32:35], v[204:207], v[76:79]
	v_mfma_f32_16x16x32_bf16 v[72:75], v[44:47], v[204:207], v[72:75]
	v_mfma_f32_16x16x32_bf16 v[60:63], v[32:35], v[212:215], v[60:63]
	v_mfma_f32_16x16x32_bf16 v[56:59], v[44:47], v[212:215], v[56:59]
	v_mfma_f32_16x16x32_bf16 v[36:39], v[32:35], v[220:223], v[36:39]
	v_mfma_f32_16x16x32_bf16 v[24:27], v[44:47], v[220:223], v[24:27]
	v_mfma_f32_16x16x32_bf16 v[12:15], v[32:35], v[228:231], v[12:15]
	v_mfma_f32_16x16x32_bf16 v[8:11], v[44:47], v[228:231], v[8:11]
	s_setprio 0
	s_barrier
	v_add_u32_e32 v144, 0x14000, v178
	ds_read_b128 v[28:31], v144
	ds_read_b128 v[32:35], v144 offset:1024
	ds_read_b128 v[40:43], v144 offset:2048
	ds_read_b128 v[44:47], v144 offset:3072
	ds_read_b128 v[200:203], v190 offset:0
	ds_read_b128 v[204:207], v190 offset:1024
	ds_read_b128 v[208:211], v190 offset:2048
	ds_read_b128 v[212:215], v190 offset:3072
	ds_read_b128 v[216:219], v190 offset:4096
	ds_read_b128 v[220:223], v190 offset:5120
	ds_read_b128 v[224:227], v190 offset:6144
	ds_read_b128 v[228:231], v190 offset:7168
	v_lshl_add_u64 v[176:177], s[88:89], 0, v[160:161]
	s_add_i32 m0, s9, 0xc000
	v_lshl_add_u64 v[232:233], s[88:89], 0, v[162:163]
	global_load_lds_dwordx4 v[176:177], off
	s_add_i32 m0, s9, 0xe000
	v_lshl_add_u64 v[234:235], s[82:83], 0, v[160:161]
	global_load_lds_dwordx4 v[232:233], off
	s_add_i32 m0, s9, 0x18000
	v_lshl_add_u64 v[236:237], s[82:83], 0, v[162:163]
	global_load_lds_dwordx4 v[234:235], off
	s_add_i32 m0, s9, 0x1a000
	s_add_u32 s88, s88, 0x80
	s_addc_u32 s89, s89, 0
	global_load_lds_dwordx4 v[236:237], off
	s_add_u32 s82, s82, 0x80
	s_addc_u32 s83, s83, 0
	s_waitcnt vmcnt(8)
	s_waitcnt lgkmcnt(0)
	s_barrier
	s_setprio 1
	v_mfma_f32_16x16x32_bf16 v[76:79], v[28:31], v[200:203], v[76:79]
	v_mfma_f32_16x16x32_bf16 v[72:75], v[40:43], v[200:203], v[72:75]
	v_mfma_f32_16x16x32_bf16 v[60:63], v[28:31], v[208:211], v[60:63]
	v_mfma_f32_16x16x32_bf16 v[56:59], v[40:43], v[208:211], v[56:59]
	v_mfma_f32_16x16x32_bf16 v[36:39], v[28:31], v[216:219], v[36:39]
	v_mfma_f32_16x16x32_bf16 v[24:27], v[40:43], v[216:219], v[24:27]
	v_mfma_f32_16x16x32_bf16 v[12:15], v[28:31], v[224:227], v[12:15]
	v_mfma_f32_16x16x32_bf16 v[8:11], v[40:43], v[224:227], v[8:11]
	v_mfma_f32_16x16x32_bf16 v[76:79], v[32:35], v[204:207], v[76:79]
	v_mfma_f32_16x16x32_bf16 v[72:75], v[44:47], v[204:207], v[72:75]
	v_mfma_f32_16x16x32_bf16 v[60:63], v[32:35], v[212:215], v[60:63]
	v_mfma_f32_16x16x32_bf16 v[56:59], v[44:47], v[212:215], v[56:59]
	v_mfma_f32_16x16x32_bf16 v[36:39], v[32:35], v[220:223], v[36:39]
	v_mfma_f32_16x16x32_bf16 v[24:27], v[44:47], v[220:223], v[24:27]
	v_mfma_f32_16x16x32_bf16 v[12:15], v[32:35], v[228:231], v[12:15]
	v_mfma_f32_16x16x32_bf16 v[8:11], v[44:47], v[228:231], v[8:11]
	s_setprio 0
	s_barrier
	v_add_u32_e32 v144, 0x1c000, v178
	ds_read_b128 v[28:31], v144
	ds_read_b128 v[32:35], v144 offset:1024
	ds_read_b128 v[40:43], v144 offset:2048
	ds_read_b128 v[44:47], v144 offset:3072
	ds_read_b128 v[200:203], v190 offset:32768
	ds_read_b128 v[204:207], v190 offset:33792
	ds_read_b128 v[208:211], v190 offset:34816
	ds_read_b128 v[212:215], v190 offset:35840
	ds_read_b128 v[216:219], v190 offset:36864
	ds_read_b128 v[220:223], v190 offset:37888
	ds_read_b128 v[224:227], v190 offset:38912
	ds_read_b128 v[228:231], v190 offset:39936
	v_lshl_add_u64 v[176:177], s[88:89], 0, v[160:161]
	s_add_i32 m0, s9, 0x0
	v_lshl_add_u64 v[232:233], s[88:89], 0, v[162:163]
	global_load_lds_dwordx4 v[176:177], off
	s_add_i32 m0, s9, 0x2000
	v_lshl_add_u64 v[234:235], s[82:83], 0, v[160:161]
	global_load_lds_dwordx4 v[232:233], off
	s_add_i32 m0, s9, 0x14000
	v_lshl_add_u64 v[236:237], s[82:83], 0, v[162:163]
	global_load_lds_dwordx4 v[234:235], off
	s_add_i32 m0, s9, 0x16000
	s_add_u32 s88, s88, 0x80
	s_addc_u32 s89, s89, 0
	global_load_lds_dwordx4 v[236:237], off
	s_add_u32 s82, s82, 0x80
	s_addc_u32 s83, s83, 0
	s_waitcnt vmcnt(8)
	s_waitcnt lgkmcnt(0)
	s_barrier
	s_setprio 1
	v_mfma_f32_16x16x32_bf16 v[76:79], v[28:31], v[200:203], v[76:79]
	v_mfma_f32_16x16x32_bf16 v[72:75], v[40:43], v[200:203], v[72:75]
	v_mfma_f32_16x16x32_bf16 v[60:63], v[28:31], v[208:211], v[60:63]
	v_mfma_f32_16x16x32_bf16 v[56:59], v[40:43], v[208:211], v[56:59]
	v_mfma_f32_16x16x32_bf16 v[36:39], v[28:31], v[216:219], v[36:39]
	v_mfma_f32_16x16x32_bf16 v[24:27], v[40:43], v[216:219], v[24:27]
	v_mfma_f32_16x16x32_bf16 v[12:15], v[28:31], v[224:227], v[12:15]
	v_mfma_f32_16x16x32_bf16 v[8:11], v[40:43], v[224:227], v[8:11]
	v_mfma_f32_16x16x32_bf16 v[76:79], v[32:35], v[204:207], v[76:79]
	v_mfma_f32_16x16x32_bf16 v[72:75], v[44:47], v[204:207], v[72:75]
	v_mfma_f32_16x16x32_bf16 v[60:63], v[32:35], v[212:215], v[60:63]
	v_mfma_f32_16x16x32_bf16 v[56:59], v[44:47], v[212:215], v[56:59]
	v_mfma_f32_16x16x32_bf16 v[36:39], v[32:35], v[220:223], v[36:39]
	v_mfma_f32_16x16x32_bf16 v[24:27], v[44:47], v[220:223], v[24:27]
	v_mfma_f32_16x16x32_bf16 v[12:15], v[32:35], v[228:231], v[12:15]
	v_mfma_f32_16x16x32_bf16 v[8:11], v[44:47], v[228:231], v[8:11]
	s_setprio 0
	s_barrier
	s_add_i32 s55, s55, 1
	s_cmp_lt_u32 s55, 7
	s_cbranch_scc1 .Lq_lout_2_k
	v_add_u32_e32 v144, 0x10000, v178
	ds_read_b128 v[28:31], v144
	ds_read_b128 v[32:35], v144 offset:1024
	ds_read_b128 v[40:43], v144 offset:2048
	ds_read_b128 v[44:47], v144 offset:3072
	ds_read_b128 v[200:203], v190 offset:16384
	ds_read_b128 v[204:207], v190 offset:17408
	ds_read_b128 v[208:211], v190 offset:18432
	ds_read_b128 v[212:215], v190 offset:19456
	ds_read_b128 v[216:219], v190 offset:20480
	ds_read_b128 v[220:223], v190 offset:21504
	ds_read_b128 v[224:227], v190 offset:22528
	ds_read_b128 v[228:231], v190 offset:23552
	v_lshl_add_u64 v[176:177], s[88:89], 0, v[160:161]
	s_add_i32 m0, s9, 0x8000
	v_lshl_add_u64 v[232:233], s[88:89], 0, v[162:163]
	global_load_lds_dwordx4 v[176:177], off
	s_add_i32 m0, s9, 0xa000
	v_lshl_add_u64 v[234:235], s[82:83], 0, v[160:161]
	global_load_lds_dwordx4 v[232:233], off
	s_add_i32 m0, s9, 0x1c000
	v_lshl_add_u64 v[236:237], s[82:83], 0, v[162:163]
	global_load_lds_dwordx4 v[234:235], off
	s_add_i32 m0, s9, 0x1e000
	s_add_u32 s88, s88, 0x80
	s_addc_u32 s89, s89, 0
	global_load_lds_dwordx4 v[236:237], off
	s_add_u32 s82, s82, 0x80
	s_addc_u32 s83, s83, 0
	s_waitcnt vmcnt(8)
	s_waitcnt lgkmcnt(0)
	s_barrier
	s_setprio 1
	v_mfma_f32_16x16x32_bf16 v[76:79], v[28:31], v[200:203], v[76:79]
	v_mfma_f32_16x16x32_bf16 v[72:75], v[40:43], v[200:203], v[72:75]
	v_mfma_f32_16x16x32_bf16 v[60:63], v[28:31], v[208:211], v[60:63]
	v_mfma_f32_16x16x32_bf16 v[56:59], v[40:43], v[208:211], v[56:59]
	v_mfma_f32_16x16x32_bf16 v[36:39], v[28:31], v[216:219], v[36:39]
	v_mfma_f32_16x16x32_bf16 v[24:27], v[40:43], v[216:219], v[24:27]
	v_mfma_f32_16x16x32_bf16 v[12:15], v[28:31], v[224:227], v[12:15]
	v_mfma_f32_16x16x32_bf16 v[8:11], v[40:43], v[224:227], v[8:11]
	v_mfma_f32_16x16x32_bf16 v[76:79], v[32:35], v[204:207], v[76:79]
	v_mfma_f32_16x16x32_bf16 v[72:75], v[44:47], v[204:207], v[72:75]
	v_mfma_f32_16x16x32_bf16 v[60:63], v[32:35], v[212:215], v[60:63]
	v_mfma_f32_16x16x32_bf16 v[56:59], v[44:47], v[212:215], v[56:59]
	v_mfma_f32_16x16x32_bf16 v[36:39], v[32:35], v[220:223], v[36:39]
	v_mfma_f32_16x16x32_bf16 v[24:27], v[44:47], v[220:223], v[24:27]
	v_mfma_f32_16x16x32_bf16 v[12:15], v[32:35], v[228:231], v[12:15]
	v_mfma_f32_16x16x32_bf16 v[8:11], v[44:47], v[228:231], v[8:11]
	s_setprio 0
	s_barrier
	v_add_u32_e32 v144, 0x18000, v178
	ds_read_b128 v[28:31], v144
	ds_read_b128 v[32:35], v144 offset:1024
	ds_read_b128 v[40:43], v144 offset:2048
	ds_read_b128 v[44:47], v144 offset:3072
	ds_read_b128 v[200:203], v190 offset:49152
	ds_read_b128 v[204:207], v190 offset:50176
	ds_read_b128 v[208:211], v190 offset:51200
	ds_read_b128 v[212:215], v190 offset:52224
	ds_read_b128 v[216:219], v190 offset:53248
	ds_read_b128 v[220:223], v190 offset:54272
	ds_read_b128 v[224:227], v190 offset:55296
	ds_read_b128 v[228:231], v190 offset:56320
	s_waitcnt vmcnt(4)
	s_waitcnt lgkmcnt(0)
	s_barrier
	s_setprio 1
	v_mfma_f32_16x16x32_bf16 v[76:79], v[28:31], v[200:203], v[76:79]
	v_mfma_f32_16x16x32_bf16 v[72:75], v[40:43], v[200:203], v[72:75]
	v_mfma_f32_16x16x32_bf16 v[60:63], v[28:31], v[208:211], v[60:63]
	v_mfma_f32_16x16x32_bf16 v[56:59], v[40:43], v[208:211], v[56:59]
	v_mfma_f32_16x16x32_bf16 v[36:39], v[28:31], v[216:219], v[36:39]
	v_mfma_f32_16x16x32_bf16 v[24:27], v[40:43], v[216:219], v[24:27]
	v_mfma_f32_16x16x32_bf16 v[12:15], v[28:31], v[224:227], v[12:15]
	v_mfma_f32_16x16x32_bf16 v[8:11], v[40:43], v[224:227], v[8:11]
	v_mfma_f32_16x16x32_bf16 v[76:79], v[32:35], v[204:207], v[76:79]
	v_mfma_f32_16x16x32_bf16 v[72:75], v[44:47], v[204:207], v[72:75]
	v_mfma_f32_16x16x32_bf16 v[60:63], v[32:35], v[212:215], v[60:63]
	v_mfma_f32_16x16x32_bf16 v[56:59], v[44:47], v[212:215], v[56:59]
	v_mfma_f32_16x16x32_bf16 v[36:39], v[32:35], v[220:223], v[36:39]
	v_mfma_f32_16x16x32_bf16 v[24:27], v[44:47], v[220:223], v[24:27]
	v_mfma_f32_16x16x32_bf16 v[12:15], v[32:35], v[228:231], v[12:15]
	v_mfma_f32_16x16x32_bf16 v[8:11], v[44:47], v[228:231], v[8:11]
	s_setprio 0
	s_barrier
	v_add_u32_e32 v144, 0x14000, v178
	ds_read_b128 v[28:31], v144
	ds_read_b128 v[32:35], v144 offset:1024
	ds_read_b128 v[40:43], v144 offset:2048
	ds_read_b128 v[44:47], v144 offset:3072
	ds_read_b128 v[200:203], v190 offset:0
	ds_read_b128 v[204:207], v190 offset:1024
	ds_read_b128 v[208:211], v190 offset:2048
	ds_read_b128 v[212:215], v190 offset:3072
	ds_read_b128 v[216:219], v190 offset:4096
	ds_read_b128 v[220:223], v190 offset:5120
	ds_read_b128 v[224:227], v190 offset:6144
	ds_read_b128 v[228:231], v190 offset:7168
	s_waitcnt vmcnt(0)
	s_waitcnt lgkmcnt(0)
	s_barrier
	s_setprio 1
	v_mfma_f32_16x16x32_bf16 v[76:79], v[28:31], v[200:203], v[76:79]
	v_mfma_f32_16x16x32_bf16 v[72:75], v[40:43], v[200:203], v[72:75]
	v_mfma_f32_16x16x32_bf16 v[60:63], v[28:31], v[208:211], v[60:63]
	v_mfma_f32_16x16x32_bf16 v[56:59], v[40:43], v[208:211], v[56:59]
	v_mfma_f32_16x16x32_bf16 v[36:39], v[28:31], v[216:219], v[36:39]
	v_mfma_f32_16x16x32_bf16 v[24:27], v[40:43], v[216:219], v[24:27]
	v_mfma_f32_16x16x32_bf16 v[12:15], v[28:31], v[224:227], v[12:15]
	v_mfma_f32_16x16x32_bf16 v[8:11], v[40:43], v[224:227], v[8:11]
	v_mfma_f32_16x16x32_bf16 v[76:79], v[32:35], v[204:207], v[76:79]
	v_mfma_f32_16x16x32_bf16 v[72:75], v[44:47], v[204:207], v[72:75]
	v_mfma_f32_16x16x32_bf16 v[60:63], v[32:35], v[212:215], v[60:63]
	v_mfma_f32_16x16x32_bf16 v[56:59], v[44:47], v[212:215], v[56:59]
	v_mfma_f32_16x16x32_bf16 v[36:39], v[32:35], v[220:223], v[36:39]
	v_mfma_f32_16x16x32_bf16 v[24:27], v[44:47], v[220:223], v[24:27]
	v_mfma_f32_16x16x32_bf16 v[12:15], v[32:35], v[228:231], v[12:15]
	v_mfma_f32_16x16x32_bf16 v[8:11], v[44:47], v[228:231], v[8:11]
	s_setprio 0
	s_barrier
	v_add_u32_e32 v144, 0x1c000, v178
	ds_read_b128 v[28:31], v144
	ds_read_b128 v[32:35], v144 offset:1024
	ds_read_b128 v[40:43], v144 offset:2048
	ds_read_b128 v[44:47], v144 offset:3072
	ds_read_b128 v[200:203], v190 offset:32768
	ds_read_b128 v[204:207], v190 offset:33792
	ds_read_b128 v[208:211], v190 offset:34816
	ds_read_b128 v[212:215], v190 offset:35840
	ds_read_b128 v[216:219], v190 offset:36864
	ds_read_b128 v[220:223], v190 offset:37888
	ds_read_b128 v[224:227], v190 offset:38912
	ds_read_b128 v[228:231], v190 offset:39936
	s_waitcnt lgkmcnt(0)
	s_barrier
	s_setprio 1
	v_mfma_f32_16x16x32_bf16 v[76:79], v[28:31], v[200:203], v[76:79]
	v_mfma_f32_16x16x32_bf16 v[72:75], v[40:43], v[200:203], v[72:75]
	v_mfma_f32_16x16x32_bf16 v[60:63], v[28:31], v[208:211], v[60:63]
	v_mfma_f32_16x16x32_bf16 v[56:59], v[40:43], v[208:211], v[56:59]
	v_mfma_f32_16x16x32_bf16 v[36:39], v[28:31], v[216:219], v[36:39]
	v_mfma_f32_16x16x32_bf16 v[24:27], v[40:43], v[216:219], v[24:27]
	v_mfma_f32_16x16x32_bf16 v[12:15], v[28:31], v[224:227], v[12:15]
	v_mfma_f32_16x16x32_bf16 v[8:11], v[40:43], v[224:227], v[8:11]
	v_mfma_f32_16x16x32_bf16 v[76:79], v[32:35], v[204:207], v[76:79]
	v_mfma_f32_16x16x32_bf16 v[72:75], v[44:47], v[204:207], v[72:75]
	v_mfma_f32_16x16x32_bf16 v[60:63], v[32:35], v[212:215], v[60:63]
	v_mfma_f32_16x16x32_bf16 v[56:59], v[44:47], v[212:215], v[56:59]
	v_mfma_f32_16x16x32_bf16 v[36:39], v[32:35], v[220:223], v[36:39]
	v_mfma_f32_16x16x32_bf16 v[24:27], v[44:47], v[220:223], v[24:27]
	v_mfma_f32_16x16x32_bf16 v[12:15], v[32:35], v[228:231], v[12:15]
	v_mfma_f32_16x16x32_bf16 v[8:11], v[44:47], v[228:231], v[8:11]
	s_setprio 0
	s_barrier
	s_branch .Lq_lout_exit

.Lq_lout_3_k:
	v_add_u32_e32 v144, 0x14000, v178
	ds_read_b128 v[168:171], v144
	ds_read_b128 v[172:175], v144 offset:1024
	ds_read_b128 v[192:195], v144 offset:2048
	ds_read_b128 v[196:199], v144 offset:3072
	ds_read_b128 v[200:203], v190 offset:16384
	ds_read_b128 v[204:207], v190 offset:17408
	ds_read_b128 v[208:211], v190 offset:18432
	ds_read_b128 v[212:215], v190 offset:19456
	ds_read_b128 v[216:219], v190 offset:20480
	ds_read_b128 v[220:223], v190 offset:21504
	ds_read_b128 v[224:227], v190 offset:22528
	ds_read_b128 v[228:231], v190 offset:23552
	v_lshl_add_u64 v[176:177], s[88:89], 0, v[160:161]
	s_add_i32 m0, s9, 0x8000
	v_lshl_add_u64 v[232:233], s[88:89], 0, v[162:163]
	global_load_lds_dwordx4 v[176:177], off
	s_add_i32 m0, s9, 0xa000
	v_lshl_add_u64 v[234:235], s[82:83], 0, v[160:161]
	global_load_lds_dwordx4 v[232:233], off
	s_add_i32 m0, s9, 0x18000
	v_lshl_add_u64 v[236:237], s[82:83], 0, v[162:163]
	global_load_lds_dwordx4 v[234:235], off
	s_add_i32 m0, s9, 0x1a000
	s_add_u32 s88, s88, 0x80
	s_addc_u32 s89, s89, 0
	global_load_lds_dwordx4 v[236:237], off
	s_add_u32 s82, s82, 0x80
	s_addc_u32 s83, s83, 0
	s_waitcnt vmcnt(8)
	s_waitcnt lgkmcnt(0)
	s_barrier
	s_setprio 1
	v_mfma_f32_16x16x32_bf16 v[20:23], v[168:171], v[216:219], v[20:23]
	v_mfma_f32_16x16x32_bf16 v[16:19], v[192:195], v[216:219], v[16:19]
	v_mfma_f32_16x16x32_bf16 v[4:7], v[168:171], v[224:227], v[4:7]
	v_mfma_f32_16x16x32_bf16 v[0:3], v[192:195], v[224:227], v[0:3]
	v_mfma_f32_16x16x32_bf16 v[68:71], v[168:171], v[200:203], v[68:71]
	v_mfma_f32_16x16x32_bf16 v[64:67], v[192:195], v[200:203], v[64:67]
	v_mfma_f32_16x16x32_bf16 v[52:55], v[168:171], v[208:211], v[52:55]
	v_mfma_f32_16x16x32_bf16 v[48:51], v[192:195], v[208:211], v[48:51]
	v_mfma_f32_16x16x32_bf16 v[20:23], v[172:175], v[220:223], v[20:23]
	v_mfma_f32_16x16x32_bf16 v[16:19], v[196:199], v[220:223], v[16:19]
	v_mfma_f32_16x16x32_bf16 v[4:7], v[172:175], v[228:231], v[4:7]
	v_mfma_f32_16x16x32_bf16 v[0:3], v[196:199], v[228:231], v[0:3]
	v_mfma_f32_16x16x32_bf16 v[68:71], v[172:175], v[204:207], v[68:71]
	v_mfma_f32_16x16x32_bf16 v[64:67], v[196:199], v[204:207], v[64:67]
	v_mfma_f32_16x16x32_bf16 v[52:55], v[172:175], v[212:215], v[52:55]
	v_mfma_f32_16x16x32_bf16 v[48:51], v[196:199], v[212:215], v[48:51]
	s_setprio 0
	s_barrier
	v_add_u32_e32 v144, 0x1c000, v178
	ds_read_b128 v[168:171], v144
	ds_read_b128 v[172:175], v144 offset:1024
	ds_read_b128 v[192:195], v144 offset:2048
	ds_read_b128 v[196:199], v144 offset:3072
	ds_read_b128 v[200:203], v190 offset:49152
	ds_read_b128 v[204:207], v190 offset:50176
	ds_read_b128 v[208:211], v190 offset:51200
	ds_read_b128 v[212:215], v190 offset:52224
	ds_read_b128 v[216:219], v190 offset:53248
	ds_read_b128 v[220:223], v190 offset:54272
	ds_read_b128 v[224:227], v190 offset:55296
	ds_read_b128 v[228:231], v190 offset:56320
	v_lshl_add_u64 v[176:177], s[88:89], 0, v[160:161]
	s_add_i32 m0, s9, 0x4000
	v_lshl_add_u64 v[232:233], s[88:89], 0, v[162:163]
	global_load_lds_dwordx4 v[176:177], off
	s_add_i32 m0, s9, 0x6000
	v_lshl_add_u64 v[234:235], s[82:83], 0, v[160:161]
	global_load_lds_dwordx4 v[232:233], off
	s_add_i32 m0, s9, 0x14000
	v_lshl_add_u64 v[236:237], s[82:83], 0, v[162:163]
	global_load_lds_dwordx4 v[234:235], off
	s_add_i32 m0, s9, 0x16000
	s_add_u32 s88, s88, 0x80
	s_addc_u32 s89, s89, 0
	global_load_lds_dwordx4 v[236:237], off
	s_add_u32 s82, s82, 0x80
	s_addc_u32 s83, s83, 0
	s_waitcnt vmcnt(8)
	s_waitcnt lgkmcnt(0)
	s_barrier
	s_setprio 1
	v_mfma_f32_16x16x32_bf16 v[20:23], v[168:171], v[216:219], v[20:23]
	v_mfma_f32_16x16x32_bf16 v[16:19], v[192:195], v[216:219], v[16:19]
	v_mfma_f32_16x16x32_bf16 v[4:7], v[168:171], v[224:227], v[4:7]
	v_mfma_f32_16x16x32_bf16 v[0:3], v[192:195], v[224:227], v[0:3]
	v_mfma_f32_16x16x32_bf16 v[68:71], v[168:171], v[200:203], v[68:71]
	v_mfma_f32_16x16x32_bf16 v[64:67], v[192:195], v[200:203], v[64:67]
	v_mfma_f32_16x16x32_bf16 v[52:55], v[168:171], v[208:211], v[52:55]
	v_mfma_f32_16x16x32_bf16 v[48:51], v[192:195], v[208:211], v[48:51]
	v_mfma_f32_16x16x32_bf16 v[20:23], v[172:175], v[220:223], v[20:23]
	v_mfma_f32_16x16x32_bf16 v[16:19], v[196:199], v[220:223], v[16:19]
	v_mfma_f32_16x16x32_bf16 v[4:7], v[172:175], v[228:231], v[4:7]
	v_mfma_f32_16x16x32_bf16 v[0:3], v[196:199], v[228:231], v[0:3]
	v_mfma_f32_16x16x32_bf16 v[68:71], v[172:175], v[204:207], v[68:71]
	v_mfma_f32_16x16x32_bf16 v[64:67], v[196:199], v[204:207], v[64:67]
	v_mfma_f32_16x16x32_bf16 v[52:55], v[172:175], v[212:215], v[52:55]
	v_mfma_f32_16x16x32_bf16 v[48:51], v[196:199], v[212:215], v[48:51]
	s_setprio 0
	s_barrier
	v_add_u32_e32 v144, 0x10000, v178
	ds_read_b128 v[168:171], v144
	ds_read_b128 v[172:175], v144 offset:1024
	ds_read_b128 v[192:195], v144 offset:2048
	ds_read_b128 v[196:199], v144 offset:3072
	ds_read_b128 v[200:203], v190 offset:0
	ds_read_b128 v[204:207], v190 offset:1024
	ds_read_b128 v[208:211], v190 offset:2048
	ds_read_b128 v[212:215], v190 offset:3072
	ds_read_b128 v[216:219], v190 offset:4096
	ds_read_b128 v[220:223], v190 offset:5120
	ds_read_b128 v[224:227], v190 offset:6144
	ds_read_b128 v[228:231], v190 offset:7168
	v_lshl_add_u64 v[176:177], s[88:89], 0, v[160:161]
	s_add_i32 m0, s9, 0xc000
	v_lshl_add_u64 v[232:233], s[88:89], 0, v[162:163]
	global_load_lds_dwordx4 v[176:177], off
	s_add_i32 m0, s9, 0xe000
	v_lshl_add_u64 v[234:235], s[82:83], 0, v[160:161]
	global_load_lds_dwordx4 v[232:233], off
	s_add_i32 m0, s9, 0x1c000
	v_lshl_add_u64 v[236:237], s[82:83], 0, v[162:163]
	global_load_lds_dwordx4 v[234:235], off
	s_add_i32 m0, s9, 0x1e000
	s_add_u32 s88, s88, 0x80
	s_addc_u32 s89, s89, 0
	global_load_lds_dwordx4 v[236:237], off
	s_add_u32 s82, s82, 0x80
	s_addc_u32 s83, s83, 0
	s_waitcnt vmcnt(8)
	s_waitcnt lgkmcnt(0)
	s_barrier
	s_setprio 1
	v_mfma_f32_16x16x32_bf16 v[20:23], v[168:171], v[216:219], v[20:23]
	v_mfma_f32_16x16x32_bf16 v[16:19], v[192:195], v[216:219], v[16:19]
	v_mfma_f32_16x16x32_bf16 v[4:7], v[168:171], v[224:227], v[4:7]
	v_mfma_f32_16x16x32_bf16 v[0:3], v[192:195], v[224:227], v[0:3]
	v_mfma_f32_16x16x32_bf16 v[68:71], v[168:171], v[200:203], v[68:71]
	v_mfma_f32_16x16x32_bf16 v[64:67], v[192:195], v[200:203], v[64:67]
	v_mfma_f32_16x16x32_bf16 v[52:55], v[168:171], v[208:211], v[52:55]
	v_mfma_f32_16x16x32_bf16 v[48:51], v[192:195], v[208:211], v[48:51]
	v_mfma_f32_16x16x32_bf16 v[20:23], v[172:175], v[220:223], v[20:23]
	v_mfma_f32_16x16x32_bf16 v[16:19], v[196:199], v[220:223], v[16:19]
	v_mfma_f32_16x16x32_bf16 v[4:7], v[172:175], v[228:231], v[4:7]
	v_mfma_f32_16x16x32_bf16 v[0:3], v[196:199], v[228:231], v[0:3]
	v_mfma_f32_16x16x32_bf16 v[68:71], v[172:175], v[204:207], v[68:71]
	v_mfma_f32_16x16x32_bf16 v[64:67], v[196:199], v[204:207], v[64:67]
	v_mfma_f32_16x16x32_bf16 v[52:55], v[172:175], v[212:215], v[52:55]
	v_mfma_f32_16x16x32_bf16 v[48:51], v[196:199], v[212:215], v[48:51]
	s_setprio 0
	s_barrier
	v_add_u32_e32 v144, 0x18000, v178
	ds_read_b128 v[168:171], v144
	ds_read_b128 v[172:175], v144 offset:1024
	ds_read_b128 v[192:195], v144 offset:2048
	ds_read_b128 v[196:199], v144 offset:3072
	ds_read_b128 v[200:203], v190 offset:32768
	ds_read_b128 v[204:207], v190 offset:33792
	ds_read_b128 v[208:211], v190 offset:34816
	ds_read_b128 v[212:215], v190 offset:35840
	ds_read_b128 v[216:219], v190 offset:36864
	ds_read_b128 v[220:223], v190 offset:37888
	ds_read_b128 v[224:227], v190 offset:38912
	ds_read_b128 v[228:231], v190 offset:39936
	v_lshl_add_u64 v[176:177], s[88:89], 0, v[160:161]
	s_add_i32 m0, s9, 0x0
	v_lshl_add_u64 v[232:233], s[88:89], 0, v[162:163]
	global_load_lds_dwordx4 v[176:177], off
	s_add_i32 m0, s9, 0x2000
	v_lshl_add_u64 v[234:235], s[82:83], 0, v[160:161]
	global_load_lds_dwordx4 v[232:233], off
	s_add_i32 m0, s9, 0x10000
	v_lshl_add_u64 v[236:237], s[82:83], 0, v[162:163]
	global_load_lds_dwordx4 v[234:235], off
	s_add_i32 m0, s9, 0x12000
	s_add_u32 s88, s88, 0x80
	s_addc_u32 s89, s89, 0
	global_load_lds_dwordx4 v[236:237], off
	s_add_u32 s82, s82, 0x80
	s_addc_u32 s83, s83, 0
	s_waitcnt vmcnt(8)
	s_waitcnt lgkmcnt(0)
	s_barrier
	s_setprio 1
	v_mfma_f32_16x16x32_bf16 v[20:23], v[168:171], v[216:219], v[20:23]
	v_mfma_f32_16x16x32_bf16 v[16:19], v[192:195], v[216:219], v[16:19]
	v_mfma_f32_16x16x32_bf16 v[4:7], v[168:171], v[224:227], v[4:7]
	v_mfma_f32_16x16x32_bf16 v[0:3], v[192:195], v[224:227], v[0:3]
	v_mfma_f32_16x16x32_bf16 v[68:71], v[168:171], v[200:203], v[68:71]
	v_mfma_f32_16x16x32_bf16 v[64:67], v[192:195], v[200:203], v[64:67]
	v_mfma_f32_16x16x32_bf16 v[52:55], v[168:171], v[208:211], v[52:55]
	v_mfma_f32_16x16x32_bf16 v[48:51], v[192:195], v[208:211], v[48:51]
	v_mfma_f32_16x16x32_bf16 v[20:23], v[172:175], v[220:223], v[20:23]
	v_mfma_f32_16x16x32_bf16 v[16:19], v[196:199], v[220:223], v[16:19]
	v_mfma_f32_16x16x32_bf16 v[4:7], v[172:175], v[228:231], v[4:7]
	v_mfma_f32_16x16x32_bf16 v[0:3], v[196:199], v[228:231], v[0:3]
	v_mfma_f32_16x16x32_bf16 v[68:71], v[172:175], v[204:207], v[68:71]
	v_mfma_f32_16x16x32_bf16 v[64:67], v[196:199], v[204:207], v[64:67]
	v_mfma_f32_16x16x32_bf16 v[52:55], v[172:175], v[212:215], v[52:55]
	v_mfma_f32_16x16x32_bf16 v[48:51], v[196:199], v[212:215], v[48:51]
	s_setprio 0
	s_barrier
	s_add_i32 s55, s55, 1
	s_cmp_lt_u32 s55, 7
	s_cbranch_scc1 .Lq_lout_3_k
	v_add_u32_e32 v144, 0x14000, v178
	ds_read_b128 v[168:171], v144
	ds_read_b128 v[172:175], v144 offset:1024
	ds_read_b128 v[192:195], v144 offset:2048
	ds_read_b128 v[196:199], v144 offset:3072
	ds_read_b128 v[200:203], v190 offset:16384
	ds_read_b128 v[204:207], v190 offset:17408
	ds_read_b128 v[208:211], v190 offset:18432
	ds_read_b128 v[212:215], v190 offset:19456
	ds_read_b128 v[216:219], v190 offset:20480
	ds_read_b128 v[220:223], v190 offset:21504
	ds_read_b128 v[224:227], v190 offset:22528
	ds_read_b128 v[228:231], v190 offset:23552
	v_lshl_add_u64 v[176:177], s[88:89], 0, v[160:161]
	s_add_i32 m0, s9, 0x8000
	v_lshl_add_u64 v[232:233], s[88:89], 0, v[162:163]
	global_load_lds_dwordx4 v[176:177], off
	s_add_i32 m0, s9, 0xa000
	v_lshl_add_u64 v[234:235], s[82:83], 0, v[160:161]
	global_load_lds_dwordx4 v[232:233], off
	s_add_i32 m0, s9, 0x18000
	v_lshl_add_u64 v[236:237], s[82:83], 0, v[162:163]
	global_load_lds_dwordx4 v[234:235], off
	s_add_i32 m0, s9, 0x1a000
	s_add_u32 s88, s88, 0x80
	s_addc_u32 s89, s89, 0
	global_load_lds_dwordx4 v[236:237], off
	s_add_u32 s82, s82, 0x80
	s_addc_u32 s83, s83, 0
	s_waitcnt vmcnt(8)
	s_waitcnt lgkmcnt(0)
	s_barrier
	s_setprio 1
	v_mfma_f32_16x16x32_bf16 v[20:23], v[168:171], v[216:219], v[20:23]
	v_mfma_f32_16x16x32_bf16 v[16:19], v[192:195], v[216:219], v[16:19]
	v_mfma_f32_16x16x32_bf16 v[4:7], v[168:171], v[224:227], v[4:7]
	v_mfma_f32_16x16x32_bf16 v[0:3], v[192:195], v[224:227], v[0:3]
	v_mfma_f32_16x16x32_bf16 v[68:71], v[168:171], v[200:203], v[68:71]
	v_mfma_f32_16x16x32_bf16 v[64:67], v[192:195], v[200:203], v[64:67]
	v_mfma_f32_16x16x32_bf16 v[52:55], v[168:171], v[208:211], v[52:55]
	v_mfma_f32_16x16x32_bf16 v[48:51], v[192:195], v[208:211], v[48:51]
	v_mfma_f32_16x16x32_bf16 v[20:23], v[172:175], v[220:223], v[20:23]
	v_mfma_f32_16x16x32_bf16 v[16:19], v[196:199], v[220:223], v[16:19]
	v_mfma_f32_16x16x32_bf16 v[4:7], v[172:175], v[228:231], v[4:7]
	v_mfma_f32_16x16x32_bf16 v[0:3], v[196:199], v[228:231], v[0:3]
	v_mfma_f32_16x16x32_bf16 v[68:71], v[172:175], v[204:207], v[68:71]
	v_mfma_f32_16x16x32_bf16 v[64:67], v[196:199], v[204:207], v[64:67]
	v_mfma_f32_16x16x32_bf16 v[52:55], v[172:175], v[212:215], v[52:55]
	v_mfma_f32_16x16x32_bf16 v[48:51], v[196:199], v[212:215], v[48:51]
	s_setprio 0
	s_barrier
	v_add_u32_e32 v144, 0x1c000, v178
	ds_read_b128 v[168:171], v144
	ds_read_b128 v[172:175], v144 offset:1024
	ds_read_b128 v[192:195], v144 offset:2048
	ds_read_b128 v[196:199], v144 offset:3072
	ds_read_b128 v[200:203], v190 offset:49152
	ds_read_b128 v[204:207], v190 offset:50176
	ds_read_b128 v[208:211], v190 offset:51200
	ds_read_b128 v[212:215], v190 offset:52224
	ds_read_b128 v[216:219], v190 offset:53248
	ds_read_b128 v[220:223], v190 offset:54272
	ds_read_b128 v[224:227], v190 offset:55296
	ds_read_b128 v[228:231], v190 offset:56320
	s_waitcnt vmcnt(4)
	s_waitcnt lgkmcnt(0)
	s_barrier
	s_setprio 1
	v_mfma_f32_16x16x32_bf16 v[20:23], v[168:171], v[216:219], v[20:23]
	v_mfma_f32_16x16x32_bf16 v[16:19], v[192:195], v[216:219], v[16:19]
	v_mfma_f32_16x16x32_bf16 v[4:7], v[168:171], v[224:227], v[4:7]
	v_mfma_f32_16x16x32_bf16 v[0:3], v[192:195], v[224:227], v[0:3]
	v_mfma_f32_16x16x32_bf16 v[68:71], v[168:171], v[200:203], v[68:71]
	v_mfma_f32_16x16x32_bf16 v[64:67], v[192:195], v[200:203], v[64:67]
	v_mfma_f32_16x16x32_bf16 v[52:55], v[168:171], v[208:211], v[52:55]
	v_mfma_f32_16x16x32_bf16 v[48:51], v[192:195], v[208:211], v[48:51]
	v_mfma_f32_16x16x32_bf16 v[20:23], v[172:175], v[220:223], v[20:23]
	v_mfma_f32_16x16x32_bf16 v[16:19], v[196:199], v[220:223], v[16:19]
	v_mfma_f32_16x16x32_bf16 v[4:7], v[172:175], v[228:231], v[4:7]
	v_mfma_f32_16x16x32_bf16 v[0:3], v[196:199], v[228:231], v[0:3]
	v_mfma_f32_16x16x32_bf16 v[68:71], v[172:175], v[204:207], v[68:71]
	v_mfma_f32_16x16x32_bf16 v[64:67], v[196:199], v[204:207], v[64:67]
	v_mfma_f32_16x16x32_bf16 v[52:55], v[172:175], v[212:215], v[52:55]
	v_mfma_f32_16x16x32_bf16 v[48:51], v[196:199], v[212:215], v[48:51]
	s_setprio 0
	s_barrier
	v_add_u32_e32 v144, 0x10000, v178
	ds_read_b128 v[168:171], v144
	ds_read_b128 v[172:175], v144 offset:1024
	ds_read_b128 v[192:195], v144 offset:2048
	ds_read_b128 v[196:199], v144 offset:3072
	ds_read_b128 v[200:203], v190 offset:0
	ds_read_b128 v[204:207], v190 offset:1024
	ds_read_b128 v[208:211], v190 offset:2048
	ds_read_b128 v[212:215], v190 offset:3072
	ds_read_b128 v[216:219], v190 offset:4096
	ds_read_b128 v[220:223], v190 offset:5120
	ds_read_b128 v[224:227], v190 offset:6144
	ds_read_b128 v[228:231], v190 offset:7168
	s_waitcnt vmcnt(0)
	s_waitcnt lgkmcnt(0)
	s_barrier
	s_setprio 1
	v_mfma_f32_16x16x32_bf16 v[20:23], v[168:171], v[216:219], v[20:23]
	v_mfma_f32_16x16x32_bf16 v[16:19], v[192:195], v[216:219], v[16:19]
	v_mfma_f32_16x16x32_bf16 v[4:7], v[168:171], v[224:227], v[4:7]
	v_mfma_f32_16x16x32_bf16 v[0:3], v[192:195], v[224:227], v[0:3]
	v_mfma_f32_16x16x32_bf16 v[68:71], v[168:171], v[200:203], v[68:71]
	v_mfma_f32_16x16x32_bf16 v[64:67], v[192:195], v[200:203], v[64:67]
	v_mfma_f32_16x16x32_bf16 v[52:55], v[168:171], v[208:211], v[52:55]
	v_mfma_f32_16x16x32_bf16 v[48:51], v[192:195], v[208:211], v[48:51]
	v_mfma_f32_16x16x32_bf16 v[20:23], v[172:175], v[220:223], v[20:23]
	v_mfma_f32_16x16x32_bf16 v[16:19], v[196:199], v[220:223], v[16:19]
	v_mfma_f32_16x16x32_bf16 v[4:7], v[172:175], v[228:231], v[4:7]
	v_mfma_f32_16x16x32_bf16 v[0:3], v[196:199], v[228:231], v[0:3]
	v_mfma_f32_16x16x32_bf16 v[68:71], v[172:175], v[204:207], v[68:71]
	v_mfma_f32_16x16x32_bf16 v[64:67], v[196:199], v[204:207], v[64:67]
	v_mfma_f32_16x16x32_bf16 v[52:55], v[172:175], v[212:215], v[52:55]
	v_mfma_f32_16x16x32_bf16 v[48:51], v[196:199], v[212:215], v[48:51]
	s_setprio 0
	s_barrier
	v_add_u32_e32 v144, 0x18000, v178
	ds_read_b128 v[168:171], v144
	ds_read_b128 v[172:175], v144 offset:1024
	ds_read_b128 v[192:195], v144 offset:2048
	ds_read_b128 v[196:199], v144 offset:3072
	ds_read_b128 v[200:203], v190 offset:32768
	ds_read_b128 v[204:207], v190 offset:33792
	ds_read_b128 v[208:211], v190 offset:34816
	ds_read_b128 v[212:215], v190 offset:35840
	ds_read_b128 v[216:219], v190 offset:36864
	ds_read_b128 v[220:223], v190 offset:37888
	ds_read_b128 v[224:227], v190 offset:38912
	ds_read_b128 v[228:231], v190 offset:39936
	s_waitcnt lgkmcnt(0)
	s_barrier
	s_setprio 1
	v_mfma_f32_16x16x32_bf16 v[20:23], v[168:171], v[216:219], v[20:23]
	v_mfma_f32_16x16x32_bf16 v[16:19], v[192:195], v[216:219], v[16:19]
	v_mfma_f32_16x16x32_bf16 v[4:7], v[168:171], v[224:227], v[4:7]
	v_mfma_f32_16x16x32_bf16 v[0:3], v[192:195], v[224:227], v[0:3]
	v_mfma_f32_16x16x32_bf16 v[68:71], v[168:171], v[200:203], v[68:71]
	v_mfma_f32_16x16x32_bf16 v[64:67], v[192:195], v[200:203], v[64:67]
	v_mfma_f32_16x16x32_bf16 v[52:55], v[168:171], v[208:211], v[52:55]
	v_mfma_f32_16x16x32_bf16 v[48:51], v[192:195], v[208:211], v[48:51]
	v_mfma_f32_16x16x32_bf16 v[20:23], v[172:175], v[220:223], v[20:23]
	v_mfma_f32_16x16x32_bf16 v[16:19], v[196:199], v[220:223], v[16:19]
	v_mfma_f32_16x16x32_bf16 v[4:7], v[172:175], v[228:231], v[4:7]
	v_mfma_f32_16x16x32_bf16 v[0:3], v[196:199], v[228:231], v[0:3]
	v_mfma_f32_16x16x32_bf16 v[68:71], v[172:175], v[204:207], v[68:71]
	v_mfma_f32_16x16x32_bf16 v[64:67], v[196:199], v[204:207], v[64:67]
	v_mfma_f32_16x16x32_bf16 v[52:55], v[172:175], v[212:215], v[52:55]
	v_mfma_f32_16x16x32_bf16 v[48:51], v[196:199], v[212:215], v[48:51]
	s_setprio 0
	s_barrier
	s_branch .Lq_lout_exit

.Lq_abi_0_k:
	v_add_u32_e32 v142, 0x10000, v160
	ds_read_b128 v[138:141], v142
	ds_read_b128 v[164:167], v142 offset:1024
	ds_read_b128 v[168:171], v142 offset:2048
	ds_read_b128 v[172:175], v142 offset:3072
	ds_read_b128 v[202:205], v162 offset:0
	ds_read_b128 v[206:209], v162 offset:1024
	ds_read_b128 v[210:213], v162 offset:2048
	ds_read_b128 v[214:217], v162 offset:3072
	ds_read_b128 v[218:221], v162 offset:4096
	ds_read_b128 v[222:225], v162 offset:5120
	ds_read_b128 v[226:229], v162 offset:6144
	ds_read_b128 v[230:233], v162 offset:7168
	v_lshl_add_u64 v[234:235], s[74:75], 0, v[128:129]
	s_add_i32 m0, s5, 0xc000
	v_lshl_add_u64 v[236:237], s[74:75], 0, v[130:131]
	global_load_lds_dwordx4 v[234:235], off
	s_add_i32 m0, s5, 0xe000
	v_lshl_add_u64 v[238:239], s[2:3], 0, v[144:145]
	global_load_lds_dwordx4 v[236:237], off
	s_add_i32 m0, s5, 0x1c000
	v_lshl_add_u64 v[240:241], s[2:3], 0, v[132:133]
	global_load_lds_dwordx4 v[238:239], off
	s_add_i32 m0, s5, 0x1e000
	s_add_u32 s74, s74, 0x80
	s_addc_u32 s75, s75, 0
	global_load_lds_dwordx4 v[240:241], off
	s_add_u32 s2, s2, 0x80
	s_addc_u32 s3, s3, 0
	s_waitcnt vmcnt(8)
	s_waitcnt lgkmcnt(0)
	s_barrier
	s_setprio 1
	v_mfma_f32_16x16x32_bf16 v[124:127], v[138:141], v[202:205], v[124:127]
	v_mfma_f32_16x16x32_bf16 v[120:123], v[168:171], v[202:205], v[120:123]
	v_mfma_f32_16x16x32_bf16 v[108:111], v[138:141], v[210:213], v[108:111]
	v_mfma_f32_16x16x32_bf16 v[104:107], v[168:171], v[210:213], v[104:107]
	v_mfma_f32_16x16x32_bf16 v[92:95], v[138:141], v[218:221], v[92:95]
	v_mfma_f32_16x16x32_bf16 v[88:91], v[168:171], v[218:221], v[88:91]
	v_mfma_f32_16x16x32_bf16 v[76:79], v[138:141], v[226:229], v[76:79]
	v_mfma_f32_16x16x32_bf16 v[72:75], v[168:171], v[226:229], v[72:75]
	v_mfma_f32_16x16x32_bf16 v[124:127], v[164:167], v[206:209], v[124:127]
	v_mfma_f32_16x16x32_bf16 v[120:123], v[172:175], v[206:209], v[120:123]
	v_mfma_f32_16x16x32_bf16 v[108:111], v[164:167], v[214:217], v[108:111]
	v_mfma_f32_16x16x32_bf16 v[104:107], v[172:175], v[214:217], v[104:107]
	v_mfma_f32_16x16x32_bf16 v[92:95], v[164:167], v[222:225], v[92:95]
	v_mfma_f32_16x16x32_bf16 v[88:91], v[172:175], v[222:225], v[88:91]
	v_mfma_f32_16x16x32_bf16 v[76:79], v[164:167], v[230:233], v[76:79]
	v_mfma_f32_16x16x32_bf16 v[72:75], v[172:175], v[230:233], v[72:75]
	s_setprio 0
	s_barrier
	v_add_u32_e32 v142, 0x18000, v160
	ds_read_b128 v[138:141], v142
	ds_read_b128 v[164:167], v142 offset:1024
	ds_read_b128 v[168:171], v142 offset:2048
	ds_read_b128 v[172:175], v142 offset:3072
	ds_read_b128 v[202:205], v162 offset:32768
	ds_read_b128 v[206:209], v162 offset:33792
	ds_read_b128 v[210:213], v162 offset:34816
	ds_read_b128 v[214:217], v162 offset:35840
	ds_read_b128 v[218:221], v162 offset:36864
	ds_read_b128 v[222:225], v162 offset:37888
	ds_read_b128 v[226:229], v162 offset:38912
	ds_read_b128 v[230:233], v162 offset:39936
	v_lshl_add_u64 v[234:235], s[74:75], 0, v[128:129]
	s_add_i32 m0, s5, 0x0
	v_lshl_add_u64 v[236:237], s[74:75], 0, v[130:131]
	global_load_lds_dwordx4 v[234:235], off
	s_add_i32 m0, s5, 0x2000
	v_lshl_add_u64 v[238:239], s[2:3], 0, v[144:145]
	global_load_lds_dwordx4 v[236:237], off
	s_add_i32 m0, s5, 0x10000
	v_lshl_add_u64 v[240:241], s[2:3], 0, v[132:133]
	global_load_lds_dwordx4 v[238:239], off
	s_add_i32 m0, s5, 0x12000
	s_add_u32 s74, s74, 0x80
	s_addc_u32 s75, s75, 0
	global_load_lds_dwordx4 v[240:241], off
	s_add_u32 s2, s2, 0x80
	s_addc_u32 s3, s3, 0
	s_waitcnt vmcnt(8)
	s_waitcnt lgkmcnt(0)
	s_barrier
	s_setprio 1
	v_mfma_f32_16x16x32_bf16 v[124:127], v[138:141], v[202:205], v[124:127]
	v_mfma_f32_16x16x32_bf16 v[120:123], v[168:171], v[202:205], v[120:123]
	v_mfma_f32_16x16x32_bf16 v[108:111], v[138:141], v[210:213], v[108:111]
	v_mfma_f32_16x16x32_bf16 v[104:107], v[168:171], v[210:213], v[104:107]
	v_mfma_f32_16x16x32_bf16 v[92:95], v[138:141], v[218:221], v[92:95]
	v_mfma_f32_16x16x32_bf16 v[88:91], v[168:171], v[218:221], v[88:91]
	v_mfma_f32_16x16x32_bf16 v[76:79], v[138:141], v[226:229], v[76:79]
	v_mfma_f32_16x16x32_bf16 v[72:75], v[168:171], v[226:229], v[72:75]
	v_mfma_f32_16x16x32_bf16 v[124:127], v[164:167], v[206:209], v[124:127]
	v_mfma_f32_16x16x32_bf16 v[120:123], v[172:175], v[206:209], v[120:123]
	v_mfma_f32_16x16x32_bf16 v[108:111], v[164:167], v[214:217], v[108:111]
	v_mfma_f32_16x16x32_bf16 v[104:107], v[172:175], v[214:217], v[104:107]
	v_mfma_f32_16x16x32_bf16 v[92:95], v[164:167], v[222:225], v[92:95]
	v_mfma_f32_16x16x32_bf16 v[88:91], v[172:175], v[222:225], v[88:91]
	v_mfma_f32_16x16x32_bf16 v[76:79], v[164:167], v[230:233], v[76:79]
	v_mfma_f32_16x16x32_bf16 v[72:75], v[172:175], v[230:233], v[72:75]
	s_setprio 0
	s_barrier
	v_add_u32_e32 v142, 0x14000, v160
	ds_read_b128 v[138:141], v142
	ds_read_b128 v[164:167], v142 offset:1024
	ds_read_b128 v[168:171], v142 offset:2048
	ds_read_b128 v[172:175], v142 offset:3072
	ds_read_b128 v[202:205], v162 offset:16384
	ds_read_b128 v[206:209], v162 offset:17408
	ds_read_b128 v[210:213], v162 offset:18432
	ds_read_b128 v[214:217], v162 offset:19456
	ds_read_b128 v[218:221], v162 offset:20480
	ds_read_b128 v[222:225], v162 offset:21504
	ds_read_b128 v[226:229], v162 offset:22528
	ds_read_b128 v[230:233], v162 offset:23552
	v_lshl_add_u64 v[234:235], s[74:75], 0, v[128:129]
	s_add_i32 m0, s5, 0x8000
	v_lshl_add_u64 v[236:237], s[74:75], 0, v[130:131]
	global_load_lds_dwordx4 v[234:235], off
	s_add_i32 m0, s5, 0xa000
	v_lshl_add_u64 v[238:239], s[2:3], 0, v[144:145]
	global_load_lds_dwordx4 v[236:237], off
	s_add_i32 m0, s5, 0x18000
	v_lshl_add_u64 v[240:241], s[2:3], 0, v[132:133]
	global_load_lds_dwordx4 v[238:239], off
	s_add_i32 m0, s5, 0x1a000
	s_add_u32 s74, s74, 0x80
	s_addc_u32 s75, s75, 0
	global_load_lds_dwordx4 v[240:241], off
	s_add_u32 s2, s2, 0x80
	s_addc_u32 s3, s3, 0
	s_waitcnt vmcnt(8)
	s_waitcnt lgkmcnt(0)
	s_barrier
	s_setprio 1
	v_mfma_f32_16x16x32_bf16 v[124:127], v[138:141], v[202:205], v[124:127]
	v_mfma_f32_16x16x32_bf16 v[120:123], v[168:171], v[202:205], v[120:123]
	v_mfma_f32_16x16x32_bf16 v[108:111], v[138:141], v[210:213], v[108:111]
	v_mfma_f32_16x16x32_bf16 v[104:107], v[168:171], v[210:213], v[104:107]
	v_mfma_f32_16x16x32_bf16 v[92:95], v[138:141], v[218:221], v[92:95]
	v_mfma_f32_16x16x32_bf16 v[88:91], v[168:171], v[218:221], v[88:91]
	v_mfma_f32_16x16x32_bf16 v[76:79], v[138:141], v[226:229], v[76:79]
	v_mfma_f32_16x16x32_bf16 v[72:75], v[168:171], v[226:229], v[72:75]
	v_mfma_f32_16x16x32_bf16 v[124:127], v[164:167], v[206:209], v[124:127]
	v_mfma_f32_16x16x32_bf16 v[120:123], v[172:175], v[206:209], v[120:123]
	v_mfma_f32_16x16x32_bf16 v[108:111], v[164:167], v[214:217], v[108:111]
	v_mfma_f32_16x16x32_bf16 v[104:107], v[172:175], v[214:217], v[104:107]
	v_mfma_f32_16x16x32_bf16 v[92:95], v[164:167], v[222:225], v[92:95]
	v_mfma_f32_16x16x32_bf16 v[88:91], v[172:175], v[222:225], v[88:91]
	v_mfma_f32_16x16x32_bf16 v[76:79], v[164:167], v[230:233], v[76:79]
	v_mfma_f32_16x16x32_bf16 v[72:75], v[172:175], v[230:233], v[72:75]
	s_setprio 0
	s_barrier
	v_add_u32_e32 v142, 0x1c000, v160
	ds_read_b128 v[138:141], v142
	ds_read_b128 v[164:167], v142 offset:1024
	ds_read_b128 v[168:171], v142 offset:2048
	ds_read_b128 v[172:175], v142 offset:3072
	ds_read_b128 v[202:205], v162 offset:49152
	ds_read_b128 v[206:209], v162 offset:50176
	ds_read_b128 v[210:213], v162 offset:51200
	ds_read_b128 v[214:217], v162 offset:52224
	ds_read_b128 v[218:221], v162 offset:53248
	ds_read_b128 v[222:225], v162 offset:54272
	ds_read_b128 v[226:229], v162 offset:55296
	ds_read_b128 v[230:233], v162 offset:56320
	v_lshl_add_u64 v[234:235], s[74:75], 0, v[128:129]
	s_add_i32 m0, s5, 0x4000
	v_lshl_add_u64 v[236:237], s[74:75], 0, v[130:131]
	global_load_lds_dwordx4 v[234:235], off
	s_add_i32 m0, s5, 0x6000
	v_lshl_add_u64 v[238:239], s[2:3], 0, v[144:145]
	global_load_lds_dwordx4 v[236:237], off
	s_add_i32 m0, s5, 0x14000
	v_lshl_add_u64 v[240:241], s[2:3], 0, v[132:133]
	global_load_lds_dwordx4 v[238:239], off
	s_add_i32 m0, s5, 0x16000
	s_add_u32 s74, s74, 0x80
	s_addc_u32 s75, s75, 0
	global_load_lds_dwordx4 v[240:241], off
	s_add_u32 s2, s2, 0x80
	s_addc_u32 s3, s3, 0
	s_waitcnt vmcnt(8)
	s_waitcnt lgkmcnt(0)
	s_barrier
	s_setprio 1
	v_mfma_f32_16x16x32_bf16 v[124:127], v[138:141], v[202:205], v[124:127]
	v_mfma_f32_16x16x32_bf16 v[120:123], v[168:171], v[202:205], v[120:123]
	v_mfma_f32_16x16x32_bf16 v[108:111], v[138:141], v[210:213], v[108:111]
	v_mfma_f32_16x16x32_bf16 v[104:107], v[168:171], v[210:213], v[104:107]
	v_mfma_f32_16x16x32_bf16 v[92:95], v[138:141], v[218:221], v[92:95]
	v_mfma_f32_16x16x32_bf16 v[88:91], v[168:171], v[218:221], v[88:91]
	v_mfma_f32_16x16x32_bf16 v[76:79], v[138:141], v[226:229], v[76:79]
	v_mfma_f32_16x16x32_bf16 v[72:75], v[168:171], v[226:229], v[72:75]
	v_mfma_f32_16x16x32_bf16 v[124:127], v[164:167], v[206:209], v[124:127]
	v_mfma_f32_16x16x32_bf16 v[120:123], v[172:175], v[206:209], v[120:123]
	v_mfma_f32_16x16x32_bf16 v[108:111], v[164:167], v[214:217], v[108:111]
	v_mfma_f32_16x16x32_bf16 v[104:107], v[172:175], v[214:217], v[104:107]
	v_mfma_f32_16x16x32_bf16 v[92:95], v[164:167], v[222:225], v[92:95]
	v_mfma_f32_16x16x32_bf16 v[88:91], v[172:175], v[222:225], v[88:91]
	v_mfma_f32_16x16x32_bf16 v[76:79], v[164:167], v[230:233], v[76:79]
	v_mfma_f32_16x16x32_bf16 v[72:75], v[172:175], v[230:233], v[72:75]
	s_setprio 0
	s_barrier
	s_add_i32 s8, s8, 1
	s_cmp_lt_u32 s8, 7
	s_cbranch_scc1 .Lq_abi_0_k
	v_add_u32_e32 v142, 0x10000, v160
	ds_read_b128 v[138:141], v142
	ds_read_b128 v[164:167], v142 offset:1024
	ds_read_b128 v[168:171], v142 offset:2048
	ds_read_b128 v[172:175], v142 offset:3072
	ds_read_b128 v[202:205], v162 offset:0
	ds_read_b128 v[206:209], v162 offset:1024
	ds_read_b128 v[210:213], v162 offset:2048
	ds_read_b128 v[214:217], v162 offset:3072
	ds_read_b128 v[218:221], v162 offset:4096
	ds_read_b128 v[222:225], v162 offset:5120
	ds_read_b128 v[226:229], v162 offset:6144
	ds_read_b128 v[230:233], v162 offset:7168
	v_lshl_add_u64 v[234:235], s[74:75], 0, v[128:129]
	s_add_i32 m0, s5, 0xc000
	v_lshl_add_u64 v[236:237], s[74:75], 0, v[130:131]
	global_load_lds_dwordx4 v[234:235], off
	s_add_i32 m0, s5, 0xe000
	v_lshl_add_u64 v[238:239], s[2:3], 0, v[144:145]
	global_load_lds_dwordx4 v[236:237], off
	s_add_i32 m0, s5, 0x1c000
	v_lshl_add_u64 v[240:241], s[2:3], 0, v[132:133]
	global_load_lds_dwordx4 v[238:239], off
	s_add_i32 m0, s5, 0x1e000
	s_add_u32 s74, s74, 0x80
	s_addc_u32 s75, s75, 0
	global_load_lds_dwordx4 v[240:241], off
	s_add_u32 s2, s2, 0x80
	s_addc_u32 s3, s3, 0
	s_waitcnt vmcnt(8)
	s_waitcnt lgkmcnt(0)
	s_barrier
	s_setprio 1
	v_mfma_f32_16x16x32_bf16 v[124:127], v[138:141], v[202:205], v[124:127]
	v_mfma_f32_16x16x32_bf16 v[120:123], v[168:171], v[202:205], v[120:123]
	v_mfma_f32_16x16x32_bf16 v[108:111], v[138:141], v[210:213], v[108:111]
	v_mfma_f32_16x16x32_bf16 v[104:107], v[168:171], v[210:213], v[104:107]
	v_mfma_f32_16x16x32_bf16 v[92:95], v[138:141], v[218:221], v[92:95]
	v_mfma_f32_16x16x32_bf16 v[88:91], v[168:171], v[218:221], v[88:91]
	v_mfma_f32_16x16x32_bf16 v[76:79], v[138:141], v[226:229], v[76:79]
	v_mfma_f32_16x16x32_bf16 v[72:75], v[168:171], v[226:229], v[72:75]
	v_mfma_f32_16x16x32_bf16 v[124:127], v[164:167], v[206:209], v[124:127]
	v_mfma_f32_16x16x32_bf16 v[120:123], v[172:175], v[206:209], v[120:123]
	v_mfma_f32_16x16x32_bf16 v[108:111], v[164:167], v[214:217], v[108:111]
	v_mfma_f32_16x16x32_bf16 v[104:107], v[172:175], v[214:217], v[104:107]
	v_mfma_f32_16x16x32_bf16 v[92:95], v[164:167], v[222:225], v[92:95]
	v_mfma_f32_16x16x32_bf16 v[88:91], v[172:175], v[222:225], v[88:91]
	v_mfma_f32_16x16x32_bf16 v[76:79], v[164:167], v[230:233], v[76:79]
	v_mfma_f32_16x16x32_bf16 v[72:75], v[172:175], v[230:233], v[72:75]
	s_setprio 0
	s_barrier
	v_add_u32_e32 v142, 0x18000, v160
	ds_read_b128 v[138:141], v142
	ds_read_b128 v[164:167], v142 offset:1024
	ds_read_b128 v[168:171], v142 offset:2048
	ds_read_b128 v[172:175], v142 offset:3072
	ds_read_b128 v[202:205], v162 offset:32768
	ds_read_b128 v[206:209], v162 offset:33792
	ds_read_b128 v[210:213], v162 offset:34816
	ds_read_b128 v[214:217], v162 offset:35840
	ds_read_b128 v[218:221], v162 offset:36864
	ds_read_b128 v[222:225], v162 offset:37888
	ds_read_b128 v[226:229], v162 offset:38912
	ds_read_b128 v[230:233], v162 offset:39936
	s_waitcnt vmcnt(4)
	s_waitcnt lgkmcnt(0)
	s_barrier
	s_setprio 1
	v_mfma_f32_16x16x32_bf16 v[124:127], v[138:141], v[202:205], v[124:127]
	v_mfma_f32_16x16x32_bf16 v[120:123], v[168:171], v[202:205], v[120:123]
	v_mfma_f32_16x16x32_bf16 v[108:111], v[138:141], v[210:213], v[108:111]
	v_mfma_f32_16x16x32_bf16 v[104:107], v[168:171], v[210:213], v[104:107]
	v_mfma_f32_16x16x32_bf16 v[92:95], v[138:141], v[218:221], v[92:95]
	v_mfma_f32_16x16x32_bf16 v[88:91], v[168:171], v[218:221], v[88:91]
	v_mfma_f32_16x16x32_bf16 v[76:79], v[138:141], v[226:229], v[76:79]
	v_mfma_f32_16x16x32_bf16 v[72:75], v[168:171], v[226:229], v[72:75]
	v_mfma_f32_16x16x32_bf16 v[124:127], v[164:167], v[206:209], v[124:127]
	v_mfma_f32_16x16x32_bf16 v[120:123], v[172:175], v[206:209], v[120:123]
	v_mfma_f32_16x16x32_bf16 v[108:111], v[164:167], v[214:217], v[108:111]
	v_mfma_f32_16x16x32_bf16 v[104:107], v[172:175], v[214:217], v[104:107]
	v_mfma_f32_16x16x32_bf16 v[92:95], v[164:167], v[222:225], v[92:95]
	v_mfma_f32_16x16x32_bf16 v[88:91], v[172:175], v[222:225], v[88:91]
	v_mfma_f32_16x16x32_bf16 v[76:79], v[164:167], v[230:233], v[76:79]
	v_mfma_f32_16x16x32_bf16 v[72:75], v[172:175], v[230:233], v[72:75]
	s_setprio 0
	s_barrier
	v_add_u32_e32 v142, 0x14000, v160
	ds_read_b128 v[138:141], v142
	ds_read_b128 v[164:167], v142 offset:1024
	ds_read_b128 v[168:171], v142 offset:2048
	ds_read_b128 v[172:175], v142 offset:3072
	ds_read_b128 v[202:205], v162 offset:16384
	ds_read_b128 v[206:209], v162 offset:17408
	ds_read_b128 v[210:213], v162 offset:18432
	ds_read_b128 v[214:217], v162 offset:19456
	ds_read_b128 v[218:221], v162 offset:20480
	ds_read_b128 v[222:225], v162 offset:21504
	ds_read_b128 v[226:229], v162 offset:22528
	ds_read_b128 v[230:233], v162 offset:23552
	s_waitcnt vmcnt(0)
	s_waitcnt lgkmcnt(0)
	s_barrier
	s_setprio 1
	v_mfma_f32_16x16x32_bf16 v[124:127], v[138:141], v[202:205], v[124:127]
	v_mfma_f32_16x16x32_bf16 v[120:123], v[168:171], v[202:205], v[120:123]
	v_mfma_f32_16x16x32_bf16 v[108:111], v[138:141], v[210:213], v[108:111]
	v_mfma_f32_16x16x32_bf16 v[104:107], v[168:171], v[210:213], v[104:107]
	v_mfma_f32_16x16x32_bf16 v[92:95], v[138:141], v[218:221], v[92:95]
	v_mfma_f32_16x16x32_bf16 v[88:91], v[168:171], v[218:221], v[88:91]
	v_mfma_f32_16x16x32_bf16 v[76:79], v[138:141], v[226:229], v[76:79]
	v_mfma_f32_16x16x32_bf16 v[72:75], v[168:171], v[226:229], v[72:75]
	v_mfma_f32_16x16x32_bf16 v[124:127], v[164:167], v[206:209], v[124:127]
	v_mfma_f32_16x16x32_bf16 v[120:123], v[172:175], v[206:209], v[120:123]
	v_mfma_f32_16x16x32_bf16 v[108:111], v[164:167], v[214:217], v[108:111]
	v_mfma_f32_16x16x32_bf16 v[104:107], v[172:175], v[214:217], v[104:107]
	v_mfma_f32_16x16x32_bf16 v[92:95], v[164:167], v[222:225], v[92:95]
	v_mfma_f32_16x16x32_bf16 v[88:91], v[172:175], v[222:225], v[88:91]
	v_mfma_f32_16x16x32_bf16 v[76:79], v[164:167], v[230:233], v[76:79]
	v_mfma_f32_16x16x32_bf16 v[72:75], v[172:175], v[230:233], v[72:75]
	s_setprio 0
	s_barrier
	v_add_u32_e32 v142, 0x1c000, v160
	ds_read_b128 v[138:141], v142
	ds_read_b128 v[164:167], v142 offset:1024
	ds_read_b128 v[168:171], v142 offset:2048
	ds_read_b128 v[172:175], v142 offset:3072
	ds_read_b128 v[202:205], v162 offset:49152
	ds_read_b128 v[206:209], v162 offset:50176
	ds_read_b128 v[210:213], v162 offset:51200
	ds_read_b128 v[214:217], v162 offset:52224
	ds_read_b128 v[218:221], v162 offset:53248
	ds_read_b128 v[222:225], v162 offset:54272
	ds_read_b128 v[226:229], v162 offset:55296
	ds_read_b128 v[230:233], v162 offset:56320
	s_waitcnt lgkmcnt(0)
	s_barrier
	s_setprio 1
	v_mfma_f32_16x16x32_bf16 v[124:127], v[138:141], v[202:205], v[124:127]
	v_mfma_f32_16x16x32_bf16 v[120:123], v[168:171], v[202:205], v[120:123]
	v_mfma_f32_16x16x32_bf16 v[108:111], v[138:141], v[210:213], v[108:111]
	v_mfma_f32_16x16x32_bf16 v[104:107], v[168:171], v[210:213], v[104:107]
	v_mfma_f32_16x16x32_bf16 v[92:95], v[138:141], v[218:221], v[92:95]
	v_mfma_f32_16x16x32_bf16 v[88:91], v[168:171], v[218:221], v[88:91]
	v_mfma_f32_16x16x32_bf16 v[76:79], v[138:141], v[226:229], v[76:79]
	v_mfma_f32_16x16x32_bf16 v[72:75], v[168:171], v[226:229], v[72:75]
	v_mfma_f32_16x16x32_bf16 v[124:127], v[164:167], v[206:209], v[124:127]
	v_mfma_f32_16x16x32_bf16 v[120:123], v[172:175], v[206:209], v[120:123]
	v_mfma_f32_16x16x32_bf16 v[108:111], v[164:167], v[214:217], v[108:111]
	v_mfma_f32_16x16x32_bf16 v[104:107], v[172:175], v[214:217], v[104:107]
	v_mfma_f32_16x16x32_bf16 v[92:95], v[164:167], v[222:225], v[92:95]
	v_mfma_f32_16x16x32_bf16 v[88:91], v[172:175], v[222:225], v[88:91]
	v_mfma_f32_16x16x32_bf16 v[76:79], v[164:167], v[230:233], v[76:79]
	v_mfma_f32_16x16x32_bf16 v[72:75], v[172:175], v[230:233], v[72:75]
	s_setprio 0
	s_barrier
	s_branch .Lq_abi_exit

.Lq_abi_1_k:
	v_add_u32_e32 v142, 0x14000, v160
	ds_read_b128 v[176:179], v142
	ds_read_b128 v[190:193], v142 offset:1024
	ds_read_b128 v[194:197], v142 offset:2048
	ds_read_b128 v[198:201], v142 offset:3072
	ds_read_b128 v[202:205], v162 offset:0
	ds_read_b128 v[206:209], v162 offset:1024
	ds_read_b128 v[210:213], v162 offset:2048
	ds_read_b128 v[214:217], v162 offset:3072
	ds_read_b128 v[218:221], v162 offset:4096
	ds_read_b128 v[222:225], v162 offset:5120
	ds_read_b128 v[226:229], v162 offset:6144
	ds_read_b128 v[230:233], v162 offset:7168
	v_lshl_add_u64 v[234:235], s[74:75], 0, v[128:129]
	s_add_i32 m0, s5, 0xc000
	v_lshl_add_u64 v[236:237], s[74:75], 0, v[130:131]
	global_load_lds_dwordx4 v[234:235], off
	s_add_i32 m0, s5, 0xe000
	v_lshl_add_u64 v[238:239], s[2:3], 0, v[144:145]
	global_load_lds_dwordx4 v[236:237], off
	s_add_i32 m0, s5, 0x18000
	v_lshl_add_u64 v[240:241], s[2:3], 0, v[132:133]
	global_load_lds_dwordx4 v[238:239], off
	s_add_i32 m0, s5, 0x1a000
	s_add_u32 s74, s74, 0x80
	s_addc_u32 s75, s75, 0
	global_load_lds_dwordx4 v[240:241], off
	s_add_u32 s2, s2, 0x80
	s_addc_u32 s3, s3, 0
	s_waitcnt vmcnt(8)
	s_waitcnt lgkmcnt(0)
	s_barrier
	s_setprio 1
	v_mfma_f32_16x16x32_bf16 v[116:119], v[176:179], v[202:205], v[116:119]
	v_mfma_f32_16x16x32_bf16 v[112:115], v[194:197], v[202:205], v[112:115]
	v_mfma_f32_16x16x32_bf16 v[100:103], v[176:179], v[210:213], v[100:103]
	v_mfma_f32_16x16x32_bf16 v[96:99], v[194:197], v[210:213], v[96:99]
	v_mfma_f32_16x16x32_bf16 v[84:87], v[176:179], v[218:221], v[84:87]
	v_mfma_f32_16x16x32_bf16 v[80:83], v[194:197], v[218:221], v[80:83]
	v_mfma_f32_16x16x32_bf16 v[68:71], v[176:179], v[226:229], v[68:71]
	v_mfma_f32_16x16x32_bf16 v[64:67], v[194:197], v[226:229], v[64:67]
	v_mfma_f32_16x16x32_bf16 v[116:119], v[190:193], v[206:209], v[116:119]
	v_mfma_f32_16x16x32_bf16 v[112:115], v[198:201], v[206:209], v[112:115]
	v_mfma_f32_16x16x32_bf16 v[100:103], v[190:193], v[214:217], v[100:103]
	v_mfma_f32_16x16x32_bf16 v[96:99], v[198:201], v[214:217], v[96:99]
	v_mfma_f32_16x16x32_bf16 v[84:87], v[190:193], v[222:225], v[84:87]
	v_mfma_f32_16x16x32_bf16 v[80:83], v[198:201], v[222:225], v[80:83]
	v_mfma_f32_16x16x32_bf16 v[68:71], v[190:193], v[230:233], v[68:71]
	v_mfma_f32_16x16x32_bf16 v[64:67], v[198:201], v[230:233], v[64:67]
	s_setprio 0
	s_barrier
	v_add_u32_e32 v142, 0x1c000, v160
	ds_read_b128 v[176:179], v142
	ds_read_b128 v[190:193], v142 offset:1024
	ds_read_b128 v[194:197], v142 offset:2048
	ds_read_b128 v[198:201], v142 offset:3072
	ds_read_b128 v[202:205], v162 offset:32768
	ds_read_b128 v[206:209], v162 offset:33792
	ds_read_b128 v[210:213], v162 offset:34816
	ds_read_b128 v[214:217], v162 offset:35840
	ds_read_b128 v[218:221], v162 offset:36864
	ds_read_b128 v[222:225], v162 offset:37888
	ds_read_b128 v[226:229], v162 offset:38912
	ds_read_b128 v[230:233], v162 offset:39936
	v_lshl_add_u64 v[234:235], s[74:75], 0, v[128:129]
	s_add_i32 m0, s5, 0x0
	v_lshl_add_u64 v[236:237], s[74:75], 0, v[130:131]
	global_load_lds_dwordx4 v[234:235], off
	s_add_i32 m0, s5, 0x2000
	v_lshl_add_u64 v[238:239], s[2:3], 0, v[144:145]
	global_load_lds_dwordx4 v[236:237], off
	s_add_i32 m0, s5, 0x14000
	v_lshl_add_u64 v[240:241], s[2:3], 0, v[132:133]
	global_load_lds_dwordx4 v[238:239], off
	s_add_i32 m0, s5, 0x16000
	s_add_u32 s74, s74, 0x80
	s_addc_u32 s75, s75, 0
	global_load_lds_dwordx4 v[240:241], off
	s_add_u32 s2, s2, 0x80
	s_addc_u32 s3, s3, 0
	s_waitcnt vmcnt(8)
	s_waitcnt lgkmcnt(0)
	s_barrier
	s_setprio 1
	v_mfma_f32_16x16x32_bf16 v[116:119], v[176:179], v[202:205], v[116:119]
	v_mfma_f32_16x16x32_bf16 v[112:115], v[194:197], v[202:205], v[112:115]
	v_mfma_f32_16x16x32_bf16 v[100:103], v[176:179], v[210:213], v[100:103]
	v_mfma_f32_16x16x32_bf16 v[96:99], v[194:197], v[210:213], v[96:99]
	v_mfma_f32_16x16x32_bf16 v[84:87], v[176:179], v[218:221], v[84:87]
	v_mfma_f32_16x16x32_bf16 v[80:83], v[194:197], v[218:221], v[80:83]
	v_mfma_f32_16x16x32_bf16 v[68:71], v[176:179], v[226:229], v[68:71]
	v_mfma_f32_16x16x32_bf16 v[64:67], v[194:197], v[226:229], v[64:67]
	v_mfma_f32_16x16x32_bf16 v[116:119], v[190:193], v[206:209], v[116:119]
	v_mfma_f32_16x16x32_bf16 v[112:115], v[198:201], v[206:209], v[112:115]
	v_mfma_f32_16x16x32_bf16 v[100:103], v[190:193], v[214:217], v[100:103]
	v_mfma_f32_16x16x32_bf16 v[96:99], v[198:201], v[214:217], v[96:99]
	v_mfma_f32_16x16x32_bf16 v[84:87], v[190:193], v[222:225], v[84:87]
	v_mfma_f32_16x16x32_bf16 v[80:83], v[198:201], v[222:225], v[80:83]
	v_mfma_f32_16x16x32_bf16 v[68:71], v[190:193], v[230:233], v[68:71]
	v_mfma_f32_16x16x32_bf16 v[64:67], v[198:201], v[230:233], v[64:67]
	s_setprio 0
	s_barrier
	v_add_u32_e32 v142, 0x10000, v160
	ds_read_b128 v[176:179], v142
	ds_read_b128 v[190:193], v142 offset:1024
	ds_read_b128 v[194:197], v142 offset:2048
	ds_read_b128 v[198:201], v142 offset:3072
	ds_read_b128 v[202:205], v162 offset:16384
	ds_read_b128 v[206:209], v162 offset:17408
	ds_read_b128 v[210:213], v162 offset:18432
	ds_read_b128 v[214:217], v162 offset:19456
	ds_read_b128 v[218:221], v162 offset:20480
	ds_read_b128 v[222:225], v162 offset:21504
	ds_read_b128 v[226:229], v162 offset:22528
	ds_read_b128 v[230:233], v162 offset:23552
	v_lshl_add_u64 v[234:235], s[74:75], 0, v[128:129]
	s_add_i32 m0, s5, 0x8000
	v_lshl_add_u64 v[236:237], s[74:75], 0, v[130:131]
	global_load_lds_dwordx4 v[234:235], off
	s_add_i32 m0, s5, 0xa000
	v_lshl_add_u64 v[238:239], s[2:3], 0, v[144:145]
	global_load_lds_dwordx4 v[236:237], off
	s_add_i32 m0, s5, 0x1c000
	v_lshl_add_u64 v[240:241], s[2:3], 0, v[132:133]
	global_load_lds_dwordx4 v[238:239], off
	s_add_i32 m0, s5, 0x1e000
	s_add_u32 s74, s74, 0x80
	s_addc_u32 s75, s75, 0
	global_load_lds_dwordx4 v[240:241], off
	s_add_u32 s2, s2, 0x80
	s_addc_u32 s3, s3, 0
	s_waitcnt vmcnt(8)
	s_waitcnt lgkmcnt(0)
	s_barrier
	s_setprio 1
	v_mfma_f32_16x16x32_bf16 v[116:119], v[176:179], v[202:205], v[116:119]
	v_mfma_f32_16x16x32_bf16 v[112:115], v[194:197], v[202:205], v[112:115]
	v_mfma_f32_16x16x32_bf16 v[100:103], v[176:179], v[210:213], v[100:103]
	v_mfma_f32_16x16x32_bf16 v[96:99], v[194:197], v[210:213], v[96:99]
	v_mfma_f32_16x16x32_bf16 v[84:87], v[176:179], v[218:221], v[84:87]
	v_mfma_f32_16x16x32_bf16 v[80:83], v[194:197], v[218:221], v[80:83]
	v_mfma_f32_16x16x32_bf16 v[68:71], v[176:179], v[226:229], v[68:71]
	v_mfma_f32_16x16x32_bf16 v[64:67], v[194:197], v[226:229], v[64:67]
	v_mfma_f32_16x16x32_bf16 v[116:119], v[190:193], v[206:209], v[116:119]
	v_mfma_f32_16x16x32_bf16 v[112:115], v[198:201], v[206:209], v[112:115]
	v_mfma_f32_16x16x32_bf16 v[100:103], v[190:193], v[214:217], v[100:103]
	v_mfma_f32_16x16x32_bf16 v[96:99], v[198:201], v[214:217], v[96:99]
	v_mfma_f32_16x16x32_bf16 v[84:87], v[190:193], v[222:225], v[84:87]
	v_mfma_f32_16x16x32_bf16 v[80:83], v[198:201], v[222:225], v[80:83]
	v_mfma_f32_16x16x32_bf16 v[68:71], v[190:193], v[230:233], v[68:71]
	v_mfma_f32_16x16x32_bf16 v[64:67], v[198:201], v[230:233], v[64:67]
	s_setprio 0
	s_barrier
	v_add_u32_e32 v142, 0x18000, v160
	ds_read_b128 v[176:179], v142
	ds_read_b128 v[190:193], v142 offset:1024
	ds_read_b128 v[194:197], v142 offset:2048
	ds_read_b128 v[198:201], v142 offset:3072
	ds_read_b128 v[202:205], v162 offset:49152
	ds_read_b128 v[206:209], v162 offset:50176
	ds_read_b128 v[210:213], v162 offset:51200
	ds_read_b128 v[214:217], v162 offset:52224
	ds_read_b128 v[218:221], v162 offset:53248
	ds_read_b128 v[222:225], v162 offset:54272
	ds_read_b128 v[226:229], v162 offset:55296
	ds_read_b128 v[230:233], v162 offset:56320
	v_lshl_add_u64 v[234:235], s[74:75], 0, v[128:129]
	s_add_i32 m0, s5, 0x4000
	v_lshl_add_u64 v[236:237], s[74:75], 0, v[130:131]
	global_load_lds_dwordx4 v[234:235], off
	s_add_i32 m0, s5, 0x6000
	v_lshl_add_u64 v[238:239], s[2:3], 0, v[144:145]
	global_load_lds_dwordx4 v[236:237], off
	s_add_i32 m0, s5, 0x10000
	v_lshl_add_u64 v[240:241], s[2:3], 0, v[132:133]
	global_load_lds_dwordx4 v[238:239], off
	s_add_i32 m0, s5, 0x12000
	s_add_u32 s74, s74, 0x80
	s_addc_u32 s75, s75, 0
	global_load_lds_dwordx4 v[240:241], off
	s_add_u32 s2, s2, 0x80
	s_addc_u32 s3, s3, 0
	s_waitcnt vmcnt(8)
	s_waitcnt lgkmcnt(0)
	s_barrier
	s_setprio 1
	v_mfma_f32_16x16x32_bf16 v[116:119], v[176:179], v[202:205], v[116:119]
	v_mfma_f32_16x16x32_bf16 v[112:115], v[194:197], v[202:205], v[112:115]
	v_mfma_f32_16x16x32_bf16 v[100:103], v[176:179], v[210:213], v[100:103]
	v_mfma_f32_16x16x32_bf16 v[96:99], v[194:197], v[210:213], v[96:99]
	v_mfma_f32_16x16x32_bf16 v[84:87], v[176:179], v[218:221], v[84:87]
	v_mfma_f32_16x16x32_bf16 v[80:83], v[194:197], v[218:221], v[80:83]
	v_mfma_f32_16x16x32_bf16 v[68:71], v[176:179], v[226:229], v[68:71]
	v_mfma_f32_16x16x32_bf16 v[64:67], v[194:197], v[226:229], v[64:67]
	v_mfma_f32_16x16x32_bf16 v[116:119], v[190:193], v[206:209], v[116:119]
	v_mfma_f32_16x16x32_bf16 v[112:115], v[198:201], v[206:209], v[112:115]
	v_mfma_f32_16x16x32_bf16 v[100:103], v[190:193], v[214:217], v[100:103]
	v_mfma_f32_16x16x32_bf16 v[96:99], v[198:201], v[214:217], v[96:99]
	v_mfma_f32_16x16x32_bf16 v[84:87], v[190:193], v[222:225], v[84:87]
	v_mfma_f32_16x16x32_bf16 v[80:83], v[198:201], v[222:225], v[80:83]
	v_mfma_f32_16x16x32_bf16 v[68:71], v[190:193], v[230:233], v[68:71]
	v_mfma_f32_16x16x32_bf16 v[64:67], v[198:201], v[230:233], v[64:67]
	s_setprio 0
	s_barrier
	s_add_i32 s8, s8, 1
	s_cmp_lt_u32 s8, 7
	s_cbranch_scc1 .Lq_abi_1_k
	v_add_u32_e32 v142, 0x14000, v160
	ds_read_b128 v[176:179], v142
	ds_read_b128 v[190:193], v142 offset:1024
	ds_read_b128 v[194:197], v142 offset:2048
	ds_read_b128 v[198:201], v142 offset:3072
	ds_read_b128 v[202:205], v162 offset:0
	ds_read_b128 v[206:209], v162 offset:1024
	ds_read_b128 v[210:213], v162 offset:2048
	ds_read_b128 v[214:217], v162 offset:3072
	ds_read_b128 v[218:221], v162 offset:4096
	ds_read_b128 v[222:225], v162 offset:5120
	ds_read_b128 v[226:229], v162 offset:6144
	ds_read_b128 v[230:233], v162 offset:7168
	v_lshl_add_u64 v[234:235], s[74:75], 0, v[128:129]
	s_add_i32 m0, s5, 0xc000
	v_lshl_add_u64 v[236:237], s[74:75], 0, v[130:131]
	global_load_lds_dwordx4 v[234:235], off
	s_add_i32 m0, s5, 0xe000
	v_lshl_add_u64 v[238:239], s[2:3], 0, v[144:145]
	global_load_lds_dwordx4 v[236:237], off
	s_add_i32 m0, s5, 0x18000
	v_lshl_add_u64 v[240:241], s[2:3], 0, v[132:133]
	global_load_lds_dwordx4 v[238:239], off
	s_add_i32 m0, s5, 0x1a000
	s_add_u32 s74, s74, 0x80
	s_addc_u32 s75, s75, 0
	global_load_lds_dwordx4 v[240:241], off
	s_add_u32 s2, s2, 0x80
	s_addc_u32 s3, s3, 0
	s_waitcnt vmcnt(8)
	s_waitcnt lgkmcnt(0)
	s_barrier
	s_setprio 1
	v_mfma_f32_16x16x32_bf16 v[116:119], v[176:179], v[202:205], v[116:119]
	v_mfma_f32_16x16x32_bf16 v[112:115], v[194:197], v[202:205], v[112:115]
	v_mfma_f32_16x16x32_bf16 v[100:103], v[176:179], v[210:213], v[100:103]
	v_mfma_f32_16x16x32_bf16 v[96:99], v[194:197], v[210:213], v[96:99]
	v_mfma_f32_16x16x32_bf16 v[84:87], v[176:179], v[218:221], v[84:87]
	v_mfma_f32_16x16x32_bf16 v[80:83], v[194:197], v[218:221], v[80:83]
	v_mfma_f32_16x16x32_bf16 v[68:71], v[176:179], v[226:229], v[68:71]
	v_mfma_f32_16x16x32_bf16 v[64:67], v[194:197], v[226:229], v[64:67]
	v_mfma_f32_16x16x32_bf16 v[116:119], v[190:193], v[206:209], v[116:119]
	v_mfma_f32_16x16x32_bf16 v[112:115], v[198:201], v[206:209], v[112:115]
	v_mfma_f32_16x16x32_bf16 v[100:103], v[190:193], v[214:217], v[100:103]
	v_mfma_f32_16x16x32_bf16 v[96:99], v[198:201], v[214:217], v[96:99]
	v_mfma_f32_16x16x32_bf16 v[84:87], v[190:193], v[222:225], v[84:87]
	v_mfma_f32_16x16x32_bf16 v[80:83], v[198:201], v[222:225], v[80:83]
	v_mfma_f32_16x16x32_bf16 v[68:71], v[190:193], v[230:233], v[68:71]
	v_mfma_f32_16x16x32_bf16 v[64:67], v[198:201], v[230:233], v[64:67]
	s_setprio 0
	s_barrier
	v_add_u32_e32 v142, 0x1c000, v160
	ds_read_b128 v[176:179], v142
	ds_read_b128 v[190:193], v142 offset:1024
	ds_read_b128 v[194:197], v142 offset:2048
	ds_read_b128 v[198:201], v142 offset:3072
	ds_read_b128 v[202:205], v162 offset:32768
	ds_read_b128 v[206:209], v162 offset:33792
	ds_read_b128 v[210:213], v162 offset:34816
	ds_read_b128 v[214:217], v162 offset:35840
	ds_read_b128 v[218:221], v162 offset:36864
	ds_read_b128 v[222:225], v162 offset:37888
	ds_read_b128 v[226:229], v162 offset:38912
	ds_read_b128 v[230:233], v162 offset:39936
	s_waitcnt vmcnt(4)
	s_waitcnt lgkmcnt(0)
	s_barrier
	s_setprio 1
	v_mfma_f32_16x16x32_bf16 v[116:119], v[176:179], v[202:205], v[116:119]
	v_mfma_f32_16x16x32_bf16 v[112:115], v[194:197], v[202:205], v[112:115]
	v_mfma_f32_16x16x32_bf16 v[100:103], v[176:179], v[210:213], v[100:103]
	v_mfma_f32_16x16x32_bf16 v[96:99], v[194:197], v[210:213], v[96:99]
	v_mfma_f32_16x16x32_bf16 v[84:87], v[176:179], v[218:221], v[84:87]
	v_mfma_f32_16x16x32_bf16 v[80:83], v[194:197], v[218:221], v[80:83]
	v_mfma_f32_16x16x32_bf16 v[68:71], v[176:179], v[226:229], v[68:71]
	v_mfma_f32_16x16x32_bf16 v[64:67], v[194:197], v[226:229], v[64:67]
	v_mfma_f32_16x16x32_bf16 v[116:119], v[190:193], v[206:209], v[116:119]
	v_mfma_f32_16x16x32_bf16 v[112:115], v[198:201], v[206:209], v[112:115]
	v_mfma_f32_16x16x32_bf16 v[100:103], v[190:193], v[214:217], v[100:103]
	v_mfma_f32_16x16x32_bf16 v[96:99], v[198:201], v[214:217], v[96:99]
	v_mfma_f32_16x16x32_bf16 v[84:87], v[190:193], v[222:225], v[84:87]
	v_mfma_f32_16x16x32_bf16 v[80:83], v[198:201], v[222:225], v[80:83]
	v_mfma_f32_16x16x32_bf16 v[68:71], v[190:193], v[230:233], v[68:71]
	v_mfma_f32_16x16x32_bf16 v[64:67], v[198:201], v[230:233], v[64:67]
	s_setprio 0
	s_barrier
	v_add_u32_e32 v142, 0x10000, v160
	ds_read_b128 v[176:179], v142
	ds_read_b128 v[190:193], v142 offset:1024
	ds_read_b128 v[194:197], v142 offset:2048
	ds_read_b128 v[198:201], v142 offset:3072
	ds_read_b128 v[202:205], v162 offset:16384
	ds_read_b128 v[206:209], v162 offset:17408
	ds_read_b128 v[210:213], v162 offset:18432
	ds_read_b128 v[214:217], v162 offset:19456
	ds_read_b128 v[218:221], v162 offset:20480
	ds_read_b128 v[222:225], v162 offset:21504
	ds_read_b128 v[226:229], v162 offset:22528
	ds_read_b128 v[230:233], v162 offset:23552
	s_waitcnt vmcnt(0)
	s_waitcnt lgkmcnt(0)
	s_barrier
	s_setprio 1
	v_mfma_f32_16x16x32_bf16 v[116:119], v[176:179], v[202:205], v[116:119]
	v_mfma_f32_16x16x32_bf16 v[112:115], v[194:197], v[202:205], v[112:115]
	v_mfma_f32_16x16x32_bf16 v[100:103], v[176:179], v[210:213], v[100:103]
	v_mfma_f32_16x16x32_bf16 v[96:99], v[194:197], v[210:213], v[96:99]
	v_mfma_f32_16x16x32_bf16 v[84:87], v[176:179], v[218:221], v[84:87]
	v_mfma_f32_16x16x32_bf16 v[80:83], v[194:197], v[218:221], v[80:83]
	v_mfma_f32_16x16x32_bf16 v[68:71], v[176:179], v[226:229], v[68:71]
	v_mfma_f32_16x16x32_bf16 v[64:67], v[194:197], v[226:229], v[64:67]
	v_mfma_f32_16x16x32_bf16 v[116:119], v[190:193], v[206:209], v[116:119]
	v_mfma_f32_16x16x32_bf16 v[112:115], v[198:201], v[206:209], v[112:115]
	v_mfma_f32_16x16x32_bf16 v[100:103], v[190:193], v[214:217], v[100:103]
	v_mfma_f32_16x16x32_bf16 v[96:99], v[198:201], v[214:217], v[96:99]
	v_mfma_f32_16x16x32_bf16 v[84:87], v[190:193], v[222:225], v[84:87]
	v_mfma_f32_16x16x32_bf16 v[80:83], v[198:201], v[222:225], v[80:83]
	v_mfma_f32_16x16x32_bf16 v[68:71], v[190:193], v[230:233], v[68:71]
	v_mfma_f32_16x16x32_bf16 v[64:67], v[198:201], v[230:233], v[64:67]
	s_setprio 0
	s_barrier
	v_add_u32_e32 v142, 0x18000, v160
	ds_read_b128 v[176:179], v142
	ds_read_b128 v[190:193], v142 offset:1024
	ds_read_b128 v[194:197], v142 offset:2048
	ds_read_b128 v[198:201], v142 offset:3072
	ds_read_b128 v[202:205], v162 offset:49152
	ds_read_b128 v[206:209], v162 offset:50176
	ds_read_b128 v[210:213], v162 offset:51200
	ds_read_b128 v[214:217], v162 offset:52224
	ds_read_b128 v[218:221], v162 offset:53248
	ds_read_b128 v[222:225], v162 offset:54272
	ds_read_b128 v[226:229], v162 offset:55296
	ds_read_b128 v[230:233], v162 offset:56320
	s_waitcnt lgkmcnt(0)
	s_barrier
	s_setprio 1
	v_mfma_f32_16x16x32_bf16 v[116:119], v[176:179], v[202:205], v[116:119]
	v_mfma_f32_16x16x32_bf16 v[112:115], v[194:197], v[202:205], v[112:115]
	v_mfma_f32_16x16x32_bf16 v[100:103], v[176:179], v[210:213], v[100:103]
	v_mfma_f32_16x16x32_bf16 v[96:99], v[194:197], v[210:213], v[96:99]
	v_mfma_f32_16x16x32_bf16 v[84:87], v[176:179], v[218:221], v[84:87]
	v_mfma_f32_16x16x32_bf16 v[80:83], v[194:197], v[218:221], v[80:83]
	v_mfma_f32_16x16x32_bf16 v[68:71], v[176:179], v[226:229], v[68:71]
	v_mfma_f32_16x16x32_bf16 v[64:67], v[194:197], v[226:229], v[64:67]
	v_mfma_f32_16x16x32_bf16 v[116:119], v[190:193], v[206:209], v[116:119]
	v_mfma_f32_16x16x32_bf16 v[112:115], v[198:201], v[206:209], v[112:115]
	v_mfma_f32_16x16x32_bf16 v[100:103], v[190:193], v[214:217], v[100:103]
	v_mfma_f32_16x16x32_bf16 v[96:99], v[198:201], v[214:217], v[96:99]
	v_mfma_f32_16x16x32_bf16 v[84:87], v[190:193], v[222:225], v[84:87]
	v_mfma_f32_16x16x32_bf16 v[80:83], v[198:201], v[222:225], v[80:83]
	v_mfma_f32_16x16x32_bf16 v[68:71], v[190:193], v[230:233], v[68:71]
	v_mfma_f32_16x16x32_bf16 v[64:67], v[198:201], v[230:233], v[64:67]
	s_setprio 0
	s_barrier
	s_branch .Lq_abi_exit

.Lq_abi_2_k:
	v_add_u32_e32 v142, 0x10000, v160
	ds_read_b128 v[138:141], v142
	ds_read_b128 v[164:167], v142 offset:1024
	ds_read_b128 v[168:171], v142 offset:2048
	ds_read_b128 v[172:175], v142 offset:3072
	ds_read_b128 v[202:205], v162 offset:16384
	ds_read_b128 v[206:209], v162 offset:17408
	ds_read_b128 v[210:213], v162 offset:18432
	ds_read_b128 v[214:217], v162 offset:19456
	ds_read_b128 v[218:221], v162 offset:20480
	ds_read_b128 v[222:225], v162 offset:21504
	ds_read_b128 v[226:229], v162 offset:22528
	ds_read_b128 v[230:233], v162 offset:23552
	v_lshl_add_u64 v[234:235], s[74:75], 0, v[128:129]
	s_add_i32 m0, s5, 0x8000
	v_lshl_add_u64 v[236:237], s[74:75], 0, v[130:131]
	global_load_lds_dwordx4 v[234:235], off
	s_add_i32 m0, s5, 0xa000
	v_lshl_add_u64 v[238:239], s[2:3], 0, v[144:145]
	global_load_lds_dwordx4 v[236:237], off
	s_add_i32 m0, s5, 0x1c000
	v_lshl_add_u64 v[240:241], s[2:3], 0, v[132:133]
	global_load_lds_dwordx4 v[238:239], off
	s_add_i32 m0, s5, 0x1e000
	s_add_u32 s74, s74, 0x80
	s_addc_u32 s75, s75, 0
	global_load_lds_dwordx4 v[240:241], off
	s_add_u32 s2, s2, 0x80
	s_addc_u32 s3, s3, 0
	s_waitcnt vmcnt(8)
	s_waitcnt lgkmcnt(0)
	s_barrier
	s_setprio 1
	v_mfma_f32_16x16x32_bf16 v[60:63], v[138:141], v[202:205], v[60:63]
	v_mfma_f32_16x16x32_bf16 v[56:59], v[168:171], v[202:205], v[56:59]
	v_mfma_f32_16x16x32_bf16 v[44:47], v[138:141], v[210:213], v[44:47]
	v_mfma_f32_16x16x32_bf16 v[40:43], v[168:171], v[210:213], v[40:43]
	v_mfma_f32_16x16x32_bf16 v[28:31], v[138:141], v[218:221], v[28:31]
	v_mfma_f32_16x16x32_bf16 v[24:27], v[168:171], v[218:221], v[24:27]
	v_mfma_f32_16x16x32_bf16 v[12:15], v[138:141], v[226:229], v[12:15]
	v_mfma_f32_16x16x32_bf16 v[8:11], v[168:171], v[226:229], v[8:11]
	v_mfma_f32_16x16x32_bf16 v[60:63], v[164:167], v[206:209], v[60:63]
	v_mfma_f32_16x16x32_bf16 v[56:59], v[172:175], v[206:209], v[56:59]
	v_mfma_f32_16x16x32_bf16 v[44:47], v[164:167], v[214:217], v[44:47]
	v_mfma_f32_16x16x32_bf16 v[40:43], v[172:175], v[214:217], v[40:43]
	v_mfma_f32_16x16x32_bf16 v[28:31], v[164:167], v[222:225], v[28:31]
	v_mfma_f32_16x16x32_bf16 v[24:27], v[172:175], v[222:225], v[24:27]
	v_mfma_f32_16x16x32_bf16 v[12:15], v[164:167], v[230:233], v[12:15]
	v_mfma_f32_16x16x32_bf16 v[8:11], v[172:175], v[230:233], v[8:11]
	s_setprio 0
	s_barrier
	v_add_u32_e32 v142, 0x18000, v160
	ds_read_b128 v[138:141], v142
	ds_read_b128 v[164:167], v142 offset:1024
	ds_read_b128 v[168:171], v142 offset:2048
	ds_read_b128 v[172:175], v142 offset:3072
	ds_read_b128 v[202:205], v162 offset:49152
	ds_read_b128 v[206:209], v162 offset:50176
	ds_read_b128 v[210:213], v162 offset:51200
	ds_read_b128 v[214:217], v162 offset:52224
	ds_read_b128 v[218:221], v162 offset:53248
	ds_read_b128 v[222:225], v162 offset:54272
	ds_read_b128 v[226:229], v162 offset:55296
	ds_read_b128 v[230:233], v162 offset:56320
	v_lshl_add_u64 v[234:235], s[74:75], 0, v[128:129]
	s_add_i32 m0, s5, 0x4000
	v_lshl_add_u64 v[236:237], s[74:75], 0, v[130:131]
	global_load_lds_dwordx4 v[234:235], off
	s_add_i32 m0, s5, 0x6000
	v_lshl_add_u64 v[238:239], s[2:3], 0, v[144:145]
	global_load_lds_dwordx4 v[236:237], off
	s_add_i32 m0, s5, 0x10000
	v_lshl_add_u64 v[240:241], s[2:3], 0, v[132:133]
	global_load_lds_dwordx4 v[238:239], off
	s_add_i32 m0, s5, 0x12000
	s_add_u32 s74, s74, 0x80
	s_addc_u32 s75, s75, 0
	global_load_lds_dwordx4 v[240:241], off
	s_add_u32 s2, s2, 0x80
	s_addc_u32 s3, s3, 0
	s_waitcnt vmcnt(8)
	s_waitcnt lgkmcnt(0)
	s_barrier
	s_setprio 1
	v_mfma_f32_16x16x32_bf16 v[60:63], v[138:141], v[202:205], v[60:63]
	v_mfma_f32_16x16x32_bf16 v[56:59], v[168:171], v[202:205], v[56:59]
	v_mfma_f32_16x16x32_bf16 v[44:47], v[138:141], v[210:213], v[44:47]
	v_mfma_f32_16x16x32_bf16 v[40:43], v[168:171], v[210:213], v[40:43]
	v_mfma_f32_16x16x32_bf16 v[28:31], v[138:141], v[218:221], v[28:31]
	v_mfma_f32_16x16x32_bf16 v[24:27], v[168:171], v[218:221], v[24:27]
	v_mfma_f32_16x16x32_bf16 v[12:15], v[138:141], v[226:229], v[12:15]
	v_mfma_f32_16x16x32_bf16 v[8:11], v[168:171], v[226:229], v[8:11]
	v_mfma_f32_16x16x32_bf16 v[60:63], v[164:167], v[206:209], v[60:63]
	v_mfma_f32_16x16x32_bf16 v[56:59], v[172:175], v[206:209], v[56:59]
	v_mfma_f32_16x16x32_bf16 v[44:47], v[164:167], v[214:217], v[44:47]
	v_mfma_f32_16x16x32_bf16 v[40:43], v[172:175], v[214:217], v[40:43]
	v_mfma_f32_16x16x32_bf16 v[28:31], v[164:167], v[222:225], v[28:31]
	v_mfma_f32_16x16x32_bf16 v[24:27], v[172:175], v[222:225], v[24:27]
	v_mfma_f32_16x16x32_bf16 v[12:15], v[164:167], v[230:233], v[12:15]
	v_mfma_f32_16x16x32_bf16 v[8:11], v[172:175], v[230:233], v[8:11]
	s_setprio 0
	s_barrier
	v_add_u32_e32 v142, 0x14000, v160
	ds_read_b128 v[138:141], v142
	ds_read_b128 v[164:167], v142 offset:1024
	ds_read_b128 v[168:171], v142 offset:2048
	ds_read_b128 v[172:175], v142 offset:3072
	ds_read_b128 v[202:205], v162 offset:0
	ds_read_b128 v[206:209], v162 offset:1024
	ds_read_b128 v[210:213], v162 offset:2048
	ds_read_b128 v[214:217], v162 offset:3072
	ds_read_b128 v[218:221], v162 offset:4096
	ds_read_b128 v[222:225], v162 offset:5120
	ds_read_b128 v[226:229], v162 offset:6144
	ds_read_b128 v[230:233], v162 offset:7168
	v_lshl_add_u64 v[234:235], s[74:75], 0, v[128:129]
	s_add_i32 m0, s5, 0xc000
	v_lshl_add_u64 v[236:237], s[74:75], 0, v[130:131]
	global_load_lds_dwordx4 v[234:235], off
	s_add_i32 m0, s5, 0xe000
	v_lshl_add_u64 v[238:239], s[2:3], 0, v[144:145]
	global_load_lds_dwordx4 v[236:237], off
	s_add_i32 m0, s5, 0x18000
	v_lshl_add_u64 v[240:241], s[2:3], 0, v[132:133]
	global_load_lds_dwordx4 v[238:239], off
	s_add_i32 m0, s5, 0x1a000
	s_add_u32 s74, s74, 0x80
	s_addc_u32 s75, s75, 0
	global_load_lds_dwordx4 v[240:241], off
	s_add_u32 s2, s2, 0x80
	s_addc_u32 s3, s3, 0
	s_waitcnt vmcnt(8)
	s_waitcnt lgkmcnt(0)
	s_barrier
	s_setprio 1
	v_mfma_f32_16x16x32_bf16 v[60:63], v[138:141], v[202:205], v[60:63]
	v_mfma_f32_16x16x32_bf16 v[56:59], v[168:171], v[202:205], v[56:59]
	v_mfma_f32_16x16x32_bf16 v[44:47], v[138:141], v[210:213], v[44:47]
	v_mfma_f32_16x16x32_bf16 v[40:43], v[168:171], v[210:213], v[40:43]
	v_mfma_f32_16x16x32_bf16 v[28:31], v[138:141], v[218:221], v[28:31]
	v_mfma_f32_16x16x32_bf16 v[24:27], v[168:171], v[218:221], v[24:27]
	v_mfma_f32_16x16x32_bf16 v[12:15], v[138:141], v[226:229], v[12:15]
	v_mfma_f32_16x16x32_bf16 v[8:11], v[168:171], v[226:229], v[8:11]
	v_mfma_f32_16x16x32_bf16 v[60:63], v[164:167], v[206:209], v[60:63]
	v_mfma_f32_16x16x32_bf16 v[56:59], v[172:175], v[206:209], v[56:59]
	v_mfma_f32_16x16x32_bf16 v[44:47], v[164:167], v[214:217], v[44:47]
	v_mfma_f32_16x16x32_bf16 v[40:43], v[172:175], v[214:217], v[40:43]
	v_mfma_f32_16x16x32_bf16 v[28:31], v[164:167], v[222:225], v[28:31]
	v_mfma_f32_16x16x32_bf16 v[24:27], v[172:175], v[222:225], v[24:27]
	v_mfma_f32_16x16x32_bf16 v[12:15], v[164:167], v[230:233], v[12:15]
	v_mfma_f32_16x16x32_bf16 v[8:11], v[172:175], v[230:233], v[8:11]
	s_setprio 0
	s_barrier
	v_add_u32_e32 v142, 0x1c000, v160
	ds_read_b128 v[138:141], v142
	ds_read_b128 v[164:167], v142 offset:1024
	ds_read_b128 v[168:171], v142 offset:2048
	ds_read_b128 v[172:175], v142 offset:3072
	ds_read_b128 v[202:205], v162 offset:32768
	ds_read_b128 v[206:209], v162 offset:33792
	ds_read_b128 v[210:213], v162 offset:34816
	ds_read_b128 v[214:217], v162 offset:35840
	ds_read_b128 v[218:221], v162 offset:36864
	ds_read_b128 v[222:225], v162 offset:37888
	ds_read_b128 v[226:229], v162 offset:38912
	ds_read_b128 v[230:233], v162 offset:39936
	v_lshl_add_u64 v[234:235], s[74:75], 0, v[128:129]
	s_add_i32 m0, s5, 0x0
	v_lshl_add_u64 v[236:237], s[74:75], 0, v[130:131]
	global_load_lds_dwordx4 v[234:235], off
	s_add_i32 m0, s5, 0x2000
	v_lshl_add_u64 v[238:239], s[2:3], 0, v[144:145]
	global_load_lds_dwordx4 v[236:237], off
	s_add_i32 m0, s5, 0x14000
	v_lshl_add_u64 v[240:241], s[2:3], 0, v[132:133]
	global_load_lds_dwordx4 v[238:239], off
	s_add_i32 m0, s5, 0x16000
	s_add_u32 s74, s74, 0x80
	s_addc_u32 s75, s75, 0
	global_load_lds_dwordx4 v[240:241], off
	s_add_u32 s2, s2, 0x80
	s_addc_u32 s3, s3, 0
	s_waitcnt vmcnt(8)
	s_waitcnt lgkmcnt(0)
	s_barrier
	s_setprio 1
	v_mfma_f32_16x16x32_bf16 v[60:63], v[138:141], v[202:205], v[60:63]
	v_mfma_f32_16x16x32_bf16 v[56:59], v[168:171], v[202:205], v[56:59]
	v_mfma_f32_16x16x32_bf16 v[44:47], v[138:141], v[210:213], v[44:47]
	v_mfma_f32_16x16x32_bf16 v[40:43], v[168:171], v[210:213], v[40:43]
	v_mfma_f32_16x16x32_bf16 v[28:31], v[138:141], v[218:221], v[28:31]
	v_mfma_f32_16x16x32_bf16 v[24:27], v[168:171], v[218:221], v[24:27]
	v_mfma_f32_16x16x32_bf16 v[12:15], v[138:141], v[226:229], v[12:15]
	v_mfma_f32_16x16x32_bf16 v[8:11], v[168:171], v[226:229], v[8:11]
	v_mfma_f32_16x16x32_bf16 v[60:63], v[164:167], v[206:209], v[60:63]
	v_mfma_f32_16x16x32_bf16 v[56:59], v[172:175], v[206:209], v[56:59]
	v_mfma_f32_16x16x32_bf16 v[44:47], v[164:167], v[214:217], v[44:47]
	v_mfma_f32_16x16x32_bf16 v[40:43], v[172:175], v[214:217], v[40:43]
	v_mfma_f32_16x16x32_bf16 v[28:31], v[164:167], v[222:225], v[28:31]
	v_mfma_f32_16x16x32_bf16 v[24:27], v[172:175], v[222:225], v[24:27]
	v_mfma_f32_16x16x32_bf16 v[12:15], v[164:167], v[230:233], v[12:15]
	v_mfma_f32_16x16x32_bf16 v[8:11], v[172:175], v[230:233], v[8:11]
	s_setprio 0
	s_barrier
	s_add_i32 s8, s8, 1
	s_cmp_lt_u32 s8, 7
	s_cbranch_scc1 .Lq_abi_2_k
	v_add_u32_e32 v142, 0x10000, v160
	ds_read_b128 v[138:141], v142
	ds_read_b128 v[164:167], v142 offset:1024
	ds_read_b128 v[168:171], v142 offset:2048
	ds_read_b128 v[172:175], v142 offset:3072
	ds_read_b128 v[202:205], v162 offset:16384
	ds_read_b128 v[206:209], v162 offset:17408
	ds_read_b128 v[210:213], v162 offset:18432
	ds_read_b128 v[214:217], v162 offset:19456
	ds_read_b128 v[218:221], v162 offset:20480
	ds_read_b128 v[222:225], v162 offset:21504
	ds_read_b128 v[226:229], v162 offset:22528
	ds_read_b128 v[230:233], v162 offset:23552
	v_lshl_add_u64 v[234:235], s[74:75], 0, v[128:129]
	s_add_i32 m0, s5, 0x8000
	v_lshl_add_u64 v[236:237], s[74:75], 0, v[130:131]
	global_load_lds_dwordx4 v[234:235], off
	s_add_i32 m0, s5, 0xa000
	v_lshl_add_u64 v[238:239], s[2:3], 0, v[144:145]
	global_load_lds_dwordx4 v[236:237], off
	s_add_i32 m0, s5, 0x1c000
	v_lshl_add_u64 v[240:241], s[2:3], 0, v[132:133]
	global_load_lds_dwordx4 v[238:239], off
	s_add_i32 m0, s5, 0x1e000
	s_add_u32 s74, s74, 0x80
	s_addc_u32 s75, s75, 0
	global_load_lds_dwordx4 v[240:241], off
	s_add_u32 s2, s2, 0x80
	s_addc_u32 s3, s3, 0
	s_waitcnt vmcnt(8)
	s_waitcnt lgkmcnt(0)
	s_barrier
	s_setprio 1
	v_mfma_f32_16x16x32_bf16 v[60:63], v[138:141], v[202:205], v[60:63]
	v_mfma_f32_16x16x32_bf16 v[56:59], v[168:171], v[202:205], v[56:59]
	v_mfma_f32_16x16x32_bf16 v[44:47], v[138:141], v[210:213], v[44:47]
	v_mfma_f32_16x16x32_bf16 v[40:43], v[168:171], v[210:213], v[40:43]
	v_mfma_f32_16x16x32_bf16 v[28:31], v[138:141], v[218:221], v[28:31]
	v_mfma_f32_16x16x32_bf16 v[24:27], v[168:171], v[218:221], v[24:27]
	v_mfma_f32_16x16x32_bf16 v[12:15], v[138:141], v[226:229], v[12:15]
	v_mfma_f32_16x16x32_bf16 v[8:11], v[168:171], v[226:229], v[8:11]
	v_mfma_f32_16x16x32_bf16 v[60:63], v[164:167], v[206:209], v[60:63]
	v_mfma_f32_16x16x32_bf16 v[56:59], v[172:175], v[206:209], v[56:59]
	v_mfma_f32_16x16x32_bf16 v[44:47], v[164:167], v[214:217], v[44:47]
	v_mfma_f32_16x16x32_bf16 v[40:43], v[172:175], v[214:217], v[40:43]
	v_mfma_f32_16x16x32_bf16 v[28:31], v[164:167], v[222:225], v[28:31]
	v_mfma_f32_16x16x32_bf16 v[24:27], v[172:175], v[222:225], v[24:27]
	v_mfma_f32_16x16x32_bf16 v[12:15], v[164:167], v[230:233], v[12:15]
	v_mfma_f32_16x16x32_bf16 v[8:11], v[172:175], v[230:233], v[8:11]
	s_setprio 0
	s_barrier
	v_add_u32_e32 v142, 0x18000, v160
	ds_read_b128 v[138:141], v142
	ds_read_b128 v[164:167], v142 offset:1024
	ds_read_b128 v[168:171], v142 offset:2048
	ds_read_b128 v[172:175], v142 offset:3072
	ds_read_b128 v[202:205], v162 offset:49152
	ds_read_b128 v[206:209], v162 offset:50176
	ds_read_b128 v[210:213], v162 offset:51200
	ds_read_b128 v[214:217], v162 offset:52224
	ds_read_b128 v[218:221], v162 offset:53248
	ds_read_b128 v[222:225], v162 offset:54272
	ds_read_b128 v[226:229], v162 offset:55296
	ds_read_b128 v[230:233], v162 offset:56320
	s_waitcnt vmcnt(4)
	s_waitcnt lgkmcnt(0)
	s_barrier
	s_setprio 1
	v_mfma_f32_16x16x32_bf16 v[60:63], v[138:141], v[202:205], v[60:63]
	v_mfma_f32_16x16x32_bf16 v[56:59], v[168:171], v[202:205], v[56:59]
	v_mfma_f32_16x16x32_bf16 v[44:47], v[138:141], v[210:213], v[44:47]
	v_mfma_f32_16x16x32_bf16 v[40:43], v[168:171], v[210:213], v[40:43]
	v_mfma_f32_16x16x32_bf16 v[28:31], v[138:141], v[218:221], v[28:31]
	v_mfma_f32_16x16x32_bf16 v[24:27], v[168:171], v[218:221], v[24:27]
	v_mfma_f32_16x16x32_bf16 v[12:15], v[138:141], v[226:229], v[12:15]
	v_mfma_f32_16x16x32_bf16 v[8:11], v[168:171], v[226:229], v[8:11]
	v_mfma_f32_16x16x32_bf16 v[60:63], v[164:167], v[206:209], v[60:63]
	v_mfma_f32_16x16x32_bf16 v[56:59], v[172:175], v[206:209], v[56:59]
	v_mfma_f32_16x16x32_bf16 v[44:47], v[164:167], v[214:217], v[44:47]
	v_mfma_f32_16x16x32_bf16 v[40:43], v[172:175], v[214:217], v[40:43]
	v_mfma_f32_16x16x32_bf16 v[28:31], v[164:167], v[222:225], v[28:31]
	v_mfma_f32_16x16x32_bf16 v[24:27], v[172:175], v[222:225], v[24:27]
	v_mfma_f32_16x16x32_bf16 v[12:15], v[164:167], v[230:233], v[12:15]
	v_mfma_f32_16x16x32_bf16 v[8:11], v[172:175], v[230:233], v[8:11]
	s_setprio 0
	s_barrier
	v_add_u32_e32 v142, 0x14000, v160
	ds_read_b128 v[138:141], v142
	ds_read_b128 v[164:167], v142 offset:1024
	ds_read_b128 v[168:171], v142 offset:2048
	ds_read_b128 v[172:175], v142 offset:3072
	ds_read_b128 v[202:205], v162 offset:0
	ds_read_b128 v[206:209], v162 offset:1024
	ds_read_b128 v[210:213], v162 offset:2048
	ds_read_b128 v[214:217], v162 offset:3072
	ds_read_b128 v[218:221], v162 offset:4096
	ds_read_b128 v[222:225], v162 offset:5120
	ds_read_b128 v[226:229], v162 offset:6144
	ds_read_b128 v[230:233], v162 offset:7168
	s_waitcnt vmcnt(0)
	s_waitcnt lgkmcnt(0)
	s_barrier
	s_setprio 1
	v_mfma_f32_16x16x32_bf16 v[60:63], v[138:141], v[202:205], v[60:63]
	v_mfma_f32_16x16x32_bf16 v[56:59], v[168:171], v[202:205], v[56:59]
	v_mfma_f32_16x16x32_bf16 v[44:47], v[138:141], v[210:213], v[44:47]
	v_mfma_f32_16x16x32_bf16 v[40:43], v[168:171], v[210:213], v[40:43]
	v_mfma_f32_16x16x32_bf16 v[28:31], v[138:141], v[218:221], v[28:31]
	v_mfma_f32_16x16x32_bf16 v[24:27], v[168:171], v[218:221], v[24:27]
	v_mfma_f32_16x16x32_bf16 v[12:15], v[138:141], v[226:229], v[12:15]
	v_mfma_f32_16x16x32_bf16 v[8:11], v[168:171], v[226:229], v[8:11]
	v_mfma_f32_16x16x32_bf16 v[60:63], v[164:167], v[206:209], v[60:63]
	v_mfma_f32_16x16x32_bf16 v[56:59], v[172:175], v[206:209], v[56:59]
	v_mfma_f32_16x16x32_bf16 v[44:47], v[164:167], v[214:217], v[44:47]
	v_mfma_f32_16x16x32_bf16 v[40:43], v[172:175], v[214:217], v[40:43]
	v_mfma_f32_16x16x32_bf16 v[28:31], v[164:167], v[222:225], v[28:31]
	v_mfma_f32_16x16x32_bf16 v[24:27], v[172:175], v[222:225], v[24:27]
	v_mfma_f32_16x16x32_bf16 v[12:15], v[164:167], v[230:233], v[12:15]
	v_mfma_f32_16x16x32_bf16 v[8:11], v[172:175], v[230:233], v[8:11]
	s_setprio 0
	s_barrier
	v_add_u32_e32 v142, 0x1c000, v160
	ds_read_b128 v[138:141], v142
	ds_read_b128 v[164:167], v142 offset:1024
	ds_read_b128 v[168:171], v142 offset:2048
	ds_read_b128 v[172:175], v142 offset:3072
	ds_read_b128 v[202:205], v162 offset:32768
	ds_read_b128 v[206:209], v162 offset:33792
	ds_read_b128 v[210:213], v162 offset:34816
	ds_read_b128 v[214:217], v162 offset:35840
	ds_read_b128 v[218:221], v162 offset:36864
	ds_read_b128 v[222:225], v162 offset:37888
	ds_read_b128 v[226:229], v162 offset:38912
	ds_read_b128 v[230:233], v162 offset:39936
	s_waitcnt lgkmcnt(0)
	s_barrier
	s_setprio 1
	v_mfma_f32_16x16x32_bf16 v[60:63], v[138:141], v[202:205], v[60:63]
	v_mfma_f32_16x16x32_bf16 v[56:59], v[168:171], v[202:205], v[56:59]
	v_mfma_f32_16x16x32_bf16 v[44:47], v[138:141], v[210:213], v[44:47]
	v_mfma_f32_16x16x32_bf16 v[40:43], v[168:171], v[210:213], v[40:43]
	v_mfma_f32_16x16x32_bf16 v[28:31], v[138:141], v[218:221], v[28:31]
	v_mfma_f32_16x16x32_bf16 v[24:27], v[168:171], v[218:221], v[24:27]
	v_mfma_f32_16x16x32_bf16 v[12:15], v[138:141], v[226:229], v[12:15]
	v_mfma_f32_16x16x32_bf16 v[8:11], v[168:171], v[226:229], v[8:11]
	v_mfma_f32_16x16x32_bf16 v[60:63], v[164:167], v[206:209], v[60:63]
	v_mfma_f32_16x16x32_bf16 v[56:59], v[172:175], v[206:209], v[56:59]
	v_mfma_f32_16x16x32_bf16 v[44:47], v[164:167], v[214:217], v[44:47]
	v_mfma_f32_16x16x32_bf16 v[40:43], v[172:175], v[214:217], v[40:43]
	v_mfma_f32_16x16x32_bf16 v[28:31], v[164:167], v[222:225], v[28:31]
	v_mfma_f32_16x16x32_bf16 v[24:27], v[172:175], v[222:225], v[24:27]
	v_mfma_f32_16x16x32_bf16 v[12:15], v[164:167], v[230:233], v[12:15]
	v_mfma_f32_16x16x32_bf16 v[8:11], v[172:175], v[230:233], v[8:11]
	s_setprio 0
	s_barrier
	s_branch .Lq_abi_exit

.Lq_abi_3_k:
	v_add_u32_e32 v142, 0x14000, v160
	ds_read_b128 v[176:179], v142
	ds_read_b128 v[190:193], v142 offset:1024
	ds_read_b128 v[194:197], v142 offset:2048
	ds_read_b128 v[198:201], v142 offset:3072
	ds_read_b128 v[202:205], v162 offset:16384
	ds_read_b128 v[206:209], v162 offset:17408
	ds_read_b128 v[210:213], v162 offset:18432
	ds_read_b128 v[214:217], v162 offset:19456
	ds_read_b128 v[218:221], v162 offset:20480
	ds_read_b128 v[222:225], v162 offset:21504
	ds_read_b128 v[226:229], v162 offset:22528
	ds_read_b128 v[230:233], v162 offset:23552
	v_lshl_add_u64 v[234:235], s[74:75], 0, v[128:129]
	s_add_i32 m0, s5, 0x8000
	v_lshl_add_u64 v[236:237], s[74:75], 0, v[130:131]
	global_load_lds_dwordx4 v[234:235], off
	s_add_i32 m0, s5, 0xa000
	v_lshl_add_u64 v[238:239], s[2:3], 0, v[144:145]
	global_load_lds_dwordx4 v[236:237], off
	s_add_i32 m0, s5, 0x18000
	v_lshl_add_u64 v[240:241], s[2:3], 0, v[132:133]
	global_load_lds_dwordx4 v[238:239], off
	s_add_i32 m0, s5, 0x1a000
	s_add_u32 s74, s74, 0x80
	s_addc_u32 s75, s75, 0
	global_load_lds_dwordx4 v[240:241], off
	s_add_u32 s2, s2, 0x80
	s_addc_u32 s3, s3, 0
	s_waitcnt vmcnt(8)
	s_waitcnt lgkmcnt(0)
	s_barrier
	s_setprio 1
	v_mfma_f32_16x16x32_bf16 v[52:55], v[176:179], v[202:205], v[52:55]
	v_mfma_f32_16x16x32_bf16 v[48:51], v[194:197], v[202:205], v[48:51]
	v_mfma_f32_16x16x32_bf16 v[36:39], v[176:179], v[210:213], v[36:39]
	v_mfma_f32_16x16x32_bf16 v[32:35], v[194:197], v[210:213], v[32:35]
	v_mfma_f32_16x16x32_bf16 v[20:23], v[176:179], v[218:221], v[20:23]
	v_mfma_f32_16x16x32_bf16 v[16:19], v[194:197], v[218:221], v[16:19]
	v_mfma_f32_16x16x32_bf16 v[4:7], v[176:179], v[226:229], v[4:7]
	v_mfma_f32_16x16x32_bf16 v[0:3], v[194:197], v[226:229], v[0:3]
	v_mfma_f32_16x16x32_bf16 v[52:55], v[190:193], v[206:209], v[52:55]
	v_mfma_f32_16x16x32_bf16 v[48:51], v[198:201], v[206:209], v[48:51]
	v_mfma_f32_16x16x32_bf16 v[36:39], v[190:193], v[214:217], v[36:39]
	v_mfma_f32_16x16x32_bf16 v[32:35], v[198:201], v[214:217], v[32:35]
	v_mfma_f32_16x16x32_bf16 v[20:23], v[190:193], v[222:225], v[20:23]
	v_mfma_f32_16x16x32_bf16 v[16:19], v[198:201], v[222:225], v[16:19]
	v_mfma_f32_16x16x32_bf16 v[4:7], v[190:193], v[230:233], v[4:7]
	v_mfma_f32_16x16x32_bf16 v[0:3], v[198:201], v[230:233], v[0:3]
	s_setprio 0
	s_barrier
	v_add_u32_e32 v142, 0x1c000, v160
	ds_read_b128 v[176:179], v142
	ds_read_b128 v[190:193], v142 offset:1024
	ds_read_b128 v[194:197], v142 offset:2048
	ds_read_b128 v[198:201], v142 offset:3072
	ds_read_b128 v[202:205], v162 offset:49152
	ds_read_b128 v[206:209], v162 offset:50176
	ds_read_b128 v[210:213], v162 offset:51200
	ds_read_b128 v[214:217], v162 offset:52224
	ds_read_b128 v[218:221], v162 offset:53248
	ds_read_b128 v[222:225], v162 offset:54272
	ds_read_b128 v[226:229], v162 offset:55296
	ds_read_b128 v[230:233], v162 offset:56320
	v_lshl_add_u64 v[234:235], s[74:75], 0, v[128:129]
	s_add_i32 m0, s5, 0x4000
	v_lshl_add_u64 v[236:237], s[74:75], 0, v[130:131]
	global_load_lds_dwordx4 v[234:235], off
	s_add_i32 m0, s5, 0x6000
	v_lshl_add_u64 v[238:239], s[2:3], 0, v[144:145]
	global_load_lds_dwordx4 v[236:237], off
	s_add_i32 m0, s5, 0x14000
	v_lshl_add_u64 v[240:241], s[2:3], 0, v[132:133]
	global_load_lds_dwordx4 v[238:239], off
	s_add_i32 m0, s5, 0x16000
	s_add_u32 s74, s74, 0x80
	s_addc_u32 s75, s75, 0
	global_load_lds_dwordx4 v[240:241], off
	s_add_u32 s2, s2, 0x80
	s_addc_u32 s3, s3, 0
	s_waitcnt vmcnt(8)
	s_waitcnt lgkmcnt(0)
	s_barrier
	s_setprio 1
	v_mfma_f32_16x16x32_bf16 v[52:55], v[176:179], v[202:205], v[52:55]
	v_mfma_f32_16x16x32_bf16 v[48:51], v[194:197], v[202:205], v[48:51]
	v_mfma_f32_16x16x32_bf16 v[36:39], v[176:179], v[210:213], v[36:39]
	v_mfma_f32_16x16x32_bf16 v[32:35], v[194:197], v[210:213], v[32:35]
	v_mfma_f32_16x16x32_bf16 v[20:23], v[176:179], v[218:221], v[20:23]
	v_mfma_f32_16x16x32_bf16 v[16:19], v[194:197], v[218:221], v[16:19]
	v_mfma_f32_16x16x32_bf16 v[4:7], v[176:179], v[226:229], v[4:7]
	v_mfma_f32_16x16x32_bf16 v[0:3], v[194:197], v[226:229], v[0:3]
	v_mfma_f32_16x16x32_bf16 v[52:55], v[190:193], v[206:209], v[52:55]
	v_mfma_f32_16x16x32_bf16 v[48:51], v[198:201], v[206:209], v[48:51]
	v_mfma_f32_16x16x32_bf16 v[36:39], v[190:193], v[214:217], v[36:39]
	v_mfma_f32_16x16x32_bf16 v[32:35], v[198:201], v[214:217], v[32:35]
	v_mfma_f32_16x16x32_bf16 v[20:23], v[190:193], v[222:225], v[20:23]
	v_mfma_f32_16x16x32_bf16 v[16:19], v[198:201], v[222:225], v[16:19]
	v_mfma_f32_16x16x32_bf16 v[4:7], v[190:193], v[230:233], v[4:7]
	v_mfma_f32_16x16x32_bf16 v[0:3], v[198:201], v[230:233], v[0:3]
	s_setprio 0
	s_barrier
	v_add_u32_e32 v142, 0x10000, v160
	ds_read_b128 v[176:179], v142
	ds_read_b128 v[190:193], v142 offset:1024
	ds_read_b128 v[194:197], v142 offset:2048
	ds_read_b128 v[198:201], v142 offset:3072
	ds_read_b128 v[202:205], v162 offset:0
	ds_read_b128 v[206:209], v162 offset:1024
	ds_read_b128 v[210:213], v162 offset:2048
	ds_read_b128 v[214:217], v162 offset:3072
	ds_read_b128 v[218:221], v162 offset:4096
	ds_read_b128 v[222:225], v162 offset:5120
	ds_read_b128 v[226:229], v162 offset:6144
	ds_read_b128 v[230:233], v162 offset:7168
	v_lshl_add_u64 v[234:235], s[74:75], 0, v[128:129]
	s_add_i32 m0, s5, 0xc000
	v_lshl_add_u64 v[236:237], s[74:75], 0, v[130:131]
	global_load_lds_dwordx4 v[234:235], off
	s_add_i32 m0, s5, 0xe000
	v_lshl_add_u64 v[238:239], s[2:3], 0, v[144:145]
	global_load_lds_dwordx4 v[236:237], off
	s_add_i32 m0, s5, 0x1c000
	v_lshl_add_u64 v[240:241], s[2:3], 0, v[132:133]
	global_load_lds_dwordx4 v[238:239], off
	s_add_i32 m0, s5, 0x1e000
	s_add_u32 s74, s74, 0x80
	s_addc_u32 s75, s75, 0
	global_load_lds_dwordx4 v[240:241], off
	s_add_u32 s2, s2, 0x80
	s_addc_u32 s3, s3, 0
	s_waitcnt vmcnt(8)
	s_waitcnt lgkmcnt(0)
	s_barrier
	s_setprio 1
	v_mfma_f32_16x16x32_bf16 v[52:55], v[176:179], v[202:205], v[52:55]
	v_mfma_f32_16x16x32_bf16 v[48:51], v[194:197], v[202:205], v[48:51]
	v_mfma_f32_16x16x32_bf16 v[36:39], v[176:179], v[210:213], v[36:39]
	v_mfma_f32_16x16x32_bf16 v[32:35], v[194:197], v[210:213], v[32:35]
	v_mfma_f32_16x16x32_bf16 v[20:23], v[176:179], v[218:221], v[20:23]
	v_mfma_f32_16x16x32_bf16 v[16:19], v[194:197], v[218:221], v[16:19]
	v_mfma_f32_16x16x32_bf16 v[4:7], v[176:179], v[226:229], v[4:7]
	v_mfma_f32_16x16x32_bf16 v[0:3], v[194:197], v[226:229], v[0:3]
	v_mfma_f32_16x16x32_bf16 v[52:55], v[190:193], v[206:209], v[52:55]
	v_mfma_f32_16x16x32_bf16 v[48:51], v[198:201], v[206:209], v[48:51]
	v_mfma_f32_16x16x32_bf16 v[36:39], v[190:193], v[214:217], v[36:39]
	v_mfma_f32_16x16x32_bf16 v[32:35], v[198:201], v[214:217], v[32:35]
	v_mfma_f32_16x16x32_bf16 v[20:23], v[190:193], v[222:225], v[20:23]
	v_mfma_f32_16x16x32_bf16 v[16:19], v[198:201], v[222:225], v[16:19]
	v_mfma_f32_16x16x32_bf16 v[4:7], v[190:193], v[230:233], v[4:7]
	v_mfma_f32_16x16x32_bf16 v[0:3], v[198:201], v[230:233], v[0:3]
	s_setprio 0
	s_barrier
	v_add_u32_e32 v142, 0x18000, v160
	ds_read_b128 v[176:179], v142
	ds_read_b128 v[190:193], v142 offset:1024
	ds_read_b128 v[194:197], v142 offset:2048
	ds_read_b128 v[198:201], v142 offset:3072
	ds_read_b128 v[202:205], v162 offset:32768
	ds_read_b128 v[206:209], v162 offset:33792
	ds_read_b128 v[210:213], v162 offset:34816
	ds_read_b128 v[214:217], v162 offset:35840
	ds_read_b128 v[218:221], v162 offset:36864
	ds_read_b128 v[222:225], v162 offset:37888
	ds_read_b128 v[226:229], v162 offset:38912
	ds_read_b128 v[230:233], v162 offset:39936
	v_lshl_add_u64 v[234:235], s[74:75], 0, v[128:129]
	s_add_i32 m0, s5, 0x0
	v_lshl_add_u64 v[236:237], s[74:75], 0, v[130:131]
	global_load_lds_dwordx4 v[234:235], off
	s_add_i32 m0, s5, 0x2000
	v_lshl_add_u64 v[238:239], s[2:3], 0, v[144:145]
	global_load_lds_dwordx4 v[236:237], off
	s_add_i32 m0, s5, 0x10000
	v_lshl_add_u64 v[240:241], s[2:3], 0, v[132:133]
	global_load_lds_dwordx4 v[238:239], off
	s_add_i32 m0, s5, 0x12000
	s_add_u32 s74, s74, 0x80
	s_addc_u32 s75, s75, 0
	global_load_lds_dwordx4 v[240:241], off
	s_add_u32 s2, s2, 0x80
	s_addc_u32 s3, s3, 0
	s_waitcnt vmcnt(8)
	s_waitcnt lgkmcnt(0)
	s_barrier
	s_setprio 1
	v_mfma_f32_16x16x32_bf16 v[52:55], v[176:179], v[202:205], v[52:55]
	v_mfma_f32_16x16x32_bf16 v[48:51], v[194:197], v[202:205], v[48:51]
	v_mfma_f32_16x16x32_bf16 v[36:39], v[176:179], v[210:213], v[36:39]
	v_mfma_f32_16x16x32_bf16 v[32:35], v[194:197], v[210:213], v[32:35]
	v_mfma_f32_16x16x32_bf16 v[20:23], v[176:179], v[218:221], v[20:23]
	v_mfma_f32_16x16x32_bf16 v[16:19], v[194:197], v[218:221], v[16:19]
	v_mfma_f32_16x16x32_bf16 v[4:7], v[176:179], v[226:229], v[4:7]
	v_mfma_f32_16x16x32_bf16 v[0:3], v[194:197], v[226:229], v[0:3]
	v_mfma_f32_16x16x32_bf16 v[52:55], v[190:193], v[206:209], v[52:55]
	v_mfma_f32_16x16x32_bf16 v[48:51], v[198:201], v[206:209], v[48:51]
	v_mfma_f32_16x16x32_bf16 v[36:39], v[190:193], v[214:217], v[36:39]
	v_mfma_f32_16x16x32_bf16 v[32:35], v[198:201], v[214:217], v[32:35]
	v_mfma_f32_16x16x32_bf16 v[20:23], v[190:193], v[222:225], v[20:23]
	v_mfma_f32_16x16x32_bf16 v[16:19], v[198:201], v[222:225], v[16:19]
	v_mfma_f32_16x16x32_bf16 v[4:7], v[190:193], v[230:233], v[4:7]
	v_mfma_f32_16x16x32_bf16 v[0:3], v[198:201], v[230:233], v[0:3]
	s_setprio 0
	s_barrier
	s_add_i32 s8, s8, 1
	s_cmp_lt_u32 s8, 7
	s_cbranch_scc1 .Lq_abi_3_k
	v_add_u32_e32 v142, 0x14000, v160
	ds_read_b128 v[176:179], v142
	ds_read_b128 v[190:193], v142 offset:1024
	ds_read_b128 v[194:197], v142 offset:2048
	ds_read_b128 v[198:201], v142 offset:3072
	ds_read_b128 v[202:205], v162 offset:16384
	ds_read_b128 v[206:209], v162 offset:17408
	ds_read_b128 v[210:213], v162 offset:18432
	ds_read_b128 v[214:217], v162 offset:19456
	ds_read_b128 v[218:221], v162 offset:20480
	ds_read_b128 v[222:225], v162 offset:21504
	ds_read_b128 v[226:229], v162 offset:22528
	ds_read_b128 v[230:233], v162 offset:23552
	v_lshl_add_u64 v[234:235], s[74:75], 0, v[128:129]
	s_add_i32 m0, s5, 0x8000
	v_lshl_add_u64 v[236:237], s[74:75], 0, v[130:131]
	global_load_lds_dwordx4 v[234:235], off
	s_add_i32 m0, s5, 0xa000
	v_lshl_add_u64 v[238:239], s[2:3], 0, v[144:145]
	global_load_lds_dwordx4 v[236:237], off
	s_add_i32 m0, s5, 0x18000
	v_lshl_add_u64 v[240:241], s[2:3], 0, v[132:133]
	global_load_lds_dwordx4 v[238:239], off
	s_add_i32 m0, s5, 0x1a000
	s_add_u32 s74, s74, 0x80
	s_addc_u32 s75, s75, 0
	global_load_lds_dwordx4 v[240:241], off
	s_add_u32 s2, s2, 0x80
	s_addc_u32 s3, s3, 0
	s_waitcnt vmcnt(8)
	s_waitcnt lgkmcnt(0)
	s_barrier
	s_setprio 1
	v_mfma_f32_16x16x32_bf16 v[52:55], v[176:179], v[202:205], v[52:55]
	v_mfma_f32_16x16x32_bf16 v[48:51], v[194:197], v[202:205], v[48:51]
	v_mfma_f32_16x16x32_bf16 v[36:39], v[176:179], v[210:213], v[36:39]
	v_mfma_f32_16x16x32_bf16 v[32:35], v[194:197], v[210:213], v[32:35]
	v_mfma_f32_16x16x32_bf16 v[20:23], v[176:179], v[218:221], v[20:23]
	v_mfma_f32_16x16x32_bf16 v[16:19], v[194:197], v[218:221], v[16:19]
	v_mfma_f32_16x16x32_bf16 v[4:7], v[176:179], v[226:229], v[4:7]
	v_mfma_f32_16x16x32_bf16 v[0:3], v[194:197], v[226:229], v[0:3]
	v_mfma_f32_16x16x32_bf16 v[52:55], v[190:193], v[206:209], v[52:55]
	v_mfma_f32_16x16x32_bf16 v[48:51], v[198:201], v[206:209], v[48:51]
	v_mfma_f32_16x16x32_bf16 v[36:39], v[190:193], v[214:217], v[36:39]
	v_mfma_f32_16x16x32_bf16 v[32:35], v[198:201], v[214:217], v[32:35]
	v_mfma_f32_16x16x32_bf16 v[20:23], v[190:193], v[222:225], v[20:23]
	v_mfma_f32_16x16x32_bf16 v[16:19], v[198:201], v[222:225], v[16:19]
	v_mfma_f32_16x16x32_bf16 v[4:7], v[190:193], v[230:233], v[4:7]
	v_mfma_f32_16x16x32_bf16 v[0:3], v[198:201], v[230:233], v[0:3]
	s_setprio 0
	s_barrier
	v_add_u32_e32 v142, 0x1c000, v160
	ds_read_b128 v[176:179], v142
	ds_read_b128 v[190:193], v142 offset:1024
	ds_read_b128 v[194:197], v142 offset:2048
	ds_read_b128 v[198:201], v142 offset:3072
	ds_read_b128 v[202:205], v162 offset:49152
	ds_read_b128 v[206:209], v162 offset:50176
	ds_read_b128 v[210:213], v162 offset:51200
	ds_read_b128 v[214:217], v162 offset:52224
	ds_read_b128 v[218:221], v162 offset:53248
	ds_read_b128 v[222:225], v162 offset:54272
	ds_read_b128 v[226:229], v162 offset:55296
	ds_read_b128 v[230:233], v162 offset:56320
	s_waitcnt vmcnt(4)
	s_waitcnt lgkmcnt(0)
	s_barrier
	s_setprio 1
	v_mfma_f32_16x16x32_bf16 v[52:55], v[176:179], v[202:205], v[52:55]
	v_mfma_f32_16x16x32_bf16 v[48:51], v[194:197], v[202:205], v[48:51]
	v_mfma_f32_16x16x32_bf16 v[36:39], v[176:179], v[210:213], v[36:39]
	v_mfma_f32_16x16x32_bf16 v[32:35], v[194:197], v[210:213], v[32:35]
	v_mfma_f32_16x16x32_bf16 v[20:23], v[176:179], v[218:221], v[20:23]
	v_mfma_f32_16x16x32_bf16 v[16:19], v[194:197], v[218:221], v[16:19]
	v_mfma_f32_16x16x32_bf16 v[4:7], v[176:179], v[226:229], v[4:7]
	v_mfma_f32_16x16x32_bf16 v[0:3], v[194:197], v[226:229], v[0:3]
	v_mfma_f32_16x16x32_bf16 v[52:55], v[190:193], v[206:209], v[52:55]
	v_mfma_f32_16x16x32_bf16 v[48:51], v[198:201], v[206:209], v[48:51]
	v_mfma_f32_16x16x32_bf16 v[36:39], v[190:193], v[214:217], v[36:39]
	v_mfma_f32_16x16x32_bf16 v[32:35], v[198:201], v[214:217], v[32:35]
	v_mfma_f32_16x16x32_bf16 v[20:23], v[190:193], v[222:225], v[20:23]
	v_mfma_f32_16x16x32_bf16 v[16:19], v[198:201], v[222:225], v[16:19]
	v_mfma_f32_16x16x32_bf16 v[4:7], v[190:193], v[230:233], v[4:7]
	v_mfma_f32_16x16x32_bf16 v[0:3], v[198:201], v[230:233], v[0:3]
	s_setprio 0
	s_barrier
	v_add_u32_e32 v142, 0x10000, v160
	ds_read_b128 v[176:179], v142
	ds_read_b128 v[190:193], v142 offset:1024
	ds_read_b128 v[194:197], v142 offset:2048
	ds_read_b128 v[198:201], v142 offset:3072
	ds_read_b128 v[202:205], v162 offset:0
	ds_read_b128 v[206:209], v162 offset:1024
	ds_read_b128 v[210:213], v162 offset:2048
	ds_read_b128 v[214:217], v162 offset:3072
	ds_read_b128 v[218:221], v162 offset:4096
	ds_read_b128 v[222:225], v162 offset:5120
	ds_read_b128 v[226:229], v162 offset:6144
	ds_read_b128 v[230:233], v162 offset:7168
	s_waitcnt vmcnt(0)
	s_waitcnt lgkmcnt(0)
	s_barrier
	s_setprio 1
	v_mfma_f32_16x16x32_bf16 v[52:55], v[176:179], v[202:205], v[52:55]
	v_mfma_f32_16x16x32_bf16 v[48:51], v[194:197], v[202:205], v[48:51]
	v_mfma_f32_16x16x32_bf16 v[36:39], v[176:179], v[210:213], v[36:39]
	v_mfma_f32_16x16x32_bf16 v[32:35], v[194:197], v[210:213], v[32:35]
	v_mfma_f32_16x16x32_bf16 v[20:23], v[176:179], v[218:221], v[20:23]
	v_mfma_f32_16x16x32_bf16 v[16:19], v[194:197], v[218:221], v[16:19]
	v_mfma_f32_16x16x32_bf16 v[4:7], v[176:179], v[226:229], v[4:7]
	v_mfma_f32_16x16x32_bf16 v[0:3], v[194:197], v[226:229], v[0:3]
	v_mfma_f32_16x16x32_bf16 v[52:55], v[190:193], v[206:209], v[52:55]
	v_mfma_f32_16x16x32_bf16 v[48:51], v[198:201], v[206:209], v[48:51]
	v_mfma_f32_16x16x32_bf16 v[36:39], v[190:193], v[214:217], v[36:39]
	v_mfma_f32_16x16x32_bf16 v[32:35], v[198:201], v[214:217], v[32:35]
	v_mfma_f32_16x16x32_bf16 v[20:23], v[190:193], v[222:225], v[20:23]
	v_mfma_f32_16x16x32_bf16 v[16:19], v[198:201], v[222:225], v[16:19]
	v_mfma_f32_16x16x32_bf16 v[4:7], v[190:193], v[230:233], v[4:7]
	v_mfma_f32_16x16x32_bf16 v[0:3], v[198:201], v[230:233], v[0:3]
	s_setprio 0
	s_barrier
	v_add_u32_e32 v142, 0x18000, v160
	ds_read_b128 v[176:179], v142
	ds_read_b128 v[190:193], v142 offset:1024
	ds_read_b128 v[194:197], v142 offset:2048
	ds_read_b128 v[198:201], v142 offset:3072
	ds_read_b128 v[202:205], v162 offset:32768
	ds_read_b128 v[206:209], v162 offset:33792
	ds_read_b128 v[210:213], v162 offset:34816
	ds_read_b128 v[214:217], v162 offset:35840
	ds_read_b128 v[218:221], v162 offset:36864
	ds_read_b128 v[222:225], v162 offset:37888
	ds_read_b128 v[226:229], v162 offset:38912
	ds_read_b128 v[230:233], v162 offset:39936
	s_waitcnt lgkmcnt(0)
	s_barrier
	s_setprio 1
	v_mfma_f32_16x16x32_bf16 v[52:55], v[176:179], v[202:205], v[52:55]
	v_mfma_f32_16x16x32_bf16 v[48:51], v[194:197], v[202:205], v[48:51]
	v_mfma_f32_16x16x32_bf16 v[36:39], v[176:179], v[210:213], v[36:39]
	v_mfma_f32_16x16x32_bf16 v[32:35], v[194:197], v[210:213], v[32:35]
	v_mfma_f32_16x16x32_bf16 v[20:23], v[176:179], v[218:221], v[20:23]
	v_mfma_f32_16x16x32_bf16 v[16:19], v[194:197], v[218:221], v[16:19]
	v_mfma_f32_16x16x32_bf16 v[4:7], v[176:179], v[226:229], v[4:7]
	v_mfma_f32_16x16x32_bf16 v[0:3], v[194:197], v[226:229], v[0:3]
	v_mfma_f32_16x16x32_bf16 v[52:55], v[190:193], v[206:209], v[52:55]
	v_mfma_f32_16x16x32_bf16 v[48:51], v[198:201], v[206:209], v[48:51]
	v_mfma_f32_16x16x32_bf16 v[36:39], v[190:193], v[214:217], v[36:39]
	v_mfma_f32_16x16x32_bf16 v[32:35], v[198:201], v[214:217], v[32:35]
	v_mfma_f32_16x16x32_bf16 v[20:23], v[190:193], v[222:225], v[20:23]
	v_mfma_f32_16x16x32_bf16 v[16:19], v[198:201], v[222:225], v[16:19]
	v_mfma_f32_16x16x32_bf16 v[4:7], v[190:193], v[230:233], v[4:7]
	v_mfma_f32_16x16x32_bf16 v[0:3], v[198:201], v[230:233], v[0:3]
	s_setprio 0
	s_barrier
	s_branch .Lq_abi_exit

.Lq_smp_0_k:
	v_add_u32_e32 v161, 0x10000, v38
	ds_read_b128 v[40:43], v161
	ds_read_b128 v[48:51], v161 offset:1024
	ds_read_b128 v[162:165], v161 offset:2048
	ds_read_b128 v[166:169], v161 offset:3072
	ds_read_b128 v[198:201], v39 offset:0
	ds_read_b128 v[202:205], v39 offset:1024
	ds_read_b128 v[206:209], v39 offset:2048
	ds_read_b128 v[210:213], v39 offset:3072
	ds_read_b128 v[214:217], v39 offset:4096
	ds_read_b128 v[218:221], v39 offset:5120
	ds_read_b128 v[222:225], v39 offset:6144
	ds_read_b128 v[226:229], v39 offset:7168
	v_lshl_add_u64 v[178:179], s[14:15], 0, v[144:145]
	s_add_i32 m0, s1, 0xc000
	v_lshl_add_u64 v[230:231], s[14:15], 0, v[28:29]
	global_load_lds_dwordx4 v[178:179], off
	s_add_i32 m0, s1, 0xe000
	v_lshl_add_u64 v[232:233], s[2:3], 0, v[144:145]
	global_load_lds_dwordx4 v[230:231], off
	s_add_i32 m0, s1, 0x1c000
	v_lshl_add_u64 v[234:235], s[2:3], 0, v[28:29]
	global_load_lds_dwordx4 v[232:233], off
	s_add_i32 m0, s1, 0x1e000
	s_add_u32 s14, s14, 0x80
	s_addc_u32 s15, s15, 0
	global_load_lds_dwordx4 v[234:235], off
	s_add_u32 s2, s2, 0x80
	s_addc_u32 s3, s3, 0
	s_waitcnt vmcnt(8)
	s_waitcnt lgkmcnt(0)
	s_barrier
	s_setprio 1
	v_mfma_f32_16x16x32_bf16 v[140:143], v[40:43], v[198:201], v[140:143]
	v_mfma_f32_16x16x32_bf16 v[136:139], v[162:165], v[198:201], v[136:139]
	v_mfma_f32_16x16x32_bf16 v[124:127], v[40:43], v[206:209], v[124:127]
	v_mfma_f32_16x16x32_bf16 v[120:123], v[162:165], v[206:209], v[120:123]
	v_mfma_f32_16x16x32_bf16 v[108:111], v[40:43], v[214:217], v[108:111]
	v_mfma_f32_16x16x32_bf16 v[104:107], v[162:165], v[214:217], v[104:107]
	v_mfma_f32_16x16x32_bf16 v[92:95], v[40:43], v[222:225], v[92:95]
	v_mfma_f32_16x16x32_bf16 v[88:91], v[162:165], v[222:225], v[88:91]
	v_mfma_f32_16x16x32_bf16 v[140:143], v[48:51], v[202:205], v[140:143]
	v_mfma_f32_16x16x32_bf16 v[136:139], v[166:169], v[202:205], v[136:139]
	v_mfma_f32_16x16x32_bf16 v[124:127], v[48:51], v[210:213], v[124:127]
	v_mfma_f32_16x16x32_bf16 v[120:123], v[166:169], v[210:213], v[120:123]
	v_mfma_f32_16x16x32_bf16 v[108:111], v[48:51], v[218:221], v[108:111]
	v_mfma_f32_16x16x32_bf16 v[104:107], v[166:169], v[218:221], v[104:107]
	v_mfma_f32_16x16x32_bf16 v[92:95], v[48:51], v[226:229], v[92:95]
	v_mfma_f32_16x16x32_bf16 v[88:91], v[166:169], v[226:229], v[88:91]
	s_setprio 0
	s_barrier
	v_add_u32_e32 v161, 0x18000, v38
	ds_read_b128 v[40:43], v161
	ds_read_b128 v[48:51], v161 offset:1024
	ds_read_b128 v[162:165], v161 offset:2048
	ds_read_b128 v[166:169], v161 offset:3072
	ds_read_b128 v[198:201], v39 offset:32768
	ds_read_b128 v[202:205], v39 offset:33792
	ds_read_b128 v[206:209], v39 offset:34816
	ds_read_b128 v[210:213], v39 offset:35840
	ds_read_b128 v[214:217], v39 offset:36864
	ds_read_b128 v[218:221], v39 offset:37888
	ds_read_b128 v[222:225], v39 offset:38912
	ds_read_b128 v[226:229], v39 offset:39936
	v_lshl_add_u64 v[178:179], s[14:15], 0, v[144:145]
	s_add_i32 m0, s1, 0x0
	v_lshl_add_u64 v[230:231], s[14:15], 0, v[28:29]
	global_load_lds_dwordx4 v[178:179], off
	s_add_i32 m0, s1, 0x2000
	v_lshl_add_u64 v[232:233], s[2:3], 0, v[144:145]
	global_load_lds_dwordx4 v[230:231], off
	s_add_i32 m0, s1, 0x10000
	v_lshl_add_u64 v[234:235], s[2:3], 0, v[28:29]
	global_load_lds_dwordx4 v[232:233], off
	s_add_i32 m0, s1, 0x12000
	s_add_u32 s14, s14, 0x80
	s_addc_u32 s15, s15, 0
	global_load_lds_dwordx4 v[234:235], off
	s_add_u32 s2, s2, 0x80
	s_addc_u32 s3, s3, 0
	s_waitcnt vmcnt(8)
	s_waitcnt lgkmcnt(0)
	s_barrier
	s_setprio 1
	v_mfma_f32_16x16x32_bf16 v[140:143], v[40:43], v[198:201], v[140:143]
	v_mfma_f32_16x16x32_bf16 v[136:139], v[162:165], v[198:201], v[136:139]
	v_mfma_f32_16x16x32_bf16 v[124:127], v[40:43], v[206:209], v[124:127]
	v_mfma_f32_16x16x32_bf16 v[120:123], v[162:165], v[206:209], v[120:123]
	v_mfma_f32_16x16x32_bf16 v[108:111], v[40:43], v[214:217], v[108:111]
	v_mfma_f32_16x16x32_bf16 v[104:107], v[162:165], v[214:217], v[104:107]
	v_mfma_f32_16x16x32_bf16 v[92:95], v[40:43], v[222:225], v[92:95]
	v_mfma_f32_16x16x32_bf16 v[88:91], v[162:165], v[222:225], v[88:91]
	v_mfma_f32_16x16x32_bf16 v[140:143], v[48:51], v[202:205], v[140:143]
	v_mfma_f32_16x16x32_bf16 v[136:139], v[166:169], v[202:205], v[136:139]
	v_mfma_f32_16x16x32_bf16 v[124:127], v[48:51], v[210:213], v[124:127]
	v_mfma_f32_16x16x32_bf16 v[120:123], v[166:169], v[210:213], v[120:123]
	v_mfma_f32_16x16x32_bf16 v[108:111], v[48:51], v[218:221], v[108:111]
	v_mfma_f32_16x16x32_bf16 v[104:107], v[166:169], v[218:221], v[104:107]
	v_mfma_f32_16x16x32_bf16 v[92:95], v[48:51], v[226:229], v[92:95]
	v_mfma_f32_16x16x32_bf16 v[88:91], v[166:169], v[226:229], v[88:91]
	s_setprio 0
	s_barrier
	v_add_u32_e32 v161, 0x14000, v38
	ds_read_b128 v[40:43], v161
	ds_read_b128 v[48:51], v161 offset:1024
	ds_read_b128 v[162:165], v161 offset:2048
	ds_read_b128 v[166:169], v161 offset:3072
	ds_read_b128 v[198:201], v39 offset:16384
	ds_read_b128 v[202:205], v39 offset:17408
	ds_read_b128 v[206:209], v39 offset:18432
	ds_read_b128 v[210:213], v39 offset:19456
	ds_read_b128 v[214:217], v39 offset:20480
	ds_read_b128 v[218:221], v39 offset:21504
	ds_read_b128 v[222:225], v39 offset:22528
	ds_read_b128 v[226:229], v39 offset:23552
	v_lshl_add_u64 v[178:179], s[14:15], 0, v[144:145]
	s_add_i32 m0, s1, 0x8000
	v_lshl_add_u64 v[230:231], s[14:15], 0, v[28:29]
	global_load_lds_dwordx4 v[178:179], off
	s_add_i32 m0, s1, 0xa000
	v_lshl_add_u64 v[232:233], s[2:3], 0, v[144:145]
	global_load_lds_dwordx4 v[230:231], off
	s_add_i32 m0, s1, 0x18000
	v_lshl_add_u64 v[234:235], s[2:3], 0, v[28:29]
	global_load_lds_dwordx4 v[232:233], off
	s_add_i32 m0, s1, 0x1a000
	s_add_u32 s14, s14, 0x80
	s_addc_u32 s15, s15, 0
	global_load_lds_dwordx4 v[234:235], off
	s_add_u32 s2, s2, 0x80
	s_addc_u32 s3, s3, 0
	s_waitcnt vmcnt(8)
	s_waitcnt lgkmcnt(0)
	s_barrier
	s_setprio 1
	v_mfma_f32_16x16x32_bf16 v[140:143], v[40:43], v[198:201], v[140:143]
	v_mfma_f32_16x16x32_bf16 v[136:139], v[162:165], v[198:201], v[136:139]
	v_mfma_f32_16x16x32_bf16 v[124:127], v[40:43], v[206:209], v[124:127]
	v_mfma_f32_16x16x32_bf16 v[120:123], v[162:165], v[206:209], v[120:123]
	v_mfma_f32_16x16x32_bf16 v[108:111], v[40:43], v[214:217], v[108:111]
	v_mfma_f32_16x16x32_bf16 v[104:107], v[162:165], v[214:217], v[104:107]
	v_mfma_f32_16x16x32_bf16 v[92:95], v[40:43], v[222:225], v[92:95]
	v_mfma_f32_16x16x32_bf16 v[88:91], v[162:165], v[222:225], v[88:91]
	v_mfma_f32_16x16x32_bf16 v[140:143], v[48:51], v[202:205], v[140:143]
	v_mfma_f32_16x16x32_bf16 v[136:139], v[166:169], v[202:205], v[136:139]
	v_mfma_f32_16x16x32_bf16 v[124:127], v[48:51], v[210:213], v[124:127]
	v_mfma_f32_16x16x32_bf16 v[120:123], v[166:169], v[210:213], v[120:123]
	v_mfma_f32_16x16x32_bf16 v[108:111], v[48:51], v[218:221], v[108:111]
	v_mfma_f32_16x16x32_bf16 v[104:107], v[166:169], v[218:221], v[104:107]
	v_mfma_f32_16x16x32_bf16 v[92:95], v[48:51], v[226:229], v[92:95]
	v_mfma_f32_16x16x32_bf16 v[88:91], v[166:169], v[226:229], v[88:91]
	s_setprio 0
	s_barrier
	v_add_u32_e32 v161, 0x1c000, v38
	ds_read_b128 v[40:43], v161
	ds_read_b128 v[48:51], v161 offset:1024
	ds_read_b128 v[162:165], v161 offset:2048
	ds_read_b128 v[166:169], v161 offset:3072
	ds_read_b128 v[198:201], v39 offset:49152
	ds_read_b128 v[202:205], v39 offset:50176
	ds_read_b128 v[206:209], v39 offset:51200
	ds_read_b128 v[210:213], v39 offset:52224
	ds_read_b128 v[214:217], v39 offset:53248
	ds_read_b128 v[218:221], v39 offset:54272
	ds_read_b128 v[222:225], v39 offset:55296
	ds_read_b128 v[226:229], v39 offset:56320
	v_lshl_add_u64 v[178:179], s[14:15], 0, v[144:145]
	s_add_i32 m0, s1, 0x4000
	v_lshl_add_u64 v[230:231], s[14:15], 0, v[28:29]
	global_load_lds_dwordx4 v[178:179], off
	s_add_i32 m0, s1, 0x6000
	v_lshl_add_u64 v[232:233], s[2:3], 0, v[144:145]
	global_load_lds_dwordx4 v[230:231], off
	s_add_i32 m0, s1, 0x14000
	v_lshl_add_u64 v[234:235], s[2:3], 0, v[28:29]
	global_load_lds_dwordx4 v[232:233], off
	s_add_i32 m0, s1, 0x16000
	s_add_u32 s14, s14, 0x80
	s_addc_u32 s15, s15, 0
	global_load_lds_dwordx4 v[234:235], off
	s_add_u32 s2, s2, 0x80
	s_addc_u32 s3, s3, 0
	s_waitcnt vmcnt(8)
	s_waitcnt lgkmcnt(0)
	s_barrier
	s_setprio 1
	v_mfma_f32_16x16x32_bf16 v[140:143], v[40:43], v[198:201], v[140:143]
	v_mfma_f32_16x16x32_bf16 v[136:139], v[162:165], v[198:201], v[136:139]
	v_mfma_f32_16x16x32_bf16 v[124:127], v[40:43], v[206:209], v[124:127]
	v_mfma_f32_16x16x32_bf16 v[120:123], v[162:165], v[206:209], v[120:123]
	v_mfma_f32_16x16x32_bf16 v[108:111], v[40:43], v[214:217], v[108:111]
	v_mfma_f32_16x16x32_bf16 v[104:107], v[162:165], v[214:217], v[104:107]
	v_mfma_f32_16x16x32_bf16 v[92:95], v[40:43], v[222:225], v[92:95]
	v_mfma_f32_16x16x32_bf16 v[88:91], v[162:165], v[222:225], v[88:91]
	v_mfma_f32_16x16x32_bf16 v[140:143], v[48:51], v[202:205], v[140:143]
	v_mfma_f32_16x16x32_bf16 v[136:139], v[166:169], v[202:205], v[136:139]
	v_mfma_f32_16x16x32_bf16 v[124:127], v[48:51], v[210:213], v[124:127]
	v_mfma_f32_16x16x32_bf16 v[120:123], v[166:169], v[210:213], v[120:123]
	v_mfma_f32_16x16x32_bf16 v[108:111], v[48:51], v[218:221], v[108:111]
	v_mfma_f32_16x16x32_bf16 v[104:107], v[166:169], v[218:221], v[104:107]
	v_mfma_f32_16x16x32_bf16 v[92:95], v[48:51], v[226:229], v[92:95]
	v_mfma_f32_16x16x32_bf16 v[88:91], v[166:169], v[226:229], v[88:91]
	s_setprio 0
	s_barrier
	s_add_i32 s55, s55, 1
	s_cmp_lt_u32 s55, 7
	s_cbranch_scc1 .Lq_smp_0_k
	v_add_u32_e32 v161, 0x10000, v38
	ds_read_b128 v[40:43], v161
	ds_read_b128 v[48:51], v161 offset:1024
	ds_read_b128 v[162:165], v161 offset:2048
	ds_read_b128 v[166:169], v161 offset:3072
	ds_read_b128 v[198:201], v39 offset:0
	ds_read_b128 v[202:205], v39 offset:1024
	ds_read_b128 v[206:209], v39 offset:2048
	ds_read_b128 v[210:213], v39 offset:3072
	ds_read_b128 v[214:217], v39 offset:4096
	ds_read_b128 v[218:221], v39 offset:5120
	ds_read_b128 v[222:225], v39 offset:6144
	ds_read_b128 v[226:229], v39 offset:7168
	v_lshl_add_u64 v[178:179], s[14:15], 0, v[144:145]
	s_add_i32 m0, s1, 0xc000
	v_lshl_add_u64 v[230:231], s[14:15], 0, v[28:29]
	global_load_lds_dwordx4 v[178:179], off
	s_add_i32 m0, s1, 0xe000
	v_lshl_add_u64 v[232:233], s[2:3], 0, v[144:145]
	global_load_lds_dwordx4 v[230:231], off
	s_add_i32 m0, s1, 0x1c000
	v_lshl_add_u64 v[234:235], s[2:3], 0, v[28:29]
	global_load_lds_dwordx4 v[232:233], off
	s_add_i32 m0, s1, 0x1e000
	s_add_u32 s14, s14, 0x80
	s_addc_u32 s15, s15, 0
	global_load_lds_dwordx4 v[234:235], off
	s_add_u32 s2, s2, 0x80
	s_addc_u32 s3, s3, 0
	s_waitcnt vmcnt(8)
	s_waitcnt lgkmcnt(0)
	s_barrier
	s_setprio 1
	v_mfma_f32_16x16x32_bf16 v[140:143], v[40:43], v[198:201], v[140:143]
	v_mfma_f32_16x16x32_bf16 v[136:139], v[162:165], v[198:201], v[136:139]
	v_mfma_f32_16x16x32_bf16 v[124:127], v[40:43], v[206:209], v[124:127]
	v_mfma_f32_16x16x32_bf16 v[120:123], v[162:165], v[206:209], v[120:123]
	v_mfma_f32_16x16x32_bf16 v[108:111], v[40:43], v[214:217], v[108:111]
	v_mfma_f32_16x16x32_bf16 v[104:107], v[162:165], v[214:217], v[104:107]
	v_mfma_f32_16x16x32_bf16 v[92:95], v[40:43], v[222:225], v[92:95]
	v_mfma_f32_16x16x32_bf16 v[88:91], v[162:165], v[222:225], v[88:91]
	v_mfma_f32_16x16x32_bf16 v[140:143], v[48:51], v[202:205], v[140:143]
	v_mfma_f32_16x16x32_bf16 v[136:139], v[166:169], v[202:205], v[136:139]
	v_mfma_f32_16x16x32_bf16 v[124:127], v[48:51], v[210:213], v[124:127]
	v_mfma_f32_16x16x32_bf16 v[120:123], v[166:169], v[210:213], v[120:123]
	v_mfma_f32_16x16x32_bf16 v[108:111], v[48:51], v[218:221], v[108:111]
	v_mfma_f32_16x16x32_bf16 v[104:107], v[166:169], v[218:221], v[104:107]
	v_mfma_f32_16x16x32_bf16 v[92:95], v[48:51], v[226:229], v[92:95]
	v_mfma_f32_16x16x32_bf16 v[88:91], v[166:169], v[226:229], v[88:91]
	s_setprio 0
	s_barrier
	v_add_u32_e32 v161, 0x18000, v38
	ds_read_b128 v[40:43], v161
	ds_read_b128 v[48:51], v161 offset:1024
	ds_read_b128 v[162:165], v161 offset:2048
	ds_read_b128 v[166:169], v161 offset:3072
	ds_read_b128 v[198:201], v39 offset:32768
	ds_read_b128 v[202:205], v39 offset:33792
	ds_read_b128 v[206:209], v39 offset:34816
	ds_read_b128 v[210:213], v39 offset:35840
	ds_read_b128 v[214:217], v39 offset:36864
	ds_read_b128 v[218:221], v39 offset:37888
	ds_read_b128 v[222:225], v39 offset:38912
	ds_read_b128 v[226:229], v39 offset:39936
	s_waitcnt vmcnt(4)
	s_waitcnt lgkmcnt(0)
	s_barrier
	s_setprio 1
	v_mfma_f32_16x16x32_bf16 v[140:143], v[40:43], v[198:201], v[140:143]
	v_mfma_f32_16x16x32_bf16 v[136:139], v[162:165], v[198:201], v[136:139]
	v_mfma_f32_16x16x32_bf16 v[124:127], v[40:43], v[206:209], v[124:127]
	v_mfma_f32_16x16x32_bf16 v[120:123], v[162:165], v[206:209], v[120:123]
	v_mfma_f32_16x16x32_bf16 v[108:111], v[40:43], v[214:217], v[108:111]
	v_mfma_f32_16x16x32_bf16 v[104:107], v[162:165], v[214:217], v[104:107]
	v_mfma_f32_16x16x32_bf16 v[92:95], v[40:43], v[222:225], v[92:95]
	v_mfma_f32_16x16x32_bf16 v[88:91], v[162:165], v[222:225], v[88:91]
	v_mfma_f32_16x16x32_bf16 v[140:143], v[48:51], v[202:205], v[140:143]
	v_mfma_f32_16x16x32_bf16 v[136:139], v[166:169], v[202:205], v[136:139]
	v_mfma_f32_16x16x32_bf16 v[124:127], v[48:51], v[210:213], v[124:127]
	v_mfma_f32_16x16x32_bf16 v[120:123], v[166:169], v[210:213], v[120:123]
	v_mfma_f32_16x16x32_bf16 v[108:111], v[48:51], v[218:221], v[108:111]
	v_mfma_f32_16x16x32_bf16 v[104:107], v[166:169], v[218:221], v[104:107]
	v_mfma_f32_16x16x32_bf16 v[92:95], v[48:51], v[226:229], v[92:95]
	v_mfma_f32_16x16x32_bf16 v[88:91], v[166:169], v[226:229], v[88:91]
	s_setprio 0
	s_barrier
	v_add_u32_e32 v161, 0x14000, v38
	ds_read_b128 v[40:43], v161
	ds_read_b128 v[48:51], v161 offset:1024
	ds_read_b128 v[162:165], v161 offset:2048
	ds_read_b128 v[166:169], v161 offset:3072
	ds_read_b128 v[198:201], v39 offset:16384
	ds_read_b128 v[202:205], v39 offset:17408
	ds_read_b128 v[206:209], v39 offset:18432
	ds_read_b128 v[210:213], v39 offset:19456
	ds_read_b128 v[214:217], v39 offset:20480
	ds_read_b128 v[218:221], v39 offset:21504
	ds_read_b128 v[222:225], v39 offset:22528
	ds_read_b128 v[226:229], v39 offset:23552
	s_waitcnt vmcnt(0)
	s_waitcnt lgkmcnt(0)
	s_barrier
	s_setprio 1
	v_mfma_f32_16x16x32_bf16 v[140:143], v[40:43], v[198:201], v[140:143]
	v_mfma_f32_16x16x32_bf16 v[136:139], v[162:165], v[198:201], v[136:139]
	v_mfma_f32_16x16x32_bf16 v[124:127], v[40:43], v[206:209], v[124:127]
	v_mfma_f32_16x16x32_bf16 v[120:123], v[162:165], v[206:209], v[120:123]
	v_mfma_f32_16x16x32_bf16 v[108:111], v[40:43], v[214:217], v[108:111]
	v_mfma_f32_16x16x32_bf16 v[104:107], v[162:165], v[214:217], v[104:107]
	v_mfma_f32_16x16x32_bf16 v[92:95], v[40:43], v[222:225], v[92:95]
	v_mfma_f32_16x16x32_bf16 v[88:91], v[162:165], v[222:225], v[88:91]
	v_mfma_f32_16x16x32_bf16 v[140:143], v[48:51], v[202:205], v[140:143]
	v_mfma_f32_16x16x32_bf16 v[136:139], v[166:169], v[202:205], v[136:139]
	v_mfma_f32_16x16x32_bf16 v[124:127], v[48:51], v[210:213], v[124:127]
	v_mfma_f32_16x16x32_bf16 v[120:123], v[166:169], v[210:213], v[120:123]
	v_mfma_f32_16x16x32_bf16 v[108:111], v[48:51], v[218:221], v[108:111]
	v_mfma_f32_16x16x32_bf16 v[104:107], v[166:169], v[218:221], v[104:107]
	v_mfma_f32_16x16x32_bf16 v[92:95], v[48:51], v[226:229], v[92:95]
	v_mfma_f32_16x16x32_bf16 v[88:91], v[166:169], v[226:229], v[88:91]
	s_setprio 0
	s_barrier
	v_add_u32_e32 v161, 0x1c000, v38
	ds_read_b128 v[40:43], v161
	ds_read_b128 v[48:51], v161 offset:1024
	ds_read_b128 v[162:165], v161 offset:2048
	ds_read_b128 v[166:169], v161 offset:3072
	ds_read_b128 v[198:201], v39 offset:49152
	ds_read_b128 v[202:205], v39 offset:50176
	ds_read_b128 v[206:209], v39 offset:51200
	ds_read_b128 v[210:213], v39 offset:52224
	ds_read_b128 v[214:217], v39 offset:53248
	ds_read_b128 v[218:221], v39 offset:54272
	ds_read_b128 v[222:225], v39 offset:55296
	ds_read_b128 v[226:229], v39 offset:56320
	s_waitcnt lgkmcnt(0)
	s_barrier
	s_setprio 1
	v_mfma_f32_16x16x32_bf16 v[140:143], v[40:43], v[198:201], v[140:143]
	v_mfma_f32_16x16x32_bf16 v[136:139], v[162:165], v[198:201], v[136:139]
	v_mfma_f32_16x16x32_bf16 v[124:127], v[40:43], v[206:209], v[124:127]
	v_mfma_f32_16x16x32_bf16 v[120:123], v[162:165], v[206:209], v[120:123]
	v_mfma_f32_16x16x32_bf16 v[108:111], v[40:43], v[214:217], v[108:111]
	v_mfma_f32_16x16x32_bf16 v[104:107], v[162:165], v[214:217], v[104:107]
	v_mfma_f32_16x16x32_bf16 v[92:95], v[40:43], v[222:225], v[92:95]
	v_mfma_f32_16x16x32_bf16 v[88:91], v[162:165], v[222:225], v[88:91]
	v_mfma_f32_16x16x32_bf16 v[140:143], v[48:51], v[202:205], v[140:143]
	v_mfma_f32_16x16x32_bf16 v[136:139], v[166:169], v[202:205], v[136:139]
	v_mfma_f32_16x16x32_bf16 v[124:127], v[48:51], v[210:213], v[124:127]
	v_mfma_f32_16x16x32_bf16 v[120:123], v[166:169], v[210:213], v[120:123]
	v_mfma_f32_16x16x32_bf16 v[108:111], v[48:51], v[218:221], v[108:111]
	v_mfma_f32_16x16x32_bf16 v[104:107], v[166:169], v[218:221], v[104:107]
	v_mfma_f32_16x16x32_bf16 v[92:95], v[48:51], v[226:229], v[92:95]
	v_mfma_f32_16x16x32_bf16 v[88:91], v[166:169], v[226:229], v[88:91]
	s_setprio 0
	s_barrier
	s_branch .Lq_smp_exit

.Lq_smp_1_k:
	v_add_u32_e32 v161, 0x14000, v38
	ds_read_b128 v[170:173], v161
	ds_read_b128 v[174:177], v161 offset:1024
	ds_read_b128 v[190:193], v161 offset:2048
	ds_read_b128 v[194:197], v161 offset:3072
	ds_read_b128 v[198:201], v39 offset:0
	ds_read_b128 v[202:205], v39 offset:1024
	ds_read_b128 v[206:209], v39 offset:2048
	ds_read_b128 v[210:213], v39 offset:3072
	ds_read_b128 v[214:217], v39 offset:4096
	ds_read_b128 v[218:221], v39 offset:5120
	ds_read_b128 v[222:225], v39 offset:6144
	ds_read_b128 v[226:229], v39 offset:7168
	v_lshl_add_u64 v[178:179], s[14:15], 0, v[144:145]
	s_add_i32 m0, s1, 0xc000
	v_lshl_add_u64 v[230:231], s[14:15], 0, v[28:29]
	global_load_lds_dwordx4 v[178:179], off
	s_add_i32 m0, s1, 0xe000
	v_lshl_add_u64 v[232:233], s[2:3], 0, v[144:145]
	global_load_lds_dwordx4 v[230:231], off
	s_add_i32 m0, s1, 0x18000
	v_lshl_add_u64 v[234:235], s[2:3], 0, v[28:29]
	global_load_lds_dwordx4 v[232:233], off
	s_add_i32 m0, s1, 0x1a000
	s_add_u32 s14, s14, 0x80
	s_addc_u32 s15, s15, 0
	global_load_lds_dwordx4 v[234:235], off
	s_add_u32 s2, s2, 0x80
	s_addc_u32 s3, s3, 0
	s_waitcnt vmcnt(8)
	s_waitcnt lgkmcnt(0)
	s_barrier
	s_setprio 1
	v_mfma_f32_16x16x32_bf16 v[132:135], v[170:173], v[198:201], v[132:135]
	v_mfma_f32_16x16x32_bf16 v[128:131], v[190:193], v[198:201], v[128:131]
	v_mfma_f32_16x16x32_bf16 v[116:119], v[170:173], v[206:209], v[116:119]
	v_mfma_f32_16x16x32_bf16 v[112:115], v[190:193], v[206:209], v[112:115]
	v_mfma_f32_16x16x32_bf16 v[100:103], v[170:173], v[214:217], v[100:103]
	v_mfma_f32_16x16x32_bf16 v[96:99], v[190:193], v[214:217], v[96:99]
	v_mfma_f32_16x16x32_bf16 v[84:87], v[170:173], v[222:225], v[84:87]
	v_mfma_f32_16x16x32_bf16 v[80:83], v[190:193], v[222:225], v[80:83]
	v_mfma_f32_16x16x32_bf16 v[132:135], v[174:177], v[202:205], v[132:135]
	v_mfma_f32_16x16x32_bf16 v[128:131], v[194:197], v[202:205], v[128:131]
	v_mfma_f32_16x16x32_bf16 v[116:119], v[174:177], v[210:213], v[116:119]
	v_mfma_f32_16x16x32_bf16 v[112:115], v[194:197], v[210:213], v[112:115]
	v_mfma_f32_16x16x32_bf16 v[100:103], v[174:177], v[218:221], v[100:103]
	v_mfma_f32_16x16x32_bf16 v[96:99], v[194:197], v[218:221], v[96:99]
	v_mfma_f32_16x16x32_bf16 v[84:87], v[174:177], v[226:229], v[84:87]
	v_mfma_f32_16x16x32_bf16 v[80:83], v[194:197], v[226:229], v[80:83]
	s_setprio 0
	s_barrier
	v_add_u32_e32 v161, 0x1c000, v38
	ds_read_b128 v[170:173], v161
	ds_read_b128 v[174:177], v161 offset:1024
	ds_read_b128 v[190:193], v161 offset:2048
	ds_read_b128 v[194:197], v161 offset:3072
	ds_read_b128 v[198:201], v39 offset:32768
	ds_read_b128 v[202:205], v39 offset:33792
	ds_read_b128 v[206:209], v39 offset:34816
	ds_read_b128 v[210:213], v39 offset:35840
	ds_read_b128 v[214:217], v39 offset:36864
	ds_read_b128 v[218:221], v39 offset:37888
	ds_read_b128 v[222:225], v39 offset:38912
	ds_read_b128 v[226:229], v39 offset:39936
	v_lshl_add_u64 v[178:179], s[14:15], 0, v[144:145]
	s_add_i32 m0, s1, 0x0
	v_lshl_add_u64 v[230:231], s[14:15], 0, v[28:29]
	global_load_lds_dwordx4 v[178:179], off
	s_add_i32 m0, s1, 0x2000
	v_lshl_add_u64 v[232:233], s[2:3], 0, v[144:145]
	global_load_lds_dwordx4 v[230:231], off
	s_add_i32 m0, s1, 0x14000
	v_lshl_add_u64 v[234:235], s[2:3], 0, v[28:29]
	global_load_lds_dwordx4 v[232:233], off
	s_add_i32 m0, s1, 0x16000
	s_add_u32 s14, s14, 0x80
	s_addc_u32 s15, s15, 0
	global_load_lds_dwordx4 v[234:235], off
	s_add_u32 s2, s2, 0x80
	s_addc_u32 s3, s3, 0
	s_waitcnt vmcnt(8)
	s_waitcnt lgkmcnt(0)
	s_barrier
	s_setprio 1
	v_mfma_f32_16x16x32_bf16 v[132:135], v[170:173], v[198:201], v[132:135]
	v_mfma_f32_16x16x32_bf16 v[128:131], v[190:193], v[198:201], v[128:131]
	v_mfma_f32_16x16x32_bf16 v[116:119], v[170:173], v[206:209], v[116:119]
	v_mfma_f32_16x16x32_bf16 v[112:115], v[190:193], v[206:209], v[112:115]
	v_mfma_f32_16x16x32_bf16 v[100:103], v[170:173], v[214:217], v[100:103]
	v_mfma_f32_16x16x32_bf16 v[96:99], v[190:193], v[214:217], v[96:99]
	v_mfma_f32_16x16x32_bf16 v[84:87], v[170:173], v[222:225], v[84:87]
	v_mfma_f32_16x16x32_bf16 v[80:83], v[190:193], v[222:225], v[80:83]
	v_mfma_f32_16x16x32_bf16 v[132:135], v[174:177], v[202:205], v[132:135]
	v_mfma_f32_16x16x32_bf16 v[128:131], v[194:197], v[202:205], v[128:131]
	v_mfma_f32_16x16x32_bf16 v[116:119], v[174:177], v[210:213], v[116:119]
	v_mfma_f32_16x16x32_bf16 v[112:115], v[194:197], v[210:213], v[112:115]
	v_mfma_f32_16x16x32_bf16 v[100:103], v[174:177], v[218:221], v[100:103]
	v_mfma_f32_16x16x32_bf16 v[96:99], v[194:197], v[218:221], v[96:99]
	v_mfma_f32_16x16x32_bf16 v[84:87], v[174:177], v[226:229], v[84:87]
	v_mfma_f32_16x16x32_bf16 v[80:83], v[194:197], v[226:229], v[80:83]
	s_setprio 0
	s_barrier
	v_add_u32_e32 v161, 0x10000, v38
	ds_read_b128 v[170:173], v161
	ds_read_b128 v[174:177], v161 offset:1024
	ds_read_b128 v[190:193], v161 offset:2048
	ds_read_b128 v[194:197], v161 offset:3072
	ds_read_b128 v[198:201], v39 offset:16384
	ds_read_b128 v[202:205], v39 offset:17408
	ds_read_b128 v[206:209], v39 offset:18432
	ds_read_b128 v[210:213], v39 offset:19456
	ds_read_b128 v[214:217], v39 offset:20480
	ds_read_b128 v[218:221], v39 offset:21504
	ds_read_b128 v[222:225], v39 offset:22528
	ds_read_b128 v[226:229], v39 offset:23552
	v_lshl_add_u64 v[178:179], s[14:15], 0, v[144:145]
	s_add_i32 m0, s1, 0x8000
	v_lshl_add_u64 v[230:231], s[14:15], 0, v[28:29]
	global_load_lds_dwordx4 v[178:179], off
	s_add_i32 m0, s1, 0xa000
	v_lshl_add_u64 v[232:233], s[2:3], 0, v[144:145]
	global_load_lds_dwordx4 v[230:231], off
	s_add_i32 m0, s1, 0x1c000
	v_lshl_add_u64 v[234:235], s[2:3], 0, v[28:29]
	global_load_lds_dwordx4 v[232:233], off
	s_add_i32 m0, s1, 0x1e000
	s_add_u32 s14, s14, 0x80
	s_addc_u32 s15, s15, 0
	global_load_lds_dwordx4 v[234:235], off
	s_add_u32 s2, s2, 0x80
	s_addc_u32 s3, s3, 0
	s_waitcnt vmcnt(8)
	s_waitcnt lgkmcnt(0)
	s_barrier
	s_setprio 1
	v_mfma_f32_16x16x32_bf16 v[132:135], v[170:173], v[198:201], v[132:135]
	v_mfma_f32_16x16x32_bf16 v[128:131], v[190:193], v[198:201], v[128:131]
	v_mfma_f32_16x16x32_bf16 v[116:119], v[170:173], v[206:209], v[116:119]
	v_mfma_f32_16x16x32_bf16 v[112:115], v[190:193], v[206:209], v[112:115]
	v_mfma_f32_16x16x32_bf16 v[100:103], v[170:173], v[214:217], v[100:103]
	v_mfma_f32_16x16x32_bf16 v[96:99], v[190:193], v[214:217], v[96:99]
	v_mfma_f32_16x16x32_bf16 v[84:87], v[170:173], v[222:225], v[84:87]
	v_mfma_f32_16x16x32_bf16 v[80:83], v[190:193], v[222:225], v[80:83]
	v_mfma_f32_16x16x32_bf16 v[132:135], v[174:177], v[202:205], v[132:135]
	v_mfma_f32_16x16x32_bf16 v[128:131], v[194:197], v[202:205], v[128:131]
	v_mfma_f32_16x16x32_bf16 v[116:119], v[174:177], v[210:213], v[116:119]
	v_mfma_f32_16x16x32_bf16 v[112:115], v[194:197], v[210:213], v[112:115]
	v_mfma_f32_16x16x32_bf16 v[100:103], v[174:177], v[218:221], v[100:103]
	v_mfma_f32_16x16x32_bf16 v[96:99], v[194:197], v[218:221], v[96:99]
	v_mfma_f32_16x16x32_bf16 v[84:87], v[174:177], v[226:229], v[84:87]
	v_mfma_f32_16x16x32_bf16 v[80:83], v[194:197], v[226:229], v[80:83]
	s_setprio 0
	s_barrier
	v_add_u32_e32 v161, 0x18000, v38
	ds_read_b128 v[170:173], v161
	ds_read_b128 v[174:177], v161 offset:1024
	ds_read_b128 v[190:193], v161 offset:2048
	ds_read_b128 v[194:197], v161 offset:3072
	ds_read_b128 v[198:201], v39 offset:49152
	ds_read_b128 v[202:205], v39 offset:50176
	ds_read_b128 v[206:209], v39 offset:51200
	ds_read_b128 v[210:213], v39 offset:52224
	ds_read_b128 v[214:217], v39 offset:53248
	ds_read_b128 v[218:221], v39 offset:54272
	ds_read_b128 v[222:225], v39 offset:55296
	ds_read_b128 v[226:229], v39 offset:56320
	v_lshl_add_u64 v[178:179], s[14:15], 0, v[144:145]
	s_add_i32 m0, s1, 0x4000
	v_lshl_add_u64 v[230:231], s[14:15], 0, v[28:29]
	global_load_lds_dwordx4 v[178:179], off
	s_add_i32 m0, s1, 0x6000
	v_lshl_add_u64 v[232:233], s[2:3], 0, v[144:145]
	global_load_lds_dwordx4 v[230:231], off
	s_add_i32 m0, s1, 0x10000
	v_lshl_add_u64 v[234:235], s[2:3], 0, v[28:29]
	global_load_lds_dwordx4 v[232:233], off
	s_add_i32 m0, s1, 0x12000
	s_add_u32 s14, s14, 0x80
	s_addc_u32 s15, s15, 0
	global_load_lds_dwordx4 v[234:235], off
	s_add_u32 s2, s2, 0x80
	s_addc_u32 s3, s3, 0
	s_waitcnt vmcnt(8)
	s_waitcnt lgkmcnt(0)
	s_barrier
	s_setprio 1
	v_mfma_f32_16x16x32_bf16 v[132:135], v[170:173], v[198:201], v[132:135]
	v_mfma_f32_16x16x32_bf16 v[128:131], v[190:193], v[198:201], v[128:131]
	v_mfma_f32_16x16x32_bf16 v[116:119], v[170:173], v[206:209], v[116:119]
	v_mfma_f32_16x16x32_bf16 v[112:115], v[190:193], v[206:209], v[112:115]
	v_mfma_f32_16x16x32_bf16 v[100:103], v[170:173], v[214:217], v[100:103]
	v_mfma_f32_16x16x32_bf16 v[96:99], v[190:193], v[214:217], v[96:99]
	v_mfma_f32_16x16x32_bf16 v[84:87], v[170:173], v[222:225], v[84:87]
	v_mfma_f32_16x16x32_bf16 v[80:83], v[190:193], v[222:225], v[80:83]
	v_mfma_f32_16x16x32_bf16 v[132:135], v[174:177], v[202:205], v[132:135]
	v_mfma_f32_16x16x32_bf16 v[128:131], v[194:197], v[202:205], v[128:131]
	v_mfma_f32_16x16x32_bf16 v[116:119], v[174:177], v[210:213], v[116:119]
	v_mfma_f32_16x16x32_bf16 v[112:115], v[194:197], v[210:213], v[112:115]
	v_mfma_f32_16x16x32_bf16 v[100:103], v[174:177], v[218:221], v[100:103]
	v_mfma_f32_16x16x32_bf16 v[96:99], v[194:197], v[218:221], v[96:99]
	v_mfma_f32_16x16x32_bf16 v[84:87], v[174:177], v[226:229], v[84:87]
	v_mfma_f32_16x16x32_bf16 v[80:83], v[194:197], v[226:229], v[80:83]
	s_setprio 0
	s_barrier
	s_add_i32 s55, s55, 1
	s_cmp_lt_u32 s55, 7
	s_cbranch_scc1 .Lq_smp_1_k
	v_add_u32_e32 v161, 0x14000, v38
	ds_read_b128 v[170:173], v161
	ds_read_b128 v[174:177], v161 offset:1024
	ds_read_b128 v[190:193], v161 offset:2048
	ds_read_b128 v[194:197], v161 offset:3072
	ds_read_b128 v[198:201], v39 offset:0
	ds_read_b128 v[202:205], v39 offset:1024
	ds_read_b128 v[206:209], v39 offset:2048
	ds_read_b128 v[210:213], v39 offset:3072
	ds_read_b128 v[214:217], v39 offset:4096
	ds_read_b128 v[218:221], v39 offset:5120
	ds_read_b128 v[222:225], v39 offset:6144
	ds_read_b128 v[226:229], v39 offset:7168
	v_lshl_add_u64 v[178:179], s[14:15], 0, v[144:145]
	s_add_i32 m0, s1, 0xc000
	v_lshl_add_u64 v[230:231], s[14:15], 0, v[28:29]
	global_load_lds_dwordx4 v[178:179], off
	s_add_i32 m0, s1, 0xe000
	v_lshl_add_u64 v[232:233], s[2:3], 0, v[144:145]
	global_load_lds_dwordx4 v[230:231], off
	s_add_i32 m0, s1, 0x18000
	v_lshl_add_u64 v[234:235], s[2:3], 0, v[28:29]
	global_load_lds_dwordx4 v[232:233], off
	s_add_i32 m0, s1, 0x1a000
	s_add_u32 s14, s14, 0x80
	s_addc_u32 s15, s15, 0
	global_load_lds_dwordx4 v[234:235], off
	s_add_u32 s2, s2, 0x80
	s_addc_u32 s3, s3, 0
	s_waitcnt vmcnt(8)
	s_waitcnt lgkmcnt(0)
	s_barrier
	s_setprio 1
	v_mfma_f32_16x16x32_bf16 v[132:135], v[170:173], v[198:201], v[132:135]
	v_mfma_f32_16x16x32_bf16 v[128:131], v[190:193], v[198:201], v[128:131]
	v_mfma_f32_16x16x32_bf16 v[116:119], v[170:173], v[206:209], v[116:119]
	v_mfma_f32_16x16x32_bf16 v[112:115], v[190:193], v[206:209], v[112:115]
	v_mfma_f32_16x16x32_bf16 v[100:103], v[170:173], v[214:217], v[100:103]
	v_mfma_f32_16x16x32_bf16 v[96:99], v[190:193], v[214:217], v[96:99]
	v_mfma_f32_16x16x32_bf16 v[84:87], v[170:173], v[222:225], v[84:87]
	v_mfma_f32_16x16x32_bf16 v[80:83], v[190:193], v[222:225], v[80:83]
	v_mfma_f32_16x16x32_bf16 v[132:135], v[174:177], v[202:205], v[132:135]
	v_mfma_f32_16x16x32_bf16 v[128:131], v[194:197], v[202:205], v[128:131]
	v_mfma_f32_16x16x32_bf16 v[116:119], v[174:177], v[210:213], v[116:119]
	v_mfma_f32_16x16x32_bf16 v[112:115], v[194:197], v[210:213], v[112:115]
	v_mfma_f32_16x16x32_bf16 v[100:103], v[174:177], v[218:221], v[100:103]
	v_mfma_f32_16x16x32_bf16 v[96:99], v[194:197], v[218:221], v[96:99]
	v_mfma_f32_16x16x32_bf16 v[84:87], v[174:177], v[226:229], v[84:87]
	v_mfma_f32_16x16x32_bf16 v[80:83], v[194:197], v[226:229], v[80:83]
	s_setprio 0
	s_barrier
	v_add_u32_e32 v161, 0x1c000, v38
	ds_read_b128 v[170:173], v161
	ds_read_b128 v[174:177], v161 offset:1024
	ds_read_b128 v[190:193], v161 offset:2048
	ds_read_b128 v[194:197], v161 offset:3072
	ds_read_b128 v[198:201], v39 offset:32768
	ds_read_b128 v[202:205], v39 offset:33792
	ds_read_b128 v[206:209], v39 offset:34816
	ds_read_b128 v[210:213], v39 offset:35840
	ds_read_b128 v[214:217], v39 offset:36864
	ds_read_b128 v[218:221], v39 offset:37888
	ds_read_b128 v[222:225], v39 offset:38912
	ds_read_b128 v[226:229], v39 offset:39936
	s_waitcnt vmcnt(4)
	s_waitcnt lgkmcnt(0)
	s_barrier
	s_setprio 1
	v_mfma_f32_16x16x32_bf16 v[132:135], v[170:173], v[198:201], v[132:135]
	v_mfma_f32_16x16x32_bf16 v[128:131], v[190:193], v[198:201], v[128:131]
	v_mfma_f32_16x16x32_bf16 v[116:119], v[170:173], v[206:209], v[116:119]
	v_mfma_f32_16x16x32_bf16 v[112:115], v[190:193], v[206:209], v[112:115]
	v_mfma_f32_16x16x32_bf16 v[100:103], v[170:173], v[214:217], v[100:103]
	v_mfma_f32_16x16x32_bf16 v[96:99], v[190:193], v[214:217], v[96:99]
	v_mfma_f32_16x16x32_bf16 v[84:87], v[170:173], v[222:225], v[84:87]
	v_mfma_f32_16x16x32_bf16 v[80:83], v[190:193], v[222:225], v[80:83]
	v_mfma_f32_16x16x32_bf16 v[132:135], v[174:177], v[202:205], v[132:135]
	v_mfma_f32_16x16x32_bf16 v[128:131], v[194:197], v[202:205], v[128:131]
	v_mfma_f32_16x16x32_bf16 v[116:119], v[174:177], v[210:213], v[116:119]
	v_mfma_f32_16x16x32_bf16 v[112:115], v[194:197], v[210:213], v[112:115]
	v_mfma_f32_16x16x32_bf16 v[100:103], v[174:177], v[218:221], v[100:103]
	v_mfma_f32_16x16x32_bf16 v[96:99], v[194:197], v[218:221], v[96:99]
	v_mfma_f32_16x16x32_bf16 v[84:87], v[174:177], v[226:229], v[84:87]
	v_mfma_f32_16x16x32_bf16 v[80:83], v[194:197], v[226:229], v[80:83]
	s_setprio 0
	s_barrier
	v_add_u32_e32 v161, 0x10000, v38
	ds_read_b128 v[170:173], v161
	ds_read_b128 v[174:177], v161 offset:1024
	ds_read_b128 v[190:193], v161 offset:2048
	ds_read_b128 v[194:197], v161 offset:3072
	ds_read_b128 v[198:201], v39 offset:16384
	ds_read_b128 v[202:205], v39 offset:17408
	ds_read_b128 v[206:209], v39 offset:18432
	ds_read_b128 v[210:213], v39 offset:19456
	ds_read_b128 v[214:217], v39 offset:20480
	ds_read_b128 v[218:221], v39 offset:21504
	ds_read_b128 v[222:225], v39 offset:22528
	ds_read_b128 v[226:229], v39 offset:23552
	s_waitcnt vmcnt(0)
	s_waitcnt lgkmcnt(0)
	s_barrier
	s_setprio 1
	v_mfma_f32_16x16x32_bf16 v[132:135], v[170:173], v[198:201], v[132:135]
	v_mfma_f32_16x16x32_bf16 v[128:131], v[190:193], v[198:201], v[128:131]
	v_mfma_f32_16x16x32_bf16 v[116:119], v[170:173], v[206:209], v[116:119]
	v_mfma_f32_16x16x32_bf16 v[112:115], v[190:193], v[206:209], v[112:115]
	v_mfma_f32_16x16x32_bf16 v[100:103], v[170:173], v[214:217], v[100:103]
	v_mfma_f32_16x16x32_bf16 v[96:99], v[190:193], v[214:217], v[96:99]
	v_mfma_f32_16x16x32_bf16 v[84:87], v[170:173], v[222:225], v[84:87]
	v_mfma_f32_16x16x32_bf16 v[80:83], v[190:193], v[222:225], v[80:83]
	v_mfma_f32_16x16x32_bf16 v[132:135], v[174:177], v[202:205], v[132:135]
	v_mfma_f32_16x16x32_bf16 v[128:131], v[194:197], v[202:205], v[128:131]
	v_mfma_f32_16x16x32_bf16 v[116:119], v[174:177], v[210:213], v[116:119]
	v_mfma_f32_16x16x32_bf16 v[112:115], v[194:197], v[210:213], v[112:115]
	v_mfma_f32_16x16x32_bf16 v[100:103], v[174:177], v[218:221], v[100:103]
	v_mfma_f32_16x16x32_bf16 v[96:99], v[194:197], v[218:221], v[96:99]
	v_mfma_f32_16x16x32_bf16 v[84:87], v[174:177], v[226:229], v[84:87]
	v_mfma_f32_16x16x32_bf16 v[80:83], v[194:197], v[226:229], v[80:83]
	s_setprio 0
	s_barrier
	v_add_u32_e32 v161, 0x18000, v38
	ds_read_b128 v[170:173], v161
	ds_read_b128 v[174:177], v161 offset:1024
	ds_read_b128 v[190:193], v161 offset:2048
	ds_read_b128 v[194:197], v161 offset:3072
	ds_read_b128 v[198:201], v39 offset:49152
	ds_read_b128 v[202:205], v39 offset:50176
	ds_read_b128 v[206:209], v39 offset:51200
	ds_read_b128 v[210:213], v39 offset:52224
	ds_read_b128 v[214:217], v39 offset:53248
	ds_read_b128 v[218:221], v39 offset:54272
	ds_read_b128 v[222:225], v39 offset:55296
	ds_read_b128 v[226:229], v39 offset:56320
	s_waitcnt lgkmcnt(0)
	s_barrier
	s_setprio 1
	v_mfma_f32_16x16x32_bf16 v[132:135], v[170:173], v[198:201], v[132:135]
	v_mfma_f32_16x16x32_bf16 v[128:131], v[190:193], v[198:201], v[128:131]
	v_mfma_f32_16x16x32_bf16 v[116:119], v[170:173], v[206:209], v[116:119]
	v_mfma_f32_16x16x32_bf16 v[112:115], v[190:193], v[206:209], v[112:115]
	v_mfma_f32_16x16x32_bf16 v[100:103], v[170:173], v[214:217], v[100:103]
	v_mfma_f32_16x16x32_bf16 v[96:99], v[190:193], v[214:217], v[96:99]
	v_mfma_f32_16x16x32_bf16 v[84:87], v[170:173], v[222:225], v[84:87]
	v_mfma_f32_16x16x32_bf16 v[80:83], v[190:193], v[222:225], v[80:83]
	v_mfma_f32_16x16x32_bf16 v[132:135], v[174:177], v[202:205], v[132:135]
	v_mfma_f32_16x16x32_bf16 v[128:131], v[194:197], v[202:205], v[128:131]
	v_mfma_f32_16x16x32_bf16 v[116:119], v[174:177], v[210:213], v[116:119]
	v_mfma_f32_16x16x32_bf16 v[112:115], v[194:197], v[210:213], v[112:115]
	v_mfma_f32_16x16x32_bf16 v[100:103], v[174:177], v[218:221], v[100:103]
	v_mfma_f32_16x16x32_bf16 v[96:99], v[194:197], v[218:221], v[96:99]
	v_mfma_f32_16x16x32_bf16 v[84:87], v[174:177], v[226:229], v[84:87]
	v_mfma_f32_16x16x32_bf16 v[80:83], v[194:197], v[226:229], v[80:83]
	s_setprio 0
	s_barrier
	s_branch .Lq_smp_exit

.Lq_smp_2_k:
	v_add_u32_e32 v161, 0x10000, v38
	ds_read_b128 v[40:43], v161
	ds_read_b128 v[48:51], v161 offset:1024
	ds_read_b128 v[162:165], v161 offset:2048
	ds_read_b128 v[166:169], v161 offset:3072
	ds_read_b128 v[198:201], v39 offset:16384
	ds_read_b128 v[202:205], v39 offset:17408
	ds_read_b128 v[206:209], v39 offset:18432
	ds_read_b128 v[210:213], v39 offset:19456
	ds_read_b128 v[214:217], v39 offset:20480
	ds_read_b128 v[218:221], v39 offset:21504
	ds_read_b128 v[222:225], v39 offset:22528
	ds_read_b128 v[226:229], v39 offset:23552
	v_lshl_add_u64 v[178:179], s[14:15], 0, v[144:145]
	s_add_i32 m0, s1, 0x8000
	v_lshl_add_u64 v[230:231], s[14:15], 0, v[28:29]
	global_load_lds_dwordx4 v[178:179], off
	s_add_i32 m0, s1, 0xa000
	v_lshl_add_u64 v[232:233], s[2:3], 0, v[144:145]
	global_load_lds_dwordx4 v[230:231], off
	s_add_i32 m0, s1, 0x1c000
	v_lshl_add_u64 v[234:235], s[2:3], 0, v[28:29]
	global_load_lds_dwordx4 v[232:233], off
	s_add_i32 m0, s1, 0x1e000
	s_add_u32 s14, s14, 0x80
	s_addc_u32 s15, s15, 0
	global_load_lds_dwordx4 v[234:235], off
	s_add_u32 s2, s2, 0x80
	s_addc_u32 s3, s3, 0
	s_waitcnt vmcnt(8)
	s_waitcnt lgkmcnt(0)
	s_barrier
	s_setprio 1
	v_mfma_f32_16x16x32_bf16 v[76:79], v[40:43], v[198:201], v[76:79]
	v_mfma_f32_16x16x32_bf16 v[72:75], v[162:165], v[198:201], v[72:75]
	v_mfma_f32_16x16x32_bf16 v[60:63], v[40:43], v[206:209], v[60:63]
	v_mfma_f32_16x16x32_bf16 v[56:59], v[162:165], v[206:209], v[56:59]
	v_mfma_f32_16x16x32_bf16 v[32:35], v[40:43], v[214:217], v[32:35]
	v_mfma_f32_16x16x32_bf16 v[24:27], v[162:165], v[214:217], v[24:27]
	v_mfma_f32_16x16x32_bf16 v[12:15], v[40:43], v[222:225], v[12:15]
	v_mfma_f32_16x16x32_bf16 v[8:11], v[162:165], v[222:225], v[8:11]
	v_mfma_f32_16x16x32_bf16 v[76:79], v[48:51], v[202:205], v[76:79]
	v_mfma_f32_16x16x32_bf16 v[72:75], v[166:169], v[202:205], v[72:75]
	v_mfma_f32_16x16x32_bf16 v[60:63], v[48:51], v[210:213], v[60:63]
	v_mfma_f32_16x16x32_bf16 v[56:59], v[166:169], v[210:213], v[56:59]
	v_mfma_f32_16x16x32_bf16 v[32:35], v[48:51], v[218:221], v[32:35]
	v_mfma_f32_16x16x32_bf16 v[24:27], v[166:169], v[218:221], v[24:27]
	v_mfma_f32_16x16x32_bf16 v[12:15], v[48:51], v[226:229], v[12:15]
	v_mfma_f32_16x16x32_bf16 v[8:11], v[166:169], v[226:229], v[8:11]
	s_setprio 0
	s_barrier
	v_add_u32_e32 v161, 0x18000, v38
	ds_read_b128 v[40:43], v161
	ds_read_b128 v[48:51], v161 offset:1024
	ds_read_b128 v[162:165], v161 offset:2048
	ds_read_b128 v[166:169], v161 offset:3072
	ds_read_b128 v[198:201], v39 offset:49152
	ds_read_b128 v[202:205], v39 offset:50176
	ds_read_b128 v[206:209], v39 offset:51200
	ds_read_b128 v[210:213], v39 offset:52224
	ds_read_b128 v[214:217], v39 offset:53248
	ds_read_b128 v[218:221], v39 offset:54272
	ds_read_b128 v[222:225], v39 offset:55296
	ds_read_b128 v[226:229], v39 offset:56320
	v_lshl_add_u64 v[178:179], s[14:15], 0, v[144:145]
	s_add_i32 m0, s1, 0x4000
	v_lshl_add_u64 v[230:231], s[14:15], 0, v[28:29]
	global_load_lds_dwordx4 v[178:179], off
	s_add_i32 m0, s1, 0x6000
	v_lshl_add_u64 v[232:233], s[2:3], 0, v[144:145]
	global_load_lds_dwordx4 v[230:231], off
	s_add_i32 m0, s1, 0x10000
	v_lshl_add_u64 v[234:235], s[2:3], 0, v[28:29]
	global_load_lds_dwordx4 v[232:233], off
	s_add_i32 m0, s1, 0x12000
	s_add_u32 s14, s14, 0x80
	s_addc_u32 s15, s15, 0
	global_load_lds_dwordx4 v[234:235], off
	s_add_u32 s2, s2, 0x80
	s_addc_u32 s3, s3, 0
	s_waitcnt vmcnt(8)
	s_waitcnt lgkmcnt(0)
	s_barrier
	s_setprio 1
	v_mfma_f32_16x16x32_bf16 v[76:79], v[40:43], v[198:201], v[76:79]
	v_mfma_f32_16x16x32_bf16 v[72:75], v[162:165], v[198:201], v[72:75]
	v_mfma_f32_16x16x32_bf16 v[60:63], v[40:43], v[206:209], v[60:63]
	v_mfma_f32_16x16x32_bf16 v[56:59], v[162:165], v[206:209], v[56:59]
	v_mfma_f32_16x16x32_bf16 v[32:35], v[40:43], v[214:217], v[32:35]
	v_mfma_f32_16x16x32_bf16 v[24:27], v[162:165], v[214:217], v[24:27]
	v_mfma_f32_16x16x32_bf16 v[12:15], v[40:43], v[222:225], v[12:15]
	v_mfma_f32_16x16x32_bf16 v[8:11], v[162:165], v[222:225], v[8:11]
	v_mfma_f32_16x16x32_bf16 v[76:79], v[48:51], v[202:205], v[76:79]
	v_mfma_f32_16x16x32_bf16 v[72:75], v[166:169], v[202:205], v[72:75]
	v_mfma_f32_16x16x32_bf16 v[60:63], v[48:51], v[210:213], v[60:63]
	v_mfma_f32_16x16x32_bf16 v[56:59], v[166:169], v[210:213], v[56:59]
	v_mfma_f32_16x16x32_bf16 v[32:35], v[48:51], v[218:221], v[32:35]
	v_mfma_f32_16x16x32_bf16 v[24:27], v[166:169], v[218:221], v[24:27]
	v_mfma_f32_16x16x32_bf16 v[12:15], v[48:51], v[226:229], v[12:15]
	v_mfma_f32_16x16x32_bf16 v[8:11], v[166:169], v[226:229], v[8:11]
	s_setprio 0
	s_barrier
	v_add_u32_e32 v161, 0x14000, v38
	ds_read_b128 v[40:43], v161
	ds_read_b128 v[48:51], v161 offset:1024
	ds_read_b128 v[162:165], v161 offset:2048
	ds_read_b128 v[166:169], v161 offset:3072
	ds_read_b128 v[198:201], v39 offset:0
	ds_read_b128 v[202:205], v39 offset:1024
	ds_read_b128 v[206:209], v39 offset:2048
	ds_read_b128 v[210:213], v39 offset:3072
	ds_read_b128 v[214:217], v39 offset:4096
	ds_read_b128 v[218:221], v39 offset:5120
	ds_read_b128 v[222:225], v39 offset:6144
	ds_read_b128 v[226:229], v39 offset:7168
	v_lshl_add_u64 v[178:179], s[14:15], 0, v[144:145]
	s_add_i32 m0, s1, 0xc000
	v_lshl_add_u64 v[230:231], s[14:15], 0, v[28:29]
	global_load_lds_dwordx4 v[178:179], off
	s_add_i32 m0, s1, 0xe000
	v_lshl_add_u64 v[232:233], s[2:3], 0, v[144:145]
	global_load_lds_dwordx4 v[230:231], off
	s_add_i32 m0, s1, 0x18000
	v_lshl_add_u64 v[234:235], s[2:3], 0, v[28:29]
	global_load_lds_dwordx4 v[232:233], off
	s_add_i32 m0, s1, 0x1a000
	s_add_u32 s14, s14, 0x80
	s_addc_u32 s15, s15, 0
	global_load_lds_dwordx4 v[234:235], off
	s_add_u32 s2, s2, 0x80
	s_addc_u32 s3, s3, 0
	s_waitcnt vmcnt(8)
	s_waitcnt lgkmcnt(0)
	s_barrier
	s_setprio 1
	v_mfma_f32_16x16x32_bf16 v[76:79], v[40:43], v[198:201], v[76:79]
	v_mfma_f32_16x16x32_bf16 v[72:75], v[162:165], v[198:201], v[72:75]
	v_mfma_f32_16x16x32_bf16 v[60:63], v[40:43], v[206:209], v[60:63]
	v_mfma_f32_16x16x32_bf16 v[56:59], v[162:165], v[206:209], v[56:59]
	v_mfma_f32_16x16x32_bf16 v[32:35], v[40:43], v[214:217], v[32:35]
	v_mfma_f32_16x16x32_bf16 v[24:27], v[162:165], v[214:217], v[24:27]
	v_mfma_f32_16x16x32_bf16 v[12:15], v[40:43], v[222:225], v[12:15]
	v_mfma_f32_16x16x32_bf16 v[8:11], v[162:165], v[222:225], v[8:11]
	v_mfma_f32_16x16x32_bf16 v[76:79], v[48:51], v[202:205], v[76:79]
	v_mfma_f32_16x16x32_bf16 v[72:75], v[166:169], v[202:205], v[72:75]
	v_mfma_f32_16x16x32_bf16 v[60:63], v[48:51], v[210:213], v[60:63]
	v_mfma_f32_16x16x32_bf16 v[56:59], v[166:169], v[210:213], v[56:59]
	v_mfma_f32_16x16x32_bf16 v[32:35], v[48:51], v[218:221], v[32:35]
	v_mfma_f32_16x16x32_bf16 v[24:27], v[166:169], v[218:221], v[24:27]
	v_mfma_f32_16x16x32_bf16 v[12:15], v[48:51], v[226:229], v[12:15]
	v_mfma_f32_16x16x32_bf16 v[8:11], v[166:169], v[226:229], v[8:11]
	s_setprio 0
	s_barrier
	v_add_u32_e32 v161, 0x1c000, v38
	ds_read_b128 v[40:43], v161
	ds_read_b128 v[48:51], v161 offset:1024
	ds_read_b128 v[162:165], v161 offset:2048
	ds_read_b128 v[166:169], v161 offset:3072
	ds_read_b128 v[198:201], v39 offset:32768
	ds_read_b128 v[202:205], v39 offset:33792
	ds_read_b128 v[206:209], v39 offset:34816
	ds_read_b128 v[210:213], v39 offset:35840
	ds_read_b128 v[214:217], v39 offset:36864
	ds_read_b128 v[218:221], v39 offset:37888
	ds_read_b128 v[222:225], v39 offset:38912
	ds_read_b128 v[226:229], v39 offset:39936
	v_lshl_add_u64 v[178:179], s[14:15], 0, v[144:145]
	s_add_i32 m0, s1, 0x0
	v_lshl_add_u64 v[230:231], s[14:15], 0, v[28:29]
	global_load_lds_dwordx4 v[178:179], off
	s_add_i32 m0, s1, 0x2000
	v_lshl_add_u64 v[232:233], s[2:3], 0, v[144:145]
	global_load_lds_dwordx4 v[230:231], off
	s_add_i32 m0, s1, 0x14000
	v_lshl_add_u64 v[234:235], s[2:3], 0, v[28:29]
	global_load_lds_dwordx4 v[232:233], off
	s_add_i32 m0, s1, 0x16000
	s_add_u32 s14, s14, 0x80
	s_addc_u32 s15, s15, 0
	global_load_lds_dwordx4 v[234:235], off
	s_add_u32 s2, s2, 0x80
	s_addc_u32 s3, s3, 0
	s_waitcnt vmcnt(8)
	s_waitcnt lgkmcnt(0)
	s_barrier
	s_setprio 1
	v_mfma_f32_16x16x32_bf16 v[76:79], v[40:43], v[198:201], v[76:79]
	v_mfma_f32_16x16x32_bf16 v[72:75], v[162:165], v[198:201], v[72:75]
	v_mfma_f32_16x16x32_bf16 v[60:63], v[40:43], v[206:209], v[60:63]
	v_mfma_f32_16x16x32_bf16 v[56:59], v[162:165], v[206:209], v[56:59]
	v_mfma_f32_16x16x32_bf16 v[32:35], v[40:43], v[214:217], v[32:35]
	v_mfma_f32_16x16x32_bf16 v[24:27], v[162:165], v[214:217], v[24:27]
	v_mfma_f32_16x16x32_bf16 v[12:15], v[40:43], v[222:225], v[12:15]
	v_mfma_f32_16x16x32_bf16 v[8:11], v[162:165], v[222:225], v[8:11]
	v_mfma_f32_16x16x32_bf16 v[76:79], v[48:51], v[202:205], v[76:79]
	v_mfma_f32_16x16x32_bf16 v[72:75], v[166:169], v[202:205], v[72:75]
	v_mfma_f32_16x16x32_bf16 v[60:63], v[48:51], v[210:213], v[60:63]
	v_mfma_f32_16x16x32_bf16 v[56:59], v[166:169], v[210:213], v[56:59]
	v_mfma_f32_16x16x32_bf16 v[32:35], v[48:51], v[218:221], v[32:35]
	v_mfma_f32_16x16x32_bf16 v[24:27], v[166:169], v[218:221], v[24:27]
	v_mfma_f32_16x16x32_bf16 v[12:15], v[48:51], v[226:229], v[12:15]
	v_mfma_f32_16x16x32_bf16 v[8:11], v[166:169], v[226:229], v[8:11]
	s_setprio 0
	s_barrier
	s_add_i32 s55, s55, 1
	s_cmp_lt_u32 s55, 7
	s_cbranch_scc1 .Lq_smp_2_k
	v_add_u32_e32 v161, 0x10000, v38
	ds_read_b128 v[40:43], v161
	ds_read_b128 v[48:51], v161 offset:1024
	ds_read_b128 v[162:165], v161 offset:2048
	ds_read_b128 v[166:169], v161 offset:3072
	ds_read_b128 v[198:201], v39 offset:16384
	ds_read_b128 v[202:205], v39 offset:17408
	ds_read_b128 v[206:209], v39 offset:18432
	ds_read_b128 v[210:213], v39 offset:19456
	ds_read_b128 v[214:217], v39 offset:20480
	ds_read_b128 v[218:221], v39 offset:21504
	ds_read_b128 v[222:225], v39 offset:22528
	ds_read_b128 v[226:229], v39 offset:23552
	v_lshl_add_u64 v[178:179], s[14:15], 0, v[144:145]
	s_add_i32 m0, s1, 0x8000
	v_lshl_add_u64 v[230:231], s[14:15], 0, v[28:29]
	global_load_lds_dwordx4 v[178:179], off
	s_add_i32 m0, s1, 0xa000
	v_lshl_add_u64 v[232:233], s[2:3], 0, v[144:145]
	global_load_lds_dwordx4 v[230:231], off
	s_add_i32 m0, s1, 0x1c000
	v_lshl_add_u64 v[234:235], s[2:3], 0, v[28:29]
	global_load_lds_dwordx4 v[232:233], off
	s_add_i32 m0, s1, 0x1e000
	s_add_u32 s14, s14, 0x80
	s_addc_u32 s15, s15, 0
	global_load_lds_dwordx4 v[234:235], off
	s_add_u32 s2, s2, 0x80
	s_addc_u32 s3, s3, 0
	s_waitcnt vmcnt(8)
	s_waitcnt lgkmcnt(0)
	s_barrier
	s_setprio 1
	v_mfma_f32_16x16x32_bf16 v[76:79], v[40:43], v[198:201], v[76:79]
	v_mfma_f32_16x16x32_bf16 v[72:75], v[162:165], v[198:201], v[72:75]
	v_mfma_f32_16x16x32_bf16 v[60:63], v[40:43], v[206:209], v[60:63]
	v_mfma_f32_16x16x32_bf16 v[56:59], v[162:165], v[206:209], v[56:59]
	v_mfma_f32_16x16x32_bf16 v[32:35], v[40:43], v[214:217], v[32:35]
	v_mfma_f32_16x16x32_bf16 v[24:27], v[162:165], v[214:217], v[24:27]
	v_mfma_f32_16x16x32_bf16 v[12:15], v[40:43], v[222:225], v[12:15]
	v_mfma_f32_16x16x32_bf16 v[8:11], v[162:165], v[222:225], v[8:11]
	v_mfma_f32_16x16x32_bf16 v[76:79], v[48:51], v[202:205], v[76:79]
	v_mfma_f32_16x16x32_bf16 v[72:75], v[166:169], v[202:205], v[72:75]
	v_mfma_f32_16x16x32_bf16 v[60:63], v[48:51], v[210:213], v[60:63]
	v_mfma_f32_16x16x32_bf16 v[56:59], v[166:169], v[210:213], v[56:59]
	v_mfma_f32_16x16x32_bf16 v[32:35], v[48:51], v[218:221], v[32:35]
	v_mfma_f32_16x16x32_bf16 v[24:27], v[166:169], v[218:221], v[24:27]
	v_mfma_f32_16x16x32_bf16 v[12:15], v[48:51], v[226:229], v[12:15]
	v_mfma_f32_16x16x32_bf16 v[8:11], v[166:169], v[226:229], v[8:11]
	s_setprio 0
	s_barrier
	v_add_u32_e32 v161, 0x18000, v38
	ds_read_b128 v[40:43], v161
	ds_read_b128 v[48:51], v161 offset:1024
	ds_read_b128 v[162:165], v161 offset:2048
	ds_read_b128 v[166:169], v161 offset:3072
	ds_read_b128 v[198:201], v39 offset:49152
	ds_read_b128 v[202:205], v39 offset:50176
	ds_read_b128 v[206:209], v39 offset:51200
	ds_read_b128 v[210:213], v39 offset:52224
	ds_read_b128 v[214:217], v39 offset:53248
	ds_read_b128 v[218:221], v39 offset:54272
	ds_read_b128 v[222:225], v39 offset:55296
	ds_read_b128 v[226:229], v39 offset:56320
	s_waitcnt vmcnt(4)
	s_waitcnt lgkmcnt(0)
	s_barrier
	s_setprio 1
	v_mfma_f32_16x16x32_bf16 v[76:79], v[40:43], v[198:201], v[76:79]
	v_mfma_f32_16x16x32_bf16 v[72:75], v[162:165], v[198:201], v[72:75]
	v_mfma_f32_16x16x32_bf16 v[60:63], v[40:43], v[206:209], v[60:63]
	v_mfma_f32_16x16x32_bf16 v[56:59], v[162:165], v[206:209], v[56:59]
	v_mfma_f32_16x16x32_bf16 v[32:35], v[40:43], v[214:217], v[32:35]
	v_mfma_f32_16x16x32_bf16 v[24:27], v[162:165], v[214:217], v[24:27]
	v_mfma_f32_16x16x32_bf16 v[12:15], v[40:43], v[222:225], v[12:15]
	v_mfma_f32_16x16x32_bf16 v[8:11], v[162:165], v[222:225], v[8:11]
	v_mfma_f32_16x16x32_bf16 v[76:79], v[48:51], v[202:205], v[76:79]
	v_mfma_f32_16x16x32_bf16 v[72:75], v[166:169], v[202:205], v[72:75]
	v_mfma_f32_16x16x32_bf16 v[60:63], v[48:51], v[210:213], v[60:63]
	v_mfma_f32_16x16x32_bf16 v[56:59], v[166:169], v[210:213], v[56:59]
	v_mfma_f32_16x16x32_bf16 v[32:35], v[48:51], v[218:221], v[32:35]
	v_mfma_f32_16x16x32_bf16 v[24:27], v[166:169], v[218:221], v[24:27]
	v_mfma_f32_16x16x32_bf16 v[12:15], v[48:51], v[226:229], v[12:15]
	v_mfma_f32_16x16x32_bf16 v[8:11], v[166:169], v[226:229], v[8:11]
	s_setprio 0
	s_barrier
	v_add_u32_e32 v161, 0x14000, v38
	ds_read_b128 v[40:43], v161
	ds_read_b128 v[48:51], v161 offset:1024
	ds_read_b128 v[162:165], v161 offset:2048
	ds_read_b128 v[166:169], v161 offset:3072
	ds_read_b128 v[198:201], v39 offset:0
	ds_read_b128 v[202:205], v39 offset:1024
	ds_read_b128 v[206:209], v39 offset:2048
	ds_read_b128 v[210:213], v39 offset:3072
	ds_read_b128 v[214:217], v39 offset:4096
	ds_read_b128 v[218:221], v39 offset:5120
	ds_read_b128 v[222:225], v39 offset:6144
	ds_read_b128 v[226:229], v39 offset:7168
	s_waitcnt vmcnt(0)
	s_waitcnt lgkmcnt(0)
	s_barrier
	s_setprio 1
	v_mfma_f32_16x16x32_bf16 v[76:79], v[40:43], v[198:201], v[76:79]
	v_mfma_f32_16x16x32_bf16 v[72:75], v[162:165], v[198:201], v[72:75]
	v_mfma_f32_16x16x32_bf16 v[60:63], v[40:43], v[206:209], v[60:63]
	v_mfma_f32_16x16x32_bf16 v[56:59], v[162:165], v[206:209], v[56:59]
	v_mfma_f32_16x16x32_bf16 v[32:35], v[40:43], v[214:217], v[32:35]
	v_mfma_f32_16x16x32_bf16 v[24:27], v[162:165], v[214:217], v[24:27]
	v_mfma_f32_16x16x32_bf16 v[12:15], v[40:43], v[222:225], v[12:15]
	v_mfma_f32_16x16x32_bf16 v[8:11], v[162:165], v[222:225], v[8:11]
	v_mfma_f32_16x16x32_bf16 v[76:79], v[48:51], v[202:205], v[76:79]
	v_mfma_f32_16x16x32_bf16 v[72:75], v[166:169], v[202:205], v[72:75]
	v_mfma_f32_16x16x32_bf16 v[60:63], v[48:51], v[210:213], v[60:63]
	v_mfma_f32_16x16x32_bf16 v[56:59], v[166:169], v[210:213], v[56:59]
	v_mfma_f32_16x16x32_bf16 v[32:35], v[48:51], v[218:221], v[32:35]
	v_mfma_f32_16x16x32_bf16 v[24:27], v[166:169], v[218:221], v[24:27]
	v_mfma_f32_16x16x32_bf16 v[12:15], v[48:51], v[226:229], v[12:15]
	v_mfma_f32_16x16x32_bf16 v[8:11], v[166:169], v[226:229], v[8:11]
	s_setprio 0
	s_barrier
	v_add_u32_e32 v161, 0x1c000, v38
	ds_read_b128 v[40:43], v161
	ds_read_b128 v[48:51], v161 offset:1024
	ds_read_b128 v[162:165], v161 offset:2048
	ds_read_b128 v[166:169], v161 offset:3072
	ds_read_b128 v[198:201], v39 offset:32768
	ds_read_b128 v[202:205], v39 offset:33792
	ds_read_b128 v[206:209], v39 offset:34816
	ds_read_b128 v[210:213], v39 offset:35840
	ds_read_b128 v[214:217], v39 offset:36864
	ds_read_b128 v[218:221], v39 offset:37888
	ds_read_b128 v[222:225], v39 offset:38912
	ds_read_b128 v[226:229], v39 offset:39936
	s_waitcnt lgkmcnt(0)
	s_barrier
	s_setprio 1
	v_mfma_f32_16x16x32_bf16 v[76:79], v[40:43], v[198:201], v[76:79]
	v_mfma_f32_16x16x32_bf16 v[72:75], v[162:165], v[198:201], v[72:75]
	v_mfma_f32_16x16x32_bf16 v[60:63], v[40:43], v[206:209], v[60:63]
	v_mfma_f32_16x16x32_bf16 v[56:59], v[162:165], v[206:209], v[56:59]
	v_mfma_f32_16x16x32_bf16 v[32:35], v[40:43], v[214:217], v[32:35]
	v_mfma_f32_16x16x32_bf16 v[24:27], v[162:165], v[214:217], v[24:27]
	v_mfma_f32_16x16x32_bf16 v[12:15], v[40:43], v[222:225], v[12:15]
	v_mfma_f32_16x16x32_bf16 v[8:11], v[162:165], v[222:225], v[8:11]
	v_mfma_f32_16x16x32_bf16 v[76:79], v[48:51], v[202:205], v[76:79]
	v_mfma_f32_16x16x32_bf16 v[72:75], v[166:169], v[202:205], v[72:75]
	v_mfma_f32_16x16x32_bf16 v[60:63], v[48:51], v[210:213], v[60:63]
	v_mfma_f32_16x16x32_bf16 v[56:59], v[166:169], v[210:213], v[56:59]
	v_mfma_f32_16x16x32_bf16 v[32:35], v[48:51], v[218:221], v[32:35]
	v_mfma_f32_16x16x32_bf16 v[24:27], v[166:169], v[218:221], v[24:27]
	v_mfma_f32_16x16x32_bf16 v[12:15], v[48:51], v[226:229], v[12:15]
	v_mfma_f32_16x16x32_bf16 v[8:11], v[166:169], v[226:229], v[8:11]
	s_setprio 0
	s_barrier
	s_branch .Lq_smp_exit

.Lq_smp_3_k:
	v_add_u32_e32 v161, 0x14000, v38
	ds_read_b128 v[170:173], v161
	ds_read_b128 v[174:177], v161 offset:1024
	ds_read_b128 v[190:193], v161 offset:2048
	ds_read_b128 v[194:197], v161 offset:3072
	ds_read_b128 v[198:201], v39 offset:16384
	ds_read_b128 v[202:205], v39 offset:17408
	ds_read_b128 v[206:209], v39 offset:18432
	ds_read_b128 v[210:213], v39 offset:19456
	ds_read_b128 v[214:217], v39 offset:20480
	ds_read_b128 v[218:221], v39 offset:21504
	ds_read_b128 v[222:225], v39 offset:22528
	ds_read_b128 v[226:229], v39 offset:23552
	v_lshl_add_u64 v[178:179], s[14:15], 0, v[144:145]
	s_add_i32 m0, s1, 0x8000
	v_lshl_add_u64 v[230:231], s[14:15], 0, v[28:29]
	global_load_lds_dwordx4 v[178:179], off
	s_add_i32 m0, s1, 0xa000
	v_lshl_add_u64 v[232:233], s[2:3], 0, v[144:145]
	global_load_lds_dwordx4 v[230:231], off
	s_add_i32 m0, s1, 0x18000
	v_lshl_add_u64 v[234:235], s[2:3], 0, v[28:29]
	global_load_lds_dwordx4 v[232:233], off
	s_add_i32 m0, s1, 0x1a000
	s_add_u32 s14, s14, 0x80
	s_addc_u32 s15, s15, 0
	global_load_lds_dwordx4 v[234:235], off
	s_add_u32 s2, s2, 0x80
	s_addc_u32 s3, s3, 0
	s_waitcnt vmcnt(8)
	s_waitcnt lgkmcnt(0)
	s_barrier
	s_setprio 1
	v_mfma_f32_16x16x32_bf16 v[52:55], v[170:173], v[206:209], v[52:55]
	v_mfma_f32_16x16x32_bf16 v[44:47], v[190:193], v[206:209], v[44:47]
	v_mfma_f32_16x16x32_bf16 v[20:23], v[170:173], v[214:217], v[20:23]
	v_mfma_f32_16x16x32_bf16 v[16:19], v[190:193], v[214:217], v[16:19]
	v_mfma_f32_16x16x32_bf16 v[4:7], v[170:173], v[222:225], v[4:7]
	v_mfma_f32_16x16x32_bf16 v[0:3], v[190:193], v[222:225], v[0:3]
	v_mfma_f32_16x16x32_bf16 v[68:71], v[170:173], v[198:201], v[68:71]
	v_mfma_f32_16x16x32_bf16 v[64:67], v[190:193], v[198:201], v[64:67]
	v_mfma_f32_16x16x32_bf16 v[52:55], v[174:177], v[210:213], v[52:55]
	v_mfma_f32_16x16x32_bf16 v[44:47], v[194:197], v[210:213], v[44:47]
	v_mfma_f32_16x16x32_bf16 v[20:23], v[174:177], v[218:221], v[20:23]
	v_mfma_f32_16x16x32_bf16 v[16:19], v[194:197], v[218:221], v[16:19]
	v_mfma_f32_16x16x32_bf16 v[4:7], v[174:177], v[226:229], v[4:7]
	v_mfma_f32_16x16x32_bf16 v[0:3], v[194:197], v[226:229], v[0:3]
	v_mfma_f32_16x16x32_bf16 v[68:71], v[174:177], v[202:205], v[68:71]
	v_mfma_f32_16x16x32_bf16 v[64:67], v[194:197], v[202:205], v[64:67]
	s_setprio 0
	s_barrier
	v_add_u32_e32 v161, 0x1c000, v38
	ds_read_b128 v[170:173], v161
	ds_read_b128 v[174:177], v161 offset:1024
	ds_read_b128 v[190:193], v161 offset:2048
	ds_read_b128 v[194:197], v161 offset:3072
	ds_read_b128 v[198:201], v39 offset:49152
	ds_read_b128 v[202:205], v39 offset:50176
	ds_read_b128 v[206:209], v39 offset:51200
	ds_read_b128 v[210:213], v39 offset:52224
	ds_read_b128 v[214:217], v39 offset:53248
	ds_read_b128 v[218:221], v39 offset:54272
	ds_read_b128 v[222:225], v39 offset:55296
	ds_read_b128 v[226:229], v39 offset:56320
	v_lshl_add_u64 v[178:179], s[14:15], 0, v[144:145]
	s_add_i32 m0, s1, 0x4000
	v_lshl_add_u64 v[230:231], s[14:15], 0, v[28:29]
	global_load_lds_dwordx4 v[178:179], off
	s_add_i32 m0, s1, 0x6000
	v_lshl_add_u64 v[232:233], s[2:3], 0, v[144:145]
	global_load_lds_dwordx4 v[230:231], off
	s_add_i32 m0, s1, 0x14000
	v_lshl_add_u64 v[234:235], s[2:3], 0, v[28:29]
	global_load_lds_dwordx4 v[232:233], off
	s_add_i32 m0, s1, 0x16000
	s_add_u32 s14, s14, 0x80
	s_addc_u32 s15, s15, 0
	global_load_lds_dwordx4 v[234:235], off
	s_add_u32 s2, s2, 0x80
	s_addc_u32 s3, s3, 0
	s_waitcnt vmcnt(8)
	s_waitcnt lgkmcnt(0)
	s_barrier
	s_setprio 1
	v_mfma_f32_16x16x32_bf16 v[52:55], v[170:173], v[206:209], v[52:55]
	v_mfma_f32_16x16x32_bf16 v[44:47], v[190:193], v[206:209], v[44:47]
	v_mfma_f32_16x16x32_bf16 v[20:23], v[170:173], v[214:217], v[20:23]
	v_mfma_f32_16x16x32_bf16 v[16:19], v[190:193], v[214:217], v[16:19]
	v_mfma_f32_16x16x32_bf16 v[4:7], v[170:173], v[222:225], v[4:7]
	v_mfma_f32_16x16x32_bf16 v[0:3], v[190:193], v[222:225], v[0:3]
	v_mfma_f32_16x16x32_bf16 v[68:71], v[170:173], v[198:201], v[68:71]
	v_mfma_f32_16x16x32_bf16 v[64:67], v[190:193], v[198:201], v[64:67]
	v_mfma_f32_16x16x32_bf16 v[52:55], v[174:177], v[210:213], v[52:55]
	v_mfma_f32_16x16x32_bf16 v[44:47], v[194:197], v[210:213], v[44:47]
	v_mfma_f32_16x16x32_bf16 v[20:23], v[174:177], v[218:221], v[20:23]
	v_mfma_f32_16x16x32_bf16 v[16:19], v[194:197], v[218:221], v[16:19]
	v_mfma_f32_16x16x32_bf16 v[4:7], v[174:177], v[226:229], v[4:7]
	v_mfma_f32_16x16x32_bf16 v[0:3], v[194:197], v[226:229], v[0:3]
	v_mfma_f32_16x16x32_bf16 v[68:71], v[174:177], v[202:205], v[68:71]
	v_mfma_f32_16x16x32_bf16 v[64:67], v[194:197], v[202:205], v[64:67]
	s_setprio 0
	s_barrier
	v_add_u32_e32 v161, 0x10000, v38
	ds_read_b128 v[170:173], v161
	ds_read_b128 v[174:177], v161 offset:1024
	ds_read_b128 v[190:193], v161 offset:2048
	ds_read_b128 v[194:197], v161 offset:3072
	ds_read_b128 v[198:201], v39 offset:0
	ds_read_b128 v[202:205], v39 offset:1024
	ds_read_b128 v[206:209], v39 offset:2048
	ds_read_b128 v[210:213], v39 offset:3072
	ds_read_b128 v[214:217], v39 offset:4096
	ds_read_b128 v[218:221], v39 offset:5120
	ds_read_b128 v[222:225], v39 offset:6144
	ds_read_b128 v[226:229], v39 offset:7168
	v_lshl_add_u64 v[178:179], s[14:15], 0, v[144:145]
	s_add_i32 m0, s1, 0xc000
	v_lshl_add_u64 v[230:231], s[14:15], 0, v[28:29]
	global_load_lds_dwordx4 v[178:179], off
	s_add_i32 m0, s1, 0xe000
	v_lshl_add_u64 v[232:233], s[2:3], 0, v[144:145]
	global_load_lds_dwordx4 v[230:231], off
	s_add_i32 m0, s1, 0x1c000
	v_lshl_add_u64 v[234:235], s[2:3], 0, v[28:29]
	global_load_lds_dwordx4 v[232:233], off
	s_add_i32 m0, s1, 0x1e000
	s_add_u32 s14, s14, 0x80
	s_addc_u32 s15, s15, 0
	global_load_lds_dwordx4 v[234:235], off
	s_add_u32 s2, s2, 0x80
	s_addc_u32 s3, s3, 0
	s_waitcnt vmcnt(8)
	s_waitcnt lgkmcnt(0)
	s_barrier
	s_setprio 1
	v_mfma_f32_16x16x32_bf16 v[52:55], v[170:173], v[206:209], v[52:55]
	v_mfma_f32_16x16x32_bf16 v[44:47], v[190:193], v[206:209], v[44:47]
	v_mfma_f32_16x16x32_bf16 v[20:23], v[170:173], v[214:217], v[20:23]
	v_mfma_f32_16x16x32_bf16 v[16:19], v[190:193], v[214:217], v[16:19]
	v_mfma_f32_16x16x32_bf16 v[4:7], v[170:173], v[222:225], v[4:7]
	v_mfma_f32_16x16x32_bf16 v[0:3], v[190:193], v[222:225], v[0:3]
	v_mfma_f32_16x16x32_bf16 v[68:71], v[170:173], v[198:201], v[68:71]
	v_mfma_f32_16x16x32_bf16 v[64:67], v[190:193], v[198:201], v[64:67]
	v_mfma_f32_16x16x32_bf16 v[52:55], v[174:177], v[210:213], v[52:55]
	v_mfma_f32_16x16x32_bf16 v[44:47], v[194:197], v[210:213], v[44:47]
	v_mfma_f32_16x16x32_bf16 v[20:23], v[174:177], v[218:221], v[20:23]
	v_mfma_f32_16x16x32_bf16 v[16:19], v[194:197], v[218:221], v[16:19]
	v_mfma_f32_16x16x32_bf16 v[4:7], v[174:177], v[226:229], v[4:7]
	v_mfma_f32_16x16x32_bf16 v[0:3], v[194:197], v[226:229], v[0:3]
	v_mfma_f32_16x16x32_bf16 v[68:71], v[174:177], v[202:205], v[68:71]
	v_mfma_f32_16x16x32_bf16 v[64:67], v[194:197], v[202:205], v[64:67]
	s_setprio 0
	s_barrier
	v_add_u32_e32 v161, 0x18000, v38
	ds_read_b128 v[170:173], v161
	ds_read_b128 v[174:177], v161 offset:1024
	ds_read_b128 v[190:193], v161 offset:2048
	ds_read_b128 v[194:197], v161 offset:3072
	ds_read_b128 v[198:201], v39 offset:32768
	ds_read_b128 v[202:205], v39 offset:33792
	ds_read_b128 v[206:209], v39 offset:34816
	ds_read_b128 v[210:213], v39 offset:35840
	ds_read_b128 v[214:217], v39 offset:36864
	ds_read_b128 v[218:221], v39 offset:37888
	ds_read_b128 v[222:225], v39 offset:38912
	ds_read_b128 v[226:229], v39 offset:39936
	v_lshl_add_u64 v[178:179], s[14:15], 0, v[144:145]
	s_add_i32 m0, s1, 0x0
	v_lshl_add_u64 v[230:231], s[14:15], 0, v[28:29]
	global_load_lds_dwordx4 v[178:179], off
	s_add_i32 m0, s1, 0x2000
	v_lshl_add_u64 v[232:233], s[2:3], 0, v[144:145]
	global_load_lds_dwordx4 v[230:231], off
	s_add_i32 m0, s1, 0x10000
	v_lshl_add_u64 v[234:235], s[2:3], 0, v[28:29]
	global_load_lds_dwordx4 v[232:233], off
	s_add_i32 m0, s1, 0x12000
	s_add_u32 s14, s14, 0x80
	s_addc_u32 s15, s15, 0
	global_load_lds_dwordx4 v[234:235], off
	s_add_u32 s2, s2, 0x80
	s_addc_u32 s3, s3, 0
	s_waitcnt vmcnt(8)
	s_waitcnt lgkmcnt(0)
	s_barrier
	s_setprio 1
	v_mfma_f32_16x16x32_bf16 v[52:55], v[170:173], v[206:209], v[52:55]
	v_mfma_f32_16x16x32_bf16 v[44:47], v[190:193], v[206:209], v[44:47]
	v_mfma_f32_16x16x32_bf16 v[20:23], v[170:173], v[214:217], v[20:23]
	v_mfma_f32_16x16x32_bf16 v[16:19], v[190:193], v[214:217], v[16:19]
	v_mfma_f32_16x16x32_bf16 v[4:7], v[170:173], v[222:225], v[4:7]
	v_mfma_f32_16x16x32_bf16 v[0:3], v[190:193], v[222:225], v[0:3]
	v_mfma_f32_16x16x32_bf16 v[68:71], v[170:173], v[198:201], v[68:71]
	v_mfma_f32_16x16x32_bf16 v[64:67], v[190:193], v[198:201], v[64:67]
	v_mfma_f32_16x16x32_bf16 v[52:55], v[174:177], v[210:213], v[52:55]
	v_mfma_f32_16x16x32_bf16 v[44:47], v[194:197], v[210:213], v[44:47]
	v_mfma_f32_16x16x32_bf16 v[20:23], v[174:177], v[218:221], v[20:23]
	v_mfma_f32_16x16x32_bf16 v[16:19], v[194:197], v[218:221], v[16:19]
	v_mfma_f32_16x16x32_bf16 v[4:7], v[174:177], v[226:229], v[4:7]
	v_mfma_f32_16x16x32_bf16 v[0:3], v[194:197], v[226:229], v[0:3]
	v_mfma_f32_16x16x32_bf16 v[68:71], v[174:177], v[202:205], v[68:71]
	v_mfma_f32_16x16x32_bf16 v[64:67], v[194:197], v[202:205], v[64:67]
	s_setprio 0
	s_barrier
	s_add_i32 s55, s55, 1
	s_cmp_lt_u32 s55, 7
	s_cbranch_scc1 .Lq_smp_3_k
	v_add_u32_e32 v161, 0x14000, v38
	ds_read_b128 v[170:173], v161
	ds_read_b128 v[174:177], v161 offset:1024
	ds_read_b128 v[190:193], v161 offset:2048
	ds_read_b128 v[194:197], v161 offset:3072
	ds_read_b128 v[198:201], v39 offset:16384
	ds_read_b128 v[202:205], v39 offset:17408
	ds_read_b128 v[206:209], v39 offset:18432
	ds_read_b128 v[210:213], v39 offset:19456
	ds_read_b128 v[214:217], v39 offset:20480
	ds_read_b128 v[218:221], v39 offset:21504
	ds_read_b128 v[222:225], v39 offset:22528
	ds_read_b128 v[226:229], v39 offset:23552
	v_lshl_add_u64 v[178:179], s[14:15], 0, v[144:145]
	s_add_i32 m0, s1, 0x8000
	v_lshl_add_u64 v[230:231], s[14:15], 0, v[28:29]
	global_load_lds_dwordx4 v[178:179], off
	s_add_i32 m0, s1, 0xa000
	v_lshl_add_u64 v[232:233], s[2:3], 0, v[144:145]
	global_load_lds_dwordx4 v[230:231], off
	s_add_i32 m0, s1, 0x18000
	v_lshl_add_u64 v[234:235], s[2:3], 0, v[28:29]
	global_load_lds_dwordx4 v[232:233], off
	s_add_i32 m0, s1, 0x1a000
	s_add_u32 s14, s14, 0x80
	s_addc_u32 s15, s15, 0
	global_load_lds_dwordx4 v[234:235], off
	s_add_u32 s2, s2, 0x80
	s_addc_u32 s3, s3, 0
	s_waitcnt vmcnt(8)
	s_waitcnt lgkmcnt(0)
	s_barrier
	s_setprio 1
	v_mfma_f32_16x16x32_bf16 v[52:55], v[170:173], v[206:209], v[52:55]
	v_mfma_f32_16x16x32_bf16 v[44:47], v[190:193], v[206:209], v[44:47]
	v_mfma_f32_16x16x32_bf16 v[20:23], v[170:173], v[214:217], v[20:23]
	v_mfma_f32_16x16x32_bf16 v[16:19], v[190:193], v[214:217], v[16:19]
	v_mfma_f32_16x16x32_bf16 v[4:7], v[170:173], v[222:225], v[4:7]
	v_mfma_f32_16x16x32_bf16 v[0:3], v[190:193], v[222:225], v[0:3]
	v_mfma_f32_16x16x32_bf16 v[68:71], v[170:173], v[198:201], v[68:71]
	v_mfma_f32_16x16x32_bf16 v[64:67], v[190:193], v[198:201], v[64:67]
	v_mfma_f32_16x16x32_bf16 v[52:55], v[174:177], v[210:213], v[52:55]
	v_mfma_f32_16x16x32_bf16 v[44:47], v[194:197], v[210:213], v[44:47]
	v_mfma_f32_16x16x32_bf16 v[20:23], v[174:177], v[218:221], v[20:23]
	v_mfma_f32_16x16x32_bf16 v[16:19], v[194:197], v[218:221], v[16:19]
	v_mfma_f32_16x16x32_bf16 v[4:7], v[174:177], v[226:229], v[4:7]
	v_mfma_f32_16x16x32_bf16 v[0:3], v[194:197], v[226:229], v[0:3]
	v_mfma_f32_16x16x32_bf16 v[68:71], v[174:177], v[202:205], v[68:71]
	v_mfma_f32_16x16x32_bf16 v[64:67], v[194:197], v[202:205], v[64:67]
	s_setprio 0
	s_barrier
	v_add_u32_e32 v161, 0x1c000, v38
	ds_read_b128 v[170:173], v161
	ds_read_b128 v[174:177], v161 offset:1024
	ds_read_b128 v[190:193], v161 offset:2048
	ds_read_b128 v[194:197], v161 offset:3072
	ds_read_b128 v[198:201], v39 offset:49152
	ds_read_b128 v[202:205], v39 offset:50176
	ds_read_b128 v[206:209], v39 offset:51200
	ds_read_b128 v[210:213], v39 offset:52224
	ds_read_b128 v[214:217], v39 offset:53248
	ds_read_b128 v[218:221], v39 offset:54272
	ds_read_b128 v[222:225], v39 offset:55296
	ds_read_b128 v[226:229], v39 offset:56320
	s_waitcnt vmcnt(4)
	s_waitcnt lgkmcnt(0)
	s_barrier
	s_setprio 1
	v_mfma_f32_16x16x32_bf16 v[52:55], v[170:173], v[206:209], v[52:55]
	v_mfma_f32_16x16x32_bf16 v[44:47], v[190:193], v[206:209], v[44:47]
	v_mfma_f32_16x16x32_bf16 v[20:23], v[170:173], v[214:217], v[20:23]
	v_mfma_f32_16x16x32_bf16 v[16:19], v[190:193], v[214:217], v[16:19]
	v_mfma_f32_16x16x32_bf16 v[4:7], v[170:173], v[222:225], v[4:7]
	v_mfma_f32_16x16x32_bf16 v[0:3], v[190:193], v[222:225], v[0:3]
	v_mfma_f32_16x16x32_bf16 v[68:71], v[170:173], v[198:201], v[68:71]
	v_mfma_f32_16x16x32_bf16 v[64:67], v[190:193], v[198:201], v[64:67]
	v_mfma_f32_16x16x32_bf16 v[52:55], v[174:177], v[210:213], v[52:55]
	v_mfma_f32_16x16x32_bf16 v[44:47], v[194:197], v[210:213], v[44:47]
	v_mfma_f32_16x16x32_bf16 v[20:23], v[174:177], v[218:221], v[20:23]
	v_mfma_f32_16x16x32_bf16 v[16:19], v[194:197], v[218:221], v[16:19]
	v_mfma_f32_16x16x32_bf16 v[4:7], v[174:177], v[226:229], v[4:7]
	v_mfma_f32_16x16x32_bf16 v[0:3], v[194:197], v[226:229], v[0:3]
	v_mfma_f32_16x16x32_bf16 v[68:71], v[174:177], v[202:205], v[68:71]
	v_mfma_f32_16x16x32_bf16 v[64:67], v[194:197], v[202:205], v[64:67]
	s_setprio 0
	s_barrier
	v_add_u32_e32 v161, 0x10000, v38
	ds_read_b128 v[170:173], v161
	ds_read_b128 v[174:177], v161 offset:1024
	ds_read_b128 v[190:193], v161 offset:2048
	ds_read_b128 v[194:197], v161 offset:3072
	ds_read_b128 v[198:201], v39 offset:0
	ds_read_b128 v[202:205], v39 offset:1024
	ds_read_b128 v[206:209], v39 offset:2048
	ds_read_b128 v[210:213], v39 offset:3072
	ds_read_b128 v[214:217], v39 offset:4096
	ds_read_b128 v[218:221], v39 offset:5120
	ds_read_b128 v[222:225], v39 offset:6144
	ds_read_b128 v[226:229], v39 offset:7168
	s_waitcnt vmcnt(0)
	s_waitcnt lgkmcnt(0)
	s_barrier
	s_setprio 1
	v_mfma_f32_16x16x32_bf16 v[52:55], v[170:173], v[206:209], v[52:55]
	v_mfma_f32_16x16x32_bf16 v[44:47], v[190:193], v[206:209], v[44:47]
	v_mfma_f32_16x16x32_bf16 v[20:23], v[170:173], v[214:217], v[20:23]
	v_mfma_f32_16x16x32_bf16 v[16:19], v[190:193], v[214:217], v[16:19]
	v_mfma_f32_16x16x32_bf16 v[4:7], v[170:173], v[222:225], v[4:7]
	v_mfma_f32_16x16x32_bf16 v[0:3], v[190:193], v[222:225], v[0:3]
	v_mfma_f32_16x16x32_bf16 v[68:71], v[170:173], v[198:201], v[68:71]
	v_mfma_f32_16x16x32_bf16 v[64:67], v[190:193], v[198:201], v[64:67]
	v_mfma_f32_16x16x32_bf16 v[52:55], v[174:177], v[210:213], v[52:55]
	v_mfma_f32_16x16x32_bf16 v[44:47], v[194:197], v[210:213], v[44:47]
	v_mfma_f32_16x16x32_bf16 v[20:23], v[174:177], v[218:221], v[20:23]
	v_mfma_f32_16x16x32_bf16 v[16:19], v[194:197], v[218:221], v[16:19]
	v_mfma_f32_16x16x32_bf16 v[4:7], v[174:177], v[226:229], v[4:7]
	v_mfma_f32_16x16x32_bf16 v[0:3], v[194:197], v[226:229], v[0:3]
	v_mfma_f32_16x16x32_bf16 v[68:71], v[174:177], v[202:205], v[68:71]
	v_mfma_f32_16x16x32_bf16 v[64:67], v[194:197], v[202:205], v[64:67]
	s_setprio 0
	s_barrier
	v_add_u32_e32 v161, 0x18000, v38
	ds_read_b128 v[170:173], v161
	ds_read_b128 v[174:177], v161 offset:1024
	ds_read_b128 v[190:193], v161 offset:2048
	ds_read_b128 v[194:197], v161 offset:3072
	ds_read_b128 v[198:201], v39 offset:32768
	ds_read_b128 v[202:205], v39 offset:33792
	ds_read_b128 v[206:209], v39 offset:34816
	ds_read_b128 v[210:213], v39 offset:35840
	ds_read_b128 v[214:217], v39 offset:36864
	ds_read_b128 v[218:221], v39 offset:37888
	ds_read_b128 v[222:225], v39 offset:38912
	ds_read_b128 v[226:229], v39 offset:39936
	s_waitcnt lgkmcnt(0)
	s_barrier
	s_setprio 1
	v_mfma_f32_16x16x32_bf16 v[52:55], v[170:173], v[206:209], v[52:55]
	v_mfma_f32_16x16x32_bf16 v[44:47], v[190:193], v[206:209], v[44:47]
	v_mfma_f32_16x16x32_bf16 v[20:23], v[170:173], v[214:217], v[20:23]
	v_mfma_f32_16x16x32_bf16 v[16:19], v[190:193], v[214:217], v[16:19]
	v_mfma_f32_16x16x32_bf16 v[4:7], v[170:173], v[222:225], v[4:7]
	v_mfma_f32_16x16x32_bf16 v[0:3], v[190:193], v[222:225], v[0:3]
	v_mfma_f32_16x16x32_bf16 v[68:71], v[170:173], v[198:201], v[68:71]
	v_mfma_f32_16x16x32_bf16 v[64:67], v[190:193], v[198:201], v[64:67]
	v_mfma_f32_16x16x32_bf16 v[52:55], v[174:177], v[210:213], v[52:55]
	v_mfma_f32_16x16x32_bf16 v[44:47], v[194:197], v[210:213], v[44:47]
	v_mfma_f32_16x16x32_bf16 v[20:23], v[174:177], v[218:221], v[20:23]
	v_mfma_f32_16x16x32_bf16 v[16:19], v[194:197], v[218:221], v[16:19]
	v_mfma_f32_16x16x32_bf16 v[4:7], v[174:177], v[226:229], v[4:7]
	v_mfma_f32_16x16x32_bf16 v[0:3], v[194:197], v[226:229], v[0:3]
	v_mfma_f32_16x16x32_bf16 v[68:71], v[174:177], v[202:205], v[68:71]
	v_mfma_f32_16x16x32_bf16 v[64:67], v[194:197], v[202:205], v[64:67]
	s_setprio 0
	s_barrier
	s_branch .Lq_smp_exit
